# baseline (speedup 1.0000x reference)
.LBB0_109:
	s_lshl_b32 s62, s86, 3
	v_cvt_f32_u32_e32 v2, s62
	s_sub_i32 s65, 0, s62
	s_abs_i32 s63, s85
	s_ashr_i32 s64, s85, 31
	v_rcp_iflag_f32_e32 v2, v2
	v_bfe_i32 v5, v171, 27, 1
	v_lshlrev_b32_e32 v169, 4, v171
	v_lshrrev_b32_e32 v5, 22, v5
	v_mul_f32_e32 v2, 0x4f7ffffe, v2
	v_cvt_u32_f32_e32 v2, v2
	v_add_u32_e32 v5, v169, v5
	v_and_b32_e32 v5, 0xfffffc00, v5
	v_sub_u32_e32 v5, v169, v5
	v_readfirstlane_b32 s68, v2
	s_mul_i32 s65, s65, s68
	s_mul_hi_u32 s65, s68, s65
	s_add_i32 s68, s68, s65
	s_mul_hi_u32 s65, s63, s68
	s_mul_i32 s68, s65, s62
	s_sub_i32 s63, s63, s68
	s_add_i32 s69, s65, 1
	s_sub_i32 s68, s63, s62
	s_cmp_ge_u32 s63, s62
	s_cselect_b32 s65, s69, s65
	s_cselect_b32 s63, s68, s63
	s_add_i32 s68, s65, 1
	s_cmp_ge_u32 s63, s62
	s_cselect_b32 s63, s68, s65
	s_xor_b32 s65, s63, s64
	s_sub_i32 s70, s65, s64
	v_lshrrev_b32_e32 v6, 4, v5
	s_mul_i32 s62, s70, s62
	v_bitop3_b32 v5, v6, v5, 32 bitop3:0x6c
	s_sub_i32 s62, s85, s62
	v_ashrrev_i32_e32 v6, 31, v5
	s_ashr_i32 s89, s62, 3
	s_lshl_b32 s62, s62, 8
	v_lshrrev_b32_e32 v6, 26, v6
	s_and_b32 s71, s62, 0x700
	s_lshl_b32 s62, s89, 8
	v_ashrrev_i32_e32 v2, 31, v171
	v_add_u32_e32 v6, v5, v6
	v_lshrrev_b32_e32 v2, 26, v2
	v_ashrrev_i32_e32 v133, 6, v6
	v_and_b32_e32 v6, 0xc0, v6
	s_ashr_i32 s63, s62, 31
	v_and_b32_e32 v3, 15, v0
	v_and_b32_e32 v4, 48, v0
	v_add_u32_e32 v2, v171, v2
	v_sub_u32_e32 v5, v5, v6
	v_and_b32_e32 v6, 32, v0
	v_lshlrev_b32_e32 v10, 2, v0
	s_lshl_b64 s[72:73], s[62:63], 6
	v_lshlrev_b32_e32 v0, 6, v0
	s_lshl_b32 s63, s65, 11
	v_ashrrev_i32_e32 v131, 6, v2
	v_lshlrev_b32_e32 v3, 6, v3
	v_and_b32_e32 v10, 32, v10
	v_and_b32_e32 v0, 0x3c0, v0
	s_or_b32 s63, s63, s71
	s_lshl_b32 s64, s64, 11
	v_or_b32_e32 v9, v3, v4
	v_bitop3_b32 v3, v3, v10, v4 bitop3:0x36
	v_bitop3_b32 v4, v0, v10, v4 bitop3:0x36
	s_sub_i32 s64, s63, s64
	v_lshlrev_b32_e32 v0, 15, v131
	s_ashr_i32 s65, s64, 31
	v_and_b32_e32 v0, 0xffff0000, v0
	v_ashrrev_i16_sdwa v5, v167, sext(v5) dst_sel:DWORD dst_unused:UNUSED_PAD src0_sel:DWORD src1_sel:BYTE_0
	s_lshl_b64 s[64:65], s[64:65], 12
	v_lshl_add_u32 v0, v133, 12, v0
	v_bfe_i32 v134, v5, 0, 16
	v_and_or_b32 v0, v2, 64, v0
	s_add_u32 s64, s54, s64
	s_waitcnt vmcnt(0)
	v_lshl_add_u32 v164, v134, 1, v0
	s_addc_u32 s65, s55, s65
	v_lshlrev_b32_e32 v14, 13, v1
	v_lshl_add_u64 v[0:1], s[64:65], 0, v[164:165]
	s_mul_i32 s64, s4, 0x1800
	s_mul_hi_u32 s63, s4, 0x1800
	s_add_u32 s64, s64, s72
	s_addc_u32 s63, s63, s73
	s_add_u32 s64, s66, s64
	v_bfe_i32 v7, v171, 6, 1
	s_addc_u32 s65, s67, s63
	s_lshl_b64 s[68:69], s[4:5], 12
	v_and_b32_e32 v7, s4, v7
	v_lshrrev_b32_e32 v8, 7, v171
	s_add_u32 s4, s68, s72
	v_add_lshl_u32 v7, v7, v8, 10
	v_lshlrev_b32_e32 v8, 6, v171
	s_addc_u32 s63, s69, s73
	v_and_b32_e32 v5, 0x3f0, v169
	v_and_b32_e32 v8, 0x3000, v8
	v_bitop3_b32 v11, v9, s77, v10 bitop3:0xde
	v_bitop3_b32 v12, v9, s78, v10 bitop3:0xde
	v_bitop3_b32 v13, v9, s79, v10 bitop3:0xde
	v_bitop3_b32 v9, v9, s80, v10 bitop3:0xde
	v_or_b32_e32 v10, 0x800, v14
	v_or_b32_e32 v15, 0x1000, v14
	s_waitcnt vmcnt(0)
	v_or_b32_e32 v16, 0x1800, v14
	v_lshl_add_u64 v[128:129], v[0:1], 0, s[20:21]
	s_add_u32 s66, s66, s4
	v_mov_b32_e32 v0, 0
	v_bitop3_b32 v164, v5, v7, v6 bitop3:0xde
	s_addc_u32 s67, s67, s63
	s_mov_b32 s4, -2
	v_add_u32_e32 v138, v11, v8
	v_add_u32_e32 v192, v3, v14
	v_add_u32_e32 v191, v4, v10
	v_add_u32_e32 v190, v4, v15
	v_add_u32_e32 v189, v4, v16
	v_add_u32_e32 v137, 0xc000, v169
	v_add_u32_e32 v136, 0xe000, v169
	v_add_u32_e32 v135, v12, v8
	v_add_u32_e32 v188, 0x10000, v169
	v_add_u32_e32 v187, 0x12000, v169
	v_add_u32_e32 v186, 0x2000, v169
	v_add_u32_e32 v185, 0x14000, v169
	v_add_u32_e32 v184, 0x16000, v169
	v_add_u32_e32 v130, v13, v8
	v_add_u32_e32 v183, 0x4000, v169
	v_add_u32_e32 v182, 0x6000, v169
	v_add_u32_e32 v132, v9, v8
	v_add_u32_e32 v181, 0x18000, v169
	v_add_u32_e32 v180, 0x1a000, v169
	v_add_u32_e32 v179, 0x8000, v169
	v_add_u32_e32 v177, 0xa000, v169
	v_add_u32_e32 v175, 0x1c000, v169
	v_add_u32_e32 v173, 0x1e000, v169
	v_mov_b32_e32 v1, v0
	v_mov_b32_e32 v2, v0
	v_mov_b32_e32 v3, v0
	v_mov_b32_e32 v4, v0
	v_mov_b32_e32 v5, v0
	v_mov_b32_e32 v6, v0
	v_mov_b32_e32 v7, v0
	v_mov_b32_e32 v8, v0
	v_mov_b32_e32 v9, v0
	v_mov_b32_e32 v10, v0
	v_mov_b32_e32 v11, v0
	v_mov_b32_e32 v12, v0
	v_mov_b32_e32 v13, v0
	v_mov_b32_e32 v14, v0
	v_mov_b32_e32 v15, v0
	v_mov_b32_e32 v16, v0
	v_mov_b32_e32 v17, v0
	v_mov_b32_e32 v18, v0
	v_mov_b32_e32 v19, v0
	v_mov_b32_e32 v20, v0
	v_mov_b32_e32 v21, v0
	v_mov_b32_e32 v22, v0
	v_mov_b32_e32 v23, v0
	v_mov_b32_e32 v24, v0
	v_mov_b32_e32 v25, v0
	v_mov_b32_e32 v26, v0
	v_mov_b32_e32 v27, v0
	v_mov_b32_e32 v28, v0
	v_mov_b32_e32 v29, v0
	v_mov_b32_e32 v30, v0
	v_mov_b32_e32 v31, v0
	v_mov_b32_e32 v32, v0
	v_mov_b32_e32 v33, v0
	v_mov_b32_e32 v34, v0
	v_mov_b32_e32 v35, v0
	v_mov_b32_e32 v36, v0
	v_mov_b32_e32 v37, v0
	v_mov_b32_e32 v38, v0
	v_mov_b32_e32 v39, v0
	v_mov_b32_e32 v40, v0
	v_mov_b32_e32 v41, v0
	v_mov_b32_e32 v42, v0
	v_mov_b32_e32 v43, v0
	v_mov_b32_e32 v44, v0
	v_mov_b32_e32 v45, v0
	v_mov_b32_e32 v46, v0
	v_mov_b32_e32 v47, v0
	v_mov_b32_e32 v48, v0
	v_mov_b32_e32 v49, v0
	v_mov_b32_e32 v50, v0
	v_mov_b32_e32 v51, v0
	v_mov_b32_e32 v52, v0
	v_mov_b32_e32 v53, v0
	v_mov_b32_e32 v54, v0
	v_mov_b32_e32 v55, v0
	v_mov_b32_e32 v56, v0
	v_mov_b32_e32 v57, v0
	v_mov_b32_e32 v58, v0
	v_mov_b32_e32 v59, v0
	v_mov_b32_e32 v60, v0
	v_mov_b32_e32 v61, v0
	v_mov_b32_e32 v62, v0
	v_mov_b32_e32 v63, v0
	v_mov_b32_e32 v64, v0
	v_mov_b32_e32 v65, v0
	v_mov_b32_e32 v66, v0
	v_mov_b32_e32 v67, v0
	v_mov_b32_e32 v68, v0
	v_mov_b32_e32 v69, v0
	v_mov_b32_e32 v70, v0
	v_mov_b32_e32 v71, v0
	v_mov_b32_e32 v72, v0
	v_mov_b32_e32 v73, v0
	v_mov_b32_e32 v74, v0
	v_mov_b32_e32 v75, v0
	v_mov_b32_e32 v76, v0
	v_mov_b32_e32 v77, v0
	v_mov_b32_e32 v78, v0
	v_mov_b32_e32 v79, v0
	v_mov_b32_e32 v80, v0
	v_mov_b32_e32 v81, v0
	v_mov_b32_e32 v82, v0
	v_mov_b32_e32 v83, v0
	v_mov_b32_e32 v84, v0
	v_mov_b32_e32 v85, v0
	v_mov_b32_e32 v86, v0
	v_mov_b32_e32 v87, v0
	v_mov_b32_e32 v88, v0
	v_mov_b32_e32 v89, v0
	v_mov_b32_e32 v90, v0
	v_mov_b32_e32 v91, v0
	v_mov_b32_e32 v92, v0
	v_mov_b32_e32 v93, v0
	v_mov_b32_e32 v94, v0
	v_mov_b32_e32 v95, v0
	v_mov_b32_e32 v96, v0
	v_mov_b32_e32 v97, v0
	v_mov_b32_e32 v98, v0
	v_mov_b32_e32 v99, v0
	v_mov_b32_e32 v100, v0
	v_mov_b32_e32 v101, v0
	v_mov_b32_e32 v102, v0
	v_mov_b32_e32 v103, v0
	v_mov_b32_e32 v104, v0
	v_mov_b32_e32 v105, v0
	v_mov_b32_e32 v106, v0
	v_mov_b32_e32 v107, v0
	v_mov_b32_e32 v108, v0
	v_mov_b32_e32 v109, v0
	v_mov_b32_e32 v110, v0
	v_mov_b32_e32 v111, v0
	v_mov_b32_e32 v112, v0
	v_mov_b32_e32 v113, v0
	v_mov_b32_e32 v114, v0
	v_mov_b32_e32 v115, v0
	v_mov_b32_e32 v116, v0
	v_mov_b32_e32 v117, v0
	v_mov_b32_e32 v118, v0
	v_mov_b32_e32 v119, v0
	v_mov_b32_e32 v120, v0
	v_mov_b32_e32 v121, v0
	v_mov_b32_e32 v122, v0
	v_mov_b32_e32 v123, v0
	v_mov_b32_e32 v124, v0
	v_mov_b32_e32 v125, v0
	v_mov_b32_e32 v126, v0
	v_mov_b32_e32 v127, v0
	s_barrier
	v_readlane_b32 s98, v242, 1
	s_nop 3
	s_cmp_lt_u32 s98, 4
	s_cbranch_scc1 .Lprio_110
	s_setprio 1
.Lprio_110:
	v_readfirstlane_b32 s63, v137
	v_lshl_add_u64 v[142:143], v[128:129], 0, s[22:23]
	s_mov_b32 m0, s63
	v_readfirstlane_b32 s63, v136
	global_load_lds_dwordx4 v[142:143], off
	v_lshl_add_u64 v[142:143], v[128:129], 0, s[24:25]
	s_mov_b32 m0, s63
	s_nop 0
	global_load_lds_dwordx4 v[142:143], off
.LBB0_110:
	ds_read_b128 v[140:143], v138
	ds_read_b128 v[144:147], v138 offset:1024
	ds_read_b128 v[148:151], v138 offset:2048
	ds_read_b128 v[152:155], v138 offset:3072
	ds_read_b128 v[156:159], v192
	ds_read_b128 v[160:163], v192 offset:1024
	ds_read_b128 v[194:197], v191
	ds_read_b128 v[198:201], v191 offset:1024
	ds_read_b128 v[202:205], v190
	ds_read_b128 v[206:209], v190 offset:1024
	ds_read_b128 v[210:213], v189
	ds_read_b128 v[214:217], v189 offset:1024
	s_waitcnt lgkmcnt(8)
	s_waitcnt vmcnt(10)
	s_barrier
	s_waitcnt lgkmcnt(0)
	s_waitcnt lgkmcnt(0)
	v_mfma_f32_16x16x32_bf16 v[124:127], v[140:143], v[156:159], v[124:127]
	v_mfma_f32_16x16x32_bf16 v[120:123], v[148:151], v[156:159], v[120:123]
	v_mfma_f32_16x16x32_bf16 v[116:119], v[140:143], v[194:197], v[116:119]
	v_mfma_f32_16x16x32_bf16 v[112:115], v[148:151], v[194:197], v[112:115]
	v_mfma_f32_16x16x32_bf16 v[108:111], v[140:143], v[202:205], v[108:111]
	v_mfma_f32_16x16x32_bf16 v[104:107], v[148:151], v[202:205], v[104:107]
	v_mfma_f32_16x16x32_bf16 v[100:103], v[140:143], v[210:213], v[100:103]
	v_mfma_f32_16x16x32_bf16 v[96:99], v[148:151], v[210:213], v[96:99]
	v_mfma_f32_16x16x32_bf16 v[124:127], v[144:147], v[160:163], v[124:127]
	v_mfma_f32_16x16x32_bf16 v[120:123], v[152:155], v[160:163], v[120:123]
	v_mfma_f32_16x16x32_bf16 v[116:119], v[144:147], v[198:201], v[116:119]
	v_mfma_f32_16x16x32_bf16 v[112:115], v[152:155], v[198:201], v[112:115]
	v_mfma_f32_16x16x32_bf16 v[108:111], v[144:147], v[206:209], v[108:111]
	v_mfma_f32_16x16x32_bf16 v[104:107], v[152:155], v[206:209], v[104:107]
	v_mfma_f32_16x16x32_bf16 v[100:103], v[144:147], v[214:217], v[100:103]
	v_mfma_f32_16x16x32_bf16 v[96:99], v[152:155], v[214:217], v[96:99]
	s_barrier
	v_readfirstlane_b32 s63, v188
	v_lshl_add_u64 v[234:235], s[66:67], 0, v[164:165]
	s_mov_b32 m0, s63
	v_readfirstlane_b32 s63, v187
	ds_read_b128 v[218:221], v135
	ds_read_b128 v[222:225], v135 offset:1024
	ds_read_b128 v[226:229], v135 offset:2048
	ds_read_b128 v[230:233], v135 offset:3072
	global_load_lds_dwordx4 v[234:235], off
	v_lshl_add_u64 v[236:237], v[234:235], 0, s[10:11]
	s_mov_b32 m0, s63
	s_nop 0
	global_load_lds_dwordx4 v[236:237], off
	v_readfirstlane_b32 s63, v169
	v_lshl_add_u64 v[236:237], v[128:129], 0, s[26:27]
	s_mov_b32 m0, s63
	v_readfirstlane_b32 s63, v186
	global_load_lds_dwordx4 v[236:237], off
	v_lshl_add_u64 v[236:237], v[128:129], 0, s[28:29]
	s_mov_b32 m0, s63
	s_nop 0
	global_load_lds_dwordx4 v[236:237], off
	s_waitcnt vmcnt(12)
	s_barrier
	s_waitcnt lgkmcnt(0)
	s_waitcnt lgkmcnt(0)
	v_mfma_f32_16x16x32_bf16 v[92:95], v[218:221], v[156:159], v[92:95]
	v_mfma_f32_16x16x32_bf16 v[88:91], v[226:229], v[156:159], v[88:91]
	v_mfma_f32_16x16x32_bf16 v[84:87], v[218:221], v[194:197], v[84:87]
	v_mfma_f32_16x16x32_bf16 v[80:83], v[226:229], v[194:197], v[80:83]
	v_mfma_f32_16x16x32_bf16 v[76:79], v[218:221], v[202:205], v[76:79]
	v_mfma_f32_16x16x32_bf16 v[72:75], v[226:229], v[202:205], v[72:75]
	v_mfma_f32_16x16x32_bf16 v[68:71], v[218:221], v[210:213], v[68:71]
	v_mfma_f32_16x16x32_bf16 v[64:67], v[226:229], v[210:213], v[64:67]
	v_mfma_f32_16x16x32_bf16 v[92:95], v[222:225], v[160:163], v[92:95]
	v_mfma_f32_16x16x32_bf16 v[88:91], v[230:233], v[160:163], v[88:91]
	v_mfma_f32_16x16x32_bf16 v[84:87], v[222:225], v[198:201], v[84:87]
	v_mfma_f32_16x16x32_bf16 v[80:83], v[230:233], v[198:201], v[80:83]
	v_mfma_f32_16x16x32_bf16 v[76:79], v[222:225], v[206:209], v[76:79]
	v_mfma_f32_16x16x32_bf16 v[72:75], v[230:233], v[206:209], v[72:75]
	v_mfma_f32_16x16x32_bf16 v[68:71], v[222:225], v[214:217], v[68:71]
	v_mfma_f32_16x16x32_bf16 v[64:67], v[230:233], v[214:217], v[64:67]
	s_barrier
	ds_read_b128 v[156:159], v192 offset:16384
	ds_read_b128 v[160:163], v192 offset:17408
	ds_read_b128 v[194:197], v191 offset:16384
	ds_read_b128 v[198:201], v191 offset:17408
	ds_read_b128 v[202:205], v190 offset:16384
	ds_read_b128 v[206:209], v190 offset:17408
	ds_read_b128 v[210:213], v189 offset:16384
	ds_read_b128 v[214:217], v189 offset:17408
	v_readfirstlane_b32 s63, v185
	v_lshl_add_u64 v[236:237], v[234:235], 0, s[30:31]
	s_mov_b32 m0, s63
	v_readfirstlane_b32 s63, v184
	global_load_lds_dwordx4 v[236:237], off
	v_lshl_add_u64 v[236:237], v[234:235], 0, s[34:35]
	s_mov_b32 m0, s63
	s_nop 0
	global_load_lds_dwordx4 v[236:237], off
	s_barrier
	s_waitcnt lgkmcnt(0)
	s_waitcnt lgkmcnt(0)
	v_mfma_f32_16x16x32_bf16 v[60:63], v[140:143], v[156:159], v[60:63]
	v_mfma_f32_16x16x32_bf16 v[56:59], v[148:151], v[156:159], v[56:59]
	v_mfma_f32_16x16x32_bf16 v[52:55], v[140:143], v[194:197], v[52:55]
	v_mfma_f32_16x16x32_bf16 v[48:51], v[148:151], v[194:197], v[48:51]
	v_mfma_f32_16x16x32_bf16 v[44:47], v[140:143], v[202:205], v[44:47]
	v_mfma_f32_16x16x32_bf16 v[40:43], v[148:151], v[202:205], v[40:43]
	v_mfma_f32_16x16x32_bf16 v[36:39], v[140:143], v[210:213], v[36:39]
	v_mfma_f32_16x16x32_bf16 v[32:35], v[148:151], v[210:213], v[32:35]
	v_mfma_f32_16x16x32_bf16 v[60:63], v[144:147], v[160:163], v[60:63]
	v_mfma_f32_16x16x32_bf16 v[56:59], v[152:155], v[160:163], v[56:59]
	v_mfma_f32_16x16x32_bf16 v[52:55], v[144:147], v[198:201], v[52:55]
	v_mfma_f32_16x16x32_bf16 v[48:51], v[152:155], v[198:201], v[48:51]
	v_mfma_f32_16x16x32_bf16 v[44:47], v[144:147], v[206:209], v[44:47]
	v_mfma_f32_16x16x32_bf16 v[40:43], v[152:155], v[206:209], v[40:43]
	v_mfma_f32_16x16x32_bf16 v[36:39], v[144:147], v[214:217], v[36:39]
	v_mfma_f32_16x16x32_bf16 v[32:35], v[152:155], v[214:217], v[32:35]
	s_barrier
	v_readfirstlane_b32 s63, v183
	v_lshl_add_u64 v[142:143], v[128:129], 0, s[40:41]
	s_mov_b32 m0, s63
	v_readfirstlane_b32 s63, v182
	global_load_lds_dwordx4 v[142:143], off
	s_mov_b32 m0, s63
	s_nop 0
	global_load_lds_dwordx4 v[128:129], off
	s_waitcnt vmcnt(12)
	s_barrier
	v_mfma_f32_16x16x32_bf16 v[28:31], v[218:221], v[156:159], v[28:31]
	v_mfma_f32_16x16x32_bf16 v[24:27], v[226:229], v[156:159], v[24:27]
	v_mfma_f32_16x16x32_bf16 v[20:23], v[218:221], v[194:197], v[20:23]
	v_mfma_f32_16x16x32_bf16 v[16:19], v[226:229], v[194:197], v[16:19]
	v_mfma_f32_16x16x32_bf16 v[12:15], v[218:221], v[202:205], v[12:15]
	v_mfma_f32_16x16x32_bf16 v[8:11], v[226:229], v[202:205], v[8:11]
	v_mfma_f32_16x16x32_bf16 v[4:7], v[218:221], v[210:213], v[4:7]
	v_mfma_f32_16x16x32_bf16 v[0:3], v[226:229], v[210:213], v[0:3]
	v_mfma_f32_16x16x32_bf16 v[28:31], v[222:225], v[160:163], v[28:31]
	v_mfma_f32_16x16x32_bf16 v[24:27], v[230:233], v[160:163], v[24:27]
	v_mfma_f32_16x16x32_bf16 v[20:23], v[222:225], v[198:201], v[20:23]
	v_mfma_f32_16x16x32_bf16 v[16:19], v[230:233], v[198:201], v[16:19]
	v_mfma_f32_16x16x32_bf16 v[12:15], v[222:225], v[206:209], v[12:15]
	v_mfma_f32_16x16x32_bf16 v[8:11], v[230:233], v[206:209], v[8:11]
	v_mfma_f32_16x16x32_bf16 v[4:7], v[222:225], v[214:217], v[4:7]
	v_mfma_f32_16x16x32_bf16 v[0:3], v[230:233], v[214:217], v[0:3]
	s_barrier
	ds_read_b128 v[140:143], v130
	ds_read_b128 v[144:147], v130 offset:1024
	ds_read_b128 v[148:151], v130 offset:2048
	ds_read_b128 v[152:155], v130 offset:3072
	ds_read_b128 v[156:159], v192 offset:32768
	ds_read_b128 v[160:163], v192 offset:33792
	ds_read_b128 v[194:197], v191 offset:32768
	ds_read_b128 v[198:201], v191 offset:33792
	ds_read_b128 v[202:205], v190 offset:32768
	ds_read_b128 v[206:209], v190 offset:33792
	ds_read_b128 v[210:213], v189 offset:32768
	ds_read_b128 v[214:217], v189 offset:33792
	s_waitcnt lgkmcnt(8)
	s_waitcnt vmcnt(10)
	s_barrier
	s_waitcnt lgkmcnt(0)
	s_waitcnt lgkmcnt(0)
	v_mfma_f32_16x16x32_bf16 v[124:127], v[140:143], v[156:159], v[124:127]
	v_mfma_f32_16x16x32_bf16 v[120:123], v[148:151], v[156:159], v[120:123]
	v_mfma_f32_16x16x32_bf16 v[116:119], v[140:143], v[194:197], v[116:119]
	v_mfma_f32_16x16x32_bf16 v[112:115], v[148:151], v[194:197], v[112:115]
	v_mfma_f32_16x16x32_bf16 v[108:111], v[140:143], v[202:205], v[108:111]
	v_mfma_f32_16x16x32_bf16 v[104:107], v[148:151], v[202:205], v[104:107]
	v_mfma_f32_16x16x32_bf16 v[100:103], v[140:143], v[210:213], v[100:103]
	v_mfma_f32_16x16x32_bf16 v[96:99], v[148:151], v[210:213], v[96:99]
	v_mfma_f32_16x16x32_bf16 v[124:127], v[144:147], v[160:163], v[124:127]
	v_mfma_f32_16x16x32_bf16 v[120:123], v[152:155], v[160:163], v[120:123]
	v_mfma_f32_16x16x32_bf16 v[116:119], v[144:147], v[198:201], v[116:119]
	v_mfma_f32_16x16x32_bf16 v[112:115], v[152:155], v[198:201], v[112:115]
	v_mfma_f32_16x16x32_bf16 v[108:111], v[144:147], v[206:209], v[108:111]
	v_mfma_f32_16x16x32_bf16 v[104:107], v[152:155], v[206:209], v[104:107]
	v_mfma_f32_16x16x32_bf16 v[100:103], v[144:147], v[214:217], v[100:103]
	v_mfma_f32_16x16x32_bf16 v[96:99], v[152:155], v[214:217], v[96:99]
	s_barrier
	v_readfirstlane_b32 s63, v181
	v_lshl_add_u64 v[234:235], s[64:65], 0, v[164:165]
	s_mov_b32 m0, s63
	v_readfirstlane_b32 s63, v180
	ds_read_b128 v[218:221], v132
	ds_read_b128 v[222:225], v132 offset:1024
	ds_read_b128 v[226:229], v132 offset:2048
	ds_read_b128 v[230:233], v132 offset:3072
	global_load_lds_dwordx4 v[234:235], off
	v_lshl_add_u64 v[236:237], v[234:235], 0, s[10:11]
	s_mov_b32 m0, s63
	s_nop 0
	global_load_lds_dwordx4 v[236:237], off
	v_readfirstlane_b32 s63, v179
	v_lshl_add_u64 v[236:237], v[128:129], 0, s[44:45]
	s_mov_b32 m0, s63
	v_readfirstlane_b32 s63, v177
	global_load_lds_dwordx4 v[236:237], off
	v_lshl_add_u64 v[236:237], v[128:129], 0, s[46:47]
	s_mov_b32 m0, s63
	s_nop 0
	global_load_lds_dwordx4 v[236:237], off
	s_waitcnt vmcnt(12)
	s_barrier
	s_waitcnt lgkmcnt(0)
	s_waitcnt lgkmcnt(0)
	v_mfma_f32_16x16x32_bf16 v[92:95], v[218:221], v[156:159], v[92:95]
	v_mfma_f32_16x16x32_bf16 v[88:91], v[226:229], v[156:159], v[88:91]
	v_mfma_f32_16x16x32_bf16 v[84:87], v[218:221], v[194:197], v[84:87]
	v_mfma_f32_16x16x32_bf16 v[80:83], v[226:229], v[194:197], v[80:83]
	v_mfma_f32_16x16x32_bf16 v[76:79], v[218:221], v[202:205], v[76:79]
	v_mfma_f32_16x16x32_bf16 v[72:75], v[226:229], v[202:205], v[72:75]
	v_mfma_f32_16x16x32_bf16 v[68:71], v[218:221], v[210:213], v[68:71]
	v_mfma_f32_16x16x32_bf16 v[64:67], v[226:229], v[210:213], v[64:67]
	v_mfma_f32_16x16x32_bf16 v[92:95], v[222:225], v[160:163], v[92:95]
	v_mfma_f32_16x16x32_bf16 v[88:91], v[230:233], v[160:163], v[88:91]
	v_mfma_f32_16x16x32_bf16 v[84:87], v[222:225], v[198:201], v[84:87]
	v_mfma_f32_16x16x32_bf16 v[80:83], v[230:233], v[198:201], v[80:83]
	v_mfma_f32_16x16x32_bf16 v[76:79], v[222:225], v[206:209], v[76:79]
	v_mfma_f32_16x16x32_bf16 v[72:75], v[230:233], v[206:209], v[72:75]
	v_mfma_f32_16x16x32_bf16 v[68:71], v[222:225], v[214:217], v[68:71]
	v_mfma_f32_16x16x32_bf16 v[64:67], v[230:233], v[214:217], v[64:67]
	s_barrier
	ds_read_b128 v[156:159], v192 offset:49152
	ds_read_b128 v[160:163], v192 offset:50176
	ds_read_b128 v[194:197], v191 offset:49152
	ds_read_b128 v[198:201], v191 offset:50176
	ds_read_b128 v[202:205], v190 offset:49152
	ds_read_b128 v[206:209], v190 offset:50176
	ds_read_b128 v[210:213], v189 offset:49152
	ds_read_b128 v[214:217], v189 offset:50176
	v_readfirstlane_b32 s63, v175
	v_lshl_add_u64 v[236:237], v[234:235], 0, s[30:31]
	s_mov_b32 m0, s63
	v_readfirstlane_b32 s63, v173
	global_load_lds_dwordx4 v[236:237], off
	v_lshl_add_u64 v[236:237], v[234:235], 0, s[34:35]
	s_mov_b32 m0, s63
	s_nop 0
	global_load_lds_dwordx4 v[236:237], off
	s_barrier
	s_waitcnt lgkmcnt(0)
	s_waitcnt lgkmcnt(0)
	v_mfma_f32_16x16x32_bf16 v[60:63], v[140:143], v[156:159], v[60:63]
	v_mfma_f32_16x16x32_bf16 v[56:59], v[148:151], v[156:159], v[56:59]
	v_mfma_f32_16x16x32_bf16 v[52:55], v[140:143], v[194:197], v[52:55]
	v_mfma_f32_16x16x32_bf16 v[48:51], v[148:151], v[194:197], v[48:51]
	v_mfma_f32_16x16x32_bf16 v[44:47], v[140:143], v[202:205], v[44:47]
	v_mfma_f32_16x16x32_bf16 v[40:43], v[148:151], v[202:205], v[40:43]
	v_mfma_f32_16x16x32_bf16 v[36:39], v[140:143], v[210:213], v[36:39]
	v_mfma_f32_16x16x32_bf16 v[32:35], v[148:151], v[210:213], v[32:35]
	v_mfma_f32_16x16x32_bf16 v[60:63], v[144:147], v[160:163], v[60:63]
	v_mfma_f32_16x16x32_bf16 v[56:59], v[152:155], v[160:163], v[56:59]
	v_mfma_f32_16x16x32_bf16 v[52:55], v[144:147], v[198:201], v[52:55]
	v_mfma_f32_16x16x32_bf16 v[48:51], v[152:155], v[198:201], v[48:51]
	v_mfma_f32_16x16x32_bf16 v[44:47], v[144:147], v[206:209], v[44:47]
	v_mfma_f32_16x16x32_bf16 v[40:43], v[152:155], v[206:209], v[40:43]
	v_mfma_f32_16x16x32_bf16 v[36:39], v[144:147], v[214:217], v[36:39]
	v_mfma_f32_16x16x32_bf16 v[32:35], v[152:155], v[214:217], v[32:35]
	s_barrier
	v_lshl_add_u64 v[128:129], v[128:129], 0, s[56:57]
	v_readfirstlane_b32 s63, v137
	v_lshl_add_u64 v[142:143], v[128:129], 0, s[22:23]
	s_mov_b32 m0, s63
	v_readfirstlane_b32 s63, v136
	global_load_lds_dwordx4 v[142:143], off
	v_lshl_add_u64 v[142:143], v[128:129], 0, s[24:25]
	s_mov_b32 m0, s63
	s_nop 0
	global_load_lds_dwordx4 v[142:143], off
	s_waitcnt vmcnt(12)
	s_barrier
	v_mfma_f32_16x16x32_bf16 v[28:31], v[218:221], v[156:159], v[28:31]
	v_mfma_f32_16x16x32_bf16 v[24:27], v[226:229], v[156:159], v[24:27]
	v_mfma_f32_16x16x32_bf16 v[20:23], v[218:221], v[194:197], v[20:23]
	v_mfma_f32_16x16x32_bf16 v[16:19], v[226:229], v[194:197], v[16:19]
	v_mfma_f32_16x16x32_bf16 v[12:15], v[218:221], v[202:205], v[12:15]
	v_mfma_f32_16x16x32_bf16 v[8:11], v[226:229], v[202:205], v[8:11]
	v_mfma_f32_16x16x32_bf16 v[4:7], v[218:221], v[210:213], v[4:7]
	v_mfma_f32_16x16x32_bf16 v[0:3], v[226:229], v[210:213], v[0:3]
	v_mfma_f32_16x16x32_bf16 v[28:31], v[222:225], v[160:163], v[28:31]
	v_mfma_f32_16x16x32_bf16 v[24:27], v[230:233], v[160:163], v[24:27]
	v_mfma_f32_16x16x32_bf16 v[20:23], v[222:225], v[198:201], v[20:23]
	v_mfma_f32_16x16x32_bf16 v[16:19], v[230:233], v[198:201], v[16:19]
	v_mfma_f32_16x16x32_bf16 v[12:15], v[222:225], v[206:209], v[12:15]
	v_mfma_f32_16x16x32_bf16 v[8:11], v[230:233], v[206:209], v[8:11]
	v_mfma_f32_16x16x32_bf16 v[4:7], v[222:225], v[214:217], v[4:7]
	v_mfma_f32_16x16x32_bf16 v[0:3], v[230:233], v[214:217], v[0:3]
	s_add_i32 s4, s4, 2
	s_add_u32 s64, s64, s68
	s_addc_u32 s65, s65, s69
	s_add_u32 s66, s66, s68
	s_addc_u32 s67, s67, s69
	s_cmp_lt_u32 s4, 28
	s_barrier
	s_cbranch_scc1 .LBB0_110
	s_setprio 0
	s_lshl_b32 s4, s70, 11
	s_or_b32 s64, s71, s4
	s_or_b32 s66, s64, 0x80
	v_lshlrev_b32_e32 v128, 3, v131
	v_lshlrev_b32_e32 v129, 5, v131
	s_ashr_i32 s67, s66, 31
	v_and_b32_e32 v128, 0xffff0, v128
	v_and_b32_e32 v129, 32, v129
	s_lshl_b64 s[66:67], s[66:67], 12
	v_add_u32_e32 v129, v129, v134
	v_add_lshl_u32 v128, v133, v128, 12
	s_add_u32 s66, s54, s66
	v_lshl_add_u32 v164, v129, 1, v128
	s_addc_u32 s67, s55, s67
	v_lshl_add_u64 v[128:129], s[66:67], 0, v[164:165]
	v_readfirstlane_b32 s4, v137
	ds_read_b128 v[140:143], v138
	ds_read_b128 v[144:147], v138 offset:1024
	ds_read_b128 v[148:151], v138 offset:2048
	ds_read_b128 v[152:155], v138 offset:3072
	ds_read_b128 v[156:159], v192
	ds_read_b128 v[160:163], v192 offset:1024
	ds_read_b128 v[194:197], v191
	ds_read_b128 v[198:201], v191 offset:1024
	ds_read_b128 v[202:205], v190
	ds_read_b128 v[206:209], v190 offset:1024
	ds_read_b128 v[210:213], v189
	ds_read_b128 v[214:217], v189 offset:1024
	v_lshl_add_u64 v[138:139], v[128:129], 0, s[58:59]
	s_mov_b32 m0, s4
	v_readfirstlane_b32 s4, v136
	global_load_lds_dwordx4 v[138:139], off
	v_lshl_add_u64 v[128:129], v[128:129], 0, s[60:61]
	s_mov_b32 m0, s4
	s_ashr_i32 s65, s64, 31
	global_load_lds_dwordx4 v[128:129], off
	s_waitcnt vmcnt(10)
	s_barrier
	s_waitcnt lgkmcnt(0)
	s_setprio 1
	s_waitcnt lgkmcnt(0)
	v_mfma_f32_16x16x32_bf16 v[124:127], v[140:143], v[156:159], v[124:127]
	v_mfma_f32_16x16x32_bf16 v[120:123], v[148:151], v[156:159], v[120:123]
	v_mfma_f32_16x16x32_bf16 v[116:119], v[140:143], v[194:197], v[116:119]
	v_mfma_f32_16x16x32_bf16 v[112:115], v[148:151], v[194:197], v[112:115]
	v_mfma_f32_16x16x32_bf16 v[108:111], v[140:143], v[202:205], v[108:111]
	v_mfma_f32_16x16x32_bf16 v[104:107], v[148:151], v[202:205], v[104:107]
	v_mfma_f32_16x16x32_bf16 v[100:103], v[140:143], v[210:213], v[100:103]
	v_mfma_f32_16x16x32_bf16 v[96:99], v[148:151], v[210:213], v[96:99]
	v_mfma_f32_16x16x32_bf16 v[124:127], v[144:147], v[160:163], v[124:127]
	v_mfma_f32_16x16x32_bf16 v[120:123], v[152:155], v[160:163], v[120:123]
	v_mfma_f32_16x16x32_bf16 v[116:119], v[144:147], v[198:201], v[116:119]
	v_mfma_f32_16x16x32_bf16 v[112:115], v[152:155], v[198:201], v[112:115]
	v_mfma_f32_16x16x32_bf16 v[108:111], v[144:147], v[206:209], v[108:111]
	v_mfma_f32_16x16x32_bf16 v[104:107], v[152:155], v[206:209], v[104:107]
	v_mfma_f32_16x16x32_bf16 v[100:103], v[144:147], v[214:217], v[100:103]
	v_mfma_f32_16x16x32_bf16 v[96:99], v[152:155], v[214:217], v[96:99]
	s_setprio 0
	s_barrier
	ds_read_b128 v[136:139], v135
	ds_read_b128 v[218:221], v135 offset:1024
	ds_read_b128 v[222:225], v135 offset:2048
	ds_read_b128 v[226:229], v135 offset:3072
	s_barrier
	s_waitcnt lgkmcnt(0)
	s_setprio 1
	s_waitcnt lgkmcnt(0)
	v_mfma_f32_16x16x32_bf16 v[92:95], v[136:139], v[156:159], v[92:95]
	v_mfma_f32_16x16x32_bf16 v[88:91], v[222:225], v[156:159], v[88:91]
	v_mfma_f32_16x16x32_bf16 v[84:87], v[136:139], v[194:197], v[84:87]
	v_mfma_f32_16x16x32_bf16 v[80:83], v[222:225], v[194:197], v[80:83]
	v_mfma_f32_16x16x32_bf16 v[76:79], v[136:139], v[202:205], v[76:79]
	v_mfma_f32_16x16x32_bf16 v[72:75], v[222:225], v[202:205], v[72:75]
	v_mfma_f32_16x16x32_bf16 v[68:71], v[136:139], v[210:213], v[68:71]
	v_mfma_f32_16x16x32_bf16 v[64:67], v[222:225], v[210:213], v[64:67]
	v_mfma_f32_16x16x32_bf16 v[156:159], v[218:221], v[160:163], v[92:95]
	v_mfma_f32_16x16x32_bf16 v[160:163], v[226:229], v[160:163], v[88:91]
	v_mfma_f32_16x16x32_bf16 v[194:197], v[218:221], v[198:201], v[84:87]
	v_mfma_f32_16x16x32_bf16 v[198:201], v[226:229], v[198:201], v[80:83]
	v_mfma_f32_16x16x32_bf16 v[202:205], v[218:221], v[206:209], v[76:79]
	v_mfma_f32_16x16x32_bf16 v[206:209], v[226:229], v[206:209], v[72:75]
	v_mfma_f32_16x16x32_bf16 v[210:213], v[218:221], v[214:217], v[68:71]
	v_mfma_f32_16x16x32_bf16 v[214:217], v[226:229], v[214:217], v[64:67]
	s_setprio 0
	s_barrier
	s_nop 0
	ds_read_b128 v[64:67], v192 offset:16384
	ds_read_b128 v[68:71], v192 offset:17408
	ds_read_b128 v[72:75], v191 offset:16384
	ds_read_b128 v[76:79], v191 offset:17408
	ds_read_b128 v[80:83], v190 offset:16384
	ds_read_b128 v[84:87], v190 offset:17408
	ds_read_b128 v[88:91], v189 offset:16384
	ds_read_b128 v[92:95], v189 offset:17408
	s_waitcnt vmcnt(4)
	s_barrier
	s_waitcnt lgkmcnt(0)
	s_setprio 1
	s_waitcnt lgkmcnt(0)
	v_mfma_f32_16x16x32_bf16 v[60:63], v[140:143], v[64:67], v[60:63]
	v_mfma_f32_16x16x32_bf16 v[56:59], v[148:151], v[64:67], v[56:59]
	v_mfma_f32_16x16x32_bf16 v[52:55], v[140:143], v[72:75], v[52:55]
	v_mfma_f32_16x16x32_bf16 v[48:51], v[148:151], v[72:75], v[48:51]
	v_mfma_f32_16x16x32_bf16 v[230:233], v[140:143], v[80:83], v[44:47]
	v_mfma_f32_16x16x32_bf16 v[234:237], v[148:151], v[80:83], v[40:43]
	v_mfma_f32_16x16x32_bf16 v[140:143], v[140:143], v[88:91], v[36:39]
	v_mfma_f32_16x16x32_bf16 v[148:151], v[148:151], v[88:91], v[32:35]
	v_mfma_f32_16x16x32_bf16 v[32:35], v[144:147], v[68:71], v[60:63]
	v_mfma_f32_16x16x32_bf16 v[36:39], v[152:155], v[68:71], v[56:59]
	v_mfma_f32_16x16x32_bf16 v[40:43], v[144:147], v[76:79], v[52:55]
	v_mfma_f32_16x16x32_bf16 v[44:47], v[152:155], v[76:79], v[48:51]
	v_mfma_f32_16x16x32_bf16 v[48:51], v[144:147], v[84:87], v[230:233]
	v_mfma_f32_16x16x32_bf16 v[52:55], v[152:155], v[84:87], v[234:237]
	v_mfma_f32_16x16x32_bf16 v[56:59], v[144:147], v[92:95], v[140:143]
	v_mfma_f32_16x16x32_bf16 v[60:63], v[152:155], v[92:95], v[148:151]
	s_setprio 0
	s_setprio 1
	v_mfma_f32_16x16x32_bf16 v[28:31], v[136:139], v[64:67], v[28:31]
	v_mfma_f32_16x16x32_bf16 v[24:27], v[222:225], v[64:67], v[24:27]
	v_mfma_f32_16x16x32_bf16 v[20:23], v[136:139], v[72:75], v[20:23]
	v_mfma_f32_16x16x32_bf16 v[64:67], v[222:225], v[72:75], v[16:19]
	v_mfma_f32_16x16x32_bf16 v[12:15], v[136:139], v[80:83], v[12:15]
	v_mfma_f32_16x16x32_bf16 v[8:11], v[222:225], v[80:83], v[8:11]
	v_mfma_f32_16x16x32_bf16 v[72:75], v[136:139], v[88:91], v[4:7]
	v_mfma_f32_16x16x32_bf16 v[80:83], v[222:225], v[88:91], v[0:3]
	v_mfma_f32_16x16x32_bf16 v[0:3], v[218:221], v[68:71], v[28:31]
	v_mfma_f32_16x16x32_bf16 v[4:7], v[226:229], v[68:71], v[24:27]
	v_mfma_f32_16x16x32_bf16 v[16:19], v[218:221], v[76:79], v[20:23]
	v_mfma_f32_16x16x32_bf16 v[20:23], v[226:229], v[76:79], v[64:67]
	v_mfma_f32_16x16x32_bf16 v[64:67], v[218:221], v[84:87], v[12:15]
	v_mfma_f32_16x16x32_bf16 v[68:71], v[226:229], v[84:87], v[8:11]
	v_mfma_f32_16x16x32_bf16 v[72:75], v[218:221], v[92:95], v[72:75]
	v_mfma_f32_16x16x32_bf16 v[76:79], v[226:229], v[92:95], v[80:83]
	s_setprio 0
	s_barrier
	ds_read_b128 v[12:15], v130
	ds_read_b128 v[8:11], v130 offset:1024
	ds_read_b128 v[24:27], v130 offset:2048
	ds_read_b128 v[80:83], v130 offset:3072
	ds_read_b128 v[140:143], v192 offset:32768
	ds_read_b128 v[148:151], v192 offset:33792
	ds_read_b128 v[218:221], v191 offset:32768
	ds_read_b128 v[222:225], v191 offset:33792
	ds_read_b128 v[226:229], v190 offset:32768
	ds_read_b128 v[230:233], v190 offset:33792
	ds_read_b128 v[234:237], v189 offset:32768
	ds_read_b128 v[238:241], v189 offset:33792
	s_waitcnt vmcnt(2)
	s_barrier
	s_waitcnt lgkmcnt(0)
	s_setprio 1
	s_waitcnt lgkmcnt(0)
	v_mfma_f32_16x16x32_bf16 v[28:31], v[12:15], v[140:143], v[124:127]
	v_mfma_f32_16x16x32_bf16 v[84:87], v[24:27], v[140:143], v[120:123]
	v_mfma_f32_16x16x32_bf16 v[88:91], v[12:15], v[218:221], v[116:119]
	v_mfma_f32_16x16x32_bf16 v[92:95], v[24:27], v[218:221], v[112:115]
	v_mfma_f32_16x16x32_bf16 v[108:111], v[12:15], v[226:229], v[108:111]
	v_mfma_f32_16x16x32_bf16 v[104:107], v[24:27], v[226:229], v[104:107]
	v_mfma_f32_16x16x32_bf16 v[100:103], v[12:15], v[234:237], v[100:103]
	v_mfma_f32_16x16x32_bf16 v[96:99], v[24:27], v[234:237], v[96:99]
	v_mfma_f32_16x16x32_bf16 v[152:155], v[8:11], v[148:151], v[28:31]
	v_mfma_f32_16x16x32_bf16 v[144:147], v[80:83], v[148:151], v[84:87]
	v_mfma_f32_16x16x32_bf16 v[136:139], v[8:11], v[222:225], v[88:91]
	v_mfma_f32_16x16x32_bf16 v[128:131], v[80:83], v[222:225], v[92:95]
	v_mfma_f32_16x16x32_bf16 v[120:123], v[8:11], v[230:233], v[108:111]
	v_mfma_f32_16x16x32_bf16 v[112:115], v[80:83], v[230:233], v[104:107]
	v_mfma_f32_16x16x32_bf16 v[104:107], v[8:11], v[238:241], v[100:103]
	v_mfma_f32_16x16x32_bf16 v[28:31], v[80:83], v[238:241], v[96:99]
	s_setprio 0
	s_barrier
	ds_read_b128 v[92:95], v132
	ds_read_b128 v[84:87], v132 offset:1024
	ds_read_b128 v[96:99], v132 offset:2048
	ds_read_b128 v[88:91], v132 offset:3072
	s_waitcnt vmcnt(0)
	s_barrier
	s_waitcnt lgkmcnt(0)
	s_setprio 1
	s_waitcnt lgkmcnt(0)
	v_mfma_f32_16x16x32_bf16 v[100:103], v[92:95], v[140:143], v[156:159]
	v_mfma_f32_16x16x32_bf16 v[108:111], v[96:99], v[140:143], v[160:163]
	v_mfma_f32_16x16x32_bf16 v[116:119], v[92:95], v[218:221], v[194:197]
	v_mfma_f32_16x16x32_bf16 v[124:127], v[96:99], v[218:221], v[198:201]
	v_mfma_f32_16x16x32_bf16 v[160:163], v[92:95], v[226:229], v[202:205]
	v_mfma_f32_16x16x32_bf16 v[194:197], v[96:99], v[226:229], v[206:209]
	v_mfma_f32_16x16x32_bf16 v[198:201], v[92:95], v[234:237], v[210:213]
	v_mfma_f32_16x16x32_bf16 v[202:205], v[96:99], v[234:237], v[214:217]
	v_mfma_f32_16x16x32_bf16 v[156:159], v[84:87], v[148:151], v[100:103]
	v_mfma_f32_16x16x32_bf16 v[148:151], v[88:91], v[148:151], v[108:111]
	v_mfma_f32_16x16x32_bf16 v[140:143], v[84:87], v[222:225], v[116:119]
	v_mfma_f32_16x16x32_bf16 v[132:135], v[88:91], v[222:225], v[124:127]
	v_mfma_f32_16x16x32_bf16 v[124:127], v[84:87], v[230:233], v[160:163]
	v_mfma_f32_16x16x32_bf16 v[116:119], v[88:91], v[230:233], v[194:197]
	v_mfma_f32_16x16x32_bf16 v[108:111], v[84:87], v[238:241], v[198:201]
	v_mfma_f32_16x16x32_bf16 v[100:103], v[88:91], v[238:241], v[202:205]
	s_setprio 0
	s_lshl_b64 s[66:67], s[64:65], 2
	s_barrier
	v_mbcnt_lo_u32_b32 v162, -1, 0
	v_mbcnt_hi_u32_b32 v162, -1, v162
	s_add_u32 s66, s87, s66
	v_add_u32_e32 v160, s76, v162
	s_addc_u32 s67, s88, s67
	v_and_b32_e32 v164, 0x100, v160
	v_and_b32_e32 v162, 15, v162
	v_lshl_add_u64 v[160:161], s[66:67], 0, v[164:165]
	v_lshlrev_b32_e32 v164, 2, v162
	v_lshl_add_u64 v[160:161], v[160:161], 0, v[164:165]
	global_load_dword v178, v[160:161], off
	global_load_dword v176, v[160:161], off offset:64
	global_load_dword v174, v[160:161], off offset:128
	global_load_dword v164, v[160:161], off offset:192
	global_load_dword v172, v[160:161], off offset:512
	global_load_dword v170, v[160:161], off offset:576
	global_load_dword v168, v[160:161], off offset:640
	global_load_dword v166, v[160:161], off offset:704
	v_mbcnt_lo_u32_b32 v194, -1, 0
	v_mbcnt_hi_u32_b32 v194, -1, v194
	s_mov_b64 s[66:67], -1
	v_add_u32_e32 v160, s76, v194
	v_bfe_u32 v161, v160, 8, 1
	v_ashrrev_i32_e32 v196, 6, v160
	v_bfe_u32 v160, v194, 4, 2
	v_and_b32_e32 v198, 3, v196
	v_and_b32_e32 v195, 15, v194
	s_cmp_gt_i32 s74, 1
	v_lshlrev_b32_e32 v193, 6, v161
	v_lshlrev_b32_e32 v197, 4, v160
	s_cbranch_scc0 .LBB0_113
	v_lshlrev_b32_e32 v161, 6, v198
	v_or3_b32 v160, v193, v195, s64
	v_or3_b32 v161, v161, v197, s62
	v_lshl_add_u32 v199, v160, 12, v161
	s_waitcnt vmcnt(0)
	v_mul_f32_e32 v160, v178, v178
	v_pk_mul_f32 v[200:201], v[152:153], v[160:161] op_sel_hi:[1,0]
	v_pk_mul_f32 v[162:163], v[154:155], v[160:161] op_sel_hi:[1,0]
	v_pk_mul_f32 v[202:203], v[158:159], v[160:161] op_sel_hi:[1,0]
	v_pk_mul_f32 v[204:205], v[156:157], v[160:161] op_sel_hi:[1,0]
	v_mul_f32_e32 v160, v144, v200
	v_mul_f32_e32 v161, v145, v201
	v_cvt_pk_bf16_f32 v160, v160, v161
	v_mul_f32_e32 v161, v146, v162
	v_mul_f32_e32 v162, v147, v163
	v_cvt_pk_bf16_f32 v161, v161, v162
	v_mul_f32_e32 v162, v148, v204
	v_mul_f32_e32 v163, v149, v205
	v_cvt_pk_bf16_f32 v162, v162, v163
	v_mul_f32_e32 v163, v150, v202
	v_mul_f32_e32 v200, v151, v203
	v_cvt_pk_bf16_f32 v163, v163, v200
	global_store_dwordx4 v199, v[160:163], s[6:7]
	v_add_u32_e32 v206, 0x10000, v199
	s_mov_b64 s[66:67], 0
	v_mul_f32_e32 v160, v176, v176
	v_pk_mul_f32 v[200:201], v[136:137], v[160:161] op_sel_hi:[1,0]
	v_pk_mul_f32 v[162:163], v[138:139], v[160:161] op_sel_hi:[1,0]
	v_pk_mul_f32 v[202:203], v[142:143], v[160:161] op_sel_hi:[1,0]
	v_pk_mul_f32 v[204:205], v[140:141], v[160:161] op_sel_hi:[1,0]
	v_mul_f32_e32 v160, v128, v200
	v_mul_f32_e32 v161, v129, v201
	v_cvt_pk_bf16_f32 v160, v160, v161
	v_mul_f32_e32 v161, v130, v162
	v_mul_f32_e32 v162, v131, v163
	v_cvt_pk_bf16_f32 v161, v161, v162
	v_mul_f32_e32 v162, v132, v204
	v_mul_f32_e32 v163, v133, v205
	v_cvt_pk_bf16_f32 v162, v162, v163
	v_mul_f32_e32 v163, v134, v202
	v_mul_f32_e32 v200, v135, v203
	v_cvt_pk_bf16_f32 v163, v163, v200
	global_store_dwordx4 v206, v[160:163], s[6:7]
	v_add_u32_e32 v206, 0x20000, v199
	v_add_u32_e32 v199, 0x30000, v199
	v_mul_f32_e32 v160, v174, v174
	v_pk_mul_f32 v[200:201], v[120:121], v[160:161] op_sel_hi:[1,0]
	v_pk_mul_f32 v[162:163], v[122:123], v[160:161] op_sel_hi:[1,0]
	v_pk_mul_f32 v[202:203], v[126:127], v[160:161] op_sel_hi:[1,0]
	v_pk_mul_f32 v[204:205], v[124:125], v[160:161] op_sel_hi:[1,0]
	v_mul_f32_e32 v160, v112, v200
	v_mul_f32_e32 v161, v113, v201
	v_cvt_pk_bf16_f32 v160, v160, v161
	v_mul_f32_e32 v161, v114, v162
	v_mul_f32_e32 v162, v115, v163
	v_cvt_pk_bf16_f32 v161, v161, v162
	v_mul_f32_e32 v162, v116, v204
	v_mul_f32_e32 v163, v117, v205
	v_cvt_pk_bf16_f32 v162, v162, v163
	v_mul_f32_e32 v163, v118, v202
	v_mul_f32_e32 v200, v119, v203
	v_cvt_pk_bf16_f32 v163, v163, v200
	global_store_dwordx4 v206, v[160:163], s[6:7]
	s_nop 1
	v_mul_f32_e32 v160, v164, v164
	v_pk_mul_f32 v[200:201], v[104:105], v[160:161] op_sel_hi:[1,0]
	v_pk_mul_f32 v[162:163], v[106:107], v[160:161] op_sel_hi:[1,0]
	v_pk_mul_f32 v[202:203], v[110:111], v[160:161] op_sel_hi:[1,0]
	v_pk_mul_f32 v[204:205], v[108:109], v[160:161] op_sel_hi:[1,0]
	v_mul_f32_e32 v160, v28, v200
	v_mul_f32_e32 v161, v29, v201
	v_cvt_pk_bf16_f32 v160, v160, v161
	v_mul_f32_e32 v161, v30, v162
	v_mul_f32_e32 v162, v31, v163
	v_cvt_pk_bf16_f32 v161, v161, v162
	v_mul_f32_e32 v162, v100, v204
	v_mul_f32_e32 v163, v101, v205
	v_cvt_pk_bf16_f32 v162, v162, v163
	v_mul_f32_e32 v163, v102, v202
	v_mul_f32_e32 v200, v103, v203
	v_cvt_pk_bf16_f32 v163, v163, v200

.LBB0_177:
	v_bfe_i32 v5, v136, 27, 1
	v_lshlrev_b32_e32 v135, 4, v136
	v_lshrrev_b32_e32 v5, 22, v5
	v_add_u32_e32 v5, v135, v5
	v_and_b32_e32 v5, 0xfffffc00, v5
	v_sub_u32_e32 v5, v135, v5
	v_lshrrev_b32_e32 v6, 4, v5
	v_bitop3_b32 v5, v6, v5, 32 bitop3:0x6c
	v_ashrrev_i32_e32 v6, 31, v5
	v_lshrrev_b32_e32 v6, 26, v6
	v_add_u32_e32 v6, v5, v6
	v_ashrrev_i32_e32 v157, 6, v6
	v_and_b32_e32 v6, 0xc0, v6
	v_sub_u32_e32 v5, v5, v6
	v_ashrrev_i16_sdwa v5, v134, sext(v5) dst_sel:DWORD dst_unused:UNUSED_PAD src0_sel:DWORD src1_sel:BYTE_0
	v_and_b32_e32 v2, 15, v0
	v_and_b32_e32 v3, 48, v0
	v_bfe_i32 v158, v5, 0, 16
	v_and_b32_e32 v5, 32, v0
	v_lshlrev_b32_e32 v8, 2, v0
	v_lshlrev_b32_e32 v0, 6, v0
	s_movk_i32 s65, 0x3f0
	v_lshlrev_b32_e32 v2, 6, v2
	v_and_b32_e32 v8, 32, v8
	v_and_b32_e32 v0, 0x3c0, v0
	v_ashrrev_i32_e32 v4, 31, v136
	v_bitop3_b32 v5, v135, v5, s65 bitop3:0x6c
	v_or_b32_e32 v7, v2, v3
	v_bitop3_b32 v2, v2, v8, v3 bitop3:0x36
	v_bitop3_b32 v3, v0, v8, v3 bitop3:0x36
	v_lshlrev_b32_e32 v0, 11, v136
	v_lshrrev_b32_e32 v4, 26, v4
	v_and_or_b32 v0, v0, s76, v5
	v_lshlrev_b32_e32 v5, 3, v136
	s_bfe_u32 s64, s85, 0x30003
	v_add_u32_e32 v4, v136, v4
	s_mov_b32 s65, 0x14000
	v_and_b32_e32 v5, 0xfffffc00, v5
	s_lshl_b32 s24, s64, 14
	v_ashrrev_i32_e32 v156, 6, v4
	v_bitop3_b32 v10, v7, s65, v8 bitop3:0xde
	s_mov_b32 s65, 0x1c000
	v_add_u32_e32 v128, v0, v5
	v_bitop3_b32 v9, v7, s74, v8 bitop3:0xde
	v_bitop3_b32 v11, v7, s75, v8 bitop3:0xde
	v_bitop3_b32 v7, v7, s65, v8 bitop3:0xde
	v_lshl_add_u64 v[130:131], s[24:25], 0, v[128:129]
	v_lshlrev_b32_e32 v0, 15, v156
	s_lshl_b32 s24, s85, 17
	s_and_b32 s65, s85, 7
	v_and_b32_e32 v0, 0xffff0000, v0
	s_and_b32 s24, s24, 0x1800000
	s_lshl_b32 s65, s65, 20
	v_lshl_add_u32 v0, v157, 12, v0
	s_or_b32 s24, s24, s65
	v_lshlrev_b32_e32 v6, 6, v136
	v_lshlrev_b32_e32 v1, 13, v1
	v_and_or_b32 v0, v4, 64, v0
	s_add_u32 s66, s24, s90
	v_and_b32_e32 v6, 0x3000, v6
	v_or_b32_e32 v8, 0x800, v1
	v_or_b32_e32 v12, 0x1000, v1
	v_or_b32_e32 v13, 0x1800, v1
	v_lshl_add_u32 v128, v158, 1, v0
	s_addc_u32 s67, 0, 0
	v_mov_b32_e32 v0, 0
	v_lshl_add_u64 v[132:133], s[66:67], 0, v[128:129]
	s_mov_b32 s24, -2
	v_add_u32_e32 v162, v9, v6
	v_add_u32_e32 v153, v2, v1
	v_add_u32_e32 v152, v3, v8
	v_add_u32_e32 v151, v3, v12
	v_add_u32_e32 v150, v3, v13
	v_add_u32_e32 v161, 0xc000, v135
	v_add_u32_e32 v160, 0xe000, v135
	v_add_u32_e32 v159, v10, v6
	v_add_u32_e32 v149, 0x10000, v135
	v_add_u32_e32 v148, 0x12000, v135
	v_add_u32_e32 v147, 0x2000, v135
	v_add_u32_e32 v146, 0x14000, v135
	v_add_u32_e32 v145, 0x16000, v135
	v_add_u32_e32 v155, v11, v6
	v_add_u32_e32 v144, 0x4000, v135
	v_add_u32_e32 v143, 0x6000, v135
	v_add_u32_e32 v154, v7, v6
	v_add_u32_e32 v142, 0x18000, v135
	v_add_u32_e32 v141, 0x1a000, v135
	v_add_u32_e32 v140, 0x8000, v135
	v_add_u32_e32 v139, 0xa000, v135
	v_add_u32_e32 v138, 0x1c000, v135
	v_add_u32_e32 v137, 0x1e000, v135
	v_mov_b32_e32 v1, v0
	v_mov_b32_e32 v2, v0
	v_mov_b32_e32 v3, v0
	v_mov_b32_e32 v4, v0
	v_mov_b32_e32 v5, v0
	v_mov_b32_e32 v6, v0
	v_mov_b32_e32 v7, v0
	v_mov_b32_e32 v8, v0
	v_mov_b32_e32 v9, v0
	v_mov_b32_e32 v10, v0
	v_mov_b32_e32 v11, v0
	v_mov_b32_e32 v12, v0
	v_mov_b32_e32 v13, v0
	v_mov_b32_e32 v14, v0
	v_mov_b32_e32 v15, v0
	v_mov_b32_e32 v16, v0
	v_mov_b32_e32 v17, v0
	v_mov_b32_e32 v18, v0
	v_mov_b32_e32 v19, v0
	v_mov_b32_e32 v20, v0
	v_mov_b32_e32 v21, v0
	v_mov_b32_e32 v22, v0
	v_mov_b32_e32 v23, v0
	v_mov_b32_e32 v24, v0
	v_mov_b32_e32 v25, v0
	v_mov_b32_e32 v26, v0
	v_mov_b32_e32 v27, v0
	v_mov_b32_e32 v28, v0
	v_mov_b32_e32 v29, v0
	v_mov_b32_e32 v30, v0
	v_mov_b32_e32 v31, v0
	v_mov_b32_e32 v32, v0
	v_mov_b32_e32 v33, v0
	v_mov_b32_e32 v34, v0
	v_mov_b32_e32 v35, v0
	v_mov_b32_e32 v36, v0
	v_mov_b32_e32 v37, v0
	v_mov_b32_e32 v38, v0
	v_mov_b32_e32 v39, v0
	v_mov_b32_e32 v40, v0
	v_mov_b32_e32 v41, v0
	v_mov_b32_e32 v42, v0
	v_mov_b32_e32 v43, v0
	v_mov_b32_e32 v44, v0
	v_mov_b32_e32 v45, v0
	v_mov_b32_e32 v46, v0
	v_mov_b32_e32 v47, v0
	v_mov_b32_e32 v48, v0
	v_mov_b32_e32 v49, v0
	v_mov_b32_e32 v50, v0
	v_mov_b32_e32 v51, v0
	v_mov_b32_e32 v52, v0
	v_mov_b32_e32 v53, v0
	v_mov_b32_e32 v54, v0
	v_mov_b32_e32 v55, v0
	v_mov_b32_e32 v56, v0
	v_mov_b32_e32 v57, v0
	v_mov_b32_e32 v58, v0
	v_mov_b32_e32 v59, v0
	v_mov_b32_e32 v60, v0
	v_mov_b32_e32 v61, v0
	v_mov_b32_e32 v62, v0
	v_mov_b32_e32 v63, v0
	v_mov_b32_e32 v64, v0
	v_mov_b32_e32 v65, v0
	v_mov_b32_e32 v66, v0
	v_mov_b32_e32 v67, v0
	v_mov_b32_e32 v68, v0
	v_mov_b32_e32 v69, v0
	v_mov_b32_e32 v70, v0
	v_mov_b32_e32 v71, v0
	v_mov_b32_e32 v72, v0
	v_mov_b32_e32 v73, v0
	v_mov_b32_e32 v74, v0
	v_mov_b32_e32 v75, v0
	v_mov_b32_e32 v76, v0
	v_mov_b32_e32 v77, v0
	v_mov_b32_e32 v78, v0
	v_mov_b32_e32 v79, v0
	v_mov_b32_e32 v80, v0
	v_mov_b32_e32 v81, v0
	v_mov_b32_e32 v82, v0
	v_mov_b32_e32 v83, v0
	v_mov_b32_e32 v84, v0
	v_mov_b32_e32 v85, v0
	v_mov_b32_e32 v86, v0
	v_mov_b32_e32 v87, v0
	v_mov_b32_e32 v88, v0
	v_mov_b32_e32 v89, v0
	v_mov_b32_e32 v90, v0
	v_mov_b32_e32 v91, v0
	v_mov_b32_e32 v92, v0
	v_mov_b32_e32 v93, v0
	v_mov_b32_e32 v94, v0
	v_mov_b32_e32 v95, v0
	v_mov_b32_e32 v96, v0
	v_mov_b32_e32 v97, v0
	v_mov_b32_e32 v98, v0
	v_mov_b32_e32 v99, v0
	v_mov_b32_e32 v100, v0
	v_mov_b32_e32 v101, v0
	v_mov_b32_e32 v102, v0
	v_mov_b32_e32 v103, v0
	v_mov_b32_e32 v104, v0
	v_mov_b32_e32 v105, v0
	v_mov_b32_e32 v106, v0
	v_mov_b32_e32 v107, v0
	v_mov_b32_e32 v108, v0
	v_mov_b32_e32 v109, v0
	v_mov_b32_e32 v110, v0
	v_mov_b32_e32 v111, v0
	v_mov_b32_e32 v112, v0
	v_mov_b32_e32 v113, v0
	v_mov_b32_e32 v114, v0
	v_mov_b32_e32 v115, v0
	v_mov_b32_e32 v116, v0
	v_mov_b32_e32 v117, v0
	v_mov_b32_e32 v118, v0
	v_mov_b32_e32 v119, v0
	v_mov_b32_e32 v120, v0
	v_mov_b32_e32 v121, v0
	v_mov_b32_e32 v122, v0
	v_mov_b32_e32 v123, v0
	v_mov_b32_e32 v124, v0
	v_mov_b32_e32 v125, v0
	v_mov_b32_e32 v126, v0
	v_mov_b32_e32 v127, v0
	s_barrier
	v_readlane_b32 s98, v242, 1
	s_nop 3
	s_cmp_lt_u32 s98, 4
	s_cbranch_scc1 .Lprio_178
	s_setprio 1
.Lprio_178:
	v_lshl_add_u64 v[228:229], s[50:51], 0, v[132:133]
	s_mov_b64 s[66:67], 0xe080080
	v_readfirstlane_b32 s65, v161
	v_lshl_add_u64 v[166:167], v[228:229], 0, s[66:67]
	s_mov_b32 m0, s65
	s_mov_b64 s[66:67], 0xe0c0080
	v_readfirstlane_b32 s65, v160
	global_load_lds_dwordx4 v[166:167], off
	v_lshl_add_u64 v[166:167], v[228:229], 0, s[66:67]
	s_mov_b32 m0, s65
	s_nop 0
	global_load_lds_dwordx4 v[166:167], off
.LBB0_178:
	ds_read_b128 v[164:167], v162
	ds_read_b128 v[168:171], v162 offset:1024
	ds_read_b128 v[172:175], v162 offset:2048
	ds_read_b128 v[176:179], v162 offset:3072
	ds_read_b128 v[180:183], v153
	ds_read_b128 v[184:187], v153 offset:1024
	ds_read_b128 v[188:191], v152
	ds_read_b128 v[192:195], v152 offset:1024
	ds_read_b128 v[196:199], v151
	ds_read_b128 v[200:203], v151 offset:1024
	ds_read_b128 v[204:207], v150
	ds_read_b128 v[208:211], v150 offset:1024
	s_waitcnt lgkmcnt(8)
	s_waitcnt vmcnt(10)
	s_barrier
	s_waitcnt lgkmcnt(0)
	s_waitcnt lgkmcnt(0)
	v_mfma_f32_16x16x32_bf16 v[124:127], v[164:167], v[180:183], v[124:127]
	v_mfma_f32_16x16x32_bf16 v[120:123], v[172:175], v[180:183], v[120:123]
	v_mfma_f32_16x16x32_bf16 v[116:119], v[164:167], v[188:191], v[116:119]
	v_mfma_f32_16x16x32_bf16 v[112:115], v[172:175], v[188:191], v[112:115]
	v_mfma_f32_16x16x32_bf16 v[108:111], v[164:167], v[196:199], v[108:111]
	v_mfma_f32_16x16x32_bf16 v[104:107], v[172:175], v[196:199], v[104:107]
	v_mfma_f32_16x16x32_bf16 v[100:103], v[164:167], v[204:207], v[100:103]
	v_mfma_f32_16x16x32_bf16 v[96:99], v[172:175], v[204:207], v[96:99]
	v_mfma_f32_16x16x32_bf16 v[124:127], v[168:171], v[184:187], v[124:127]
	v_mfma_f32_16x16x32_bf16 v[120:123], v[176:179], v[184:187], v[120:123]
	v_mfma_f32_16x16x32_bf16 v[116:119], v[168:171], v[192:195], v[116:119]
	v_mfma_f32_16x16x32_bf16 v[112:115], v[176:179], v[192:195], v[112:115]
	v_mfma_f32_16x16x32_bf16 v[108:111], v[168:171], v[200:203], v[108:111]
	v_mfma_f32_16x16x32_bf16 v[104:107], v[176:179], v[200:203], v[104:107]
	v_mfma_f32_16x16x32_bf16 v[100:103], v[168:171], v[208:211], v[100:103]
	v_mfma_f32_16x16x32_bf16 v[96:99], v[176:179], v[208:211], v[96:99]
	s_barrier
	v_lshl_add_u64 v[230:231], s[50:51], 0, v[130:131]
	s_mov_b64 s[66:67], 0x1880000
	v_readfirstlane_b32 s65, v149
	v_lshl_add_u64 v[232:233], v[230:231], 0, s[66:67]
	s_mov_b32 m0, s65
	s_mov_b64 s[66:67], 0x1881000
	v_readfirstlane_b32 s65, v148
	ds_read_b128 v[212:215], v159
	ds_read_b128 v[216:219], v159 offset:1024
	ds_read_b128 v[220:223], v159 offset:2048
	ds_read_b128 v[224:227], v159 offset:3072
	global_load_lds_dwordx4 v[232:233], off
	v_lshl_add_u64 v[232:233], v[230:231], 0, s[66:67]
	s_mov_b32 m0, s65
	s_nop 0
	global_load_lds_dwordx4 v[232:233], off
	s_mov_b64 s[66:67], 0xe000100
	v_readfirstlane_b32 s65, v135
	v_lshl_add_u64 v[232:233], v[228:229], 0, s[66:67]
	s_mov_b32 m0, s65
	s_mov_b64 s[66:67], 0xe040100
	v_readfirstlane_b32 s65, v147
	global_load_lds_dwordx4 v[232:233], off
	v_lshl_add_u64 v[232:233], v[228:229], 0, s[66:67]
	s_mov_b32 m0, s65
	s_nop 0
	global_load_lds_dwordx4 v[232:233], off
	s_waitcnt vmcnt(12)
	s_barrier
	s_waitcnt lgkmcnt(0)
	s_waitcnt lgkmcnt(0)
	v_mfma_f32_16x16x32_bf16 v[92:95], v[212:215], v[180:183], v[92:95]
	v_mfma_f32_16x16x32_bf16 v[88:91], v[220:223], v[180:183], v[88:91]
	v_mfma_f32_16x16x32_bf16 v[84:87], v[212:215], v[188:191], v[84:87]
	v_mfma_f32_16x16x32_bf16 v[80:83], v[220:223], v[188:191], v[80:83]
	v_mfma_f32_16x16x32_bf16 v[76:79], v[212:215], v[196:199], v[76:79]
	v_mfma_f32_16x16x32_bf16 v[72:75], v[220:223], v[196:199], v[72:75]
	v_mfma_f32_16x16x32_bf16 v[68:71], v[212:215], v[204:207], v[68:71]
	v_mfma_f32_16x16x32_bf16 v[64:67], v[220:223], v[204:207], v[64:67]
	v_mfma_f32_16x16x32_bf16 v[92:95], v[216:219], v[184:187], v[92:95]
	v_mfma_f32_16x16x32_bf16 v[88:91], v[224:227], v[184:187], v[88:91]
	v_mfma_f32_16x16x32_bf16 v[84:87], v[216:219], v[192:195], v[84:87]
	v_mfma_f32_16x16x32_bf16 v[80:83], v[224:227], v[192:195], v[80:83]
	v_mfma_f32_16x16x32_bf16 v[76:79], v[216:219], v[200:203], v[76:79]
	v_mfma_f32_16x16x32_bf16 v[72:75], v[224:227], v[200:203], v[72:75]
	v_mfma_f32_16x16x32_bf16 v[68:71], v[216:219], v[208:211], v[68:71]
	v_mfma_f32_16x16x32_bf16 v[64:67], v[224:227], v[208:211], v[64:67]
	s_barrier
	ds_read_b128 v[180:183], v153 offset:16384
	ds_read_b128 v[184:187], v153 offset:17408
	ds_read_b128 v[188:191], v152 offset:16384
	ds_read_b128 v[192:195], v152 offset:17408
	ds_read_b128 v[196:199], v151 offset:16384
	ds_read_b128 v[200:203], v151 offset:17408
	ds_read_b128 v[204:207], v150 offset:16384
	ds_read_b128 v[208:211], v150 offset:17408
	s_mov_b64 s[66:67], 0x1882000
	v_readfirstlane_b32 s65, v146
	v_lshl_add_u64 v[232:233], v[230:231], 0, s[66:67]
	s_mov_b32 m0, s65
	s_mov_b64 s[66:67], 0x1883000
	v_readfirstlane_b32 s65, v145
	global_load_lds_dwordx4 v[232:233], off
	v_lshl_add_u64 v[232:233], v[230:231], 0, s[66:67]
	s_mov_b32 m0, s65
	s_nop 0
	global_load_lds_dwordx4 v[232:233], off
	s_barrier
	s_waitcnt lgkmcnt(0)
	s_waitcnt lgkmcnt(0)
	v_mfma_f32_16x16x32_bf16 v[60:63], v[164:167], v[180:183], v[60:63]
	v_mfma_f32_16x16x32_bf16 v[56:59], v[172:175], v[180:183], v[56:59]
	v_mfma_f32_16x16x32_bf16 v[52:55], v[164:167], v[188:191], v[52:55]
	v_mfma_f32_16x16x32_bf16 v[48:51], v[172:175], v[188:191], v[48:51]
	v_mfma_f32_16x16x32_bf16 v[44:47], v[164:167], v[196:199], v[44:47]
	v_mfma_f32_16x16x32_bf16 v[40:43], v[172:175], v[196:199], v[40:43]
	v_mfma_f32_16x16x32_bf16 v[36:39], v[164:167], v[204:207], v[36:39]
	v_mfma_f32_16x16x32_bf16 v[32:35], v[172:175], v[204:207], v[32:35]
	v_mfma_f32_16x16x32_bf16 v[60:63], v[168:171], v[184:187], v[60:63]
	v_mfma_f32_16x16x32_bf16 v[56:59], v[176:179], v[184:187], v[56:59]
	v_mfma_f32_16x16x32_bf16 v[52:55], v[168:171], v[192:195], v[52:55]
	v_mfma_f32_16x16x32_bf16 v[48:51], v[176:179], v[192:195], v[48:51]
	v_mfma_f32_16x16x32_bf16 v[44:47], v[168:171], v[200:203], v[44:47]
	v_mfma_f32_16x16x32_bf16 v[40:43], v[176:179], v[200:203], v[40:43]
	v_mfma_f32_16x16x32_bf16 v[36:39], v[168:171], v[208:211], v[36:39]
	v_mfma_f32_16x16x32_bf16 v[32:35], v[176:179], v[208:211], v[32:35]
	s_barrier
	v_readfirstlane_b32 s65, v144
	v_lshl_add_u64 v[166:167], v[228:229], 0, s[26:27]
	s_mov_b32 m0, s65
	v_readfirstlane_b32 s65, v143
	global_load_lds_dwordx4 v[166:167], off
	v_lshl_add_u64 v[166:167], v[228:229], 0, s[28:29]
	s_mov_b32 m0, s65
	s_nop 0
	global_load_lds_dwordx4 v[166:167], off
	s_waitcnt vmcnt(12)
	s_barrier
	v_mfma_f32_16x16x32_bf16 v[28:31], v[212:215], v[180:183], v[28:31]
	v_mfma_f32_16x16x32_bf16 v[24:27], v[220:223], v[180:183], v[24:27]
	v_mfma_f32_16x16x32_bf16 v[20:23], v[212:215], v[188:191], v[20:23]
	v_mfma_f32_16x16x32_bf16 v[16:19], v[220:223], v[188:191], v[16:19]
	v_mfma_f32_16x16x32_bf16 v[12:15], v[212:215], v[196:199], v[12:15]
	v_mfma_f32_16x16x32_bf16 v[8:11], v[220:223], v[196:199], v[8:11]
	v_mfma_f32_16x16x32_bf16 v[4:7], v[212:215], v[204:207], v[4:7]
	v_mfma_f32_16x16x32_bf16 v[0:3], v[220:223], v[204:207], v[0:3]
	v_mfma_f32_16x16x32_bf16 v[28:31], v[216:219], v[184:187], v[28:31]
	v_mfma_f32_16x16x32_bf16 v[24:27], v[224:227], v[184:187], v[24:27]
	v_mfma_f32_16x16x32_bf16 v[20:23], v[216:219], v[192:195], v[20:23]
	v_mfma_f32_16x16x32_bf16 v[16:19], v[224:227], v[192:195], v[16:19]
	v_mfma_f32_16x16x32_bf16 v[12:15], v[216:219], v[200:203], v[12:15]
	v_mfma_f32_16x16x32_bf16 v[8:11], v[224:227], v[200:203], v[8:11]
	v_mfma_f32_16x16x32_bf16 v[4:7], v[216:219], v[208:211], v[4:7]
	v_mfma_f32_16x16x32_bf16 v[0:3], v[224:227], v[208:211], v[0:3]
	s_barrier
	ds_read_b128 v[164:167], v155
	ds_read_b128 v[168:171], v155 offset:1024
	ds_read_b128 v[172:175], v155 offset:2048
	ds_read_b128 v[176:179], v155 offset:3072
	ds_read_b128 v[180:183], v153 offset:32768
	ds_read_b128 v[184:187], v153 offset:33792
	ds_read_b128 v[188:191], v152 offset:32768
	ds_read_b128 v[192:195], v152 offset:33792
	ds_read_b128 v[196:199], v151 offset:32768
	ds_read_b128 v[200:203], v151 offset:33792
	ds_read_b128 v[204:207], v150 offset:32768
	ds_read_b128 v[208:211], v150 offset:33792
	s_waitcnt lgkmcnt(8)
	s_waitcnt vmcnt(10)
	s_barrier
	s_waitcnt lgkmcnt(0)
	s_waitcnt lgkmcnt(0)
	v_mfma_f32_16x16x32_bf16 v[124:127], v[164:167], v[180:183], v[124:127]
	v_mfma_f32_16x16x32_bf16 v[120:123], v[172:175], v[180:183], v[120:123]
	v_mfma_f32_16x16x32_bf16 v[116:119], v[164:167], v[188:191], v[116:119]
	v_mfma_f32_16x16x32_bf16 v[112:115], v[172:175], v[188:191], v[112:115]
	v_mfma_f32_16x16x32_bf16 v[108:111], v[164:167], v[196:199], v[108:111]
	v_mfma_f32_16x16x32_bf16 v[104:107], v[172:175], v[196:199], v[104:107]
	v_mfma_f32_16x16x32_bf16 v[100:103], v[164:167], v[204:207], v[100:103]
	v_mfma_f32_16x16x32_bf16 v[96:99], v[172:175], v[204:207], v[96:99]
	v_mfma_f32_16x16x32_bf16 v[124:127], v[168:171], v[184:187], v[124:127]
	v_mfma_f32_16x16x32_bf16 v[120:123], v[176:179], v[184:187], v[120:123]
	v_mfma_f32_16x16x32_bf16 v[116:119], v[168:171], v[192:195], v[116:119]
	v_mfma_f32_16x16x32_bf16 v[112:115], v[176:179], v[192:195], v[112:115]
	v_mfma_f32_16x16x32_bf16 v[108:111], v[168:171], v[200:203], v[108:111]
	v_mfma_f32_16x16x32_bf16 v[104:107], v[176:179], v[200:203], v[104:107]
	v_mfma_f32_16x16x32_bf16 v[100:103], v[168:171], v[208:211], v[100:103]
	v_mfma_f32_16x16x32_bf16 v[96:99], v[176:179], v[208:211], v[96:99]
	s_barrier
	v_readfirstlane_b32 s65, v142
	v_lshl_add_u64 v[232:233], v[230:231], 0, s[30:31]
	s_mov_b32 m0, s65
	v_readfirstlane_b32 s65, v141
	ds_read_b128 v[212:215], v154
	ds_read_b128 v[216:219], v154 offset:1024
	ds_read_b128 v[220:223], v154 offset:2048
	ds_read_b128 v[224:227], v154 offset:3072
	global_load_lds_dwordx4 v[232:233], off
	v_lshl_add_u64 v[232:233], v[230:231], 0, s[34:35]
	s_mov_b32 m0, s65
	s_nop 0
	global_load_lds_dwordx4 v[232:233], off
	v_readfirstlane_b32 s65, v140
	v_lshl_add_u64 v[232:233], v[228:229], 0, s[40:41]
	s_mov_b32 m0, s65
	v_readfirstlane_b32 s65, v139
	global_load_lds_dwordx4 v[232:233], off
	v_lshl_add_u64 v[228:229], v[228:229], 0, s[44:45]
	s_mov_b32 m0, s65
	s_nop 0
	global_load_lds_dwordx4 v[228:229], off
	s_waitcnt vmcnt(12)
	s_barrier
	s_waitcnt lgkmcnt(0)
	s_waitcnt lgkmcnt(0)
	v_mfma_f32_16x16x32_bf16 v[92:95], v[212:215], v[180:183], v[92:95]
	v_mfma_f32_16x16x32_bf16 v[88:91], v[220:223], v[180:183], v[88:91]
	v_mfma_f32_16x16x32_bf16 v[84:87], v[212:215], v[188:191], v[84:87]
	v_mfma_f32_16x16x32_bf16 v[80:83], v[220:223], v[188:191], v[80:83]
	v_mfma_f32_16x16x32_bf16 v[76:79], v[212:215], v[196:199], v[76:79]
	v_mfma_f32_16x16x32_bf16 v[72:75], v[220:223], v[196:199], v[72:75]
	v_mfma_f32_16x16x32_bf16 v[68:71], v[212:215], v[204:207], v[68:71]
	v_mfma_f32_16x16x32_bf16 v[64:67], v[220:223], v[204:207], v[64:67]
	v_mfma_f32_16x16x32_bf16 v[92:95], v[216:219], v[184:187], v[92:95]
	v_mfma_f32_16x16x32_bf16 v[88:91], v[224:227], v[184:187], v[88:91]
	v_mfma_f32_16x16x32_bf16 v[84:87], v[216:219], v[192:195], v[84:87]
	v_mfma_f32_16x16x32_bf16 v[80:83], v[224:227], v[192:195], v[80:83]
	v_mfma_f32_16x16x32_bf16 v[76:79], v[216:219], v[200:203], v[76:79]
	v_mfma_f32_16x16x32_bf16 v[72:75], v[224:227], v[200:203], v[72:75]
	v_mfma_f32_16x16x32_bf16 v[68:71], v[216:219], v[208:211], v[68:71]
	v_mfma_f32_16x16x32_bf16 v[64:67], v[224:227], v[208:211], v[64:67]
	s_barrier
	ds_read_b128 v[180:183], v153 offset:49152
	ds_read_b128 v[184:187], v153 offset:50176
	ds_read_b128 v[188:191], v152 offset:49152
	ds_read_b128 v[192:195], v152 offset:50176
	ds_read_b128 v[196:199], v151 offset:49152
	ds_read_b128 v[200:203], v151 offset:50176
	ds_read_b128 v[204:207], v150 offset:49152
	ds_read_b128 v[208:211], v150 offset:50176
	v_readfirstlane_b32 s65, v138
	v_lshl_add_u64 v[232:233], v[230:231], 0, s[46:47]
	s_mov_b32 m0, s65
	v_readfirstlane_b32 s65, v137
	global_load_lds_dwordx4 v[232:233], off
	v_lshl_add_u64 v[232:233], v[230:231], 0, s[56:57]
	s_mov_b32 m0, s65
	s_nop 0
	global_load_lds_dwordx4 v[232:233], off
	s_barrier
	s_waitcnt lgkmcnt(0)
	s_waitcnt lgkmcnt(0)
	v_mfma_f32_16x16x32_bf16 v[60:63], v[164:167], v[180:183], v[60:63]
	v_mfma_f32_16x16x32_bf16 v[56:59], v[172:175], v[180:183], v[56:59]
	v_mfma_f32_16x16x32_bf16 v[52:55], v[164:167], v[188:191], v[52:55]
	v_mfma_f32_16x16x32_bf16 v[48:51], v[172:175], v[188:191], v[48:51]
	v_mfma_f32_16x16x32_bf16 v[44:47], v[164:167], v[196:199], v[44:47]
	v_mfma_f32_16x16x32_bf16 v[40:43], v[172:175], v[196:199], v[40:43]
	v_mfma_f32_16x16x32_bf16 v[36:39], v[164:167], v[204:207], v[36:39]
	v_mfma_f32_16x16x32_bf16 v[32:35], v[172:175], v[204:207], v[32:35]
	v_mfma_f32_16x16x32_bf16 v[60:63], v[168:171], v[184:187], v[60:63]
	v_mfma_f32_16x16x32_bf16 v[56:59], v[176:179], v[184:187], v[56:59]
	v_mfma_f32_16x16x32_bf16 v[52:55], v[168:171], v[192:195], v[52:55]
	v_mfma_f32_16x16x32_bf16 v[48:51], v[176:179], v[192:195], v[48:51]
	v_mfma_f32_16x16x32_bf16 v[44:47], v[168:171], v[200:203], v[44:47]
	v_mfma_f32_16x16x32_bf16 v[40:43], v[176:179], v[200:203], v[40:43]
	v_mfma_f32_16x16x32_bf16 v[36:39], v[168:171], v[208:211], v[36:39]
	v_mfma_f32_16x16x32_bf16 v[32:35], v[176:179], v[208:211], v[32:35]
	s_barrier
	v_lshl_add_u64 v[132:133], v[132:133], 0, s[58:59]
	v_lshl_add_u64 v[228:229], s[50:51], 0, v[132:133]
	s_mov_b64 s[66:67], 0xe080080
	v_readfirstlane_b32 s65, v161
	v_lshl_add_u64 v[166:167], v[228:229], 0, s[66:67]
	s_mov_b32 m0, s65
	s_mov_b64 s[66:67], 0xe0c0080
	v_readfirstlane_b32 s65, v160
	global_load_lds_dwordx4 v[166:167], off
	v_lshl_add_u64 v[166:167], v[228:229], 0, s[66:67]
	s_mov_b32 m0, s65
	s_nop 0
	global_load_lds_dwordx4 v[166:167], off
	s_waitcnt vmcnt(12)
	s_barrier
	v_mfma_f32_16x16x32_bf16 v[28:31], v[212:215], v[180:183], v[28:31]
	v_mfma_f32_16x16x32_bf16 v[24:27], v[220:223], v[180:183], v[24:27]
	v_mfma_f32_16x16x32_bf16 v[20:23], v[212:215], v[188:191], v[20:23]
	v_mfma_f32_16x16x32_bf16 v[16:19], v[220:223], v[188:191], v[16:19]
	v_mfma_f32_16x16x32_bf16 v[12:15], v[212:215], v[196:199], v[12:15]
	v_mfma_f32_16x16x32_bf16 v[8:11], v[220:223], v[196:199], v[8:11]
	v_mfma_f32_16x16x32_bf16 v[4:7], v[212:215], v[204:207], v[4:7]
	v_mfma_f32_16x16x32_bf16 v[0:3], v[220:223], v[204:207], v[0:3]
	v_mfma_f32_16x16x32_bf16 v[28:31], v[216:219], v[184:187], v[28:31]
	v_mfma_f32_16x16x32_bf16 v[24:27], v[224:227], v[184:187], v[24:27]
	v_mfma_f32_16x16x32_bf16 v[20:23], v[216:219], v[192:195], v[20:23]
	v_mfma_f32_16x16x32_bf16 v[16:19], v[224:227], v[192:195], v[16:19]
	v_mfma_f32_16x16x32_bf16 v[12:15], v[216:219], v[200:203], v[12:15]
	v_mfma_f32_16x16x32_bf16 v[8:11], v[224:227], v[200:203], v[8:11]
	v_mfma_f32_16x16x32_bf16 v[4:7], v[216:219], v[208:211], v[4:7]
	v_mfma_f32_16x16x32_bf16 v[0:3], v[224:227], v[208:211], v[0:3]
	s_add_i32 s24, s24, 2
	v_lshl_add_u64 v[130:131], v[130:131], 0, s[10:11]
	s_cmp_lt_u32 s24, 28
	s_barrier
	s_cbranch_scc1 .LBB0_178
	s_setprio 0
	s_lshl_b32 s24, s85, 5
	s_lshl_b32 s65, s85, 8
	s_and_b32 s24, s24, 0x1800
	s_and_b32 s65, s65, 0x700
	s_or_b32 s24, s65, s24
	v_lshlrev_b32_e32 v128, 3, v156
	v_lshlrev_b32_e32 v130, 5, v156
	v_and_b32_e32 v128, 0xffff0, v128
	v_and_b32_e32 v130, 32, v130
	s_lshl_b32 s65, s24, 12
	v_add_u32_e32 v130, v130, v158
	v_add_lshl_u32 v128, v157, v128, 12
	s_add_u32 s66, s68, s65
	v_lshl_add_u32 v128, v130, 1, v128
	s_addc_u32 s67, s69, 0
	v_lshl_add_u64 v[156:157], s[66:67], 0, v[128:129]
	v_readfirstlane_b32 s65, v161
	ds_read_b128 v[130:133], v162
	ds_read_b128 v[164:167], v162 offset:1024
	ds_read_b128 v[168:171], v162 offset:2048
	ds_read_b128 v[172:175], v162 offset:3072
	ds_read_b128 v[176:179], v153
	ds_read_b128 v[180:183], v153 offset:1024
	ds_read_b128 v[184:187], v152
	ds_read_b128 v[188:191], v152 offset:1024
	ds_read_b128 v[192:195], v151
	ds_read_b128 v[196:199], v151 offset:1024
	ds_read_b128 v[200:203], v150
	ds_read_b128 v[204:207], v150 offset:1024
	v_lshl_add_u64 v[162:163], v[156:157], 0, s[60:61]
	s_mov_b32 m0, s65
	v_readfirstlane_b32 s65, v160
	global_load_lds_dwordx4 v[162:163], off
	v_lshl_add_u64 v[156:157], v[156:157], 0, s[62:63]
	s_mov_b32 m0, s65
	s_nop 0
	global_load_lds_dwordx4 v[156:157], off
	s_waitcnt vmcnt(10)
	s_barrier
	s_waitcnt lgkmcnt(0)
	s_setprio 1
	s_waitcnt lgkmcnt(0)
	v_mfma_f32_16x16x32_bf16 v[124:127], v[130:133], v[176:179], v[124:127]
	v_mfma_f32_16x16x32_bf16 v[120:123], v[168:171], v[176:179], v[120:123]
	v_mfma_f32_16x16x32_bf16 v[116:119], v[130:133], v[184:187], v[116:119]
	v_mfma_f32_16x16x32_bf16 v[112:115], v[168:171], v[184:187], v[112:115]
	v_mfma_f32_16x16x32_bf16 v[108:111], v[130:133], v[192:195], v[108:111]
	v_mfma_f32_16x16x32_bf16 v[104:107], v[168:171], v[192:195], v[104:107]
	v_mfma_f32_16x16x32_bf16 v[100:103], v[130:133], v[200:203], v[100:103]
	v_mfma_f32_16x16x32_bf16 v[96:99], v[168:171], v[200:203], v[96:99]
	v_mfma_f32_16x16x32_bf16 v[124:127], v[164:167], v[180:183], v[124:127]
	v_mfma_f32_16x16x32_bf16 v[120:123], v[172:175], v[180:183], v[120:123]
	v_mfma_f32_16x16x32_bf16 v[116:119], v[164:167], v[188:191], v[116:119]
	v_mfma_f32_16x16x32_bf16 v[112:115], v[172:175], v[188:191], v[112:115]
	v_mfma_f32_16x16x32_bf16 v[108:111], v[164:167], v[196:199], v[108:111]
	v_mfma_f32_16x16x32_bf16 v[104:107], v[172:175], v[196:199], v[104:107]
	v_mfma_f32_16x16x32_bf16 v[100:103], v[164:167], v[204:207], v[100:103]
	v_mfma_f32_16x16x32_bf16 v[96:99], v[172:175], v[204:207], v[96:99]
	s_setprio 0
	s_barrier
	ds_read_b128 v[160:163], v159
	ds_read_b128 v[208:211], v159 offset:1024
	ds_read_b128 v[212:215], v159 offset:2048
	ds_read_b128 v[156:159], v159 offset:3072
	s_barrier
	s_waitcnt lgkmcnt(0)
	s_setprio 1
	s_waitcnt lgkmcnt(0)
	v_mfma_f32_16x16x32_bf16 v[92:95], v[160:163], v[176:179], v[92:95]
	v_mfma_f32_16x16x32_bf16 v[88:91], v[212:215], v[176:179], v[88:91]
	v_mfma_f32_16x16x32_bf16 v[84:87], v[160:163], v[184:187], v[84:87]
	v_mfma_f32_16x16x32_bf16 v[80:83], v[212:215], v[184:187], v[80:83]
	v_mfma_f32_16x16x32_bf16 v[76:79], v[160:163], v[192:195], v[76:79]
	v_mfma_f32_16x16x32_bf16 v[72:75], v[212:215], v[192:195], v[72:75]
	v_mfma_f32_16x16x32_bf16 v[68:71], v[160:163], v[200:203], v[68:71]
	v_mfma_f32_16x16x32_bf16 v[64:67], v[212:215], v[200:203], v[64:67]
	v_mfma_f32_16x16x32_bf16 v[176:179], v[208:211], v[180:183], v[92:95]
	v_mfma_f32_16x16x32_bf16 v[180:183], v[156:159], v[180:183], v[88:91]
	v_mfma_f32_16x16x32_bf16 v[184:187], v[208:211], v[188:191], v[84:87]
	v_mfma_f32_16x16x32_bf16 v[188:191], v[156:159], v[188:191], v[80:83]
	v_mfma_f32_16x16x32_bf16 v[192:195], v[208:211], v[196:199], v[76:79]
	v_mfma_f32_16x16x32_bf16 v[196:199], v[156:159], v[196:199], v[72:75]
	v_mfma_f32_16x16x32_bf16 v[200:203], v[208:211], v[204:207], v[68:71]
	v_mfma_f32_16x16x32_bf16 v[204:207], v[156:159], v[204:207], v[64:67]
	s_setprio 0
	s_barrier
	s_nop 0
	ds_read_b128 v[64:67], v153 offset:16384
	ds_read_b128 v[68:71], v153 offset:17408
	ds_read_b128 v[72:75], v152 offset:16384
	ds_read_b128 v[76:79], v152 offset:17408
	ds_read_b128 v[80:83], v151 offset:16384
	ds_read_b128 v[84:87], v151 offset:17408
	ds_read_b128 v[88:91], v150 offset:16384
	ds_read_b128 v[92:95], v150 offset:17408
	s_waitcnt vmcnt(4)
	s_barrier
	s_waitcnt lgkmcnt(0)
	s_setprio 1
	s_waitcnt lgkmcnt(0)
	v_mfma_f32_16x16x32_bf16 v[60:63], v[130:133], v[64:67], v[60:63]
	v_mfma_f32_16x16x32_bf16 v[56:59], v[168:171], v[64:67], v[56:59]
	v_mfma_f32_16x16x32_bf16 v[52:55], v[130:133], v[72:75], v[52:55]
	v_mfma_f32_16x16x32_bf16 v[48:51], v[168:171], v[72:75], v[48:51]
	v_mfma_f32_16x16x32_bf16 v[216:219], v[130:133], v[80:83], v[44:47]
	v_mfma_f32_16x16x32_bf16 v[220:223], v[168:171], v[80:83], v[40:43]
	v_mfma_f32_16x16x32_bf16 v[130:133], v[130:133], v[88:91], v[36:39]
	v_mfma_f32_16x16x32_bf16 v[168:171], v[168:171], v[88:91], v[32:35]
	v_mfma_f32_16x16x32_bf16 v[32:35], v[164:167], v[68:71], v[60:63]
	v_mfma_f32_16x16x32_bf16 v[36:39], v[172:175], v[68:71], v[56:59]
	v_mfma_f32_16x16x32_bf16 v[40:43], v[164:167], v[76:79], v[52:55]
	v_mfma_f32_16x16x32_bf16 v[44:47], v[172:175], v[76:79], v[48:51]
	v_mfma_f32_16x16x32_bf16 v[48:51], v[164:167], v[84:87], v[216:219]
	v_mfma_f32_16x16x32_bf16 v[52:55], v[172:175], v[84:87], v[220:223]
	v_mfma_f32_16x16x32_bf16 v[56:59], v[164:167], v[92:95], v[130:133]
	v_mfma_f32_16x16x32_bf16 v[60:63], v[172:175], v[92:95], v[168:171]
	s_setprio 0
	s_setprio 1
	v_mfma_f32_16x16x32_bf16 v[28:31], v[160:163], v[64:67], v[28:31]
	v_mfma_f32_16x16x32_bf16 v[24:27], v[212:215], v[64:67], v[24:27]
	v_mfma_f32_16x16x32_bf16 v[20:23], v[160:163], v[72:75], v[20:23]
	v_mfma_f32_16x16x32_bf16 v[64:67], v[212:215], v[72:75], v[16:19]
	v_mfma_f32_16x16x32_bf16 v[72:75], v[160:163], v[80:83], v[12:15]
	v_mfma_f32_16x16x32_bf16 v[8:11], v[212:215], v[80:83], v[8:11]
	v_mfma_f32_16x16x32_bf16 v[80:83], v[160:163], v[88:91], v[4:7]
	v_mfma_f32_16x16x32_bf16 v[0:3], v[212:215], v[88:91], v[0:3]
	v_mfma_f32_16x16x32_bf16 v[4:7], v[208:211], v[68:71], v[28:31]
	v_mfma_f32_16x16x32_bf16 v[12:15], v[156:159], v[68:71], v[24:27]
	v_mfma_f32_16x16x32_bf16 v[16:19], v[208:211], v[76:79], v[20:23]
	v_mfma_f32_16x16x32_bf16 v[20:23], v[156:159], v[76:79], v[64:67]
	v_mfma_f32_16x16x32_bf16 v[24:27], v[208:211], v[84:87], v[72:75]
	v_mfma_f32_16x16x32_bf16 v[28:31], v[156:159], v[84:87], v[8:11]
	v_mfma_f32_16x16x32_bf16 v[64:67], v[208:211], v[92:95], v[80:83]
	v_mfma_f32_16x16x32_bf16 v[68:71], v[156:159], v[92:95], v[0:3]
	s_setprio 0
	s_barrier
	ds_read_b128 v[8:11], v155
	ds_read_b128 v[0:3], v155 offset:1024
	ds_read_b128 v[76:79], v155 offset:2048
	ds_read_b128 v[72:75], v155 offset:3072
	ds_read_b128 v[130:133], v153 offset:32768
	ds_read_b128 v[156:159], v153 offset:33792
	ds_read_b128 v[160:163], v152 offset:32768
	ds_read_b128 v[164:167], v152 offset:33792
	ds_read_b128 v[168:171], v151 offset:32768
	ds_read_b128 v[172:175], v151 offset:33792
	ds_read_b128 v[208:211], v150 offset:32768
	ds_read_b128 v[212:215], v150 offset:33792
	s_waitcnt vmcnt(2)
	s_barrier
	s_waitcnt lgkmcnt(0)
	s_setprio 1
	s_waitcnt lgkmcnt(0)
	v_mfma_f32_16x16x32_bf16 v[80:83], v[8:11], v[130:133], v[124:127]
	v_mfma_f32_16x16x32_bf16 v[84:87], v[76:79], v[130:133], v[120:123]
	v_mfma_f32_16x16x32_bf16 v[88:91], v[8:11], v[160:163], v[116:119]
	v_mfma_f32_16x16x32_bf16 v[92:95], v[76:79], v[160:163], v[112:115]
	v_mfma_f32_16x16x32_bf16 v[108:111], v[8:11], v[168:171], v[108:111]
	v_mfma_f32_16x16x32_bf16 v[104:107], v[76:79], v[168:171], v[104:107]
	v_mfma_f32_16x16x32_bf16 v[100:103], v[8:11], v[208:211], v[100:103]
	v_mfma_f32_16x16x32_bf16 v[96:99], v[76:79], v[208:211], v[96:99]
	v_mfma_f32_16x16x32_bf16 v[112:115], v[0:3], v[156:159], v[80:83]
	v_mfma_f32_16x16x32_bf16 v[116:119], v[72:75], v[156:159], v[84:87]
	v_mfma_f32_16x16x32_bf16 v[120:123], v[0:3], v[164:167], v[88:91]
	v_mfma_f32_16x16x32_bf16 v[124:127], v[72:75], v[164:167], v[92:95]
	v_mfma_f32_16x16x32_bf16 v[108:111], v[0:3], v[172:175], v[108:111]
	v_mfma_f32_16x16x32_bf16 v[104:107], v[72:75], v[172:175], v[104:107]
	v_mfma_f32_16x16x32_bf16 v[100:103], v[0:3], v[212:215], v[100:103]
	v_mfma_f32_16x16x32_bf16 v[96:99], v[72:75], v[212:215], v[96:99]
	s_setprio 0
	s_barrier
	ds_read_b128 v[88:91], v154
	ds_read_b128 v[80:83], v154 offset:1024
	ds_read_b128 v[92:95], v154 offset:2048
	ds_read_b128 v[84:87], v154 offset:3072
	s_waitcnt vmcnt(0)
	s_barrier
	s_waitcnt lgkmcnt(0)
	s_setprio 1
	s_waitcnt lgkmcnt(0)
	v_mfma_f32_16x16x32_bf16 v[176:179], v[88:91], v[130:133], v[176:179]
	v_mfma_f32_16x16x32_bf16 v[130:133], v[92:95], v[130:133], v[180:183]
	v_mfma_f32_16x16x32_bf16 v[180:183], v[88:91], v[160:163], v[184:187]
	v_mfma_f32_16x16x32_bf16 v[160:163], v[92:95], v[160:163], v[188:191]
	v_mfma_f32_16x16x32_bf16 v[184:187], v[88:91], v[168:171], v[192:195]
	v_mfma_f32_16x16x32_bf16 v[168:171], v[92:95], v[168:171], v[196:199]
	v_mfma_f32_16x16x32_bf16 v[188:191], v[88:91], v[208:211], v[200:203]
	v_mfma_f32_16x16x32_bf16 v[192:195], v[92:95], v[208:211], v[204:207]
	v_mfma_f32_16x16x32_bf16 v[176:179], v[80:83], v[156:159], v[176:179]
	v_mfma_f32_16x16x32_bf16 v[130:133], v[84:87], v[156:159], v[130:133]
	v_mfma_f32_16x16x32_bf16 v[154:157], v[80:83], v[164:167], v[180:183]
	v_mfma_f32_16x16x32_bf16 v[158:161], v[84:87], v[164:167], v[160:163]
	v_mfma_f32_16x16x32_bf16 v[162:165], v[80:83], v[172:175], v[184:187]
	v_mfma_f32_16x16x32_bf16 v[166:169], v[84:87], v[172:175], v[168:171]
	v_mfma_f32_16x16x32_bf16 v[170:173], v[80:83], v[212:215], v[188:191]
	v_mfma_f32_16x16x32_bf16 v[180:183], v[84:87], v[212:215], v[192:195]
	s_setprio 0
	s_barrier
	v_mbcnt_lo_u32_b32 v128, -1, 0
	v_mbcnt_hi_u32_b32 v128, -1, v128
	v_cvt_pk_bf16_f32 v112, v112, v113
	v_cvt_pk_bf16_f32 v113, v114, v115
	v_cvt_pk_bf16_f32 v114, v116, v117
	v_cvt_pk_bf16_f32 v115, v118, v119
	s_lshl_b32 s66, s64, 9
	v_add_u32_e32 v174, s72, v128
	v_ashrrev_i32_e32 v175, 6, v174
	v_and_b32_e32 v184, 15, v128
	v_and_b32_e32 v185, 48, v128
	v_mul_lo_u32 v186, v175, s77
	v_bfe_u32 v187, v128, 3, 3
	v_lshlrev_b32_e32 v128, 4, v128
	v_add_u32_e32 v186, 0x20000, v186
	v_lshrrev_b32_e32 v174, 2, v174
	v_and_b32_e32 v128, 0x70, v128
	v_mul_u32_u24_e32 v184, 0x90, v184
	v_and_b32_e32 v174, 64, v174
	v_add3_u32 v184, v186, v184, v185
	v_or_b32_e32 v185, v186, v128
	v_or3_b32 v174, s24, v174, v187
	v_mad_u32_u24 v185, v187, s78, v185
	ds_write_b128 v184, v[112:115]
	v_cvt_pk_bf16_f32 v112, v176, v177
	v_cvt_pk_bf16_f32 v113, v178, v179
	v_cvt_pk_bf16_f32 v114, v130, v131
	v_cvt_pk_bf16_f32 v115, v132, v133
	ds_write_b128 v184, v[112:115] offset:64
	v_lshlrev_b32_e32 v175, 7, v175
	ds_read_b128 v[112:115], v185
	v_lshlrev_b32_e32 v116, 12, v174
	v_and_or_b32 v116, v175, s79, v116
	v_or3_b32 v128, v116, s66, v128
	ds_read_b128 v[116:119], v185 offset:1152
	v_lshl_add_u64 v[130:131], s[0:1], 0, v[128:129]
	s_mov_b32 s64, 0x8000
	s_waitcnt lgkmcnt(0)
	global_store_dwordx4 v128, v[112:115], s[0:1]
	v_cvt_pk_bf16_f32 v108, v108, v109
	v_cvt_pk_bf16_f32 v109, v110, v111
	v_cvt_pk_bf16_f32 v110, v104, v105
	v_cvt_pk_bf16_f32 v111, v106, v107
	v_cvt_pk_bf16_f32 v104, v162, v163
	s_nop 1
	v_add_co_u32_e32 v112, vcc, s64, v130
	v_cvt_pk_bf16_f32 v114, v124, v125
	v_cvt_pk_bf16_f32 v115, v126, v127
	v_cvt_pk_bf16_f32 v105, v164, v165
	v_cvt_pk_bf16_f32 v106, v166, v167
	s_nop 1
	v_addc_co_u32_e32 v113, vcc, 0, v131, vcc
	global_store_dwordx4 v[112:113], v[116:119], off
	v_cvt_pk_bf16_f32 v112, v120, v121
	v_cvt_pk_bf16_f32 v113, v122, v123
	ds_write_b128 v184, v[112:115]
	v_cvt_pk_bf16_f32 v112, v154, v155
	v_cvt_pk_bf16_f32 v113, v156, v157
	v_cvt_pk_bf16_f32 v114, v158, v159
	v_cvt_pk_bf16_f32 v115, v160, v161
	ds_write_b128 v184, v[112:115] offset:64
	ds_read_b128 v[112:115], v185
	ds_read_b128 v[116:119], v185 offset:1152
	v_add_co_u32_e32 v120, vcc, s74, v130
	ds_write_b128 v184, v[108:111]
	v_cvt_pk_bf16_f32 v107, v168, v169
	ds_write_b128 v184, v[104:107] offset:64
	v_addc_co_u32_e32 v121, vcc, 0, v131, vcc
	ds_read_b128 v[104:107], v185
	ds_read_b128 v[108:111], v185 offset:1152
	s_waitcnt lgkmcnt(0)
	global_store_dwordx4 v[120:121], v[112:115], off
	v_cvt_pk_bf16_f32 v100, v100, v101
	v_cvt_pk_bf16_f32 v101, v102, v103
	v_cvt_pk_bf16_f32 v102, v96, v97
	v_cvt_pk_bf16_f32 v103, v98, v99
	ds_write_b128 v184, v[100:103]
	s_nop 0
	v_add_co_u32_e32 v112, vcc, s75, v130
	v_cvt_pk_bf16_f32 v96, v170, v171
	v_cvt_pk_bf16_f32 v97, v172, v173
	v_cvt_pk_bf16_f32 v98, v180, v181
	v_cvt_pk_bf16_f32 v99, v182, v183
	s_nop 1
	v_addc_co_u32_e32 v113, vcc, 0, v131, vcc
	global_store_dwordx4 v[112:113], v[116:119], off
	v_add_co_u32_e32 v112, vcc, s76, v130
	ds_write_b128 v184, v[96:99] offset:64
	s_nop 0
	v_addc_co_u32_e32 v113, vcc, 0, v131, vcc
	ds_read_b128 v[96:99], v185
	ds_read_b128 v[100:103], v185 offset:1152
	global_store_dwordx4 v[112:113], v[104:107], off
	s_nop 1
	v_add_co_u32_e32 v104, vcc, s80, v130
	s_nop 1
	v_addc_co_u32_e32 v105, vcc, 0, v131, vcc
	global_store_dwordx4 v[104:105], v[108:111], off
	v_add_co_u32_e32 v104, vcc, s81, v130
	s_nop 1
	v_addc_co_u32_e32 v105, vcc, 0, v131, vcc
	s_waitcnt lgkmcnt(0)
	global_store_dwordx4 v[104:105], v[96:99], off
	s_nop 1
	v_add_co_u32_e32 v96, vcc, s82, v130
	s_nop 1
	v_addc_co_u32_e32 v97, vcc, 0, v131, vcc
	global_store_dwordx4 v[96:97], v[100:103], off
	ds_read_b128 v[96:99], v153 offset:49152
	ds_read_b128 v[100:103], v153 offset:50176
	ds_read_b128 v[104:107], v152 offset:49152
	ds_read_b128 v[108:111], v152 offset:50176
	ds_read_b128 v[112:115], v151 offset:49152
	ds_read_b128 v[116:119], v151 offset:50176
	ds_read_b128 v[120:123], v150 offset:49152
	ds_read_b128 v[124:127], v150 offset:50176
	s_barrier
	s_waitcnt lgkmcnt(0)
	s_setprio 1
	s_waitcnt lgkmcnt(0)
	v_mfma_f32_16x16x32_bf16 v[32:35], v[8:11], v[96:99], v[32:35]
	v_mfma_f32_16x16x32_bf16 v[36:39], v[76:79], v[96:99], v[36:39]
	v_mfma_f32_16x16x32_bf16 v[40:43], v[8:11], v[104:107], v[40:43]
	v_mfma_f32_16x16x32_bf16 v[130:133], v[76:79], v[104:107], v[44:47]
	v_mfma_f32_16x16x32_bf16 v[150:153], v[8:11], v[112:115], v[48:51]
	v_mfma_f32_16x16x32_bf16 v[52:55], v[76:79], v[112:115], v[52:55]
	v_mfma_f32_16x16x32_bf16 v[8:11], v[8:11], v[120:123], v[56:59]
	v_mfma_f32_16x16x32_bf16 v[60:63], v[76:79], v[120:123], v[60:63]
	v_mfma_f32_16x16x32_bf16 v[56:59], v[0:3], v[100:103], v[32:35]
	v_mfma_f32_16x16x32_bf16 v[48:51], v[72:75], v[100:103], v[36:39]
	v_mfma_f32_16x16x32_bf16 v[44:47], v[0:3], v[108:111], v[40:43]
	v_mfma_f32_16x16x32_bf16 v[40:43], v[72:75], v[108:111], v[130:133]
	v_mfma_f32_16x16x32_bf16 v[36:39], v[0:3], v[116:119], v[150:153]
	v_mfma_f32_16x16x32_bf16 v[32:35], v[72:75], v[116:119], v[52:55]
	v_mfma_f32_16x16x32_bf16 v[8:11], v[0:3], v[124:127], v[8:11]
	v_mfma_f32_16x16x32_bf16 v[0:3], v[72:75], v[124:127], v[60:63]
	s_setprio 0
	s_setprio 1
	v_mfma_f32_16x16x32_bf16 v[4:7], v[88:91], v[96:99], v[4:7]
	v_mfma_f32_16x16x32_bf16 v[12:15], v[92:95], v[96:99], v[12:15]
	v_mfma_f32_16x16x32_bf16 v[16:19], v[88:91], v[104:107], v[16:19]
	v_mfma_f32_16x16x32_bf16 v[20:23], v[92:95], v[104:107], v[20:23]
	v_mfma_f32_16x16x32_bf16 v[72:75], v[88:91], v[112:115], v[24:27]
	v_mfma_f32_16x16x32_bf16 v[76:79], v[92:95], v[112:115], v[28:31]
	v_mfma_f32_16x16x32_bf16 v[64:67], v[88:91], v[120:123], v[64:67]
	v_mfma_f32_16x16x32_bf16 v[68:71], v[92:95], v[120:123], v[68:71]
	v_mfma_f32_16x16x32_bf16 v[60:63], v[80:83], v[100:103], v[4:7]
	v_mfma_f32_16x16x32_bf16 v[52:55], v[84:87], v[100:103], v[12:15]
	v_mfma_f32_16x16x32_bf16 v[28:31], v[80:83], v[108:111], v[16:19]
	v_mfma_f32_16x16x32_bf16 v[24:27], v[84:87], v[108:111], v[20:23]
	v_mfma_f32_16x16x32_bf16 v[20:23], v[80:83], v[116:119], v[72:75]
	v_mfma_f32_16x16x32_bf16 v[16:19], v[84:87], v[116:119], v[76:79]
	v_mfma_f32_16x16x32_bf16 v[12:15], v[80:83], v[124:127], v[64:67]
	v_mfma_f32_16x16x32_bf16 v[4:7], v[84:87], v[124:127], v[68:71]
	s_setprio 0
	v_cmp_gt_u32_e32 vcc, s83, v136
	s_barrier
	s_and_saveexec_b64 s[64:65], vcc
	s_cbranch_execz .LBB0_181
	s_barrier

.LBB0_233:
	v_bfe_i32 v5, v179, 27, 1
	v_lshlrev_b32_e32 v169, 4, v179
	v_lshrrev_b32_e32 v5, 22, v5
	v_add_u32_e32 v5, v169, v5
	v_and_b32_e32 v5, 0xfffffc00, v5
	v_sub_u32_e32 v5, v169, v5
	v_lshrrev_b32_e32 v6, 4, v5
	v_bitop3_b32 v5, v6, v5, 32 bitop3:0x6c
	v_ashrrev_i32_e32 v6, 31, v5
	v_lshrrev_b32_e32 v6, 26, v6
	v_ashrrev_i32_e32 v4, 31, v179
	v_add_u32_e32 v6, v5, v6
	s_lshl_b32 s56, s83, 3
	v_lshrrev_b32_e32 v4, 26, v4
	v_ashrrev_i32_e32 v133, 6, v6
	v_and_b32_e32 v6, 0xc0, v6
	s_ff1_i32_b32 s57, s56
	s_add_i32 s56, s56, -1
	v_and_b32_e32 v2, 15, v0
	v_and_b32_e32 v3, 48, v0
	v_add_u32_e32 v4, v179, v4
	v_sub_u32_e32 v5, v5, v6
	v_and_b32_e32 v6, 32, v0
	v_lshlrev_b32_e32 v10, 2, v0
	v_lshlrev_b32_e32 v0, 6, v0
	s_lshr_b32 s62, s85, s57
	s_and_b32 s56, s85, s56
	s_and_b32 s63, s85, 7
	v_ashrrev_i32_e32 v131, 6, v4
	v_lshlrev_b32_e32 v2, 6, v2
	v_and_b32_e32 v10, 32, v10
	v_and_b32_e32 v0, 0x3c0, v0
	s_lshr_b32 s80, s56, 3
	v_or_b32_e32 v9, v2, v3
	v_bitop3_b32 v2, v2, v10, v3 bitop3:0x36
	v_bitop3_b32 v3, v0, v10, v3 bitop3:0x36
	s_lshl_b32 s56, s62, 11
	s_lshl_b32 s57, s63, 8
	v_lshlrev_b32_e32 v0, 16, v131
	s_or_b32 s56, s56, s57
	s_mov_b32 s57, s15
	v_and_b32_e32 v0, 0xfffe0000, v0
	s_lshl_b32 s60, s80, 14
	v_ashrrev_i16_sdwa v5, v167, sext(v5) dst_sel:DWORD dst_unused:UNUSED_PAD src0_sel:DWORD src1_sel:BYTE_0
	s_lshl_b64 s[56:57], s[56:57], 13
	v_lshl_add_u32 v0, v133, 13, v0
	v_bfe_i32 v134, v5, 0, 16
	v_and_or_b32 v0, v4, 64, v0
	s_add_u32 s56, s40, s56
	v_lshl_add_u32 v164, v134, 1, v0
	s_addc_u32 s57, s41, s57
	v_lshlrev_b32_e32 v14, 13, v1
	v_lshl_add_u64 v[0:1], s[56:57], 0, v[164:165]
	s_mul_i32 s57, s14, 0x1800
	s_mul_hi_u32 s56, s14, 0x1800
	s_add_u32 s57, s57, s60
	s_addc_u32 s58, s56, 0
	s_add_u32 s56, s65, s57
	v_bfe_i32 v7, v179, 6, 1
	s_addc_u32 s57, s66, s58
	s_lshl_b64 s[58:59], s[14:15], 12
	v_and_b32_e32 v7, s14, v7
	v_lshrrev_b32_e32 v8, 7, v179
	s_add_u32 s14, s58, s60
	v_add_lshl_u32 v7, v7, v8, 10
	v_lshlrev_b32_e32 v8, 6, v179
	s_addc_u32 s61, s59, 0
	v_and_b32_e32 v5, 0x3f0, v169
	v_and_b32_e32 v8, 0x3000, v8
	v_bitop3_b32 v11, v9, s67, v10 bitop3:0xde
	v_bitop3_b32 v12, v9, s69, v10 bitop3:0xde
	v_bitop3_b32 v13, v9, s70, v10 bitop3:0xde
	v_bitop3_b32 v9, v9, s71, v10 bitop3:0xde
	v_or_b32_e32 v10, 0x800, v14
	v_or_b32_e32 v15, 0x1000, v14
	v_or_b32_e32 v16, 0x1800, v14
	v_lshl_add_u64 v[128:129], v[0:1], 0, s[16:17]
	s_add_u32 s60, s65, s14
	v_mov_b32_e32 v0, 0
	v_bitop3_b32 v164, v5, v7, v6 bitop3:0xde
	s_addc_u32 s61, s66, s61
	s_mov_b32 s14, -2
	v_add_u32_e32 v138, v11, v8
	v_add_u32_e32 v193, v2, v14
	v_add_u32_e32 v192, v3, v10
	v_add_u32_e32 v191, v3, v15
	v_add_u32_e32 v190, v3, v16
	v_add_u32_e32 v137, 0xc000, v169
	v_add_u32_e32 v136, 0xe000, v169
	v_add_u32_e32 v135, v12, v8
	v_add_u32_e32 v189, 0x10000, v169
	v_add_u32_e32 v188, 0x12000, v169
	v_add_u32_e32 v187, 0x2000, v169
	v_add_u32_e32 v186, 0x14000, v169
	v_add_u32_e32 v185, 0x16000, v169
	v_add_u32_e32 v130, v13, v8
	v_add_u32_e32 v184, 0x4000, v169
	v_add_u32_e32 v183, 0x6000, v169
	v_add_u32_e32 v132, v9, v8
	v_add_u32_e32 v182, 0x18000, v169
	v_add_u32_e32 v181, 0x1a000, v169
	v_add_u32_e32 v177, 0x8000, v169
	v_add_u32_e32 v175, 0xa000, v169
	v_add_u32_e32 v173, 0x1c000, v169
	v_add_u32_e32 v171, 0x1e000, v169
	v_mov_b32_e32 v1, v0
	v_mov_b32_e32 v2, v0
	v_mov_b32_e32 v3, v0
	v_mov_b32_e32 v4, v0
	v_mov_b32_e32 v5, v0
	v_mov_b32_e32 v6, v0
	v_mov_b32_e32 v7, v0
	v_mov_b32_e32 v8, v0
	v_mov_b32_e32 v9, v0
	v_mov_b32_e32 v10, v0
	v_mov_b32_e32 v11, v0
	v_mov_b32_e32 v12, v0
	v_mov_b32_e32 v13, v0
	v_mov_b32_e32 v14, v0
	v_mov_b32_e32 v15, v0
	v_mov_b32_e32 v16, v0
	v_mov_b32_e32 v17, v0
	v_mov_b32_e32 v18, v0
	v_mov_b32_e32 v19, v0
	v_mov_b32_e32 v20, v0
	v_mov_b32_e32 v21, v0
	v_mov_b32_e32 v22, v0
	v_mov_b32_e32 v23, v0
	v_mov_b32_e32 v24, v0
	v_mov_b32_e32 v25, v0
	v_mov_b32_e32 v26, v0
	v_mov_b32_e32 v27, v0
	v_mov_b32_e32 v28, v0
	v_mov_b32_e32 v29, v0
	v_mov_b32_e32 v30, v0
	v_mov_b32_e32 v31, v0
	v_mov_b32_e32 v32, v0
	v_mov_b32_e32 v33, v0
	v_mov_b32_e32 v34, v0
	v_mov_b32_e32 v35, v0
	v_mov_b32_e32 v36, v0
	v_mov_b32_e32 v37, v0
	v_mov_b32_e32 v38, v0
	v_mov_b32_e32 v39, v0
	v_mov_b32_e32 v40, v0
	v_mov_b32_e32 v41, v0
	v_mov_b32_e32 v42, v0
	v_mov_b32_e32 v43, v0
	v_mov_b32_e32 v44, v0
	v_mov_b32_e32 v45, v0
	v_mov_b32_e32 v46, v0
	v_mov_b32_e32 v47, v0
	v_mov_b32_e32 v48, v0
	v_mov_b32_e32 v49, v0
	v_mov_b32_e32 v50, v0
	v_mov_b32_e32 v51, v0
	v_mov_b32_e32 v52, v0
	v_mov_b32_e32 v53, v0
	v_mov_b32_e32 v54, v0
	v_mov_b32_e32 v55, v0
	v_mov_b32_e32 v56, v0
	v_mov_b32_e32 v57, v0
	v_mov_b32_e32 v58, v0
	v_mov_b32_e32 v59, v0
	v_mov_b32_e32 v60, v0
	v_mov_b32_e32 v61, v0
	v_mov_b32_e32 v62, v0
	v_mov_b32_e32 v63, v0
	v_mov_b32_e32 v64, v0
	v_mov_b32_e32 v65, v0
	v_mov_b32_e32 v66, v0
	v_mov_b32_e32 v67, v0
	v_mov_b32_e32 v68, v0
	v_mov_b32_e32 v69, v0
	v_mov_b32_e32 v70, v0
	v_mov_b32_e32 v71, v0
	v_mov_b32_e32 v72, v0
	v_mov_b32_e32 v73, v0
	v_mov_b32_e32 v74, v0
	v_mov_b32_e32 v75, v0
	v_mov_b32_e32 v76, v0
	v_mov_b32_e32 v77, v0
	v_mov_b32_e32 v78, v0
	v_mov_b32_e32 v79, v0
	v_mov_b32_e32 v80, v0
	v_mov_b32_e32 v81, v0
	v_mov_b32_e32 v82, v0
	v_mov_b32_e32 v83, v0
	v_mov_b32_e32 v84, v0
	v_mov_b32_e32 v85, v0
	v_mov_b32_e32 v86, v0
	v_mov_b32_e32 v87, v0
	v_mov_b32_e32 v88, v0
	v_mov_b32_e32 v89, v0
	v_mov_b32_e32 v90, v0
	v_mov_b32_e32 v91, v0
	v_mov_b32_e32 v92, v0
	v_mov_b32_e32 v93, v0
	v_mov_b32_e32 v94, v0
	v_mov_b32_e32 v95, v0
	v_mov_b32_e32 v96, v0
	v_mov_b32_e32 v97, v0
	v_mov_b32_e32 v98, v0
	v_mov_b32_e32 v99, v0
	v_mov_b32_e32 v100, v0
	v_mov_b32_e32 v101, v0
	v_mov_b32_e32 v102, v0
	v_mov_b32_e32 v103, v0
	v_mov_b32_e32 v104, v0
	v_mov_b32_e32 v105, v0
	v_mov_b32_e32 v106, v0
	v_mov_b32_e32 v107, v0
	v_mov_b32_e32 v108, v0
	v_mov_b32_e32 v109, v0
	v_mov_b32_e32 v110, v0
	v_mov_b32_e32 v111, v0
	v_mov_b32_e32 v112, v0
	v_mov_b32_e32 v113, v0
	v_mov_b32_e32 v114, v0
	v_mov_b32_e32 v115, v0
	v_mov_b32_e32 v116, v0
	v_mov_b32_e32 v117, v0
	v_mov_b32_e32 v118, v0
	v_mov_b32_e32 v119, v0
	v_mov_b32_e32 v120, v0
	v_mov_b32_e32 v121, v0
	v_mov_b32_e32 v122, v0
	v_mov_b32_e32 v123, v0
	v_mov_b32_e32 v124, v0
	v_mov_b32_e32 v125, v0
	v_mov_b32_e32 v126, v0
	v_mov_b32_e32 v127, v0
	s_barrier
	v_readlane_b32 s98, v242, 1
	s_nop 3
	s_cmp_lt_u32 s98, 4
	s_cbranch_scc1 .Lprio_234
	s_setprio 1
.Lprio_234:
	v_readfirstlane_b32 s82, v137
	v_lshl_add_u64 v[142:143], v[128:129], 0, s[18:19]
	s_mov_b32 m0, s82
	v_readfirstlane_b32 s82, v136
	global_load_lds_dwordx4 v[142:143], off
	v_lshl_add_u64 v[142:143], v[128:129], 0, s[20:21]
	s_mov_b32 m0, s82
	s_nop 0
	global_load_lds_dwordx4 v[142:143], off
.LBB0_234:
	ds_read_b128 v[140:143], v138
	ds_read_b128 v[144:147], v138 offset:1024
	ds_read_b128 v[148:151], v138 offset:2048
	ds_read_b128 v[152:155], v138 offset:3072
	ds_read_b128 v[156:159], v193
	ds_read_b128 v[160:163], v193 offset:1024
	ds_read_b128 v[194:197], v192
	ds_read_b128 v[198:201], v192 offset:1024
	ds_read_b128 v[202:205], v191
	ds_read_b128 v[206:209], v191 offset:1024
	ds_read_b128 v[210:213], v190
	ds_read_b128 v[214:217], v190 offset:1024
	s_waitcnt lgkmcnt(8)
	s_waitcnt vmcnt(10)
	s_barrier
	s_waitcnt lgkmcnt(0)
	s_waitcnt lgkmcnt(0)
	v_mfma_f32_16x16x32_bf16 v[124:127], v[140:143], v[156:159], v[124:127]
	v_mfma_f32_16x16x32_bf16 v[120:123], v[148:151], v[156:159], v[120:123]
	v_mfma_f32_16x16x32_bf16 v[116:119], v[140:143], v[194:197], v[116:119]
	v_mfma_f32_16x16x32_bf16 v[112:115], v[148:151], v[194:197], v[112:115]
	v_mfma_f32_16x16x32_bf16 v[108:111], v[140:143], v[202:205], v[108:111]
	v_mfma_f32_16x16x32_bf16 v[104:107], v[148:151], v[202:205], v[104:107]
	v_mfma_f32_16x16x32_bf16 v[100:103], v[140:143], v[210:213], v[100:103]
	v_mfma_f32_16x16x32_bf16 v[96:99], v[148:151], v[210:213], v[96:99]
	v_mfma_f32_16x16x32_bf16 v[124:127], v[144:147], v[160:163], v[124:127]
	v_mfma_f32_16x16x32_bf16 v[120:123], v[152:155], v[160:163], v[120:123]
	v_mfma_f32_16x16x32_bf16 v[116:119], v[144:147], v[198:201], v[116:119]
	v_mfma_f32_16x16x32_bf16 v[112:115], v[152:155], v[198:201], v[112:115]
	v_mfma_f32_16x16x32_bf16 v[108:111], v[144:147], v[206:209], v[108:111]
	v_mfma_f32_16x16x32_bf16 v[104:107], v[152:155], v[206:209], v[104:107]
	v_mfma_f32_16x16x32_bf16 v[100:103], v[144:147], v[214:217], v[100:103]
	v_mfma_f32_16x16x32_bf16 v[96:99], v[152:155], v[214:217], v[96:99]
	s_barrier
	v_readfirstlane_b32 s82, v189
	v_lshl_add_u64 v[234:235], s[60:61], 0, v[164:165]
	s_mov_b32 m0, s82
	v_readfirstlane_b32 s82, v188
	ds_read_b128 v[218:221], v135
	ds_read_b128 v[222:225], v135 offset:1024
	ds_read_b128 v[226:229], v135 offset:2048
	ds_read_b128 v[230:233], v135 offset:3072
	global_load_lds_dwordx4 v[234:235], off
	v_lshl_add_u64 v[236:237], v[234:235], 0, s[2:3]
	s_mov_b32 m0, s82
	s_nop 0
	global_load_lds_dwordx4 v[236:237], off
	v_readfirstlane_b32 s82, v169
	v_lshl_add_u64 v[236:237], v[128:129], 0, s[22:23]
	s_mov_b32 m0, s82
	v_readfirstlane_b32 s82, v187
	global_load_lds_dwordx4 v[236:237], off
	v_lshl_add_u64 v[236:237], v[128:129], 0, s[24:25]
	s_mov_b32 m0, s82
	s_nop 0
	global_load_lds_dwordx4 v[236:237], off
	s_waitcnt vmcnt(12)
	s_barrier
	s_waitcnt lgkmcnt(0)
	s_waitcnt lgkmcnt(0)
	v_mfma_f32_16x16x32_bf16 v[92:95], v[218:221], v[156:159], v[92:95]
	v_mfma_f32_16x16x32_bf16 v[88:91], v[226:229], v[156:159], v[88:91]
	v_mfma_f32_16x16x32_bf16 v[84:87], v[218:221], v[194:197], v[84:87]
	v_mfma_f32_16x16x32_bf16 v[80:83], v[226:229], v[194:197], v[80:83]
	v_mfma_f32_16x16x32_bf16 v[76:79], v[218:221], v[202:205], v[76:79]
	v_mfma_f32_16x16x32_bf16 v[72:75], v[226:229], v[202:205], v[72:75]
	v_mfma_f32_16x16x32_bf16 v[68:71], v[218:221], v[210:213], v[68:71]
	v_mfma_f32_16x16x32_bf16 v[64:67], v[226:229], v[210:213], v[64:67]
	v_mfma_f32_16x16x32_bf16 v[92:95], v[222:225], v[160:163], v[92:95]
	v_mfma_f32_16x16x32_bf16 v[88:91], v[230:233], v[160:163], v[88:91]
	v_mfma_f32_16x16x32_bf16 v[84:87], v[222:225], v[198:201], v[84:87]
	v_mfma_f32_16x16x32_bf16 v[80:83], v[230:233], v[198:201], v[80:83]
	v_mfma_f32_16x16x32_bf16 v[76:79], v[222:225], v[206:209], v[76:79]
	v_mfma_f32_16x16x32_bf16 v[72:75], v[230:233], v[206:209], v[72:75]
	v_mfma_f32_16x16x32_bf16 v[68:71], v[222:225], v[214:217], v[68:71]
	v_mfma_f32_16x16x32_bf16 v[64:67], v[230:233], v[214:217], v[64:67]
	s_barrier
	ds_read_b128 v[156:159], v193 offset:16384
	ds_read_b128 v[160:163], v193 offset:17408
	ds_read_b128 v[194:197], v192 offset:16384
	ds_read_b128 v[198:201], v192 offset:17408
	ds_read_b128 v[202:205], v191 offset:16384
	ds_read_b128 v[206:209], v191 offset:17408
	ds_read_b128 v[210:213], v190 offset:16384
	ds_read_b128 v[214:217], v190 offset:17408
	v_readfirstlane_b32 s82, v186
	v_lshl_add_u64 v[236:237], v[234:235], 0, s[6:7]
	s_mov_b32 m0, s82
	v_readfirstlane_b32 s82, v185
	global_load_lds_dwordx4 v[236:237], off
	v_lshl_add_u64 v[236:237], v[234:235], 0, s[8:9]
	s_mov_b32 m0, s82
	s_nop 0
	global_load_lds_dwordx4 v[236:237], off
	s_barrier
	s_waitcnt lgkmcnt(0)
	s_waitcnt lgkmcnt(0)
	v_mfma_f32_16x16x32_bf16 v[60:63], v[140:143], v[156:159], v[60:63]
	v_mfma_f32_16x16x32_bf16 v[56:59], v[148:151], v[156:159], v[56:59]
	v_mfma_f32_16x16x32_bf16 v[52:55], v[140:143], v[194:197], v[52:55]
	v_mfma_f32_16x16x32_bf16 v[48:51], v[148:151], v[194:197], v[48:51]
	v_mfma_f32_16x16x32_bf16 v[44:47], v[140:143], v[202:205], v[44:47]
	v_mfma_f32_16x16x32_bf16 v[40:43], v[148:151], v[202:205], v[40:43]
	v_mfma_f32_16x16x32_bf16 v[36:39], v[140:143], v[210:213], v[36:39]
	v_mfma_f32_16x16x32_bf16 v[32:35], v[148:151], v[210:213], v[32:35]
	v_mfma_f32_16x16x32_bf16 v[60:63], v[144:147], v[160:163], v[60:63]
	v_mfma_f32_16x16x32_bf16 v[56:59], v[152:155], v[160:163], v[56:59]
	v_mfma_f32_16x16x32_bf16 v[52:55], v[144:147], v[198:201], v[52:55]
	v_mfma_f32_16x16x32_bf16 v[48:51], v[152:155], v[198:201], v[48:51]
	v_mfma_f32_16x16x32_bf16 v[44:47], v[144:147], v[206:209], v[44:47]
	v_mfma_f32_16x16x32_bf16 v[40:43], v[152:155], v[206:209], v[40:43]
	v_mfma_f32_16x16x32_bf16 v[36:39], v[144:147], v[214:217], v[36:39]
	v_mfma_f32_16x16x32_bf16 v[32:35], v[152:155], v[214:217], v[32:35]
	s_barrier
	v_readfirstlane_b32 s82, v184
	v_lshl_add_u64 v[142:143], v[128:129], 0, s[26:27]
	s_mov_b32 m0, s82
	v_readfirstlane_b32 s82, v183
	global_load_lds_dwordx4 v[142:143], off
	s_mov_b32 m0, s82
	s_nop 0
	global_load_lds_dwordx4 v[128:129], off
	s_waitcnt vmcnt(12)
	s_barrier
	v_mfma_f32_16x16x32_bf16 v[28:31], v[218:221], v[156:159], v[28:31]
	v_mfma_f32_16x16x32_bf16 v[24:27], v[226:229], v[156:159], v[24:27]
	v_mfma_f32_16x16x32_bf16 v[20:23], v[218:221], v[194:197], v[20:23]
	v_mfma_f32_16x16x32_bf16 v[16:19], v[226:229], v[194:197], v[16:19]
	v_mfma_f32_16x16x32_bf16 v[12:15], v[218:221], v[202:205], v[12:15]
	v_mfma_f32_16x16x32_bf16 v[8:11], v[226:229], v[202:205], v[8:11]
	v_mfma_f32_16x16x32_bf16 v[4:7], v[218:221], v[210:213], v[4:7]
	v_mfma_f32_16x16x32_bf16 v[0:3], v[226:229], v[210:213], v[0:3]
	v_mfma_f32_16x16x32_bf16 v[28:31], v[222:225], v[160:163], v[28:31]
	v_mfma_f32_16x16x32_bf16 v[24:27], v[230:233], v[160:163], v[24:27]
	v_mfma_f32_16x16x32_bf16 v[20:23], v[222:225], v[198:201], v[20:23]
	v_mfma_f32_16x16x32_bf16 v[16:19], v[230:233], v[198:201], v[16:19]
	v_mfma_f32_16x16x32_bf16 v[12:15], v[222:225], v[206:209], v[12:15]
	v_mfma_f32_16x16x32_bf16 v[8:11], v[230:233], v[206:209], v[8:11]
	v_mfma_f32_16x16x32_bf16 v[4:7], v[222:225], v[214:217], v[4:7]
	v_mfma_f32_16x16x32_bf16 v[0:3], v[230:233], v[214:217], v[0:3]
	s_barrier
	ds_read_b128 v[140:143], v130
	ds_read_b128 v[144:147], v130 offset:1024
	ds_read_b128 v[148:151], v130 offset:2048
	ds_read_b128 v[152:155], v130 offset:3072
	ds_read_b128 v[156:159], v193 offset:32768
	ds_read_b128 v[160:163], v193 offset:33792
	ds_read_b128 v[194:197], v192 offset:32768
	ds_read_b128 v[198:201], v192 offset:33792
	ds_read_b128 v[202:205], v191 offset:32768
	ds_read_b128 v[206:209], v191 offset:33792
	ds_read_b128 v[210:213], v190 offset:32768
	ds_read_b128 v[214:217], v190 offset:33792
	s_waitcnt lgkmcnt(8)
	s_waitcnt vmcnt(10)
	s_barrier
	s_waitcnt lgkmcnt(0)
	s_waitcnt lgkmcnt(0)
	v_mfma_f32_16x16x32_bf16 v[124:127], v[140:143], v[156:159], v[124:127]
	v_mfma_f32_16x16x32_bf16 v[120:123], v[148:151], v[156:159], v[120:123]
	v_mfma_f32_16x16x32_bf16 v[116:119], v[140:143], v[194:197], v[116:119]
	v_mfma_f32_16x16x32_bf16 v[112:115], v[148:151], v[194:197], v[112:115]
	v_mfma_f32_16x16x32_bf16 v[108:111], v[140:143], v[202:205], v[108:111]
	v_mfma_f32_16x16x32_bf16 v[104:107], v[148:151], v[202:205], v[104:107]
	v_mfma_f32_16x16x32_bf16 v[100:103], v[140:143], v[210:213], v[100:103]
	v_mfma_f32_16x16x32_bf16 v[96:99], v[148:151], v[210:213], v[96:99]
	v_mfma_f32_16x16x32_bf16 v[124:127], v[144:147], v[160:163], v[124:127]
	v_mfma_f32_16x16x32_bf16 v[120:123], v[152:155], v[160:163], v[120:123]
	v_mfma_f32_16x16x32_bf16 v[116:119], v[144:147], v[198:201], v[116:119]
	v_mfma_f32_16x16x32_bf16 v[112:115], v[152:155], v[198:201], v[112:115]
	v_mfma_f32_16x16x32_bf16 v[108:111], v[144:147], v[206:209], v[108:111]
	v_mfma_f32_16x16x32_bf16 v[104:107], v[152:155], v[206:209], v[104:107]
	v_mfma_f32_16x16x32_bf16 v[100:103], v[144:147], v[214:217], v[100:103]
	v_mfma_f32_16x16x32_bf16 v[96:99], v[152:155], v[214:217], v[96:99]
	s_barrier
	v_readfirstlane_b32 s82, v182
	v_lshl_add_u64 v[234:235], s[56:57], 0, v[164:165]
	s_mov_b32 m0, s82
	v_readfirstlane_b32 s82, v181
	ds_read_b128 v[218:221], v132
	ds_read_b128 v[222:225], v132 offset:1024
	ds_read_b128 v[226:229], v132 offset:2048
	ds_read_b128 v[230:233], v132 offset:3072
	global_load_lds_dwordx4 v[234:235], off
	v_lshl_add_u64 v[236:237], v[234:235], 0, s[2:3]
	s_mov_b32 m0, s82
	s_nop 0
	global_load_lds_dwordx4 v[236:237], off
	v_readfirstlane_b32 s82, v177
	v_lshl_add_u64 v[236:237], v[128:129], 0, s[28:29]
	s_mov_b32 m0, s82
	v_readfirstlane_b32 s82, v175
	global_load_lds_dwordx4 v[236:237], off
	v_lshl_add_u64 v[236:237], v[128:129], 0, s[30:31]
	s_mov_b32 m0, s82
	s_nop 0
	global_load_lds_dwordx4 v[236:237], off
	s_waitcnt vmcnt(12)
	s_barrier
	s_waitcnt lgkmcnt(0)
	s_waitcnt lgkmcnt(0)
	v_mfma_f32_16x16x32_bf16 v[92:95], v[218:221], v[156:159], v[92:95]
	v_mfma_f32_16x16x32_bf16 v[88:91], v[226:229], v[156:159], v[88:91]
	v_mfma_f32_16x16x32_bf16 v[84:87], v[218:221], v[194:197], v[84:87]
	v_mfma_f32_16x16x32_bf16 v[80:83], v[226:229], v[194:197], v[80:83]
	v_mfma_f32_16x16x32_bf16 v[76:79], v[218:221], v[202:205], v[76:79]
	v_mfma_f32_16x16x32_bf16 v[72:75], v[226:229], v[202:205], v[72:75]
	v_mfma_f32_16x16x32_bf16 v[68:71], v[218:221], v[210:213], v[68:71]
	v_mfma_f32_16x16x32_bf16 v[64:67], v[226:229], v[210:213], v[64:67]
	v_mfma_f32_16x16x32_bf16 v[92:95], v[222:225], v[160:163], v[92:95]
	v_mfma_f32_16x16x32_bf16 v[88:91], v[230:233], v[160:163], v[88:91]
	v_mfma_f32_16x16x32_bf16 v[84:87], v[222:225], v[198:201], v[84:87]
	v_mfma_f32_16x16x32_bf16 v[80:83], v[230:233], v[198:201], v[80:83]
	v_mfma_f32_16x16x32_bf16 v[76:79], v[222:225], v[206:209], v[76:79]
	v_mfma_f32_16x16x32_bf16 v[72:75], v[230:233], v[206:209], v[72:75]
	v_mfma_f32_16x16x32_bf16 v[68:71], v[222:225], v[214:217], v[68:71]
	v_mfma_f32_16x16x32_bf16 v[64:67], v[230:233], v[214:217], v[64:67]
	s_barrier
	ds_read_b128 v[156:159], v193 offset:49152
	ds_read_b128 v[160:163], v193 offset:50176
	ds_read_b128 v[194:197], v192 offset:49152
	ds_read_b128 v[198:201], v192 offset:50176
	ds_read_b128 v[202:205], v191 offset:49152
	ds_read_b128 v[206:209], v191 offset:50176
	ds_read_b128 v[210:213], v190 offset:49152
	ds_read_b128 v[214:217], v190 offset:50176
	v_readfirstlane_b32 s82, v173
	v_lshl_add_u64 v[236:237], v[234:235], 0, s[6:7]
	s_mov_b32 m0, s82
	v_readfirstlane_b32 s82, v171
	global_load_lds_dwordx4 v[236:237], off
	v_lshl_add_u64 v[236:237], v[234:235], 0, s[8:9]
	s_mov_b32 m0, s82
	s_nop 0
	global_load_lds_dwordx4 v[236:237], off
	s_barrier
	s_waitcnt lgkmcnt(0)
	s_waitcnt lgkmcnt(0)
	v_mfma_f32_16x16x32_bf16 v[60:63], v[140:143], v[156:159], v[60:63]
	v_mfma_f32_16x16x32_bf16 v[56:59], v[148:151], v[156:159], v[56:59]
	v_mfma_f32_16x16x32_bf16 v[52:55], v[140:143], v[194:197], v[52:55]
	v_mfma_f32_16x16x32_bf16 v[48:51], v[148:151], v[194:197], v[48:51]
	v_mfma_f32_16x16x32_bf16 v[44:47], v[140:143], v[202:205], v[44:47]
	v_mfma_f32_16x16x32_bf16 v[40:43], v[148:151], v[202:205], v[40:43]
	v_mfma_f32_16x16x32_bf16 v[36:39], v[140:143], v[210:213], v[36:39]
	v_mfma_f32_16x16x32_bf16 v[32:35], v[148:151], v[210:213], v[32:35]
	v_mfma_f32_16x16x32_bf16 v[60:63], v[144:147], v[160:163], v[60:63]
	v_mfma_f32_16x16x32_bf16 v[56:59], v[152:155], v[160:163], v[56:59]
	v_mfma_f32_16x16x32_bf16 v[52:55], v[144:147], v[198:201], v[52:55]
	v_mfma_f32_16x16x32_bf16 v[48:51], v[152:155], v[198:201], v[48:51]
	v_mfma_f32_16x16x32_bf16 v[44:47], v[144:147], v[206:209], v[44:47]
	v_mfma_f32_16x16x32_bf16 v[40:43], v[152:155], v[206:209], v[40:43]
	v_mfma_f32_16x16x32_bf16 v[36:39], v[144:147], v[214:217], v[36:39]
	v_mfma_f32_16x16x32_bf16 v[32:35], v[152:155], v[214:217], v[32:35]
	s_barrier
	v_lshl_add_u64 v[128:129], v[128:129], 0, s[34:35]
	v_readfirstlane_b32 s82, v137
	v_lshl_add_u64 v[142:143], v[128:129], 0, s[18:19]
	s_mov_b32 m0, s82
	v_readfirstlane_b32 s82, v136
	global_load_lds_dwordx4 v[142:143], off
	v_lshl_add_u64 v[142:143], v[128:129], 0, s[20:21]
	s_mov_b32 m0, s82
	s_nop 0
	global_load_lds_dwordx4 v[142:143], off
	s_waitcnt vmcnt(12)
	s_barrier
	v_mfma_f32_16x16x32_bf16 v[28:31], v[218:221], v[156:159], v[28:31]
	v_mfma_f32_16x16x32_bf16 v[24:27], v[226:229], v[156:159], v[24:27]
	v_mfma_f32_16x16x32_bf16 v[20:23], v[218:221], v[194:197], v[20:23]
	v_mfma_f32_16x16x32_bf16 v[16:19], v[226:229], v[194:197], v[16:19]
	v_mfma_f32_16x16x32_bf16 v[12:15], v[218:221], v[202:205], v[12:15]
	v_mfma_f32_16x16x32_bf16 v[8:11], v[226:229], v[202:205], v[8:11]
	v_mfma_f32_16x16x32_bf16 v[4:7], v[218:221], v[210:213], v[4:7]
	v_mfma_f32_16x16x32_bf16 v[0:3], v[226:229], v[210:213], v[0:3]
	v_mfma_f32_16x16x32_bf16 v[28:31], v[222:225], v[160:163], v[28:31]
	v_mfma_f32_16x16x32_bf16 v[24:27], v[230:233], v[160:163], v[24:27]
	v_mfma_f32_16x16x32_bf16 v[20:23], v[222:225], v[198:201], v[20:23]
	v_mfma_f32_16x16x32_bf16 v[16:19], v[230:233], v[198:201], v[16:19]
	v_mfma_f32_16x16x32_bf16 v[12:15], v[222:225], v[206:209], v[12:15]
	v_mfma_f32_16x16x32_bf16 v[8:11], v[230:233], v[206:209], v[8:11]
	v_mfma_f32_16x16x32_bf16 v[4:7], v[222:225], v[214:217], v[4:7]
	v_mfma_f32_16x16x32_bf16 v[0:3], v[230:233], v[214:217], v[0:3]
	s_add_i32 s14, s14, 2
	s_add_u32 s56, s56, s58
	s_addc_u32 s57, s57, s59
	s_add_u32 s60, s60, s58
	s_addc_u32 s61, s61, s59
	s_cmp_lt_u32 s14, 28
	s_barrier
	s_cbranch_scc1 .LBB0_234
	s_setprio 0
	s_lshl_b32 s14, s62, 3
	s_or_b32 s82, s63, s14
	s_lshl_b32 s56, s82, 8
	v_lshlrev_b32_e32 v128, 3, v131
	v_lshlrev_b32_e32 v129, 5, v131
	s_or_b32 s14, s56, 0x80
	v_and_b32_e32 v128, 0x7fff0, v128
	v_and_b32_e32 v129, 32, v129
	s_lshl_b64 s[58:59], s[14:15], 13
	v_add_u32_e32 v129, v129, v134
	v_add_lshl_u32 v128, v133, v128, 13
	s_add_u32 s58, s40, s58
	v_lshl_add_u32 v164, v129, 1, v128
	s_addc_u32 s59, s41, s59
	v_lshl_add_u64 v[128:129], s[58:59], 0, v[164:165]
	v_readfirstlane_b32 s14, v137
	ds_read_b128 v[140:143], v138
	ds_read_b128 v[144:147], v138 offset:1024
	ds_read_b128 v[148:151], v138 offset:2048
	ds_read_b128 v[152:155], v138 offset:3072
	ds_read_b128 v[156:159], v193
	ds_read_b128 v[160:163], v193 offset:1024
	ds_read_b128 v[194:197], v192
	ds_read_b128 v[198:201], v192 offset:1024
	ds_read_b128 v[202:205], v191
	ds_read_b128 v[206:209], v191 offset:1024
	ds_read_b128 v[210:213], v190
	ds_read_b128 v[214:217], v190 offset:1024
	v_lshl_add_u64 v[138:139], v[128:129], 0, s[44:45]
	s_mov_b32 m0, s14
	v_readfirstlane_b32 s14, v136
	global_load_lds_dwordx4 v[138:139], off
	v_lshl_add_u64 v[128:129], v[128:129], 0, s[46:47]
	s_mov_b32 m0, s14
	s_mov_b32 s57, s15
	global_load_lds_dwordx4 v[128:129], off
	s_waitcnt vmcnt(10)
	s_barrier
	s_waitcnt lgkmcnt(0)
	s_setprio 1
	s_waitcnt lgkmcnt(0)
	v_mfma_f32_16x16x32_bf16 v[124:127], v[140:143], v[156:159], v[124:127]
	v_mfma_f32_16x16x32_bf16 v[120:123], v[148:151], v[156:159], v[120:123]
	v_mfma_f32_16x16x32_bf16 v[116:119], v[140:143], v[194:197], v[116:119]
	v_mfma_f32_16x16x32_bf16 v[112:115], v[148:151], v[194:197], v[112:115]
	v_mfma_f32_16x16x32_bf16 v[108:111], v[140:143], v[202:205], v[108:111]
	v_mfma_f32_16x16x32_bf16 v[104:107], v[148:151], v[202:205], v[104:107]
	v_mfma_f32_16x16x32_bf16 v[100:103], v[140:143], v[210:213], v[100:103]
	v_mfma_f32_16x16x32_bf16 v[96:99], v[148:151], v[210:213], v[96:99]
	v_mfma_f32_16x16x32_bf16 v[124:127], v[144:147], v[160:163], v[124:127]
	v_mfma_f32_16x16x32_bf16 v[120:123], v[152:155], v[160:163], v[120:123]
	v_mfma_f32_16x16x32_bf16 v[116:119], v[144:147], v[198:201], v[116:119]
	v_mfma_f32_16x16x32_bf16 v[112:115], v[152:155], v[198:201], v[112:115]
	v_mfma_f32_16x16x32_bf16 v[108:111], v[144:147], v[206:209], v[108:111]
	v_mfma_f32_16x16x32_bf16 v[104:107], v[152:155], v[206:209], v[104:107]
	v_mfma_f32_16x16x32_bf16 v[100:103], v[144:147], v[214:217], v[100:103]
	v_mfma_f32_16x16x32_bf16 v[96:99], v[152:155], v[214:217], v[96:99]
	s_setprio 0
	s_barrier
	ds_read_b128 v[136:139], v135
	ds_read_b128 v[218:221], v135 offset:1024
	ds_read_b128 v[222:225], v135 offset:2048
	ds_read_b128 v[226:229], v135 offset:3072
	s_barrier
	s_waitcnt lgkmcnt(0)
	s_setprio 1
	s_waitcnt lgkmcnt(0)
	v_mfma_f32_16x16x32_bf16 v[92:95], v[136:139], v[156:159], v[92:95]
	v_mfma_f32_16x16x32_bf16 v[84:87], v[136:139], v[194:197], v[84:87]
	v_mfma_f32_16x16x32_bf16 v[80:83], v[222:225], v[194:197], v[80:83]
	v_mfma_f32_16x16x32_bf16 v[88:91], v[222:225], v[156:159], v[88:91]
	v_mfma_f32_16x16x32_bf16 v[76:79], v[136:139], v[202:205], v[76:79]
	v_mfma_f32_16x16x32_bf16 v[72:75], v[222:225], v[202:205], v[72:75]
	v_mfma_f32_16x16x32_bf16 v[68:71], v[136:139], v[210:213], v[68:71]
	v_mfma_f32_16x16x32_bf16 v[64:67], v[222:225], v[210:213], v[64:67]
	v_mfma_f32_16x16x32_bf16 v[156:159], v[218:221], v[160:163], v[92:95]
	v_mfma_f32_16x16x32_bf16 v[194:197], v[218:221], v[198:201], v[84:87]
	v_mfma_f32_16x16x32_bf16 v[198:201], v[226:229], v[198:201], v[80:83]
	v_mfma_f32_16x16x32_bf16 v[160:163], v[226:229], v[160:163], v[88:91]
	v_mfma_f32_16x16x32_bf16 v[202:205], v[218:221], v[206:209], v[76:79]
	v_mfma_f32_16x16x32_bf16 v[206:209], v[226:229], v[206:209], v[72:75]
	v_mfma_f32_16x16x32_bf16 v[210:213], v[218:221], v[214:217], v[68:71]
	v_mfma_f32_16x16x32_bf16 v[214:217], v[226:229], v[214:217], v[64:67]
	s_setprio 0
	s_barrier
	s_nop 0
	ds_read_b128 v[64:67], v193 offset:16384
	ds_read_b128 v[68:71], v193 offset:17408
	ds_read_b128 v[72:75], v192 offset:16384
	ds_read_b128 v[76:79], v192 offset:17408
	ds_read_b128 v[80:83], v191 offset:16384
	ds_read_b128 v[84:87], v191 offset:17408
	ds_read_b128 v[88:91], v190 offset:16384
	ds_read_b128 v[92:95], v190 offset:17408
	s_waitcnt vmcnt(4)
	s_barrier
	s_waitcnt lgkmcnt(0)
	s_setprio 1
	s_waitcnt lgkmcnt(0)
	v_mfma_f32_16x16x32_bf16 v[60:63], v[140:143], v[64:67], v[60:63]
	v_mfma_f32_16x16x32_bf16 v[56:59], v[148:151], v[64:67], v[56:59]
	v_mfma_f32_16x16x32_bf16 v[52:55], v[140:143], v[72:75], v[52:55]
	v_mfma_f32_16x16x32_bf16 v[48:51], v[148:151], v[72:75], v[48:51]
	v_mfma_f32_16x16x32_bf16 v[230:233], v[140:143], v[80:83], v[44:47]
	v_mfma_f32_16x16x32_bf16 v[234:237], v[148:151], v[80:83], v[40:43]
	v_mfma_f32_16x16x32_bf16 v[140:143], v[140:143], v[88:91], v[36:39]
	v_mfma_f32_16x16x32_bf16 v[148:151], v[148:151], v[88:91], v[32:35]
	v_mfma_f32_16x16x32_bf16 v[32:35], v[144:147], v[68:71], v[60:63]
	v_mfma_f32_16x16x32_bf16 v[36:39], v[152:155], v[68:71], v[56:59]
	v_mfma_f32_16x16x32_bf16 v[40:43], v[144:147], v[76:79], v[52:55]
	v_mfma_f32_16x16x32_bf16 v[44:47], v[152:155], v[76:79], v[48:51]
	v_mfma_f32_16x16x32_bf16 v[48:51], v[144:147], v[84:87], v[230:233]
	v_mfma_f32_16x16x32_bf16 v[52:55], v[152:155], v[84:87], v[234:237]
	v_mfma_f32_16x16x32_bf16 v[56:59], v[144:147], v[92:95], v[140:143]
	v_mfma_f32_16x16x32_bf16 v[60:63], v[152:155], v[92:95], v[148:151]
	s_setprio 0
	s_setprio 1
	v_mfma_f32_16x16x32_bf16 v[28:31], v[136:139], v[64:67], v[28:31]
	v_mfma_f32_16x16x32_bf16 v[24:27], v[222:225], v[64:67], v[24:27]
	v_mfma_f32_16x16x32_bf16 v[20:23], v[136:139], v[72:75], v[20:23]
	v_mfma_f32_16x16x32_bf16 v[64:67], v[222:225], v[72:75], v[16:19]
	v_mfma_f32_16x16x32_bf16 v[12:15], v[136:139], v[80:83], v[12:15]
	v_mfma_f32_16x16x32_bf16 v[8:11], v[222:225], v[80:83], v[8:11]
	v_mfma_f32_16x16x32_bf16 v[72:75], v[136:139], v[88:91], v[4:7]
	v_mfma_f32_16x16x32_bf16 v[80:83], v[222:225], v[88:91], v[0:3]
	v_mfma_f32_16x16x32_bf16 v[0:3], v[218:221], v[68:71], v[28:31]
	v_mfma_f32_16x16x32_bf16 v[4:7], v[226:229], v[68:71], v[24:27]
	v_mfma_f32_16x16x32_bf16 v[16:19], v[218:221], v[76:79], v[20:23]
	v_mfma_f32_16x16x32_bf16 v[20:23], v[226:229], v[76:79], v[64:67]
	v_mfma_f32_16x16x32_bf16 v[24:27], v[218:221], v[84:87], v[12:15]
	v_mfma_f32_16x16x32_bf16 v[28:31], v[226:229], v[84:87], v[8:11]
	v_mfma_f32_16x16x32_bf16 v[64:67], v[218:221], v[92:95], v[72:75]
	v_mfma_f32_16x16x32_bf16 v[68:71], v[226:229], v[92:95], v[80:83]
	s_setprio 0
	s_barrier
	ds_read_b128 v[12:15], v130
	ds_read_b128 v[8:11], v130 offset:1024
	ds_read_b128 v[76:79], v130 offset:2048
	ds_read_b128 v[72:75], v130 offset:3072
	ds_read_b128 v[140:143], v193 offset:32768
	ds_read_b128 v[148:151], v193 offset:33792
	ds_read_b128 v[218:221], v192 offset:32768
	ds_read_b128 v[222:225], v192 offset:33792
	ds_read_b128 v[226:229], v191 offset:32768
	ds_read_b128 v[230:233], v191 offset:33792
	ds_read_b128 v[234:237], v190 offset:32768
	ds_read_b128 v[238:241], v190 offset:33792
	s_waitcnt vmcnt(2)
	s_barrier
	s_waitcnt lgkmcnt(0)
	s_setprio 1
	s_waitcnt lgkmcnt(0)
	v_mfma_f32_16x16x32_bf16 v[80:83], v[12:15], v[140:143], v[124:127]
	v_mfma_f32_16x16x32_bf16 v[84:87], v[76:79], v[140:143], v[120:123]
	v_mfma_f32_16x16x32_bf16 v[88:91], v[12:15], v[218:221], v[116:119]
	v_mfma_f32_16x16x32_bf16 v[92:95], v[76:79], v[218:221], v[112:115]
	v_mfma_f32_16x16x32_bf16 v[108:111], v[12:15], v[226:229], v[108:111]
	v_mfma_f32_16x16x32_bf16 v[104:107], v[76:79], v[226:229], v[104:107]
	v_mfma_f32_16x16x32_bf16 v[100:103], v[12:15], v[234:237], v[100:103]
	v_mfma_f32_16x16x32_bf16 v[96:99], v[76:79], v[234:237], v[96:99]
	v_mfma_f32_16x16x32_bf16 v[152:155], v[8:11], v[148:151], v[80:83]
	v_mfma_f32_16x16x32_bf16 v[144:147], v[72:75], v[148:151], v[84:87]
	v_mfma_f32_16x16x32_bf16 v[136:139], v[8:11], v[222:225], v[88:91]
	v_mfma_f32_16x16x32_bf16 v[128:131], v[72:75], v[222:225], v[92:95]
	v_mfma_f32_16x16x32_bf16 v[120:123], v[8:11], v[230:233], v[108:111]
	v_mfma_f32_16x16x32_bf16 v[112:115], v[72:75], v[230:233], v[104:107]
	v_mfma_f32_16x16x32_bf16 v[104:107], v[8:11], v[238:241], v[100:103]
	v_mfma_f32_16x16x32_bf16 v[96:99], v[72:75], v[238:241], v[96:99]
	s_setprio 0
	s_barrier
	ds_read_b128 v[88:91], v132
	ds_read_b128 v[80:83], v132 offset:1024
	ds_read_b128 v[92:95], v132 offset:2048
	ds_read_b128 v[84:87], v132 offset:3072
	s_waitcnt vmcnt(0)
	s_barrier
	s_waitcnt lgkmcnt(0)
	s_setprio 1
	s_waitcnt lgkmcnt(0)
	v_mfma_f32_16x16x32_bf16 v[100:103], v[88:91], v[140:143], v[156:159]
	v_mfma_f32_16x16x32_bf16 v[108:111], v[92:95], v[140:143], v[160:163]
	v_mfma_f32_16x16x32_bf16 v[116:119], v[88:91], v[218:221], v[194:197]
	v_mfma_f32_16x16x32_bf16 v[124:127], v[92:95], v[218:221], v[198:201]
	v_mfma_f32_16x16x32_bf16 v[160:163], v[88:91], v[226:229], v[202:205]
	v_mfma_f32_16x16x32_bf16 v[194:197], v[92:95], v[226:229], v[206:209]
	v_mfma_f32_16x16x32_bf16 v[198:201], v[88:91], v[234:237], v[210:213]
	v_mfma_f32_16x16x32_bf16 v[202:205], v[92:95], v[234:237], v[214:217]
	v_mfma_f32_16x16x32_bf16 v[156:159], v[80:83], v[148:151], v[100:103]
	v_mfma_f32_16x16x32_bf16 v[148:151], v[84:87], v[148:151], v[108:111]
	v_mfma_f32_16x16x32_bf16 v[140:143], v[80:83], v[222:225], v[116:119]
	v_mfma_f32_16x16x32_bf16 v[132:135], v[84:87], v[222:225], v[124:127]
	v_mfma_f32_16x16x32_bf16 v[124:127], v[80:83], v[230:233], v[160:163]
	v_mfma_f32_16x16x32_bf16 v[116:119], v[84:87], v[230:233], v[194:197]
	v_mfma_f32_16x16x32_bf16 v[108:111], v[80:83], v[238:241], v[198:201]
	v_mfma_f32_16x16x32_bf16 v[100:103], v[84:87], v[238:241], v[202:205]
	s_setprio 0
	s_lshl_b64 s[58:59], s[56:57], 2
	s_barrier
	v_mbcnt_lo_u32_b32 v162, -1, 0
	v_mbcnt_hi_u32_b32 v162, -1, v162
	s_add_u32 s58, s87, s58
	v_add_u32_e32 v160, s64, v162
	s_addc_u32 s59, s88, s59
	v_and_b32_e32 v164, 0x100, v160
	v_and_b32_e32 v162, 15, v162
	v_lshl_add_u64 v[160:161], s[58:59], 0, v[164:165]
	v_lshlrev_b32_e32 v164, 2, v162
	v_lshl_add_u64 v[160:161], v[160:161], 0, v[164:165]
	global_load_dword v180, v[160:161], off
	global_load_dword v178, v[160:161], off offset:64
	global_load_dword v176, v[160:161], off offset:128
	global_load_dword v174, v[160:161], off offset:192
	global_load_dword v172, v[160:161], off offset:512
	global_load_dword v170, v[160:161], off offset:576
	global_load_dword v168, v[160:161], off offset:640
	global_load_dword v166, v[160:161], off offset:704
	v_mbcnt_lo_u32_b32 v194, -1, 0
	v_mbcnt_hi_u32_b32 v194, -1, v194
	s_cmp_lg_u32 s81, 0
	v_add_u32_e32 v160, s64, v194
	v_bfe_u32 v196, v160, 8, 1
	v_ashrrev_i32_e32 v199, 6, v160
	v_bfe_u32 v160, v194, 4, 2
	s_cselect_b64 s[58:59], -1, 0
	v_and_b32_e32 v197, 3, v199
	v_and_b32_e32 v195, 15, v194
	s_and_b64 vcc, exec, s[58:59]
	v_lshlrev_b32_e32 v198, 4, v160
	s_cbranch_vccz .LBB0_246
	s_lshl_b32 s14, s80, 22
	s_lshl_b32 s57, s82, 14
	s_add_i32 s57, s57, s14
	v_lshlrev_b32_e32 v160, 6, v195
	v_or3_b32 v160, s57, v160, v198
	v_lshl_add_u32 v160, v197, 20, v160
	v_lshl_or_b32 v164, v196, 12, v160
	s_waitcnt vmcnt(0)
	v_pk_mul_f32 v[160:161], v[154:155], v[180:181] op_sel_hi:[1,0]
	v_pk_mul_f32 v[200:201], v[146:147], v[180:181] op_sel_hi:[1,0]
	v_max_f32_e32 v160, 0, v160
	v_mul_f32_e32 v204, v160, v160
	v_max_f32_e32 v160, 0, v200
	v_pk_mul_f32 v[162:163], v[152:153], v[180:181] op_sel_hi:[1,0]
	v_mul_f32_e32 v200, v160, v160
	v_max_f32_e32 v160, 0, v161
	v_pk_mul_f32 v[202:203], v[144:145], v[180:181] op_sel_hi:[1,0]
	v_max_f32_e32 v162, 0, v162
	v_max_f32_e32 v163, 0, v163
	v_mul_f32_e32 v161, v160, v160
	v_max_f32_e32 v160, 0, v201
	v_mul_f32_e32 v162, v162, v162
	v_max_f32_e32 v202, 0, v202
	v_mul_f32_e32 v163, v163, v163
	v_max_f32_e32 v203, 0, v203
	v_mul_f32_e32 v201, v160, v160
	v_cvt_pk_bf16_f32 v160, v162, v163
	v_cvt_pk_bf16_f32 v161, v204, v161
	v_mul_f32_e32 v202, v202, v202
	v_mul_f32_e32 v203, v203, v203
	v_cvt_pk_bf16_f32 v162, v202, v203
	v_cvt_pk_bf16_f32 v163, v200, v201
	global_store_dwordx4 v164, v[160:163], s[0:1]
	v_pk_mul_f32 v[202:203], v[150:151], v[180:181] op_sel_hi:[1,0]
	v_lshl_add_u64 v[200:201], s[0:1], 0, v[164:165]
	v_pk_mul_f32 v[160:161], v[158:159], v[180:181] op_sel_hi:[1,0]
	v_pk_mul_f32 v[162:163], v[156:157], v[180:181] op_sel_hi:[1,0]
	v_max_f32_e32 v160, 0, v160
	v_mul_f32_e32 v206, v160, v160
	v_max_f32_e32 v160, 0, v202
	v_mul_f32_e32 v202, v160, v160
	v_max_f32_e32 v160, 0, v161
	v_pk_mul_f32 v[204:205], v[148:149], v[180:181] op_sel_hi:[1,0]
	v_max_f32_e32 v162, 0, v162
	v_max_f32_e32 v163, 0, v163
	v_mul_f32_e32 v161, v160, v160
	v_max_f32_e32 v160, 0, v203
	v_add_co_u32_e32 v200, vcc, s74, v200
	v_mul_f32_e32 v162, v162, v162
	v_max_f32_e32 v204, 0, v204
	v_mul_f32_e32 v163, v163, v163
	v_max_f32_e32 v205, 0, v205
	v_mul_f32_e32 v203, v160, v160
	v_cvt_pk_bf16_f32 v160, v162, v163
	v_cvt_pk_bf16_f32 v161, v206, v161
	v_addc_co_u32_e32 v201, vcc, 0, v201, vcc
	v_mul_f32_e32 v204, v204, v204
	v_mul_f32_e32 v205, v205, v205
	v_cvt_pk_bf16_f32 v162, v204, v205
	v_cvt_pk_bf16_f32 v163, v202, v203
	global_store_dwordx4 v[200:201], v[160:163], off
	v_pk_mul_f32 v[202:203], v[130:131], v[178:179] op_sel_hi:[1,0]
	v_pk_mul_f32 v[204:205], v[128:129], v[178:179] op_sel_hi:[1,0]
	v_pk_mul_f32 v[160:161], v[138:139], v[178:179] op_sel_hi:[1,0]
	v_pk_mul_f32 v[162:163], v[136:137], v[178:179] op_sel_hi:[1,0]
	v_max_f32_e32 v160, 0, v160
	v_mul_f32_e32 v206, v160, v160
	v_max_f32_e32 v160, 0, v202
	v_mul_f32_e32 v202, v160, v160
	v_max_f32_e32 v160, 0, v161
	v_max_f32_e32 v162, 0, v162
	v_max_f32_e32 v163, 0, v163
	v_mul_f32_e32 v161, v160, v160
	v_max_f32_e32 v160, 0, v203
	v_mul_f32_e32 v162, v162, v162
	v_max_f32_e32 v204, 0, v204
	v_mul_f32_e32 v163, v163, v163
	v_max_f32_e32 v205, 0, v205
	v_mul_f32_e32 v203, v160, v160
	v_cvt_pk_bf16_f32 v160, v162, v163
	v_cvt_pk_bf16_f32 v161, v206, v161
	v_mul_f32_e32 v204, v204, v204
	v_mul_f32_e32 v205, v205, v205
	v_cvt_pk_bf16_f32 v162, v204, v205
	v_cvt_pk_bf16_f32 v163, v202, v203
	global_store_dwordx4 v164, v[160:163], s[0:1] offset:1024
	v_pk_mul_f32 v[202:203], v[134:135], v[178:179] op_sel_hi:[1,0]
	v_pk_mul_f32 v[204:205], v[132:133], v[178:179] op_sel_hi:[1,0]
	v_pk_mul_f32 v[160:161], v[142:143], v[178:179] op_sel_hi:[1,0]
	v_pk_mul_f32 v[162:163], v[140:141], v[178:179] op_sel_hi:[1,0]
	v_max_f32_e32 v160, 0, v160
	v_mul_f32_e32 v206, v160, v160
	v_max_f32_e32 v160, 0, v202
	v_mul_f32_e32 v202, v160, v160
	v_max_f32_e32 v160, 0, v161
	v_max_f32_e32 v162, 0, v162
	v_max_f32_e32 v163, 0, v163
	v_mul_f32_e32 v161, v160, v160
	v_max_f32_e32 v160, 0, v203
	v_mul_f32_e32 v162, v162, v162
	v_max_f32_e32 v204, 0, v204
	v_mul_f32_e32 v163, v163, v163
	v_max_f32_e32 v205, 0, v205
	v_mul_f32_e32 v203, v160, v160
	v_cvt_pk_bf16_f32 v160, v162, v163
	v_cvt_pk_bf16_f32 v161, v206, v161
	v_mul_f32_e32 v204, v204, v204
	v_mul_f32_e32 v205, v205, v205
	v_cvt_pk_bf16_f32 v162, v204, v205
	v_cvt_pk_bf16_f32 v163, v202, v203
	global_store_dwordx4 v[200:201], v[160:163], off offset:1024
	v_pk_mul_f32 v[202:203], v[114:115], v[176:177] op_sel_hi:[1,0]
	v_pk_mul_f32 v[204:205], v[112:113], v[176:177] op_sel_hi:[1,0]
	v_pk_mul_f32 v[160:161], v[122:123], v[176:177] op_sel_hi:[1,0]
	v_pk_mul_f32 v[162:163], v[120:121], v[176:177] op_sel_hi:[1,0]
	v_max_f32_e32 v160, 0, v160
	v_mul_f32_e32 v206, v160, v160
	v_max_f32_e32 v160, 0, v202
	v_mul_f32_e32 v202, v160, v160
	v_max_f32_e32 v160, 0, v161
	v_max_f32_e32 v162, 0, v162
	v_max_f32_e32 v163, 0, v163
	v_mul_f32_e32 v161, v160, v160
	v_max_f32_e32 v160, 0, v203
	v_mul_f32_e32 v162, v162, v162
	v_max_f32_e32 v204, 0, v204
	v_mul_f32_e32 v163, v163, v163
	v_max_f32_e32 v205, 0, v205
	v_mul_f32_e32 v203, v160, v160
	v_cvt_pk_bf16_f32 v160, v162, v163
	v_cvt_pk_bf16_f32 v161, v206, v161
	v_mul_f32_e32 v204, v204, v204
	v_mul_f32_e32 v205, v205, v205
	v_cvt_pk_bf16_f32 v162, v204, v205
	v_cvt_pk_bf16_f32 v163, v202, v203
	global_store_dwordx4 v164, v[160:163], s[0:1] offset:2048
	v_pk_mul_f32 v[202:203], v[118:119], v[176:177] op_sel_hi:[1,0]
	v_pk_mul_f32 v[204:205], v[116:117], v[176:177] op_sel_hi:[1,0]
	v_pk_mul_f32 v[160:161], v[126:127], v[176:177] op_sel_hi:[1,0]
	v_pk_mul_f32 v[162:163], v[124:125], v[176:177] op_sel_hi:[1,0]
	v_max_f32_e32 v160, 0, v160
	v_mul_f32_e32 v206, v160, v160
	v_max_f32_e32 v160, 0, v202
	v_mul_f32_e32 v202, v160, v160
	v_max_f32_e32 v160, 0, v161
	v_max_f32_e32 v162, 0, v162
	v_max_f32_e32 v163, 0, v163
	v_mul_f32_e32 v161, v160, v160
	v_max_f32_e32 v160, 0, v203
	v_mul_f32_e32 v162, v162, v162
	v_max_f32_e32 v204, 0, v204
	v_mul_f32_e32 v163, v163, v163
	v_max_f32_e32 v205, 0, v205
	v_mul_f32_e32 v203, v160, v160
	v_cvt_pk_bf16_f32 v160, v162, v163
	v_cvt_pk_bf16_f32 v161, v206, v161
	v_mul_f32_e32 v204, v204, v204
	v_mul_f32_e32 v205, v205, v205
	v_cvt_pk_bf16_f32 v162, v204, v205
	v_cvt_pk_bf16_f32 v163, v202, v203
	global_store_dwordx4 v[200:201], v[160:163], off offset:2048
	v_pk_mul_f32 v[200:201], v[98:99], v[174:175] op_sel_hi:[1,0]
	v_pk_mul_f32 v[202:203], v[96:97], v[174:175] op_sel_hi:[1,0]
	v_pk_mul_f32 v[160:161], v[106:107], v[174:175] op_sel_hi:[1,0]
	v_pk_mul_f32 v[162:163], v[104:105], v[174:175] op_sel_hi:[1,0]
	v_max_f32_e32 v160, 0, v160
	v_mul_f32_e32 v204, v160, v160
	v_max_f32_e32 v160, 0, v200
	v_mul_f32_e32 v200, v160, v160
	v_max_f32_e32 v160, 0, v161
	v_max_f32_e32 v162, 0, v162
	v_max_f32_e32 v163, 0, v163
	v_mul_f32_e32 v161, v160, v160
	v_max_f32_e32 v160, 0, v201
	v_mul_f32_e32 v162, v162, v162
	v_max_f32_e32 v202, 0, v202
	v_mul_f32_e32 v163, v163, v163
	v_max_f32_e32 v203, 0, v203
	v_mul_f32_e32 v201, v160, v160
	v_cvt_pk_bf16_f32 v160, v162, v163
	v_cvt_pk_bf16_f32 v161, v204, v161
	v_mul_f32_e32 v202, v202, v202
	v_mul_f32_e32 v203, v203, v203
	v_cvt_pk_bf16_f32 v162, v202, v203
	v_cvt_pk_bf16_f32 v163, v200, v201
	global_store_dwordx4 v164, v[160:163], s[0:1] offset:3072
	v_pk_mul_f32 v[200:201], v[102:103], v[174:175] op_sel_hi:[1,0]
	v_pk_mul_f32 v[202:203], v[100:101], v[174:175] op_sel_hi:[1,0]
	v_pk_mul_f32 v[160:161], v[110:111], v[174:175] op_sel_hi:[1,0]
	v_pk_mul_f32 v[162:163], v[108:109], v[174:175] op_sel_hi:[1,0]
	v_max_f32_e32 v160, 0, v160
	v_mul_f32_e32 v204, v160, v160
	v_max_f32_e32 v160, 0, v200
	v_max_f32_e32 v162, 0, v162
	v_max_f32_e32 v163, 0, v163
	v_mul_f32_e32 v200, v160, v160
	v_max_f32_e32 v160, 0, v161
	v_mul_f32_e32 v162, v162, v162
	v_max_f32_e32 v202, 0, v202
	v_mul_f32_e32 v163, v163, v163
	v_max_f32_e32 v203, 0, v203
	v_mul_f32_e32 v161, v160, v160
	v_max_f32_e32 v160, 0, v201
	v_mul_f32_e32 v202, v202, v202
	v_mul_f32_e32 v203, v203, v203
	v_mul_f32_e32 v201, v160, v160
	v_cvt_pk_bf16_f32 v160, v162, v163
	v_cvt_pk_bf16_f32 v161, v204, v161
	v_cvt_pk_bf16_f32 v162, v202, v203
	v_cvt_pk_bf16_f32 v163, v200, v201
	v_add_u32_e32 v164, 0x80c00, v164
	s_cbranch_execnz .LBB0_238

.LBB0_273:
	v_and_b32_e32 v2, 15, v0
	s_bfe_u32 s64, s86, 0x30003
	v_and_b32_e32 v3, 48, v0
	v_lshlrev_b32_e32 v134, 4, v135
	v_and_b32_e32 v5, 32, v0
	s_movk_i32 s65, 0x3f0
	v_and_b32_e32 v6, 64, v135
	v_lshlrev_b32_e32 v2, 6, v2
	v_lshlrev_b32_e32 v9, 2, v0
	v_lshlrev_b32_e32 v0, 6, v0
	s_lshl_b32 s66, s64, 14
	v_and_b32_e32 v4, 0x3f0, v134
	v_bitop3_b32 v155, v134, v5, s65 bitop3:0x6c
	v_lshlrev_b32_e32 v156, 13, v6
	v_lshlrev_b32_e32 v7, 3, v135
	v_mul_i32_i24_e32 v6, 0xffffe800, v6
	s_add_i32 s65, s20, -2
	v_or_b32_e32 v8, v2, v3
	v_and_b32_e32 v9, 32, v9
	s_mov_b32 s67, 0x14000
	v_and_b32_e32 v0, 0x3c0, v0
	v_and_b32_e32 v157, 0xfffffc00, v7
	v_bitop3_b32 v2, v2, v9, v3 bitop3:0x36
	v_bitop3_b32 v11, v8, s67, v9 bitop3:0xde
	s_mov_b32 s67, 0x1c000
	v_bitop3_b32 v3, v0, v9, v3 bitop3:0x36
	v_bitop3_b32 v0, v6, v4, v5 bitop3:0xf6
	s_add_u32 s66, s70, s66
	v_bitop3_b32 v10, v8, s74, v9 bitop3:0xde
	v_bitop3_b32 v12, v8, s75, v9 bitop3:0xde
	v_bitop3_b32 v8, v8, s67, v9 bitop3:0xde
	v_add3_u32 v128, v0, v156, v157
	s_addc_u32 s67, s71, 0
	v_lshlrev_b32_e32 v13, 13, v1
	v_lshl_add_u64 v[0:1], s[66:67], 0, v[128:129]
	s_mov_b64 s[66:67], 0xc3000
	v_lshl_add_u64 v[130:131], v[0:1], 0, s[66:67]
	s_lshl_b32 s66, s86, 11
	s_and_b32 s67, s86, 7
	s_and_b32 s66, s66, 0x60000
	s_lshl_b32 s67, s67, 14
	s_or_b32 s66, s66, s67
	v_bitop3_b32 v0, v4, v156, v5 bitop3:0xde
	s_add_u32 s66, s68, s66
	v_add_u32_e32 v128, v0, v157
	s_addc_u32 s67, s69, 0
	v_lshlrev_b32_e32 v7, 6, v135
	v_lshl_add_u64 v[0:1], s[66:67], 0, v[128:129]
	s_mov_b64 s[66:67], 0x301000
	v_and_b32_e32 v7, 0x3000, v7
	v_or_b32_e32 v9, 0x800, v13
	v_or_b32_e32 v14, 0x1000, v13
	v_or_b32_e32 v15, 0x1800, v13
	v_lshl_add_u64 v[132:133], v[0:1], 0, s[66:67]
	v_mov_b32_e32 v0, 0
	s_mov_b32 s66, 0
	v_add_u32_e32 v161, v10, v7
	v_add_u32_e32 v152, v2, v13
	v_add_u32_e32 v151, v3, v9
	v_add_u32_e32 v150, v3, v14
	v_add_u32_e32 v149, v3, v15
	v_add_u32_e32 v160, 0xc000, v134
	v_add_u32_e32 v159, 0xe000, v134
	v_add_u32_e32 v158, v11, v7
	v_add_u32_e32 v148, 0x10000, v134
	v_add_u32_e32 v147, 0x12000, v134
	v_add_u32_e32 v146, 0x2000, v134
	v_add_u32_e32 v145, 0x14000, v134
	v_add_u32_e32 v144, 0x16000, v134
	v_add_u32_e32 v154, v12, v7
	v_add_u32_e32 v143, 0x4000, v134
	v_add_u32_e32 v142, 0x6000, v134
	v_add_u32_e32 v153, v8, v7
	v_add_u32_e32 v141, 0x18000, v134
	v_add_u32_e32 v140, 0x1a000, v134
	v_add_u32_e32 v139, 0x8000, v134
	v_add_u32_e32 v138, 0xa000, v134
	v_add_u32_e32 v137, 0x1c000, v134
	v_add_u32_e32 v136, 0x1e000, v134
	v_mov_b32_e32 v1, v0
	v_mov_b32_e32 v2, v0
	v_mov_b32_e32 v3, v0
	v_mov_b32_e32 v4, v0
	v_mov_b32_e32 v5, v0
	v_mov_b32_e32 v6, v0
	v_mov_b32_e32 v7, v0
	v_mov_b32_e32 v8, v0
	v_mov_b32_e32 v9, v0
	v_mov_b32_e32 v10, v0
	v_mov_b32_e32 v11, v0
	v_mov_b32_e32 v12, v0
	v_mov_b32_e32 v13, v0
	v_mov_b32_e32 v14, v0
	v_mov_b32_e32 v15, v0
	v_mov_b32_e32 v16, v0
	v_mov_b32_e32 v17, v0
	v_mov_b32_e32 v18, v0
	v_mov_b32_e32 v19, v0
	v_mov_b32_e32 v20, v0
	v_mov_b32_e32 v21, v0
	v_mov_b32_e32 v22, v0
	v_mov_b32_e32 v23, v0
	v_mov_b32_e32 v24, v0
	v_mov_b32_e32 v25, v0
	v_mov_b32_e32 v26, v0
	v_mov_b32_e32 v27, v0
	v_mov_b32_e32 v28, v0
	v_mov_b32_e32 v29, v0
	v_mov_b32_e32 v30, v0
	v_mov_b32_e32 v31, v0
	v_mov_b32_e32 v32, v0
	v_mov_b32_e32 v33, v0
	v_mov_b32_e32 v34, v0
	v_mov_b32_e32 v35, v0
	v_mov_b32_e32 v36, v0
	v_mov_b32_e32 v37, v0
	v_mov_b32_e32 v38, v0
	v_mov_b32_e32 v39, v0
	v_mov_b32_e32 v40, v0
	v_mov_b32_e32 v41, v0
	v_mov_b32_e32 v42, v0
	v_mov_b32_e32 v43, v0
	v_mov_b32_e32 v44, v0
	v_mov_b32_e32 v45, v0
	v_mov_b32_e32 v46, v0
	v_mov_b32_e32 v47, v0
	v_mov_b32_e32 v48, v0
	v_mov_b32_e32 v49, v0
	v_mov_b32_e32 v50, v0
	v_mov_b32_e32 v51, v0
	v_mov_b32_e32 v52, v0
	v_mov_b32_e32 v53, v0
	v_mov_b32_e32 v54, v0
	v_mov_b32_e32 v55, v0
	v_mov_b32_e32 v56, v0
	v_mov_b32_e32 v57, v0
	v_mov_b32_e32 v58, v0
	v_mov_b32_e32 v59, v0
	v_mov_b32_e32 v60, v0
	v_mov_b32_e32 v61, v0
	v_mov_b32_e32 v62, v0
	v_mov_b32_e32 v63, v0
	v_mov_b32_e32 v64, v0
	v_mov_b32_e32 v65, v0
	v_mov_b32_e32 v66, v0
	v_mov_b32_e32 v67, v0
	v_mov_b32_e32 v68, v0
	v_mov_b32_e32 v69, v0
	v_mov_b32_e32 v70, v0
	v_mov_b32_e32 v71, v0
	v_mov_b32_e32 v72, v0
	v_mov_b32_e32 v73, v0
	v_mov_b32_e32 v74, v0
	v_mov_b32_e32 v75, v0
	v_mov_b32_e32 v76, v0
	v_mov_b32_e32 v77, v0
	v_mov_b32_e32 v78, v0
	v_mov_b32_e32 v79, v0
	v_mov_b32_e32 v80, v0
	v_mov_b32_e32 v81, v0
	v_mov_b32_e32 v82, v0
	v_mov_b32_e32 v83, v0
	v_mov_b32_e32 v84, v0
	v_mov_b32_e32 v85, v0
	v_mov_b32_e32 v86, v0
	v_mov_b32_e32 v87, v0
	v_mov_b32_e32 v88, v0
	v_mov_b32_e32 v89, v0
	v_mov_b32_e32 v90, v0
	v_mov_b32_e32 v91, v0
	v_mov_b32_e32 v92, v0
	v_mov_b32_e32 v93, v0
	v_mov_b32_e32 v94, v0
	v_mov_b32_e32 v95, v0
	v_mov_b32_e32 v96, v0
	v_mov_b32_e32 v97, v0
	v_mov_b32_e32 v98, v0
	v_mov_b32_e32 v99, v0
	v_mov_b32_e32 v100, v0
	v_mov_b32_e32 v101, v0
	v_mov_b32_e32 v102, v0
	v_mov_b32_e32 v103, v0
	v_mov_b32_e32 v104, v0
	v_mov_b32_e32 v105, v0
	v_mov_b32_e32 v106, v0
	v_mov_b32_e32 v107, v0
	v_mov_b32_e32 v108, v0
	v_mov_b32_e32 v109, v0
	v_mov_b32_e32 v110, v0
	v_mov_b32_e32 v111, v0
	v_mov_b32_e32 v112, v0
	v_mov_b32_e32 v113, v0
	v_mov_b32_e32 v114, v0
	v_mov_b32_e32 v115, v0
	v_mov_b32_e32 v116, v0
	v_mov_b32_e32 v117, v0
	v_mov_b32_e32 v118, v0
	v_mov_b32_e32 v119, v0
	v_mov_b32_e32 v120, v0
	v_mov_b32_e32 v121, v0
	v_mov_b32_e32 v122, v0
	v_mov_b32_e32 v123, v0
	v_mov_b32_e32 v124, v0
	v_mov_b32_e32 v125, v0
	v_mov_b32_e32 v126, v0
	v_mov_b32_e32 v127, v0
	s_barrier
	v_readlane_b32 s98, v242, 1
	s_nop 3
	s_cmp_lt_u32 s98, 4
	s_cbranch_scc1 .Lprio_274
	s_setprio 1
.Lprio_274:
	s_mov_b32 vcc_lo, 0xffe01000
	s_mov_b32 vcc_hi, -1
	v_lshl_add_u64 v[164:165], v[132:133], 0, vcc
	v_readfirstlane_b32 s67, v160
	s_mov_b32 vcc_lo, 0xffe02000
	s_mov_b32 m0, s67
	s_mov_b32 vcc_hi, -1
	v_readfirstlane_b32 s67, v159
	global_load_lds_dwordx4 v[164:165], off
	v_lshl_add_u64 v[164:165], v[132:133], 0, vcc
	s_mov_b32 m0, s67
	s_nop 0
	global_load_lds_dwordx4 v[164:165], off
.LBB0_274:
	ds_read_b128 v[162:165], v161
	ds_read_b128 v[166:169], v161 offset:1024
	ds_read_b128 v[170:173], v161 offset:2048
	ds_read_b128 v[174:177], v161 offset:3072
	ds_read_b128 v[178:181], v152
	ds_read_b128 v[182:185], v152 offset:1024
	ds_read_b128 v[186:189], v151
	ds_read_b128 v[190:193], v151 offset:1024
	ds_read_b128 v[194:197], v150
	ds_read_b128 v[198:201], v150 offset:1024
	ds_read_b128 v[202:205], v149
	ds_read_b128 v[206:209], v149 offset:1024
	s_waitcnt lgkmcnt(8)
	s_waitcnt vmcnt(10)
	s_barrier
	s_waitcnt lgkmcnt(0)
	s_waitcnt lgkmcnt(0)
	v_mfma_f32_16x16x32_bf16 v[124:127], v[162:165], v[178:181], v[124:127]
	v_mfma_f32_16x16x32_bf16 v[120:123], v[170:173], v[178:181], v[120:123]
	v_mfma_f32_16x16x32_bf16 v[116:119], v[162:165], v[186:189], v[116:119]
	v_mfma_f32_16x16x32_bf16 v[112:115], v[170:173], v[186:189], v[112:115]
	v_mfma_f32_16x16x32_bf16 v[108:111], v[162:165], v[194:197], v[108:111]
	v_mfma_f32_16x16x32_bf16 v[104:107], v[170:173], v[194:197], v[104:107]
	v_mfma_f32_16x16x32_bf16 v[100:103], v[162:165], v[202:205], v[100:103]
	v_mfma_f32_16x16x32_bf16 v[96:99], v[170:173], v[202:205], v[96:99]
	v_mfma_f32_16x16x32_bf16 v[124:127], v[166:169], v[182:185], v[124:127]
	v_mfma_f32_16x16x32_bf16 v[120:123], v[174:177], v[182:185], v[120:123]
	v_mfma_f32_16x16x32_bf16 v[116:119], v[166:169], v[190:193], v[116:119]
	v_mfma_f32_16x16x32_bf16 v[112:115], v[174:177], v[190:193], v[112:115]
	v_mfma_f32_16x16x32_bf16 v[108:111], v[166:169], v[198:201], v[108:111]
	v_mfma_f32_16x16x32_bf16 v[104:107], v[174:177], v[198:201], v[104:107]
	v_mfma_f32_16x16x32_bf16 v[100:103], v[166:169], v[206:209], v[100:103]
	v_mfma_f32_16x16x32_bf16 v[96:99], v[174:177], v[206:209], v[96:99]
	s_barrier
	s_mov_b32 vcc_lo, 0xfffbd000
	s_mov_b32 vcc_hi, -1
	v_readfirstlane_b32 s67, v148
	v_lshl_add_u64 v[226:227], v[130:131], 0, vcc
	s_mov_b32 m0, s67
	v_readfirstlane_b32 s67, v147
	ds_read_b128 v[210:213], v158
	ds_read_b128 v[214:217], v158 offset:1024
	ds_read_b128 v[218:221], v158 offset:2048
	ds_read_b128 v[222:225], v158 offset:3072
	global_load_lds_dwordx4 v[226:227], off
	v_lshl_add_u64 v[226:227], v[130:131], 0, s[22:23]
	s_mov_b32 m0, s67
	s_add_i32 s66, s66, 2
	global_load_lds_dwordx4 v[226:227], off
	v_readfirstlane_b32 s67, v134
	v_lshl_add_u64 v[226:227], v[132:133], 0, s[24:25]
	s_mov_b32 m0, s67
	v_readfirstlane_b32 s67, v146
	global_load_lds_dwordx4 v[226:227], off
	v_lshl_add_u64 v[226:227], v[132:133], 0, s[26:27]
	s_mov_b32 m0, s67
	s_nop 0
	global_load_lds_dwordx4 v[226:227], off
	s_waitcnt vmcnt(12)
	s_barrier
	s_waitcnt lgkmcnt(0)
	s_waitcnt lgkmcnt(0)
	v_mfma_f32_16x16x32_bf16 v[92:95], v[210:213], v[178:181], v[92:95]
	v_mfma_f32_16x16x32_bf16 v[88:91], v[218:221], v[178:181], v[88:91]
	v_mfma_f32_16x16x32_bf16 v[84:87], v[210:213], v[186:189], v[84:87]
	v_mfma_f32_16x16x32_bf16 v[80:83], v[218:221], v[186:189], v[80:83]
	v_mfma_f32_16x16x32_bf16 v[76:79], v[210:213], v[194:197], v[76:79]
	v_mfma_f32_16x16x32_bf16 v[72:75], v[218:221], v[194:197], v[72:75]
	v_mfma_f32_16x16x32_bf16 v[68:71], v[210:213], v[202:205], v[68:71]
	v_mfma_f32_16x16x32_bf16 v[64:67], v[218:221], v[202:205], v[64:67]
	v_mfma_f32_16x16x32_bf16 v[92:95], v[214:217], v[182:185], v[92:95]
	v_mfma_f32_16x16x32_bf16 v[88:91], v[222:225], v[182:185], v[88:91]
	v_mfma_f32_16x16x32_bf16 v[84:87], v[214:217], v[190:193], v[84:87]
	v_mfma_f32_16x16x32_bf16 v[80:83], v[222:225], v[190:193], v[80:83]
	v_mfma_f32_16x16x32_bf16 v[76:79], v[214:217], v[198:201], v[76:79]
	v_mfma_f32_16x16x32_bf16 v[72:75], v[222:225], v[198:201], v[72:75]
	v_mfma_f32_16x16x32_bf16 v[68:71], v[214:217], v[206:209], v[68:71]
	v_mfma_f32_16x16x32_bf16 v[64:67], v[222:225], v[206:209], v[64:67]
	s_barrier
	ds_read_b128 v[178:181], v152 offset:16384
	ds_read_b128 v[182:185], v152 offset:17408
	ds_read_b128 v[186:189], v151 offset:16384
	ds_read_b128 v[190:193], v151 offset:17408
	ds_read_b128 v[194:197], v150 offset:16384
	ds_read_b128 v[198:201], v150 offset:17408
	ds_read_b128 v[202:205], v149 offset:16384
	ds_read_b128 v[206:209], v149 offset:17408
	v_readfirstlane_b32 s67, v145
	v_lshl_add_u64 v[226:227], v[130:131], 0, s[28:29]
	s_mov_b32 m0, s67
	v_readfirstlane_b32 s67, v144
	global_load_lds_dwordx4 v[226:227], off
	v_lshl_add_u64 v[226:227], v[130:131], 0, s[30:31]
	s_mov_b32 m0, s67
	s_nop 0
	global_load_lds_dwordx4 v[226:227], off
	s_barrier
	s_waitcnt lgkmcnt(0)
	s_waitcnt lgkmcnt(0)
	v_mfma_f32_16x16x32_bf16 v[60:63], v[162:165], v[178:181], v[60:63]
	v_mfma_f32_16x16x32_bf16 v[56:59], v[170:173], v[178:181], v[56:59]
	v_mfma_f32_16x16x32_bf16 v[52:55], v[162:165], v[186:189], v[52:55]
	v_mfma_f32_16x16x32_bf16 v[48:51], v[170:173], v[186:189], v[48:51]
	v_mfma_f32_16x16x32_bf16 v[44:47], v[162:165], v[194:197], v[44:47]
	v_mfma_f32_16x16x32_bf16 v[40:43], v[170:173], v[194:197], v[40:43]
	v_mfma_f32_16x16x32_bf16 v[36:39], v[162:165], v[202:205], v[36:39]
	v_mfma_f32_16x16x32_bf16 v[32:35], v[170:173], v[202:205], v[32:35]
	v_mfma_f32_16x16x32_bf16 v[60:63], v[166:169], v[182:185], v[60:63]
	v_mfma_f32_16x16x32_bf16 v[56:59], v[174:177], v[182:185], v[56:59]
	v_mfma_f32_16x16x32_bf16 v[52:55], v[166:169], v[190:193], v[52:55]
	v_mfma_f32_16x16x32_bf16 v[48:51], v[174:177], v[190:193], v[48:51]
	v_mfma_f32_16x16x32_bf16 v[44:47], v[166:169], v[198:201], v[44:47]
	v_mfma_f32_16x16x32_bf16 v[40:43], v[174:177], v[198:201], v[40:43]
	v_mfma_f32_16x16x32_bf16 v[36:39], v[166:169], v[206:209], v[36:39]
	v_mfma_f32_16x16x32_bf16 v[32:35], v[174:177], v[206:209], v[32:35]
	s_barrier
	v_readfirstlane_b32 s67, v143
	v_lshl_add_u64 v[164:165], v[132:133], 0, s[34:35]
	s_mov_b32 m0, s67
	v_readfirstlane_b32 s67, v142
	global_load_lds_dwordx4 v[164:165], off
	v_lshl_add_u64 v[164:165], v[132:133], 0, s[44:45]
	s_mov_b32 m0, s67
	s_nop 0
	global_load_lds_dwordx4 v[164:165], off
	s_waitcnt vmcnt(12)
	s_barrier
	v_mfma_f32_16x16x32_bf16 v[28:31], v[210:213], v[178:181], v[28:31]
	v_mfma_f32_16x16x32_bf16 v[24:27], v[218:221], v[178:181], v[24:27]
	v_mfma_f32_16x16x32_bf16 v[20:23], v[210:213], v[186:189], v[20:23]
	v_mfma_f32_16x16x32_bf16 v[16:19], v[218:221], v[186:189], v[16:19]
	v_mfma_f32_16x16x32_bf16 v[12:15], v[210:213], v[194:197], v[12:15]
	v_mfma_f32_16x16x32_bf16 v[8:11], v[218:221], v[194:197], v[8:11]
	v_mfma_f32_16x16x32_bf16 v[4:7], v[210:213], v[202:205], v[4:7]
	v_mfma_f32_16x16x32_bf16 v[0:3], v[218:221], v[202:205], v[0:3]
	v_mfma_f32_16x16x32_bf16 v[28:31], v[214:217], v[182:185], v[28:31]
	v_mfma_f32_16x16x32_bf16 v[24:27], v[222:225], v[182:185], v[24:27]
	v_mfma_f32_16x16x32_bf16 v[20:23], v[214:217], v[190:193], v[20:23]
	v_mfma_f32_16x16x32_bf16 v[16:19], v[222:225], v[190:193], v[16:19]
	v_mfma_f32_16x16x32_bf16 v[12:15], v[214:217], v[198:201], v[12:15]
	v_mfma_f32_16x16x32_bf16 v[8:11], v[222:225], v[198:201], v[8:11]
	v_mfma_f32_16x16x32_bf16 v[4:7], v[214:217], v[206:209], v[4:7]
	v_mfma_f32_16x16x32_bf16 v[0:3], v[222:225], v[206:209], v[0:3]
	s_barrier
	ds_read_b128 v[162:165], v154
	ds_read_b128 v[166:169], v154 offset:1024
	ds_read_b128 v[170:173], v154 offset:2048
	ds_read_b128 v[174:177], v154 offset:3072
	ds_read_b128 v[178:181], v152 offset:32768
	ds_read_b128 v[182:185], v152 offset:33792
	ds_read_b128 v[186:189], v151 offset:32768
	ds_read_b128 v[190:193], v151 offset:33792
	ds_read_b128 v[194:197], v150 offset:32768
	ds_read_b128 v[198:201], v150 offset:33792
	ds_read_b128 v[202:205], v149 offset:32768
	ds_read_b128 v[206:209], v149 offset:33792
	s_waitcnt lgkmcnt(8)
	s_waitcnt vmcnt(10)
	s_barrier
	s_waitcnt lgkmcnt(0)
	s_waitcnt lgkmcnt(0)
	v_mfma_f32_16x16x32_bf16 v[124:127], v[162:165], v[178:181], v[124:127]
	v_mfma_f32_16x16x32_bf16 v[120:123], v[170:173], v[178:181], v[120:123]
	v_mfma_f32_16x16x32_bf16 v[116:119], v[162:165], v[186:189], v[116:119]
	v_mfma_f32_16x16x32_bf16 v[112:115], v[170:173], v[186:189], v[112:115]
	v_mfma_f32_16x16x32_bf16 v[108:111], v[162:165], v[194:197], v[108:111]
	v_mfma_f32_16x16x32_bf16 v[104:107], v[170:173], v[194:197], v[104:107]
	v_mfma_f32_16x16x32_bf16 v[100:103], v[162:165], v[202:205], v[100:103]
	v_mfma_f32_16x16x32_bf16 v[96:99], v[170:173], v[202:205], v[96:99]
	v_mfma_f32_16x16x32_bf16 v[124:127], v[166:169], v[182:185], v[124:127]
	v_mfma_f32_16x16x32_bf16 v[120:123], v[174:177], v[182:185], v[120:123]
	v_mfma_f32_16x16x32_bf16 v[116:119], v[166:169], v[190:193], v[116:119]
	v_mfma_f32_16x16x32_bf16 v[112:115], v[174:177], v[190:193], v[112:115]
	v_mfma_f32_16x16x32_bf16 v[108:111], v[166:169], v[198:201], v[108:111]
	v_mfma_f32_16x16x32_bf16 v[104:107], v[174:177], v[198:201], v[104:107]
	v_mfma_f32_16x16x32_bf16 v[100:103], v[166:169], v[206:209], v[100:103]
	v_mfma_f32_16x16x32_bf16 v[96:99], v[174:177], v[206:209], v[96:99]
	s_barrier
	v_readfirstlane_b32 s67, v141
	v_lshl_add_u64 v[226:227], v[130:131], 0, s[46:47]
	s_mov_b32 m0, s67
	v_readfirstlane_b32 s67, v140
	ds_read_b128 v[210:213], v153
	ds_read_b128 v[214:217], v153 offset:1024
	ds_read_b128 v[218:221], v153 offset:2048
	ds_read_b128 v[222:225], v153 offset:3072
	global_load_lds_dwordx4 v[226:227], off
	v_lshl_add_u64 v[226:227], v[130:131], 0, s[56:57]
	s_mov_b32 m0, s67
	s_nop 0
	global_load_lds_dwordx4 v[226:227], off
	v_readfirstlane_b32 s67, v139
	v_lshl_add_u64 v[226:227], v[132:133], 0, s[58:59]
	s_mov_b32 m0, s67
	v_readfirstlane_b32 s67, v138
	global_load_lds_dwordx4 v[226:227], off
	s_mov_b32 m0, s67
	s_nop 0
	global_load_lds_dwordx4 v[132:133], off
	s_waitcnt vmcnt(12)
	s_barrier
	s_waitcnt lgkmcnt(0)
	s_waitcnt lgkmcnt(0)
	v_mfma_f32_16x16x32_bf16 v[92:95], v[210:213], v[178:181], v[92:95]
	v_mfma_f32_16x16x32_bf16 v[88:91], v[218:221], v[178:181], v[88:91]
	v_mfma_f32_16x16x32_bf16 v[84:87], v[210:213], v[186:189], v[84:87]
	v_mfma_f32_16x16x32_bf16 v[80:83], v[218:221], v[186:189], v[80:83]
	v_mfma_f32_16x16x32_bf16 v[76:79], v[210:213], v[194:197], v[76:79]
	v_mfma_f32_16x16x32_bf16 v[72:75], v[218:221], v[194:197], v[72:75]
	v_mfma_f32_16x16x32_bf16 v[68:71], v[210:213], v[202:205], v[68:71]
	v_mfma_f32_16x16x32_bf16 v[64:67], v[218:221], v[202:205], v[64:67]
	v_mfma_f32_16x16x32_bf16 v[92:95], v[214:217], v[182:185], v[92:95]
	v_mfma_f32_16x16x32_bf16 v[88:91], v[222:225], v[182:185], v[88:91]
	v_mfma_f32_16x16x32_bf16 v[84:87], v[214:217], v[190:193], v[84:87]
	v_mfma_f32_16x16x32_bf16 v[80:83], v[222:225], v[190:193], v[80:83]
	v_mfma_f32_16x16x32_bf16 v[76:79], v[214:217], v[198:201], v[76:79]
	v_mfma_f32_16x16x32_bf16 v[72:75], v[222:225], v[198:201], v[72:75]
	v_mfma_f32_16x16x32_bf16 v[68:71], v[214:217], v[206:209], v[68:71]
	v_mfma_f32_16x16x32_bf16 v[64:67], v[222:225], v[206:209], v[64:67]
	s_barrier
	ds_read_b128 v[178:181], v152 offset:49152
	ds_read_b128 v[182:185], v152 offset:50176
	ds_read_b128 v[186:189], v151 offset:49152
	ds_read_b128 v[190:193], v151 offset:50176
	ds_read_b128 v[194:197], v150 offset:49152
	ds_read_b128 v[198:201], v150 offset:50176
	ds_read_b128 v[202:205], v149 offset:49152
	ds_read_b128 v[206:209], v149 offset:50176
	v_readfirstlane_b32 s67, v137
	v_lshl_add_u64 v[226:227], v[130:131], 0, s[58:59]
	s_mov_b32 m0, s67
	v_readfirstlane_b32 s67, v136
	global_load_lds_dwordx4 v[226:227], off
	s_mov_b32 m0, s67
	s_nop 0
	global_load_lds_dwordx4 v[130:131], off
	s_barrier
	s_waitcnt lgkmcnt(0)
	s_waitcnt lgkmcnt(0)
	v_mfma_f32_16x16x32_bf16 v[60:63], v[162:165], v[178:181], v[60:63]
	v_mfma_f32_16x16x32_bf16 v[56:59], v[170:173], v[178:181], v[56:59]
	v_mfma_f32_16x16x32_bf16 v[52:55], v[162:165], v[186:189], v[52:55]
	v_mfma_f32_16x16x32_bf16 v[48:51], v[170:173], v[186:189], v[48:51]
	v_mfma_f32_16x16x32_bf16 v[44:47], v[162:165], v[194:197], v[44:47]
	v_mfma_f32_16x16x32_bf16 v[40:43], v[170:173], v[194:197], v[40:43]
	v_mfma_f32_16x16x32_bf16 v[36:39], v[162:165], v[202:205], v[36:39]
	v_mfma_f32_16x16x32_bf16 v[32:35], v[170:173], v[202:205], v[32:35]
	v_mfma_f32_16x16x32_bf16 v[60:63], v[166:169], v[182:185], v[60:63]
	v_mfma_f32_16x16x32_bf16 v[56:59], v[174:177], v[182:185], v[56:59]
	v_mfma_f32_16x16x32_bf16 v[52:55], v[166:169], v[190:193], v[52:55]
	v_mfma_f32_16x16x32_bf16 v[48:51], v[174:177], v[190:193], v[48:51]
	v_mfma_f32_16x16x32_bf16 v[44:47], v[166:169], v[198:201], v[44:47]
	v_mfma_f32_16x16x32_bf16 v[40:43], v[174:177], v[198:201], v[40:43]
	v_mfma_f32_16x16x32_bf16 v[36:39], v[166:169], v[206:209], v[36:39]
	v_mfma_f32_16x16x32_bf16 v[32:35], v[174:177], v[206:209], v[32:35]
	s_barrier
	v_lshl_add_u64 v[132:133], v[132:133], 0, s[62:63]
	s_mov_b32 vcc_lo, 0xffe01000
	s_mov_b32 vcc_hi, -1
	v_lshl_add_u64 v[164:165], v[132:133], 0, vcc
	v_readfirstlane_b32 s67, v160
	s_mov_b32 vcc_lo, 0xffe02000
	s_mov_b32 m0, s67
	s_mov_b32 vcc_hi, -1
	v_readfirstlane_b32 s67, v159
	global_load_lds_dwordx4 v[164:165], off
	v_lshl_add_u64 v[164:165], v[132:133], 0, vcc
	s_mov_b32 m0, s67
	s_nop 0
	global_load_lds_dwordx4 v[164:165], off
	s_waitcnt vmcnt(12)
	s_barrier
	v_mfma_f32_16x16x32_bf16 v[28:31], v[210:213], v[178:181], v[28:31]
	v_mfma_f32_16x16x32_bf16 v[24:27], v[218:221], v[178:181], v[24:27]
	v_mfma_f32_16x16x32_bf16 v[20:23], v[210:213], v[186:189], v[20:23]
	v_mfma_f32_16x16x32_bf16 v[16:19], v[218:221], v[186:189], v[16:19]
	v_mfma_f32_16x16x32_bf16 v[12:15], v[210:213], v[194:197], v[12:15]
	v_mfma_f32_16x16x32_bf16 v[8:11], v[218:221], v[194:197], v[8:11]
	v_mfma_f32_16x16x32_bf16 v[4:7], v[210:213], v[202:205], v[4:7]
	v_mfma_f32_16x16x32_bf16 v[0:3], v[218:221], v[202:205], v[0:3]
	v_mfma_f32_16x16x32_bf16 v[28:31], v[214:217], v[182:185], v[28:31]
	v_mfma_f32_16x16x32_bf16 v[24:27], v[222:225], v[182:185], v[24:27]
	v_mfma_f32_16x16x32_bf16 v[20:23], v[214:217], v[190:193], v[20:23]
	v_mfma_f32_16x16x32_bf16 v[16:19], v[222:225], v[190:193], v[16:19]
	v_mfma_f32_16x16x32_bf16 v[12:15], v[214:217], v[198:201], v[12:15]
	v_mfma_f32_16x16x32_bf16 v[8:11], v[222:225], v[198:201], v[8:11]
	v_mfma_f32_16x16x32_bf16 v[4:7], v[214:217], v[206:209], v[4:7]
	v_mfma_f32_16x16x32_bf16 v[0:3], v[222:225], v[206:209], v[0:3]
	v_lshl_add_u64 v[130:131], v[130:131], 0, s[60:61]
	s_cmp_lt_u32 s66, s65
	s_barrier
	s_cbranch_scc1 .LBB0_274
	s_setprio 0
	s_lshl_b32 s65, s86, 5
	s_lshl_b32 s66, s86, 8
	s_and_b32 s65, s65, 0x1800
	s_and_b32 s66, s66, 0x700
	s_or_b32 s97, s66, s65
	s_lshl_b32 s65, s97, 6
	s_add_u32 s65, s68, s65
	s_addc_u32 s86, s69, 0
	s_add_i32 s20, s20, -1
	s_lshl_b64 s[66:67], s[20:21], 20
	v_add_u32_e32 v128, v156, v157
	s_add_u32 s66, s65, s66
	v_or_b32_e32 v128, v128, v155
	s_addc_u32 s67, s86, s67
	v_lshl_add_u64 v[156:157], s[66:67], 0, v[128:129]
	v_readfirstlane_b32 s20, v160
	v_lshl_add_u64 v[206:207], v[156:157], 0, s[4:5]
	s_mov_b32 m0, s20
	v_readfirstlane_b32 s20, v159
	ds_read_b128 v[130:133], v161
	ds_read_b128 v[162:165], v161 offset:1024
	ds_read_b128 v[166:169], v161 offset:2048
	ds_read_b128 v[170:173], v161 offset:3072
	ds_read_b128 v[174:177], v152
	ds_read_b128 v[178:181], v152 offset:1024
	ds_read_b128 v[182:185], v151
	ds_read_b128 v[186:189], v151 offset:1024
	ds_read_b128 v[190:193], v150
	ds_read_b128 v[194:197], v150 offset:1024
	ds_read_b128 v[198:201], v149
	ds_read_b128 v[202:205], v149 offset:1024
	global_load_lds_dwordx4 v[206:207], off
	v_lshl_add_u64 v[156:157], v[156:157], 0, s[6:7]
	s_mov_b32 m0, s20
	s_nop 0
	global_load_lds_dwordx4 v[156:157], off
	s_waitcnt vmcnt(10)
	s_barrier
	s_waitcnt lgkmcnt(0)
	s_setprio 1
	s_waitcnt lgkmcnt(0)
	v_mfma_f32_16x16x32_bf16 v[124:127], v[130:133], v[174:177], v[124:127]
	v_mfma_f32_16x16x32_bf16 v[120:123], v[166:169], v[174:177], v[120:123]
	v_mfma_f32_16x16x32_bf16 v[116:119], v[130:133], v[182:185], v[116:119]
	v_mfma_f32_16x16x32_bf16 v[112:115], v[166:169], v[182:185], v[112:115]
	v_mfma_f32_16x16x32_bf16 v[108:111], v[130:133], v[190:193], v[108:111]
	v_mfma_f32_16x16x32_bf16 v[104:107], v[166:169], v[190:193], v[104:107]
	v_mfma_f32_16x16x32_bf16 v[100:103], v[130:133], v[198:201], v[100:103]
	v_mfma_f32_16x16x32_bf16 v[96:99], v[166:169], v[198:201], v[96:99]
	v_mfma_f32_16x16x32_bf16 v[124:127], v[162:165], v[178:181], v[124:127]
	v_mfma_f32_16x16x32_bf16 v[120:123], v[170:173], v[178:181], v[120:123]
	v_mfma_f32_16x16x32_bf16 v[116:119], v[162:165], v[186:189], v[116:119]
	v_mfma_f32_16x16x32_bf16 v[112:115], v[170:173], v[186:189], v[112:115]
	v_mfma_f32_16x16x32_bf16 v[108:111], v[162:165], v[194:197], v[108:111]
	v_mfma_f32_16x16x32_bf16 v[104:107], v[170:173], v[194:197], v[104:107]
	v_mfma_f32_16x16x32_bf16 v[100:103], v[162:165], v[202:205], v[100:103]
	v_mfma_f32_16x16x32_bf16 v[96:99], v[170:173], v[202:205], v[96:99]
	s_setprio 0
	s_barrier
	ds_read_b128 v[206:209], v158
	ds_read_b128 v[210:213], v158 offset:1024
	ds_read_b128 v[214:217], v158 offset:2048
	ds_read_b128 v[156:159], v158 offset:3072
	s_barrier
	s_waitcnt lgkmcnt(0)
	s_setprio 1
	s_waitcnt lgkmcnt(0)
	v_mfma_f32_16x16x32_bf16 v[92:95], v[206:209], v[174:177], v[92:95]
	v_mfma_f32_16x16x32_bf16 v[88:91], v[214:217], v[174:177], v[88:91]
	v_mfma_f32_16x16x32_bf16 v[84:87], v[206:209], v[182:185], v[84:87]
	v_mfma_f32_16x16x32_bf16 v[80:83], v[214:217], v[182:185], v[80:83]
	v_mfma_f32_16x16x32_bf16 v[76:79], v[206:209], v[190:193], v[76:79]
	v_mfma_f32_16x16x32_bf16 v[72:75], v[214:217], v[190:193], v[72:75]
	v_mfma_f32_16x16x32_bf16 v[68:71], v[206:209], v[198:201], v[68:71]
	v_mfma_f32_16x16x32_bf16 v[64:67], v[214:217], v[198:201], v[64:67]
	v_mfma_f32_16x16x32_bf16 v[174:177], v[210:213], v[178:181], v[92:95]
	v_mfma_f32_16x16x32_bf16 v[178:181], v[156:159], v[178:181], v[88:91]
	v_mfma_f32_16x16x32_bf16 v[182:185], v[210:213], v[186:189], v[84:87]
	v_mfma_f32_16x16x32_bf16 v[186:189], v[156:159], v[186:189], v[80:83]
	v_mfma_f32_16x16x32_bf16 v[190:193], v[210:213], v[194:197], v[76:79]
	v_mfma_f32_16x16x32_bf16 v[194:197], v[156:159], v[194:197], v[72:75]
	v_mfma_f32_16x16x32_bf16 v[198:201], v[210:213], v[202:205], v[68:71]
	v_mfma_f32_16x16x32_bf16 v[202:205], v[156:159], v[202:205], v[64:67]
	s_setprio 0
	s_barrier
	s_nop 0
	ds_read_b128 v[64:67], v152 offset:16384
	ds_read_b128 v[68:71], v152 offset:17408
	ds_read_b128 v[72:75], v151 offset:16384
	ds_read_b128 v[76:79], v151 offset:17408
	ds_read_b128 v[80:83], v150 offset:16384
	ds_read_b128 v[84:87], v150 offset:17408
	ds_read_b128 v[88:91], v149 offset:16384
	ds_read_b128 v[92:95], v149 offset:17408
	s_waitcnt vmcnt(4)
	s_barrier
	s_waitcnt lgkmcnt(0)
	s_setprio 1
	s_waitcnt lgkmcnt(0)
	v_mfma_f32_16x16x32_bf16 v[60:63], v[130:133], v[64:67], v[60:63]
	v_mfma_f32_16x16x32_bf16 v[56:59], v[166:169], v[64:67], v[56:59]
	v_mfma_f32_16x16x32_bf16 v[52:55], v[130:133], v[72:75], v[52:55]
	v_mfma_f32_16x16x32_bf16 v[48:51], v[166:169], v[72:75], v[48:51]
	v_mfma_f32_16x16x32_bf16 v[218:221], v[130:133], v[80:83], v[44:47]
	v_mfma_f32_16x16x32_bf16 v[222:225], v[166:169], v[80:83], v[40:43]
	v_mfma_f32_16x16x32_bf16 v[130:133], v[130:133], v[88:91], v[36:39]
	v_mfma_f32_16x16x32_bf16 v[166:169], v[166:169], v[88:91], v[32:35]
	v_mfma_f32_16x16x32_bf16 v[32:35], v[162:165], v[68:71], v[60:63]
	v_mfma_f32_16x16x32_bf16 v[36:39], v[170:173], v[68:71], v[56:59]
	v_mfma_f32_16x16x32_bf16 v[40:43], v[162:165], v[76:79], v[52:55]
	v_mfma_f32_16x16x32_bf16 v[44:47], v[170:173], v[76:79], v[48:51]
	v_mfma_f32_16x16x32_bf16 v[48:51], v[162:165], v[84:87], v[218:221]
	v_mfma_f32_16x16x32_bf16 v[52:55], v[170:173], v[84:87], v[222:225]
	v_mfma_f32_16x16x32_bf16 v[56:59], v[162:165], v[92:95], v[130:133]
	v_mfma_f32_16x16x32_bf16 v[60:63], v[170:173], v[92:95], v[166:169]
	s_setprio 0
	s_setprio 1
	v_mfma_f32_16x16x32_bf16 v[28:31], v[206:209], v[64:67], v[28:31]
	v_mfma_f32_16x16x32_bf16 v[24:27], v[214:217], v[64:67], v[24:27]
	v_mfma_f32_16x16x32_bf16 v[20:23], v[206:209], v[72:75], v[20:23]
	v_mfma_f32_16x16x32_bf16 v[64:67], v[214:217], v[72:75], v[16:19]
	v_mfma_f32_16x16x32_bf16 v[72:75], v[206:209], v[80:83], v[12:15]
	v_mfma_f32_16x16x32_bf16 v[8:11], v[214:217], v[80:83], v[8:11]
	v_mfma_f32_16x16x32_bf16 v[80:83], v[206:209], v[88:91], v[4:7]
	v_mfma_f32_16x16x32_bf16 v[0:3], v[214:217], v[88:91], v[0:3]
	v_mfma_f32_16x16x32_bf16 v[4:7], v[210:213], v[68:71], v[28:31]
	v_mfma_f32_16x16x32_bf16 v[12:15], v[156:159], v[68:71], v[24:27]
	v_mfma_f32_16x16x32_bf16 v[16:19], v[210:213], v[76:79], v[20:23]
	v_mfma_f32_16x16x32_bf16 v[20:23], v[156:159], v[76:79], v[64:67]
	v_mfma_f32_16x16x32_bf16 v[24:27], v[210:213], v[84:87], v[72:75]
	v_mfma_f32_16x16x32_bf16 v[28:31], v[156:159], v[84:87], v[8:11]
	v_mfma_f32_16x16x32_bf16 v[64:67], v[210:213], v[92:95], v[80:83]
	v_mfma_f32_16x16x32_bf16 v[68:71], v[156:159], v[92:95], v[0:3]
	s_setprio 0
	s_barrier
	ds_read_b128 v[8:11], v154
	ds_read_b128 v[0:3], v154 offset:1024
	ds_read_b128 v[76:79], v154 offset:2048
	ds_read_b128 v[72:75], v154 offset:3072
	ds_read_b128 v[130:133], v152 offset:32768
	ds_read_b128 v[154:157], v152 offset:33792
	ds_read_b128 v[158:161], v151 offset:32768
	ds_read_b128 v[162:165], v151 offset:33792
	ds_read_b128 v[166:169], v150 offset:32768
	ds_read_b128 v[170:173], v150 offset:33792
	ds_read_b128 v[206:209], v149 offset:32768
	ds_read_b128 v[210:213], v149 offset:33792
	s_waitcnt vmcnt(2)
	s_barrier
	s_waitcnt lgkmcnt(0)
	s_setprio 1
	s_waitcnt lgkmcnt(0)
	v_mfma_f32_16x16x32_bf16 v[80:83], v[8:11], v[130:133], v[124:127]
	v_mfma_f32_16x16x32_bf16 v[84:87], v[76:79], v[130:133], v[120:123]
	v_mfma_f32_16x16x32_bf16 v[88:91], v[8:11], v[158:161], v[116:119]
	v_mfma_f32_16x16x32_bf16 v[92:95], v[76:79], v[158:161], v[112:115]
	v_mfma_f32_16x16x32_bf16 v[108:111], v[8:11], v[166:169], v[108:111]
	v_mfma_f32_16x16x32_bf16 v[104:107], v[76:79], v[166:169], v[104:107]
	v_mfma_f32_16x16x32_bf16 v[100:103], v[8:11], v[206:209], v[100:103]
	v_mfma_f32_16x16x32_bf16 v[96:99], v[76:79], v[206:209], v[96:99]
	v_mfma_f32_16x16x32_bf16 v[112:115], v[0:3], v[154:157], v[80:83]
	v_mfma_f32_16x16x32_bf16 v[116:119], v[72:75], v[154:157], v[84:87]
	v_mfma_f32_16x16x32_bf16 v[120:123], v[0:3], v[162:165], v[88:91]
	v_mfma_f32_16x16x32_bf16 v[124:127], v[72:75], v[162:165], v[92:95]
	v_mfma_f32_16x16x32_bf16 v[108:111], v[0:3], v[170:173], v[108:111]
	v_mfma_f32_16x16x32_bf16 v[104:107], v[72:75], v[170:173], v[104:107]
	v_mfma_f32_16x16x32_bf16 v[100:103], v[0:3], v[210:213], v[100:103]
	v_mfma_f32_16x16x32_bf16 v[96:99], v[72:75], v[210:213], v[96:99]
	s_setprio 0
	s_barrier
	ds_read_b128 v[88:91], v153
	ds_read_b128 v[80:83], v153 offset:1024
	ds_read_b128 v[92:95], v153 offset:2048
	ds_read_b128 v[84:87], v153 offset:3072
	s_waitcnt vmcnt(0)
	s_barrier
	s_waitcnt lgkmcnt(0)
	s_setprio 1
	s_waitcnt lgkmcnt(0)
	v_mfma_f32_16x16x32_bf16 v[174:177], v[88:91], v[130:133], v[174:177]
	v_mfma_f32_16x16x32_bf16 v[130:133], v[92:95], v[130:133], v[178:181]
	v_mfma_f32_16x16x32_bf16 v[178:181], v[88:91], v[158:161], v[182:185]
	v_mfma_f32_16x16x32_bf16 v[158:161], v[92:95], v[158:161], v[186:189]
	v_mfma_f32_16x16x32_bf16 v[182:185], v[88:91], v[166:169], v[190:193]
	v_mfma_f32_16x16x32_bf16 v[166:169], v[92:95], v[166:169], v[194:197]
	v_mfma_f32_16x16x32_bf16 v[186:189], v[88:91], v[206:209], v[198:201]
	v_mfma_f32_16x16x32_bf16 v[190:193], v[92:95], v[206:209], v[202:205]
	v_mfma_f32_16x16x32_bf16 v[174:177], v[80:83], v[154:157], v[174:177]
	v_mfma_f32_16x16x32_bf16 v[130:133], v[84:87], v[154:157], v[130:133]
	v_mfma_f32_16x16x32_bf16 v[154:157], v[80:83], v[162:165], v[178:181]
	v_mfma_f32_16x16x32_bf16 v[158:161], v[84:87], v[162:165], v[158:161]
	v_mfma_f32_16x16x32_bf16 v[162:165], v[80:83], v[170:173], v[182:185]
	v_mfma_f32_16x16x32_bf16 v[166:169], v[84:87], v[170:173], v[166:169]
	v_mfma_f32_16x16x32_bf16 v[170:173], v[80:83], v[210:213], v[186:189]
	v_mfma_f32_16x16x32_bf16 v[178:181], v[84:87], v[210:213], v[190:193]
	s_setprio 0
	s_barrier
	v_mbcnt_lo_u32_b32 v128, -1, 0
	v_mbcnt_hi_u32_b32 v128, -1, v128
	v_cvt_pk_bf16_f32 v112, v112, v113
	v_cvt_pk_bf16_f32 v113, v114, v115
	v_cvt_pk_bf16_f32 v114, v116, v117
	v_cvt_pk_bf16_f32 v115, v118, v119
	s_lshl_b32 s89, s64, 9
	v_add_u32_e32 v153, s72, v128
	v_ashrrev_i32_e32 v182, 6, v153
	v_and_b32_e32 v183, 15, v128
	v_and_b32_e32 v184, 48, v128
	v_mul_lo_u32 v185, v182, s77
	v_bfe_u32 v186, v128, 3, 3
	v_lshlrev_b32_e32 v128, 4, v128
	v_add_u32_e32 v185, 0x20000, v185
	v_lshrrev_b32_e32 v153, 2, v153
	v_and_b32_e32 v128, 0x70, v128
	v_mul_u32_u24_e32 v183, 0x90, v183
	v_and_b32_e32 v153, 64, v153
	v_add3_u32 v183, v185, v183, v184
	v_or_b32_e32 v184, v185, v128
	v_or3_b32 v153, s97, v153, v186
	v_mad_u32_u24 v184, v186, s79, v184
	ds_write_b128 v183, v[112:115]
	v_cvt_pk_bf16_f32 v112, v174, v175
	v_cvt_pk_bf16_f32 v113, v176, v177
	v_cvt_pk_bf16_f32 v114, v130, v131
	v_cvt_pk_bf16_f32 v115, v132, v133
	ds_write_b128 v183, v[112:115] offset:64
	v_lshlrev_b32_e32 v182, 7, v182
	ds_read_b128 v[112:115], v184
	v_lshlrev_b32_e32 v116, 12, v153
	v_and_or_b32 v116, v182, s80, v116
	v_or3_b32 v128, v116, s89, v128
	ds_read_b128 v[116:119], v184 offset:1152
	v_lshl_add_u64 v[130:131], s[0:1], 0, v[128:129]
	s_mov_b32 s20, 0x8000
	s_waitcnt lgkmcnt(0)
	global_store_dwordx4 v128, v[112:115], s[0:1]
	v_cvt_pk_bf16_f32 v108, v108, v109
	v_cvt_pk_bf16_f32 v109, v110, v111
	v_cvt_pk_bf16_f32 v110, v104, v105
	v_cvt_pk_bf16_f32 v111, v106, v107
	v_cvt_pk_bf16_f32 v104, v162, v163
	s_nop 1
	v_add_co_u32_e32 v112, vcc, s20, v130
	v_cvt_pk_bf16_f32 v114, v124, v125
	v_cvt_pk_bf16_f32 v115, v126, v127
	v_cvt_pk_bf16_f32 v105, v164, v165
	v_cvt_pk_bf16_f32 v106, v166, v167
	s_nop 1
	v_addc_co_u32_e32 v113, vcc, 0, v131, vcc
	global_store_dwordx4 v[112:113], v[116:119], off
	v_cvt_pk_bf16_f32 v112, v120, v121
	v_cvt_pk_bf16_f32 v113, v122, v123
	ds_write_b128 v183, v[112:115]
	v_cvt_pk_bf16_f32 v112, v154, v155
	v_cvt_pk_bf16_f32 v113, v156, v157
	v_cvt_pk_bf16_f32 v114, v158, v159
	v_cvt_pk_bf16_f32 v115, v160, v161
	ds_write_b128 v183, v[112:115] offset:64
	ds_read_b128 v[112:115], v184
	ds_read_b128 v[116:119], v184 offset:1152
	v_add_co_u32_e32 v120, vcc, s74, v130
	ds_write_b128 v183, v[108:111]
	v_cvt_pk_bf16_f32 v107, v168, v169
	ds_write_b128 v183, v[104:107] offset:64
	v_addc_co_u32_e32 v121, vcc, 0, v131, vcc
	ds_read_b128 v[104:107], v184
	ds_read_b128 v[108:111], v184 offset:1152
	s_waitcnt lgkmcnt(0)
	global_store_dwordx4 v[120:121], v[112:115], off
	v_cvt_pk_bf16_f32 v100, v100, v101
	v_cvt_pk_bf16_f32 v101, v102, v103
	v_cvt_pk_bf16_f32 v102, v96, v97
	v_cvt_pk_bf16_f32 v103, v98, v99
	ds_write_b128 v183, v[100:103]
	s_nop 0
	v_add_co_u32_e32 v112, vcc, s75, v130
	v_cvt_pk_bf16_f32 v96, v170, v171
	v_cvt_pk_bf16_f32 v97, v172, v173
	v_cvt_pk_bf16_f32 v98, v178, v179
	v_cvt_pk_bf16_f32 v99, v180, v181
	s_nop 1
	v_addc_co_u32_e32 v113, vcc, 0, v131, vcc
	global_store_dwordx4 v[112:113], v[116:119], off
	v_add_co_u32_e32 v112, vcc, s78, v130
	ds_write_b128 v183, v[96:99] offset:64
	s_nop 0
	v_addc_co_u32_e32 v113, vcc, 0, v131, vcc
	ds_read_b128 v[96:99], v184
	ds_read_b128 v[100:103], v184 offset:1152
	global_store_dwordx4 v[112:113], v[104:107], off
	s_nop 1
	v_add_co_u32_e32 v104, vcc, s81, v130
	s_nop 1
	v_addc_co_u32_e32 v105, vcc, 0, v131, vcc
	global_store_dwordx4 v[104:105], v[108:111], off
	v_add_co_u32_e32 v104, vcc, s82, v130
	s_nop 1
	v_addc_co_u32_e32 v105, vcc, 0, v131, vcc
	s_waitcnt lgkmcnt(0)
	global_store_dwordx4 v[104:105], v[96:99], off
	s_nop 1
	v_add_co_u32_e32 v96, vcc, s83, v130
	s_nop 1
	v_addc_co_u32_e32 v97, vcc, 0, v131, vcc
	global_store_dwordx4 v[96:97], v[100:103], off
	ds_read_b128 v[96:99], v152 offset:49152
	ds_read_b128 v[100:103], v152 offset:50176
	ds_read_b128 v[104:107], v151 offset:49152
	ds_read_b128 v[108:111], v151 offset:50176
	ds_read_b128 v[112:115], v150 offset:49152
	ds_read_b128 v[116:119], v150 offset:50176
	ds_read_b128 v[120:123], v149 offset:49152
	ds_read_b128 v[124:127], v149 offset:50176
	s_barrier
	s_waitcnt lgkmcnt(0)
	s_setprio 1
	s_waitcnt lgkmcnt(0)
	v_mfma_f32_16x16x32_bf16 v[32:35], v[8:11], v[96:99], v[32:35]
	v_mfma_f32_16x16x32_bf16 v[36:39], v[76:79], v[96:99], v[36:39]
	v_mfma_f32_16x16x32_bf16 v[40:43], v[8:11], v[104:107], v[40:43]
	v_mfma_f32_16x16x32_bf16 v[130:133], v[76:79], v[104:107], v[44:47]
	v_mfma_f32_16x16x32_bf16 v[150:153], v[8:11], v[112:115], v[48:51]
	v_mfma_f32_16x16x32_bf16 v[52:55], v[76:79], v[112:115], v[52:55]
	v_mfma_f32_16x16x32_bf16 v[8:11], v[8:11], v[120:123], v[56:59]
	v_mfma_f32_16x16x32_bf16 v[60:63], v[76:79], v[120:123], v[60:63]
	v_mfma_f32_16x16x32_bf16 v[56:59], v[0:3], v[100:103], v[32:35]
	v_mfma_f32_16x16x32_bf16 v[48:51], v[72:75], v[100:103], v[36:39]
	v_mfma_f32_16x16x32_bf16 v[44:47], v[0:3], v[108:111], v[40:43]
	v_mfma_f32_16x16x32_bf16 v[40:43], v[72:75], v[108:111], v[130:133]
	v_mfma_f32_16x16x32_bf16 v[36:39], v[0:3], v[116:119], v[150:153]
	v_mfma_f32_16x16x32_bf16 v[32:35], v[72:75], v[116:119], v[52:55]
	v_mfma_f32_16x16x32_bf16 v[8:11], v[0:3], v[124:127], v[8:11]
	v_mfma_f32_16x16x32_bf16 v[0:3], v[72:75], v[124:127], v[60:63]
	s_setprio 0
	s_setprio 1
	v_mfma_f32_16x16x32_bf16 v[4:7], v[88:91], v[96:99], v[4:7]
	v_mfma_f32_16x16x32_bf16 v[12:15], v[92:95], v[96:99], v[12:15]
	v_mfma_f32_16x16x32_bf16 v[16:19], v[88:91], v[104:107], v[16:19]
	v_mfma_f32_16x16x32_bf16 v[20:23], v[92:95], v[104:107], v[20:23]
	v_mfma_f32_16x16x32_bf16 v[72:75], v[88:91], v[112:115], v[24:27]
	v_mfma_f32_16x16x32_bf16 v[76:79], v[92:95], v[112:115], v[28:31]
	v_mfma_f32_16x16x32_bf16 v[64:67], v[88:91], v[120:123], v[64:67]
	v_mfma_f32_16x16x32_bf16 v[68:71], v[92:95], v[120:123], v[68:71]
	v_mfma_f32_16x16x32_bf16 v[60:63], v[80:83], v[100:103], v[4:7]
	v_mfma_f32_16x16x32_bf16 v[52:55], v[84:87], v[100:103], v[12:15]
	v_mfma_f32_16x16x32_bf16 v[28:31], v[80:83], v[108:111], v[16:19]
	v_mfma_f32_16x16x32_bf16 v[24:27], v[84:87], v[108:111], v[20:23]
	v_mfma_f32_16x16x32_bf16 v[20:23], v[80:83], v[116:119], v[72:75]
	v_mfma_f32_16x16x32_bf16 v[16:19], v[84:87], v[116:119], v[76:79]
	v_mfma_f32_16x16x32_bf16 v[12:15], v[80:83], v[124:127], v[64:67]
	v_mfma_f32_16x16x32_bf16 v[4:7], v[84:87], v[124:127], v[68:71]
	s_setprio 0
	v_cmp_gt_u32_e32 vcc, s85, v135
	s_barrier
	s_and_saveexec_b64 s[64:65], vcc
	s_cbranch_execz .LBB0_277
	s_barrier

.LBB0_355:
	s_lshl_b32 s14, s70, 3
	v_cvt_f32_u32_e32 v2, s14
	s_sub_i32 s17, 0, s14
	s_abs_i32 s16, s69
	s_ashr_i32 s15, s69, 31
	v_rcp_iflag_f32_e32 v2, v2
	v_and_b32_e32 v3, 15, v0
	v_lshlrev_b32_e32 v3, 6, v3
	v_lshlrev_b32_e32 v6, 2, v0
	v_mul_f32_e32 v2, 0x4f7ffffe, v2
	v_cvt_u32_f32_e32 v2, v2
	v_lshlrev_b32_e32 v4, 6, v183
	v_and_b32_e32 v6, 32, v6
	v_lshlrev_b32_e32 v1, 13, v1
	v_readfirstlane_b32 s24, v2
	s_mul_i32 s17, s17, s24
	s_mul_hi_u32 s17, s24, s17
	s_add_i32 s24, s24, s17
	s_mul_hi_u32 s17, s16, s24
	s_mul_i32 s24, s17, s14
	s_sub_i32 s16, s16, s24
	s_add_i32 s25, s17, 1
	s_sub_i32 s24, s16, s14
	s_cmp_ge_u32 s16, s14
	s_cselect_b32 s17, s25, s17
	s_cselect_b32 s16, s24, s16
	s_add_i32 s24, s17, 1
	s_cmp_ge_u32 s16, s14
	s_cselect_b32 s16, s24, s17
	s_xor_b32 s16, s16, s15
	s_sub_i32 s67, s16, s15
	s_mul_i32 s14, s67, s14
	s_sub_i32 s14, s69, s14
	s_lshl_b32 s15, s67, 3
	s_and_b32 s16, s14, 7
	s_ashr_i32 s66, s14, 3
	s_or_b32 s68, s16, s15
	s_lshl_b32 s16, s66, 8
	s_lshl_b32 s14, s68, 8
	s_and_b64 s[24:25], s[22:23], exec
	s_cselect_b32 s24, s45, 0x40000
	s_cselect_b32 s36, 32, 0x80
	s_cselect_b32 s25, s46, 0x1000
	s_or_b32 s26, s14, 0x80
	s_ashr_i32 s27, s26, 31
	s_and_b64 s[28:29], s[22:23], exec
	s_cselect_b32 s37, 6, 12
	s_lshl_b64 s[26:27], s[26:27], s37
	s_add_u32 s26, s18, s26
	s_addc_u32 s27, s19, s27
	s_and_b64 s[28:29], s[22:23], exec
	s_cselect_b32 s28, 18, 7
	s_ashr_i32 s17, s16, 31
	s_and_b64 s[30:31], s[22:23], exec
	s_cselect_b32 s69, 12, 6
	s_lshl_b64 s[30:31], s[16:17], s69
	s_add_u32 s17, s20, s30
	s_addc_u32 s29, s21, s31
	s_ashr_i32 s15, s14, 31
	s_lshl_b64 s[30:31], s[14:15], s37
	s_add_u32 s15, s18, s30
	s_addc_u32 s30, s19, s31
	s_or_b32 s18, s16, s36
	s_ashr_i32 s19, s18, 31
	s_lshl_b64 s[18:19], s[18:19], s69
	v_and_b32_e32 v2, 48, v0
	s_add_u32 s20, s20, s18
	v_lshlrev_b32_e32 v0, 6, v0
	v_or_b32_e32 v5, v3, v2
	s_addc_u32 s21, s21, s19
	v_and_b32_e32 v0, 0x3c0, v0
	v_and_b32_e32 v4, 0x3000, v4
	v_bitop3_b32 v3, v3, v6, v2 bitop3:0x36
	v_bitop3_b32 v7, v5, s56, v6 bitop3:0xde
	v_bitop3_b32 v8, v5, s57, v6 bitop3:0xde
	v_bitop3_b32 v9, v5, s58, v6 bitop3:0xde
	v_bitop3_b32 v5, v5, s59, v6 bitop3:0xde
	v_bitop3_b32 v2, v0, v6, v2 bitop3:0x36
	v_or_b32_e32 v6, 0x800, v1
	v_or_b32_e32 v10, 0x1000, v1
	v_or_b32_e32 v11, 0x1800, v1
	s_and_b64 s[18:19], s[22:23], exec
	v_mov_b32_e32 v0, 0
	v_mov_b32_e32 v129, v165
	s_cselect_b32 s22, 7, 18
	s_mov_b64 s[18:19], 1
	v_add_u32_e32 v134, v7, v4
	v_add_u32_e32 v187, v3, v1
	v_add_u32_e32 v186, v2, v6
	v_add_u32_e32 v185, v2, v10
	v_add_u32_e32 v184, v2, v11
	v_add_u32_e32 v133, 0xc000, v169
	v_add_u32_e32 v132, 0xe000, v169
	v_add_u32_e32 v131, v8, v4
	v_add_u32_e32 v182, 0x10000, v169
	v_add_u32_e32 v181, 0x12000, v169
	v_add_u32_e32 v180, 0x2000, v169
	v_add_u32_e32 v179, 0x14000, v169
	v_add_u32_e32 v178, 0x16000, v169
	v_add_u32_e32 v130, v9, v4
	v_add_u32_e32 v177, 0x4000, v169
	v_add_u32_e32 v176, 0x6000, v169
	v_add_u32_e32 v136, v5, v4
	v_add_u32_e32 v175, 0x18000, v169
	v_add_u32_e32 v174, 0x1a000, v169
	v_add_u32_e32 v173, 0x8000, v169
	v_add_u32_e32 v172, 0xa000, v169
	v_add_u32_e32 v171, 0x1c000, v169
	v_add_u32_e32 v170, 0x1e000, v169
	v_mov_b32_e32 v1, v0
	v_mov_b32_e32 v2, v0
	v_mov_b32_e32 v3, v0
	v_mov_b32_e32 v4, v0
	v_mov_b32_e32 v5, v0
	v_mov_b32_e32 v6, v0
	v_mov_b32_e32 v7, v0
	v_mov_b32_e32 v8, v0
	v_mov_b32_e32 v9, v0
	v_mov_b32_e32 v10, v0
	v_mov_b32_e32 v11, v0
	v_mov_b32_e32 v12, v0
	v_mov_b32_e32 v13, v0
	v_mov_b32_e32 v14, v0
	v_mov_b32_e32 v15, v0
	v_mov_b32_e32 v16, v0
	v_mov_b32_e32 v17, v0
	v_mov_b32_e32 v18, v0
	v_mov_b32_e32 v19, v0
	v_mov_b32_e32 v20, v0
	v_mov_b32_e32 v21, v0
	v_mov_b32_e32 v22, v0
	v_mov_b32_e32 v23, v0
	v_mov_b32_e32 v24, v0
	v_mov_b32_e32 v25, v0
	v_mov_b32_e32 v26, v0
	v_mov_b32_e32 v27, v0
	v_mov_b32_e32 v28, v0
	v_mov_b32_e32 v29, v0
	v_mov_b32_e32 v30, v0
	v_mov_b32_e32 v31, v0
	v_mov_b32_e32 v32, v0
	v_mov_b32_e32 v33, v0
	v_mov_b32_e32 v34, v0
	v_mov_b32_e32 v35, v0
	v_mov_b32_e32 v36, v0
	v_mov_b32_e32 v37, v0
	v_mov_b32_e32 v38, v0
	v_mov_b32_e32 v39, v0
	v_mov_b32_e32 v40, v0
	v_mov_b32_e32 v41, v0
	v_mov_b32_e32 v42, v0
	v_mov_b32_e32 v43, v0
	v_mov_b32_e32 v44, v0
	v_mov_b32_e32 v45, v0
	v_mov_b32_e32 v46, v0
	v_mov_b32_e32 v47, v0
	v_mov_b32_e32 v48, v0
	v_mov_b32_e32 v49, v0
	v_mov_b32_e32 v50, v0
	v_mov_b32_e32 v51, v0
	v_mov_b32_e32 v52, v0
	v_mov_b32_e32 v53, v0
	v_mov_b32_e32 v54, v0
	v_mov_b32_e32 v55, v0
	v_mov_b32_e32 v56, v0
	v_mov_b32_e32 v57, v0
	v_mov_b32_e32 v58, v0
	v_mov_b32_e32 v59, v0
	v_mov_b32_e32 v60, v0
	v_mov_b32_e32 v61, v0
	v_mov_b32_e32 v62, v0
	v_mov_b32_e32 v63, v0
	v_mov_b32_e32 v64, v0
	v_mov_b32_e32 v65, v0
	v_mov_b32_e32 v66, v0
	v_mov_b32_e32 v67, v0
	v_mov_b32_e32 v68, v0
	v_mov_b32_e32 v69, v0
	v_mov_b32_e32 v70, v0
	v_mov_b32_e32 v71, v0
	v_mov_b32_e32 v72, v0
	v_mov_b32_e32 v73, v0
	v_mov_b32_e32 v74, v0
	v_mov_b32_e32 v75, v0
	v_mov_b32_e32 v76, v0
	v_mov_b32_e32 v77, v0
	v_mov_b32_e32 v78, v0
	v_mov_b32_e32 v79, v0
	v_mov_b32_e32 v80, v0
	v_mov_b32_e32 v81, v0
	v_mov_b32_e32 v82, v0
	v_mov_b32_e32 v83, v0
	v_mov_b32_e32 v84, v0
	v_mov_b32_e32 v85, v0
	v_mov_b32_e32 v86, v0
	v_mov_b32_e32 v87, v0
	v_mov_b32_e32 v88, v0
	v_mov_b32_e32 v89, v0
	v_mov_b32_e32 v90, v0
	v_mov_b32_e32 v91, v0
	v_mov_b32_e32 v92, v0
	v_mov_b32_e32 v93, v0
	v_mov_b32_e32 v94, v0
	v_mov_b32_e32 v95, v0
	v_mov_b32_e32 v96, v0
	v_mov_b32_e32 v97, v0
	v_mov_b32_e32 v98, v0
	v_mov_b32_e32 v99, v0
	v_mov_b32_e32 v100, v0
	v_mov_b32_e32 v101, v0
	v_mov_b32_e32 v102, v0
	v_mov_b32_e32 v103, v0
	v_mov_b32_e32 v104, v0
	v_mov_b32_e32 v105, v0
	v_mov_b32_e32 v106, v0
	v_mov_b32_e32 v107, v0
	v_mov_b32_e32 v108, v0
	v_mov_b32_e32 v109, v0
	v_mov_b32_e32 v110, v0
	v_mov_b32_e32 v111, v0
	v_mov_b32_e32 v112, v0
	v_mov_b32_e32 v113, v0
	v_mov_b32_e32 v114, v0
	v_mov_b32_e32 v115, v0
	v_mov_b32_e32 v116, v0
	v_mov_b32_e32 v117, v0
	v_mov_b32_e32 v118, v0
	v_mov_b32_e32 v119, v0
	v_mov_b32_e32 v120, v0
	v_mov_b32_e32 v121, v0
	v_mov_b32_e32 v122, v0
	v_mov_b32_e32 v123, v0
	v_mov_b32_e32 v124, v0
	v_mov_b32_e32 v125, v0
	v_mov_b32_e32 v126, v0
	v_mov_b32_e32 v127, v0
	s_barrier
	v_readlane_b32 s98, v242, 1
	s_nop 3
	s_cmp_lt_u32 s98, 4
	s_cbranch_scc1 .Lprio_356
	s_setprio 1
.Lprio_356:
	s_lshl_b64 s[70:71], s[18:19], s28
	s_add_u32 s70, s26, s70
	s_addc_u32 s71, s27, s71
	v_lshl_add_u64 v[162:163], s[70:71], 0, v[164:165]
	v_readfirstlane_b32 s23, v133
	s_add_u32 s70, s70, s24
	s_mov_b32 m0, s23
	s_addc_u32 s71, s71, 0
	v_readfirstlane_b32 s23, v132
	global_load_lds_dwordx4 v[162:163], off
	v_lshl_add_u64 v[162:163], s[70:71], 0, v[164:165]
	s_mov_b32 m0, s23
	s_nop 0
	global_load_lds_dwordx4 v[162:163], off
.LBB0_356:
	ds_read_b128 v[138:141], v134
	ds_read_b128 v[142:145], v134 offset:1024
	ds_read_b128 v[146:149], v134 offset:2048
	ds_read_b128 v[150:153], v134 offset:3072
	ds_read_b128 v[154:157], v187
	ds_read_b128 v[158:161], v187 offset:1024
	ds_read_b128 v[188:191], v186
	ds_read_b128 v[192:195], v186 offset:1024
	ds_read_b128 v[196:199], v185
	ds_read_b128 v[200:203], v185 offset:1024
	ds_read_b128 v[204:207], v184
	ds_read_b128 v[208:211], v184 offset:1024
	s_waitcnt lgkmcnt(8)
	s_waitcnt vmcnt(10)
	s_barrier
	s_waitcnt lgkmcnt(0)
	s_waitcnt lgkmcnt(0)
	v_mfma_f32_16x16x32_bf16 v[124:127], v[138:141], v[154:157], v[124:127]
	v_mfma_f32_16x16x32_bf16 v[120:123], v[146:149], v[154:157], v[120:123]
	v_mfma_f32_16x16x32_bf16 v[116:119], v[138:141], v[188:191], v[116:119]
	v_mfma_f32_16x16x32_bf16 v[112:115], v[146:149], v[188:191], v[112:115]
	v_mfma_f32_16x16x32_bf16 v[108:111], v[138:141], v[196:199], v[108:111]
	v_mfma_f32_16x16x32_bf16 v[104:107], v[146:149], v[196:199], v[104:107]
	v_mfma_f32_16x16x32_bf16 v[100:103], v[138:141], v[204:207], v[100:103]
	v_mfma_f32_16x16x32_bf16 v[96:99], v[146:149], v[204:207], v[96:99]
	v_mfma_f32_16x16x32_bf16 v[124:127], v[142:145], v[158:161], v[124:127]
	v_mfma_f32_16x16x32_bf16 v[120:123], v[150:153], v[158:161], v[120:123]
	v_mfma_f32_16x16x32_bf16 v[116:119], v[142:145], v[192:195], v[116:119]
	v_mfma_f32_16x16x32_bf16 v[112:115], v[150:153], v[192:195], v[112:115]
	v_mfma_f32_16x16x32_bf16 v[108:111], v[142:145], v[200:203], v[108:111]
	v_mfma_f32_16x16x32_bf16 v[104:107], v[150:153], v[200:203], v[104:107]
	v_mfma_f32_16x16x32_bf16 v[100:103], v[142:145], v[208:211], v[100:103]
	v_mfma_f32_16x16x32_bf16 v[96:99], v[150:153], v[208:211], v[96:99]
	s_barrier
	s_add_u32 s70, s18, 1
	s_addc_u32 s71, s19, 0
	s_lshl_b64 s[72:73], s[70:71], s22
	s_add_u32 s74, s17, s72
	s_addc_u32 s75, s29, s73
	v_lshl_add_u64 v[162:163], s[74:75], 0, v[128:129]
	v_readfirstlane_b32 s23, v182
	s_add_u32 s74, s74, s25
	s_mov_b32 m0, s23
	s_addc_u32 s75, s75, 0
	v_readfirstlane_b32 s23, v181
	ds_read_b128 v[212:215], v131
	ds_read_b128 v[216:219], v131 offset:1024
	ds_read_b128 v[220:223], v131 offset:2048
	ds_read_b128 v[224:227], v131 offset:3072
	global_load_lds_dwordx4 v[162:163], off
	v_lshl_add_u64 v[162:163], s[74:75], 0, v[128:129]
	s_mov_b32 m0, s23
	s_nop 0
	global_load_lds_dwordx4 v[162:163], off
	s_lshl_b64 s[70:71], s[70:71], s28
	s_add_u32 s74, s15, s70
	s_addc_u32 s75, s30, s71
	v_lshl_add_u64 v[162:163], s[74:75], 0, v[164:165]
	v_readfirstlane_b32 s23, v169
	s_add_u32 s74, s74, s24
	s_mov_b32 m0, s23
	s_addc_u32 s75, s75, 0
	v_readfirstlane_b32 s23, v180
	global_load_lds_dwordx4 v[162:163], off
	v_lshl_add_u64 v[162:163], s[74:75], 0, v[164:165]
	s_mov_b32 m0, s23
	s_nop 0
	global_load_lds_dwordx4 v[162:163], off
	s_waitcnt vmcnt(12)
	s_barrier
	s_waitcnt lgkmcnt(0)
	s_waitcnt lgkmcnt(0)
	v_mfma_f32_16x16x32_bf16 v[92:95], v[212:215], v[154:157], v[92:95]
	v_mfma_f32_16x16x32_bf16 v[88:91], v[220:223], v[154:157], v[88:91]
	v_mfma_f32_16x16x32_bf16 v[84:87], v[212:215], v[188:191], v[84:87]
	v_mfma_f32_16x16x32_bf16 v[80:83], v[220:223], v[188:191], v[80:83]
	v_mfma_f32_16x16x32_bf16 v[76:79], v[212:215], v[196:199], v[76:79]
	v_mfma_f32_16x16x32_bf16 v[72:75], v[220:223], v[196:199], v[72:75]
	v_mfma_f32_16x16x32_bf16 v[68:71], v[212:215], v[204:207], v[68:71]
	v_mfma_f32_16x16x32_bf16 v[64:67], v[220:223], v[204:207], v[64:67]
	v_mfma_f32_16x16x32_bf16 v[92:95], v[216:219], v[158:161], v[92:95]
	v_mfma_f32_16x16x32_bf16 v[88:91], v[224:227], v[158:161], v[88:91]
	v_mfma_f32_16x16x32_bf16 v[84:87], v[216:219], v[192:195], v[84:87]
	v_mfma_f32_16x16x32_bf16 v[80:83], v[224:227], v[192:195], v[80:83]
	v_mfma_f32_16x16x32_bf16 v[76:79], v[216:219], v[200:203], v[76:79]
	v_mfma_f32_16x16x32_bf16 v[72:75], v[224:227], v[200:203], v[72:75]
	v_mfma_f32_16x16x32_bf16 v[68:71], v[216:219], v[208:211], v[68:71]
	v_mfma_f32_16x16x32_bf16 v[64:67], v[224:227], v[208:211], v[64:67]
	s_barrier
	ds_read_b128 v[154:157], v187 offset:16384
	ds_read_b128 v[158:161], v187 offset:17408
	ds_read_b128 v[188:191], v186 offset:16384
	ds_read_b128 v[192:195], v186 offset:17408
	ds_read_b128 v[196:199], v185 offset:16384
	ds_read_b128 v[200:203], v185 offset:17408
	ds_read_b128 v[204:207], v184 offset:16384
	ds_read_b128 v[208:211], v184 offset:17408
	s_add_u32 s72, s20, s72
	s_addc_u32 s73, s21, s73
	v_lshl_add_u64 v[162:163], s[72:73], 0, v[128:129]
	v_readfirstlane_b32 s23, v179
	s_add_u32 s72, s72, s25
	s_mov_b32 m0, s23
	s_addc_u32 s73, s73, 0
	v_readfirstlane_b32 s23, v178
	global_load_lds_dwordx4 v[162:163], off
	v_lshl_add_u64 v[162:163], s[72:73], 0, v[128:129]
	s_mov_b32 m0, s23
	s_nop 0
	global_load_lds_dwordx4 v[162:163], off
	s_barrier
	s_waitcnt lgkmcnt(0)
	s_waitcnt lgkmcnt(0)
	v_mfma_f32_16x16x32_bf16 v[60:63], v[138:141], v[154:157], v[60:63]
	v_mfma_f32_16x16x32_bf16 v[56:59], v[146:149], v[154:157], v[56:59]
	v_mfma_f32_16x16x32_bf16 v[52:55], v[138:141], v[188:191], v[52:55]
	v_mfma_f32_16x16x32_bf16 v[48:51], v[146:149], v[188:191], v[48:51]
	v_mfma_f32_16x16x32_bf16 v[44:47], v[138:141], v[196:199], v[44:47]
	v_mfma_f32_16x16x32_bf16 v[40:43], v[146:149], v[196:199], v[40:43]
	v_mfma_f32_16x16x32_bf16 v[36:39], v[138:141], v[204:207], v[36:39]
	v_mfma_f32_16x16x32_bf16 v[32:35], v[146:149], v[204:207], v[32:35]
	v_mfma_f32_16x16x32_bf16 v[60:63], v[142:145], v[158:161], v[60:63]
	v_mfma_f32_16x16x32_bf16 v[56:59], v[150:153], v[158:161], v[56:59]
	v_mfma_f32_16x16x32_bf16 v[52:55], v[142:145], v[192:195], v[52:55]
	v_mfma_f32_16x16x32_bf16 v[48:51], v[150:153], v[192:195], v[48:51]
	v_mfma_f32_16x16x32_bf16 v[44:47], v[142:145], v[200:203], v[44:47]
	v_mfma_f32_16x16x32_bf16 v[40:43], v[150:153], v[200:203], v[40:43]
	v_mfma_f32_16x16x32_bf16 v[36:39], v[142:145], v[208:211], v[36:39]
	v_mfma_f32_16x16x32_bf16 v[32:35], v[150:153], v[208:211], v[32:35]
	s_barrier
	s_add_u32 s70, s26, s70
	s_addc_u32 s71, s27, s71
	v_lshl_add_u64 v[162:163], s[70:71], 0, v[164:165]
	v_readfirstlane_b32 s23, v177
	s_add_u32 s70, s70, s24
	s_mov_b32 m0, s23
	s_addc_u32 s71, s71, 0
	v_readfirstlane_b32 s23, v176
	global_load_lds_dwordx4 v[162:163], off
	v_lshl_add_u64 v[162:163], s[70:71], 0, v[164:165]
	s_mov_b32 m0, s23
	s_nop 0
	global_load_lds_dwordx4 v[162:163], off
	s_waitcnt vmcnt(12)
	s_barrier
	v_mfma_f32_16x16x32_bf16 v[28:31], v[212:215], v[154:157], v[28:31]
	v_mfma_f32_16x16x32_bf16 v[24:27], v[220:223], v[154:157], v[24:27]
	v_mfma_f32_16x16x32_bf16 v[20:23], v[212:215], v[188:191], v[20:23]
	v_mfma_f32_16x16x32_bf16 v[16:19], v[220:223], v[188:191], v[16:19]
	v_mfma_f32_16x16x32_bf16 v[12:15], v[212:215], v[196:199], v[12:15]
	v_mfma_f32_16x16x32_bf16 v[8:11], v[220:223], v[196:199], v[8:11]
	v_mfma_f32_16x16x32_bf16 v[4:7], v[212:215], v[204:207], v[4:7]
	v_mfma_f32_16x16x32_bf16 v[0:3], v[220:223], v[204:207], v[0:3]
	v_mfma_f32_16x16x32_bf16 v[28:31], v[216:219], v[158:161], v[28:31]
	v_mfma_f32_16x16x32_bf16 v[24:27], v[224:227], v[158:161], v[24:27]
	v_mfma_f32_16x16x32_bf16 v[20:23], v[216:219], v[192:195], v[20:23]
	v_mfma_f32_16x16x32_bf16 v[16:19], v[224:227], v[192:195], v[16:19]
	v_mfma_f32_16x16x32_bf16 v[12:15], v[216:219], v[200:203], v[12:15]
	v_mfma_f32_16x16x32_bf16 v[8:11], v[224:227], v[200:203], v[8:11]
	v_mfma_f32_16x16x32_bf16 v[4:7], v[216:219], v[208:211], v[4:7]
	v_mfma_f32_16x16x32_bf16 v[0:3], v[224:227], v[208:211], v[0:3]
	s_barrier
	ds_read_b128 v[138:141], v130
	ds_read_b128 v[142:145], v130 offset:1024
	ds_read_b128 v[146:149], v130 offset:2048
	ds_read_b128 v[150:153], v130 offset:3072
	ds_read_b128 v[154:157], v187 offset:32768
	ds_read_b128 v[158:161], v187 offset:33792
	ds_read_b128 v[188:191], v186 offset:32768
	ds_read_b128 v[192:195], v186 offset:33792
	ds_read_b128 v[196:199], v185 offset:32768
	ds_read_b128 v[200:203], v185 offset:33792
	ds_read_b128 v[204:207], v184 offset:32768
	ds_read_b128 v[208:211], v184 offset:33792
	s_waitcnt lgkmcnt(8)
	s_waitcnt vmcnt(10)
	s_barrier
	s_waitcnt lgkmcnt(0)
	s_waitcnt lgkmcnt(0)
	v_mfma_f32_16x16x32_bf16 v[124:127], v[138:141], v[154:157], v[124:127]
	v_mfma_f32_16x16x32_bf16 v[120:123], v[146:149], v[154:157], v[120:123]
	v_mfma_f32_16x16x32_bf16 v[116:119], v[138:141], v[188:191], v[116:119]
	v_mfma_f32_16x16x32_bf16 v[112:115], v[146:149], v[188:191], v[112:115]
	v_mfma_f32_16x16x32_bf16 v[108:111], v[138:141], v[196:199], v[108:111]
	v_mfma_f32_16x16x32_bf16 v[104:107], v[146:149], v[196:199], v[104:107]
	v_mfma_f32_16x16x32_bf16 v[100:103], v[138:141], v[204:207], v[100:103]
	v_mfma_f32_16x16x32_bf16 v[96:99], v[146:149], v[204:207], v[96:99]
	v_mfma_f32_16x16x32_bf16 v[124:127], v[142:145], v[158:161], v[124:127]
	v_mfma_f32_16x16x32_bf16 v[120:123], v[150:153], v[158:161], v[120:123]
	v_mfma_f32_16x16x32_bf16 v[116:119], v[142:145], v[192:195], v[116:119]
	v_mfma_f32_16x16x32_bf16 v[112:115], v[150:153], v[192:195], v[112:115]
	v_mfma_f32_16x16x32_bf16 v[108:111], v[142:145], v[200:203], v[108:111]
	v_mfma_f32_16x16x32_bf16 v[104:107], v[150:153], v[200:203], v[104:107]
	v_mfma_f32_16x16x32_bf16 v[100:103], v[142:145], v[208:211], v[100:103]
	v_mfma_f32_16x16x32_bf16 v[96:99], v[150:153], v[208:211], v[96:99]
	s_barrier
	s_add_u32 s18, s18, 2
	s_addc_u32 s19, s19, 0
	s_lshl_b64 s[70:71], s[18:19], s22
	s_add_u32 s72, s17, s70
	s_addc_u32 s73, s29, s71
	v_lshl_add_u64 v[162:163], s[72:73], 0, v[128:129]
	v_readfirstlane_b32 s23, v175
	s_add_u32 s72, s72, s25
	s_mov_b32 m0, s23
	s_addc_u32 s73, s73, 0
	v_readfirstlane_b32 s23, v174
	ds_read_b128 v[212:215], v136
	ds_read_b128 v[216:219], v136 offset:1024
	ds_read_b128 v[220:223], v136 offset:2048
	ds_read_b128 v[224:227], v136 offset:3072
	global_load_lds_dwordx4 v[162:163], off
	v_lshl_add_u64 v[162:163], s[72:73], 0, v[128:129]
	s_mov_b32 m0, s23
	s_nop 0
	global_load_lds_dwordx4 v[162:163], off
	s_lshl_b64 s[72:73], s[18:19], s28
	s_add_u32 s72, s15, s72
	s_addc_u32 s73, s30, s73
	v_lshl_add_u64 v[162:163], s[72:73], 0, v[164:165]
	v_readfirstlane_b32 s23, v173
	s_add_u32 s72, s72, s24
	s_mov_b32 m0, s23
	s_addc_u32 s73, s73, 0
	v_readfirstlane_b32 s23, v172
	global_load_lds_dwordx4 v[162:163], off
	v_lshl_add_u64 v[162:163], s[72:73], 0, v[164:165]
	s_mov_b32 m0, s23
	s_nop 0
	global_load_lds_dwordx4 v[162:163], off
	s_waitcnt vmcnt(12)
	s_barrier
	s_waitcnt lgkmcnt(0)
	s_waitcnt lgkmcnt(0)
	v_mfma_f32_16x16x32_bf16 v[92:95], v[212:215], v[154:157], v[92:95]
	v_mfma_f32_16x16x32_bf16 v[88:91], v[220:223], v[154:157], v[88:91]
	v_mfma_f32_16x16x32_bf16 v[84:87], v[212:215], v[188:191], v[84:87]
	v_mfma_f32_16x16x32_bf16 v[80:83], v[220:223], v[188:191], v[80:83]
	v_mfma_f32_16x16x32_bf16 v[76:79], v[212:215], v[196:199], v[76:79]
	v_mfma_f32_16x16x32_bf16 v[72:75], v[220:223], v[196:199], v[72:75]
	v_mfma_f32_16x16x32_bf16 v[68:71], v[212:215], v[204:207], v[68:71]
	v_mfma_f32_16x16x32_bf16 v[64:67], v[220:223], v[204:207], v[64:67]
	v_mfma_f32_16x16x32_bf16 v[92:95], v[216:219], v[158:161], v[92:95]
	v_mfma_f32_16x16x32_bf16 v[88:91], v[224:227], v[158:161], v[88:91]
	v_mfma_f32_16x16x32_bf16 v[84:87], v[216:219], v[192:195], v[84:87]
	v_mfma_f32_16x16x32_bf16 v[80:83], v[224:227], v[192:195], v[80:83]
	v_mfma_f32_16x16x32_bf16 v[76:79], v[216:219], v[200:203], v[76:79]
	v_mfma_f32_16x16x32_bf16 v[72:75], v[224:227], v[200:203], v[72:75]
	v_mfma_f32_16x16x32_bf16 v[68:71], v[216:219], v[208:211], v[68:71]
	v_mfma_f32_16x16x32_bf16 v[64:67], v[224:227], v[208:211], v[64:67]
	s_barrier
	ds_read_b128 v[154:157], v187 offset:49152
	ds_read_b128 v[158:161], v187 offset:50176
	ds_read_b128 v[188:191], v186 offset:49152
	ds_read_b128 v[192:195], v186 offset:50176
	ds_read_b128 v[196:199], v185 offset:49152
	ds_read_b128 v[200:203], v185 offset:50176
	ds_read_b128 v[204:207], v184 offset:49152
	ds_read_b128 v[208:211], v184 offset:50176
	s_add_u32 s70, s20, s70
	s_addc_u32 s71, s21, s71
	v_lshl_add_u64 v[162:163], s[70:71], 0, v[128:129]
	v_readfirstlane_b32 s23, v171
	s_add_u32 s70, s70, s25
	s_mov_b32 m0, s23
	s_addc_u32 s71, s71, 0
	v_readfirstlane_b32 s23, v170
	global_load_lds_dwordx4 v[162:163], off
	v_lshl_add_u64 v[162:163], s[70:71], 0, v[128:129]
	s_mov_b32 m0, s23
	s_nop 0
	global_load_lds_dwordx4 v[162:163], off
	s_barrier
	s_waitcnt lgkmcnt(0)
	s_waitcnt lgkmcnt(0)
	v_mfma_f32_16x16x32_bf16 v[60:63], v[138:141], v[154:157], v[60:63]
	v_mfma_f32_16x16x32_bf16 v[56:59], v[146:149], v[154:157], v[56:59]
	v_mfma_f32_16x16x32_bf16 v[52:55], v[138:141], v[188:191], v[52:55]
	v_mfma_f32_16x16x32_bf16 v[48:51], v[146:149], v[188:191], v[48:51]
	v_mfma_f32_16x16x32_bf16 v[44:47], v[138:141], v[196:199], v[44:47]
	v_mfma_f32_16x16x32_bf16 v[40:43], v[146:149], v[196:199], v[40:43]
	v_mfma_f32_16x16x32_bf16 v[36:39], v[138:141], v[204:207], v[36:39]
	v_mfma_f32_16x16x32_bf16 v[32:35], v[146:149], v[204:207], v[32:35]
	v_mfma_f32_16x16x32_bf16 v[60:63], v[142:145], v[158:161], v[60:63]
	v_mfma_f32_16x16x32_bf16 v[56:59], v[150:153], v[158:161], v[56:59]
	v_mfma_f32_16x16x32_bf16 v[52:55], v[142:145], v[192:195], v[52:55]
	v_mfma_f32_16x16x32_bf16 v[48:51], v[150:153], v[192:195], v[48:51]
	v_mfma_f32_16x16x32_bf16 v[44:47], v[142:145], v[200:203], v[44:47]
	v_mfma_f32_16x16x32_bf16 v[40:43], v[150:153], v[200:203], v[40:43]
	v_mfma_f32_16x16x32_bf16 v[36:39], v[142:145], v[208:211], v[36:39]
	v_mfma_f32_16x16x32_bf16 v[32:35], v[150:153], v[208:211], v[32:35]
	s_barrier
	s_lshl_b64 s[70:71], s[18:19], s28
	s_add_u32 s70, s26, s70
	s_addc_u32 s71, s27, s71
	v_lshl_add_u64 v[162:163], s[70:71], 0, v[164:165]
	v_readfirstlane_b32 s23, v133
	s_add_u32 s70, s70, s24
	s_mov_b32 m0, s23
	s_addc_u32 s71, s71, 0
	v_readfirstlane_b32 s23, v132
	global_load_lds_dwordx4 v[162:163], off
	v_lshl_add_u64 v[162:163], s[70:71], 0, v[164:165]
	s_mov_b32 m0, s23
	s_nop 0
	global_load_lds_dwordx4 v[162:163], off
	s_waitcnt vmcnt(12)
	s_barrier
	v_mfma_f32_16x16x32_bf16 v[28:31], v[212:215], v[154:157], v[28:31]
	v_mfma_f32_16x16x32_bf16 v[24:27], v[220:223], v[154:157], v[24:27]
	v_mfma_f32_16x16x32_bf16 v[20:23], v[212:215], v[188:191], v[20:23]
	v_mfma_f32_16x16x32_bf16 v[16:19], v[220:223], v[188:191], v[16:19]
	v_mfma_f32_16x16x32_bf16 v[12:15], v[212:215], v[196:199], v[12:15]
	v_mfma_f32_16x16x32_bf16 v[8:11], v[220:223], v[196:199], v[8:11]
	v_mfma_f32_16x16x32_bf16 v[4:7], v[212:215], v[204:207], v[4:7]
	v_mfma_f32_16x16x32_bf16 v[0:3], v[220:223], v[204:207], v[0:3]
	v_mfma_f32_16x16x32_bf16 v[28:31], v[216:219], v[158:161], v[28:31]
	v_mfma_f32_16x16x32_bf16 v[24:27], v[224:227], v[158:161], v[24:27]
	v_mfma_f32_16x16x32_bf16 v[20:23], v[216:219], v[192:195], v[20:23]
	v_mfma_f32_16x16x32_bf16 v[16:19], v[224:227], v[192:195], v[16:19]
	v_mfma_f32_16x16x32_bf16 v[12:15], v[216:219], v[200:203], v[12:15]
	v_mfma_f32_16x16x32_bf16 v[8:11], v[224:227], v[200:203], v[8:11]
	v_mfma_f32_16x16x32_bf16 v[4:7], v[216:219], v[208:211], v[4:7]
	v_mfma_f32_16x16x32_bf16 v[0:3], v[224:227], v[208:211], v[0:3]
	s_add_i32 s23, s18, -3
	s_cmp_lt_u32 s23, 28
	s_barrier
	s_cbranch_scc1 .LBB0_356
	s_setprio 0
	s_lshl_b64 s[18:19], 31, s28
	s_add_u32 s18, s26, s18
	s_addc_u32 s19, s27, s19
	v_lshl_add_u64 v[128:129], s[18:19], 0, v[164:165]
	v_readfirstlane_b32 s15, v133
	s_add_u32 s18, s18, s24
	s_mov_b32 m0, s15
	s_addc_u32 s19, s19, 0
	v_readfirstlane_b32 s15, v132
	ds_read_b128 v[138:141], v134
	ds_read_b128 v[142:145], v134 offset:1024
	ds_read_b128 v[146:149], v134 offset:2048
	ds_read_b128 v[150:153], v134 offset:3072
	ds_read_b128 v[154:157], v187
	ds_read_b128 v[158:161], v187 offset:1024
	ds_read_b128 v[188:191], v186
	ds_read_b128 v[192:195], v186 offset:1024
	ds_read_b128 v[196:199], v185
	ds_read_b128 v[200:203], v185 offset:1024
	ds_read_b128 v[204:207], v184
	ds_read_b128 v[208:211], v184 offset:1024
	global_load_lds_dwordx4 v[128:129], off
	v_lshl_add_u64 v[128:129], s[18:19], 0, v[164:165]
	s_mov_b32 m0, s15
	s_nop 0
	global_load_lds_dwordx4 v[128:129], off
	s_waitcnt vmcnt(10)
	s_barrier
	s_waitcnt lgkmcnt(0)
	s_setprio 1
	s_waitcnt lgkmcnt(0)
	v_mfma_f32_16x16x32_bf16 v[124:127], v[138:141], v[154:157], v[124:127]
	v_mfma_f32_16x16x32_bf16 v[120:123], v[146:149], v[154:157], v[120:123]
	v_mfma_f32_16x16x32_bf16 v[116:119], v[138:141], v[188:191], v[116:119]
	v_mfma_f32_16x16x32_bf16 v[112:115], v[146:149], v[188:191], v[112:115]
	v_mfma_f32_16x16x32_bf16 v[108:111], v[138:141], v[196:199], v[108:111]
	v_mfma_f32_16x16x32_bf16 v[104:107], v[146:149], v[196:199], v[104:107]
	v_mfma_f32_16x16x32_bf16 v[100:103], v[138:141], v[204:207], v[100:103]
	v_mfma_f32_16x16x32_bf16 v[96:99], v[146:149], v[204:207], v[96:99]
	v_mfma_f32_16x16x32_bf16 v[124:127], v[142:145], v[158:161], v[124:127]
	v_mfma_f32_16x16x32_bf16 v[120:123], v[150:153], v[158:161], v[120:123]
	v_mfma_f32_16x16x32_bf16 v[116:119], v[142:145], v[192:195], v[116:119]
	v_mfma_f32_16x16x32_bf16 v[112:115], v[150:153], v[192:195], v[112:115]
	v_mfma_f32_16x16x32_bf16 v[108:111], v[142:145], v[200:203], v[108:111]
	v_mfma_f32_16x16x32_bf16 v[104:107], v[150:153], v[200:203], v[104:107]
	v_mfma_f32_16x16x32_bf16 v[100:103], v[142:145], v[208:211], v[100:103]
	v_mfma_f32_16x16x32_bf16 v[96:99], v[150:153], v[208:211], v[96:99]
	s_setprio 0
	s_barrier
	ds_read_b128 v[132:135], v131
	ds_read_b128 v[212:215], v131 offset:1024
	ds_read_b128 v[216:219], v131 offset:2048
	ds_read_b128 v[220:223], v131 offset:3072
	s_barrier
	s_waitcnt lgkmcnt(0)
	s_setprio 1
	s_waitcnt lgkmcnt(0)
	v_mfma_f32_16x16x32_bf16 v[92:95], v[132:135], v[154:157], v[92:95]
	v_mfma_f32_16x16x32_bf16 v[88:91], v[216:219], v[154:157], v[88:91]
	v_mfma_f32_16x16x32_bf16 v[84:87], v[132:135], v[188:191], v[84:87]
	v_mfma_f32_16x16x32_bf16 v[80:83], v[216:219], v[188:191], v[80:83]
	v_mfma_f32_16x16x32_bf16 v[76:79], v[132:135], v[196:199], v[76:79]
	v_mfma_f32_16x16x32_bf16 v[72:75], v[216:219], v[196:199], v[72:75]
	v_mfma_f32_16x16x32_bf16 v[68:71], v[132:135], v[204:207], v[68:71]
	v_mfma_f32_16x16x32_bf16 v[64:67], v[216:219], v[204:207], v[64:67]
	v_mfma_f32_16x16x32_bf16 v[154:157], v[212:215], v[158:161], v[92:95]
	v_mfma_f32_16x16x32_bf16 v[158:161], v[220:223], v[158:161], v[88:91]
	v_mfma_f32_16x16x32_bf16 v[188:191], v[212:215], v[192:195], v[84:87]
	v_mfma_f32_16x16x32_bf16 v[192:195], v[220:223], v[192:195], v[80:83]
	v_mfma_f32_16x16x32_bf16 v[196:199], v[212:215], v[200:203], v[76:79]
	v_mfma_f32_16x16x32_bf16 v[200:203], v[220:223], v[200:203], v[72:75]
	v_mfma_f32_16x16x32_bf16 v[204:207], v[212:215], v[208:211], v[68:71]
	v_mfma_f32_16x16x32_bf16 v[208:211], v[220:223], v[208:211], v[64:67]
	s_setprio 0
	s_barrier
	s_nop 0
	ds_read_b128 v[64:67], v187 offset:16384
	ds_read_b128 v[68:71], v187 offset:17408
	ds_read_b128 v[72:75], v186 offset:16384
	ds_read_b128 v[76:79], v186 offset:17408
	ds_read_b128 v[80:83], v185 offset:16384
	ds_read_b128 v[84:87], v185 offset:17408
	ds_read_b128 v[88:91], v184 offset:16384
	ds_read_b128 v[92:95], v184 offset:17408
	s_waitcnt vmcnt(4)
	s_barrier
	s_waitcnt lgkmcnt(0)
	s_setprio 1
	s_waitcnt lgkmcnt(0)
	v_mfma_f32_16x16x32_bf16 v[60:63], v[138:141], v[64:67], v[60:63]
	v_mfma_f32_16x16x32_bf16 v[56:59], v[146:149], v[64:67], v[56:59]
	v_mfma_f32_16x16x32_bf16 v[52:55], v[138:141], v[72:75], v[52:55]
	v_mfma_f32_16x16x32_bf16 v[48:51], v[146:149], v[72:75], v[48:51]
	v_mfma_f32_16x16x32_bf16 v[224:227], v[138:141], v[80:83], v[44:47]
	v_mfma_f32_16x16x32_bf16 v[228:231], v[146:149], v[80:83], v[40:43]
	v_mfma_f32_16x16x32_bf16 v[138:141], v[138:141], v[88:91], v[36:39]
	v_mfma_f32_16x16x32_bf16 v[146:149], v[146:149], v[88:91], v[32:35]
	v_mfma_f32_16x16x32_bf16 v[32:35], v[142:145], v[68:71], v[60:63]
	v_mfma_f32_16x16x32_bf16 v[36:39], v[150:153], v[68:71], v[56:59]
	v_mfma_f32_16x16x32_bf16 v[40:43], v[142:145], v[76:79], v[52:55]
	v_mfma_f32_16x16x32_bf16 v[44:47], v[150:153], v[76:79], v[48:51]
	v_mfma_f32_16x16x32_bf16 v[48:51], v[142:145], v[84:87], v[224:227]
	v_mfma_f32_16x16x32_bf16 v[52:55], v[150:153], v[84:87], v[228:231]
	v_mfma_f32_16x16x32_bf16 v[56:59], v[142:145], v[92:95], v[138:141]
	v_mfma_f32_16x16x32_bf16 v[60:63], v[150:153], v[92:95], v[146:149]
	s_setprio 0
	s_setprio 1
	v_mfma_f32_16x16x32_bf16 v[28:31], v[132:135], v[64:67], v[28:31]
	v_mfma_f32_16x16x32_bf16 v[24:27], v[216:219], v[64:67], v[24:27]
	v_mfma_f32_16x16x32_bf16 v[20:23], v[132:135], v[72:75], v[20:23]
	v_mfma_f32_16x16x32_bf16 v[16:19], v[216:219], v[72:75], v[16:19]
	v_mfma_f32_16x16x32_bf16 v[64:67], v[132:135], v[80:83], v[12:15]
	v_mfma_f32_16x16x32_bf16 v[8:11], v[216:219], v[80:83], v[8:11]
	v_mfma_f32_16x16x32_bf16 v[72:75], v[132:135], v[88:91], v[4:7]
	v_mfma_f32_16x16x32_bf16 v[0:3], v[216:219], v[88:91], v[0:3]
	v_mfma_f32_16x16x32_bf16 v[4:7], v[212:215], v[68:71], v[28:31]
	v_mfma_f32_16x16x32_bf16 v[12:15], v[220:223], v[68:71], v[24:27]
	v_mfma_f32_16x16x32_bf16 v[20:23], v[212:215], v[76:79], v[20:23]
	v_mfma_f32_16x16x32_bf16 v[28:31], v[220:223], v[76:79], v[16:19]
	v_mfma_f32_16x16x32_bf16 v[64:67], v[212:215], v[84:87], v[64:67]
	v_mfma_f32_16x16x32_bf16 v[68:71], v[220:223], v[84:87], v[8:11]
	v_mfma_f32_16x16x32_bf16 v[72:75], v[212:215], v[92:95], v[72:75]
	v_mfma_f32_16x16x32_bf16 v[76:79], v[220:223], v[92:95], v[0:3]
	s_setprio 0
	s_barrier
	ds_read_b128 v[8:11], v130
	ds_read_b128 v[0:3], v130 offset:1024
	ds_read_b128 v[16:19], v130 offset:2048
	ds_read_b128 v[80:83], v130 offset:3072
	ds_read_b128 v[138:141], v187 offset:32768
	ds_read_b128 v[212:215], v187 offset:33792
	ds_read_b128 v[216:219], v186 offset:32768
	ds_read_b128 v[220:223], v186 offset:33792
	ds_read_b128 v[224:227], v185 offset:32768
	ds_read_b128 v[228:231], v185 offset:33792
	ds_read_b128 v[232:235], v184 offset:32768
	ds_read_b128 v[236:239], v184 offset:33792
	s_waitcnt vmcnt(2)
	s_barrier
	s_waitcnt lgkmcnt(0)
	s_setprio 1
	s_waitcnt lgkmcnt(0)
	v_mfma_f32_16x16x32_bf16 v[24:27], v[8:11], v[138:141], v[124:127]
	v_mfma_f32_16x16x32_bf16 v[84:87], v[16:19], v[138:141], v[120:123]
	v_mfma_f32_16x16x32_bf16 v[88:91], v[8:11], v[216:219], v[116:119]
	v_mfma_f32_16x16x32_bf16 v[92:95], v[16:19], v[216:219], v[112:115]
	v_mfma_f32_16x16x32_bf16 v[108:111], v[8:11], v[224:227], v[108:111]
	v_mfma_f32_16x16x32_bf16 v[104:107], v[16:19], v[224:227], v[104:107]
	v_mfma_f32_16x16x32_bf16 v[100:103], v[8:11], v[232:235], v[100:103]
	v_mfma_f32_16x16x32_bf16 v[96:99], v[16:19], v[232:235], v[96:99]
	v_mfma_f32_16x16x32_bf16 v[148:151], v[0:3], v[212:215], v[24:27]
	v_mfma_f32_16x16x32_bf16 v[144:147], v[80:83], v[212:215], v[84:87]
	v_mfma_f32_16x16x32_bf16 v[132:135], v[0:3], v[220:223], v[88:91]
	v_mfma_f32_16x16x32_bf16 v[128:131], v[80:83], v[220:223], v[92:95]
	v_mfma_f32_16x16x32_bf16 v[116:119], v[0:3], v[228:231], v[108:111]
	v_mfma_f32_16x16x32_bf16 v[112:115], v[80:83], v[228:231], v[104:107]
	v_mfma_f32_16x16x32_bf16 v[100:103], v[0:3], v[236:239], v[100:103]
	v_mfma_f32_16x16x32_bf16 v[24:27], v[80:83], v[236:239], v[96:99]
	s_setprio 0
	s_barrier
	ds_read_b128 v[92:95], v136
	ds_read_b128 v[84:87], v136 offset:1024
	ds_read_b128 v[96:99], v136 offset:2048
	ds_read_b128 v[88:91], v136 offset:3072
	s_waitcnt vmcnt(0)
	s_barrier
	s_waitcnt lgkmcnt(0)
	s_setprio 1
	s_waitcnt lgkmcnt(0)
	v_mfma_f32_16x16x32_bf16 v[104:107], v[92:95], v[138:141], v[154:157]
	v_mfma_f32_16x16x32_bf16 v[108:111], v[96:99], v[138:141], v[158:161]
	v_mfma_f32_16x16x32_bf16 v[120:123], v[92:95], v[216:219], v[188:191]
	v_mfma_f32_16x16x32_bf16 v[124:127], v[96:99], v[216:219], v[192:195]
	v_mfma_f32_16x16x32_bf16 v[160:163], v[92:95], v[224:227], v[196:199]
	v_mfma_f32_16x16x32_bf16 v[188:191], v[96:99], v[224:227], v[200:203]
	v_mfma_f32_16x16x32_bf16 v[192:195], v[92:95], v[232:235], v[204:207]
	v_mfma_f32_16x16x32_bf16 v[196:199], v[96:99], v[232:235], v[208:211]
	v_mfma_f32_16x16x32_bf16 v[156:159], v[84:87], v[212:215], v[104:107]
	v_mfma_f32_16x16x32_bf16 v[152:155], v[88:91], v[212:215], v[108:111]
	v_mfma_f32_16x16x32_bf16 v[140:143], v[84:87], v[220:223], v[120:123]
	v_mfma_f32_16x16x32_bf16 v[136:139], v[88:91], v[220:223], v[124:127]
	v_mfma_f32_16x16x32_bf16 v[124:127], v[84:87], v[228:231], v[160:163]
	v_mfma_f32_16x16x32_bf16 v[120:123], v[88:91], v[228:231], v[188:191]
	v_mfma_f32_16x16x32_bf16 v[108:111], v[84:87], v[236:239], v[192:195]
	v_mfma_f32_16x16x32_bf16 v[104:107], v[88:91], v[236:239], v[196:199]
	s_setprio 0
	s_barrier
	v_mbcnt_lo_u32_b32 v164, -1, 0
	v_mbcnt_hi_u32_b32 v164, -1, v164
	s_cmp_lt_i32 s64, 3
	v_add_u32_e32 v160, s34, v164
	v_ashrrev_i32_e32 v192, 6, v160
	v_bfe_u32 v190, v160, 8, 1
	v_and_b32_e32 v191, 3, v192
	v_and_b32_e32 v188, 15, v164
	v_bfe_u32 v189, v160, 4, 2
	s_mov_b64 s[18:19], 0
	s_cbranch_scc1 .LBB0_362
	v_lshrrev_b32_e32 v160, 4, v160
	v_lshlrev_b32_e32 v162, 9, v189
	v_lshlrev_b32_e32 v163, 9, v160
	s_mov_b64 s[20:21], -1
	s_cmp_gt_i32 s64, 3
	v_lshlrev_b32_e32 v161, 4, v188
	v_and_b32_e32 v160, 0x400, v162
	v_and_b32_e32 v162, 0x200, v163
	s_cbranch_scc0 .LBB0_360
	s_lshl_b32 s15, s66, 20
	s_lshl_b32 s20, s66, 16
	s_and_b32 s15, s15, 0xff000000
	s_and_b32 s20, s20, 0xf0000
	s_lshl_b32 s17, s68, 21
	s_or_b32 s15, s20, s15
	v_lshlrev_b32_e32 v163, 14, v191
	s_add_i32 s15, s15, s17
	v_lshlrev_b32_e32 v166, 12, v190
	v_or3_b32 v163, s15, v161, v163
	v_or3_b32 v163, v163, v166, v162
	v_add_u32_e32 v166, v163, v160
	s_mov_b64 s[20:21], 0

.LBB0_464:
	v_bfe_i32 v5, v136, 27, 1
	v_lshlrev_b32_e32 v135, 4, v136
	v_lshrrev_b32_e32 v5, 22, v5
	v_add_u32_e32 v5, v135, v5
	v_and_b32_e32 v5, 0xfffffc00, v5
	v_sub_u32_e32 v5, v135, v5
	v_lshrrev_b32_e32 v6, 4, v5
	v_bitop3_b32 v5, v6, v5, 32 bitop3:0x6c
	v_ashrrev_i32_e32 v6, 31, v5
	v_lshrrev_b32_e32 v6, 26, v6
	v_add_u32_e32 v6, v5, v6
	v_ashrrev_i32_e32 v157, 6, v6
	v_and_b32_e32 v6, 0xc0, v6
	v_sub_u32_e32 v5, v5, v6
	v_ashrrev_i16_sdwa v5, v134, sext(v5) dst_sel:DWORD dst_unused:UNUSED_PAD src0_sel:DWORD src1_sel:BYTE_0
	v_and_b32_e32 v2, 15, v0
	v_and_b32_e32 v3, 48, v0
	v_bfe_i32 v158, v5, 0, 16
	v_and_b32_e32 v5, 32, v0
	v_lshlrev_b32_e32 v8, 2, v0
	v_lshlrev_b32_e32 v0, 6, v0
	s_movk_i32 s36, 0x3f0
	v_lshlrev_b32_e32 v2, 6, v2
	v_and_b32_e32 v8, 32, v8
	v_and_b32_e32 v0, 0x3c0, v0
	v_ashrrev_i32_e32 v4, 31, v136
	v_bitop3_b32 v5, v135, v5, s36 bitop3:0x6c
	v_or_b32_e32 v7, v2, v3
	v_bitop3_b32 v2, v2, v8, v3 bitop3:0x36
	v_bitop3_b32 v3, v0, v8, v3 bitop3:0x36
	v_lshlrev_b32_e32 v0, 11, v136
	v_lshrrev_b32_e32 v4, 26, v4
	v_and_or_b32 v0, v0, s78, v5
	v_lshlrev_b32_e32 v5, 3, v136
	s_bfe_u32 s66, s86, 0x30003
	v_add_u32_e32 v4, v136, v4
	s_mov_b32 s36, 0x14000
	v_and_b32_e32 v5, 0xfffffc00, v5
	s_lshl_b32 s24, s66, 14
	v_ashrrev_i32_e32 v156, 6, v4
	v_bitop3_b32 v10, v7, s36, v8 bitop3:0xde
	s_mov_b32 s36, 0x1c000
	v_add_u32_e32 v128, v0, v5
	v_bitop3_b32 v9, v7, s76, v8 bitop3:0xde
	v_bitop3_b32 v11, v7, s77, v8 bitop3:0xde
	v_bitop3_b32 v7, v7, s36, v8 bitop3:0xde
	v_lshl_add_u64 v[130:131], s[24:25], 0, v[128:129]
	v_lshlrev_b32_e32 v0, 15, v156
	s_lshl_b32 s24, s86, 17
	s_and_b32 s36, s86, 7
	v_and_b32_e32 v0, 0xffff0000, v0
	s_and_b32 s24, s24, 0x1800000
	s_lshl_b32 s36, s36, 20
	v_lshl_add_u32 v0, v157, 12, v0
	s_or_b32 s24, s24, s36
	v_lshlrev_b32_e32 v6, 6, v136
	v_lshlrev_b32_e32 v1, 13, v1
	v_and_or_b32 v0, v4, 64, v0
	s_add_u32 s68, s24, s90
	v_and_b32_e32 v6, 0x3000, v6
	v_or_b32_e32 v8, 0x800, v1
	v_or_b32_e32 v12, 0x1000, v1
	v_or_b32_e32 v13, 0x1800, v1
	v_lshl_add_u32 v128, v158, 1, v0
	s_addc_u32 s69, 0, 0
	v_mov_b32_e32 v0, 0
	v_lshl_add_u64 v[132:133], s[68:69], 0, v[128:129]
	s_mov_b32 s24, -2
	v_add_u32_e32 v162, v9, v6
	v_add_u32_e32 v153, v2, v1
	v_add_u32_e32 v152, v3, v8
	v_add_u32_e32 v151, v3, v12
	v_add_u32_e32 v150, v3, v13
	v_add_u32_e32 v161, 0xc000, v135
	v_add_u32_e32 v160, 0xe000, v135
	v_add_u32_e32 v159, v10, v6
	v_add_u32_e32 v149, 0x10000, v135
	v_add_u32_e32 v148, 0x12000, v135
	v_add_u32_e32 v147, 0x2000, v135
	v_add_u32_e32 v146, 0x14000, v135
	v_add_u32_e32 v145, 0x16000, v135
	v_add_u32_e32 v155, v11, v6
	v_add_u32_e32 v144, 0x4000, v135
	v_add_u32_e32 v143, 0x6000, v135
	v_add_u32_e32 v154, v7, v6
	v_add_u32_e32 v142, 0x18000, v135
	v_add_u32_e32 v141, 0x1a000, v135
	v_add_u32_e32 v140, 0x8000, v135
	v_add_u32_e32 v139, 0xa000, v135
	v_add_u32_e32 v138, 0x1c000, v135
	v_add_u32_e32 v137, 0x1e000, v135
	v_mov_b32_e32 v1, v0
	v_mov_b32_e32 v2, v0
	v_mov_b32_e32 v3, v0
	v_mov_b32_e32 v4, v0
	v_mov_b32_e32 v5, v0
	v_mov_b32_e32 v6, v0
	v_mov_b32_e32 v7, v0
	v_mov_b32_e32 v8, v0
	v_mov_b32_e32 v9, v0
	v_mov_b32_e32 v10, v0
	v_mov_b32_e32 v11, v0
	v_mov_b32_e32 v12, v0
	v_mov_b32_e32 v13, v0
	v_mov_b32_e32 v14, v0
	v_mov_b32_e32 v15, v0
	v_mov_b32_e32 v16, v0
	v_mov_b32_e32 v17, v0
	v_mov_b32_e32 v18, v0
	v_mov_b32_e32 v19, v0
	v_mov_b32_e32 v20, v0
	v_mov_b32_e32 v21, v0
	v_mov_b32_e32 v22, v0
	v_mov_b32_e32 v23, v0
	v_mov_b32_e32 v24, v0
	v_mov_b32_e32 v25, v0
	v_mov_b32_e32 v26, v0
	v_mov_b32_e32 v27, v0
	v_mov_b32_e32 v28, v0
	v_mov_b32_e32 v29, v0
	v_mov_b32_e32 v30, v0
	v_mov_b32_e32 v31, v0
	v_mov_b32_e32 v32, v0
	v_mov_b32_e32 v33, v0
	v_mov_b32_e32 v34, v0
	v_mov_b32_e32 v35, v0
	v_mov_b32_e32 v36, v0
	v_mov_b32_e32 v37, v0
	v_mov_b32_e32 v38, v0
	v_mov_b32_e32 v39, v0
	v_mov_b32_e32 v40, v0
	v_mov_b32_e32 v41, v0
	v_mov_b32_e32 v42, v0
	v_mov_b32_e32 v43, v0
	v_mov_b32_e32 v44, v0
	v_mov_b32_e32 v45, v0
	v_mov_b32_e32 v46, v0
	v_mov_b32_e32 v47, v0
	v_mov_b32_e32 v48, v0
	v_mov_b32_e32 v49, v0
	v_mov_b32_e32 v50, v0
	v_mov_b32_e32 v51, v0
	v_mov_b32_e32 v52, v0
	v_mov_b32_e32 v53, v0
	v_mov_b32_e32 v54, v0
	v_mov_b32_e32 v55, v0
	v_mov_b32_e32 v56, v0
	v_mov_b32_e32 v57, v0
	v_mov_b32_e32 v58, v0
	v_mov_b32_e32 v59, v0
	v_mov_b32_e32 v60, v0
	v_mov_b32_e32 v61, v0
	v_mov_b32_e32 v62, v0
	v_mov_b32_e32 v63, v0
	v_mov_b32_e32 v64, v0
	v_mov_b32_e32 v65, v0
	v_mov_b32_e32 v66, v0
	v_mov_b32_e32 v67, v0
	v_mov_b32_e32 v68, v0
	v_mov_b32_e32 v69, v0
	v_mov_b32_e32 v70, v0
	v_mov_b32_e32 v71, v0
	v_mov_b32_e32 v72, v0
	v_mov_b32_e32 v73, v0
	v_mov_b32_e32 v74, v0
	v_mov_b32_e32 v75, v0
	v_mov_b32_e32 v76, v0
	v_mov_b32_e32 v77, v0
	v_mov_b32_e32 v78, v0
	v_mov_b32_e32 v79, v0
	v_mov_b32_e32 v80, v0
	v_mov_b32_e32 v81, v0
	v_mov_b32_e32 v82, v0
	v_mov_b32_e32 v83, v0
	v_mov_b32_e32 v84, v0
	v_mov_b32_e32 v85, v0
	v_mov_b32_e32 v86, v0
	v_mov_b32_e32 v87, v0
	v_mov_b32_e32 v88, v0
	v_mov_b32_e32 v89, v0
	v_mov_b32_e32 v90, v0
	v_mov_b32_e32 v91, v0
	v_mov_b32_e32 v92, v0
	v_mov_b32_e32 v93, v0
	v_mov_b32_e32 v94, v0
	v_mov_b32_e32 v95, v0
	v_mov_b32_e32 v96, v0
	v_mov_b32_e32 v97, v0
	v_mov_b32_e32 v98, v0
	v_mov_b32_e32 v99, v0
	v_mov_b32_e32 v100, v0
	v_mov_b32_e32 v101, v0
	v_mov_b32_e32 v102, v0
	v_mov_b32_e32 v103, v0
	v_mov_b32_e32 v104, v0
	v_mov_b32_e32 v105, v0
	v_mov_b32_e32 v106, v0
	v_mov_b32_e32 v107, v0
	v_mov_b32_e32 v108, v0
	v_mov_b32_e32 v109, v0
	v_mov_b32_e32 v110, v0
	v_mov_b32_e32 v111, v0
	v_mov_b32_e32 v112, v0
	v_mov_b32_e32 v113, v0
	v_mov_b32_e32 v114, v0
	v_mov_b32_e32 v115, v0
	v_mov_b32_e32 v116, v0
	v_mov_b32_e32 v117, v0
	v_mov_b32_e32 v118, v0
	v_mov_b32_e32 v119, v0
	v_mov_b32_e32 v120, v0
	v_mov_b32_e32 v121, v0
	v_mov_b32_e32 v122, v0
	v_mov_b32_e32 v123, v0
	v_mov_b32_e32 v124, v0
	v_mov_b32_e32 v125, v0
	v_mov_b32_e32 v126, v0
	v_mov_b32_e32 v127, v0
	s_barrier
	v_readlane_b32 s98, v242, 1
	s_nop 3
	s_cmp_lt_u32 s98, 4
	s_cbranch_scc1 .Lprio_465
	s_setprio 1
.Lprio_465:
	v_lshl_add_u64 v[228:229], s[50:51], 0, v[132:133]
	s_mov_b64 s[68:69], 0xe080080
	v_readfirstlane_b32 s36, v161
	v_lshl_add_u64 v[166:167], v[228:229], 0, s[68:69]
	s_mov_b32 m0, s36
	s_mov_b64 s[68:69], 0xe0c0080
	v_readfirstlane_b32 s36, v160
	global_load_lds_dwordx4 v[166:167], off
	v_lshl_add_u64 v[166:167], v[228:229], 0, s[68:69]
	s_mov_b32 m0, s36
	s_nop 0
	global_load_lds_dwordx4 v[166:167], off
.LBB0_465:
	ds_read_b128 v[164:167], v162
	ds_read_b128 v[168:171], v162 offset:1024
	ds_read_b128 v[172:175], v162 offset:2048
	ds_read_b128 v[176:179], v162 offset:3072
	ds_read_b128 v[180:183], v153
	ds_read_b128 v[184:187], v153 offset:1024
	ds_read_b128 v[188:191], v152
	ds_read_b128 v[192:195], v152 offset:1024
	ds_read_b128 v[196:199], v151
	ds_read_b128 v[200:203], v151 offset:1024
	ds_read_b128 v[204:207], v150
	ds_read_b128 v[208:211], v150 offset:1024
	s_waitcnt lgkmcnt(8)
	s_waitcnt vmcnt(10)
	s_barrier
	s_waitcnt lgkmcnt(0)
	s_waitcnt lgkmcnt(0)
	v_mfma_f32_16x16x32_bf16 v[124:127], v[164:167], v[180:183], v[124:127]
	v_mfma_f32_16x16x32_bf16 v[120:123], v[172:175], v[180:183], v[120:123]
	v_mfma_f32_16x16x32_bf16 v[116:119], v[164:167], v[188:191], v[116:119]
	v_mfma_f32_16x16x32_bf16 v[112:115], v[172:175], v[188:191], v[112:115]
	v_mfma_f32_16x16x32_bf16 v[108:111], v[164:167], v[196:199], v[108:111]
	v_mfma_f32_16x16x32_bf16 v[104:107], v[172:175], v[196:199], v[104:107]
	v_mfma_f32_16x16x32_bf16 v[100:103], v[164:167], v[204:207], v[100:103]
	v_mfma_f32_16x16x32_bf16 v[96:99], v[172:175], v[204:207], v[96:99]
	v_mfma_f32_16x16x32_bf16 v[124:127], v[168:171], v[184:187], v[124:127]
	v_mfma_f32_16x16x32_bf16 v[120:123], v[176:179], v[184:187], v[120:123]
	v_mfma_f32_16x16x32_bf16 v[116:119], v[168:171], v[192:195], v[116:119]
	v_mfma_f32_16x16x32_bf16 v[112:115], v[176:179], v[192:195], v[112:115]
	v_mfma_f32_16x16x32_bf16 v[108:111], v[168:171], v[200:203], v[108:111]
	v_mfma_f32_16x16x32_bf16 v[104:107], v[176:179], v[200:203], v[104:107]
	v_mfma_f32_16x16x32_bf16 v[100:103], v[168:171], v[208:211], v[100:103]
	v_mfma_f32_16x16x32_bf16 v[96:99], v[176:179], v[208:211], v[96:99]
	s_barrier
	v_lshl_add_u64 v[230:231], s[50:51], 0, v[130:131]
	s_mov_b64 s[68:69], 0x3880000
	v_readfirstlane_b32 s36, v149
	v_lshl_add_u64 v[232:233], v[230:231], 0, s[68:69]
	s_mov_b32 m0, s36
	s_mov_b64 s[68:69], 0x3881000
	v_readfirstlane_b32 s36, v148
	ds_read_b128 v[212:215], v159
	ds_read_b128 v[216:219], v159 offset:1024
	ds_read_b128 v[220:223], v159 offset:2048
	ds_read_b128 v[224:227], v159 offset:3072
	global_load_lds_dwordx4 v[232:233], off
	v_lshl_add_u64 v[232:233], v[230:231], 0, s[68:69]
	s_mov_b32 m0, s36
	s_nop 0
	global_load_lds_dwordx4 v[232:233], off
	s_mov_b64 s[68:69], 0xe000100
	v_readfirstlane_b32 s36, v135
	v_lshl_add_u64 v[232:233], v[228:229], 0, s[68:69]
	s_mov_b32 m0, s36
	s_mov_b64 s[68:69], 0xe040100
	v_readfirstlane_b32 s36, v147
	global_load_lds_dwordx4 v[232:233], off
	v_lshl_add_u64 v[232:233], v[228:229], 0, s[68:69]
	s_mov_b32 m0, s36
	s_nop 0
	global_load_lds_dwordx4 v[232:233], off
	s_waitcnt vmcnt(12)
	s_barrier
	s_waitcnt lgkmcnt(0)
	s_waitcnt lgkmcnt(0)
	v_mfma_f32_16x16x32_bf16 v[92:95], v[212:215], v[180:183], v[92:95]
	v_mfma_f32_16x16x32_bf16 v[88:91], v[220:223], v[180:183], v[88:91]
	v_mfma_f32_16x16x32_bf16 v[84:87], v[212:215], v[188:191], v[84:87]
	v_mfma_f32_16x16x32_bf16 v[80:83], v[220:223], v[188:191], v[80:83]
	v_mfma_f32_16x16x32_bf16 v[76:79], v[212:215], v[196:199], v[76:79]
	v_mfma_f32_16x16x32_bf16 v[72:75], v[220:223], v[196:199], v[72:75]
	v_mfma_f32_16x16x32_bf16 v[68:71], v[212:215], v[204:207], v[68:71]
	v_mfma_f32_16x16x32_bf16 v[64:67], v[220:223], v[204:207], v[64:67]
	v_mfma_f32_16x16x32_bf16 v[92:95], v[216:219], v[184:187], v[92:95]
	v_mfma_f32_16x16x32_bf16 v[88:91], v[224:227], v[184:187], v[88:91]
	v_mfma_f32_16x16x32_bf16 v[84:87], v[216:219], v[192:195], v[84:87]
	v_mfma_f32_16x16x32_bf16 v[80:83], v[224:227], v[192:195], v[80:83]
	v_mfma_f32_16x16x32_bf16 v[76:79], v[216:219], v[200:203], v[76:79]
	v_mfma_f32_16x16x32_bf16 v[72:75], v[224:227], v[200:203], v[72:75]
	v_mfma_f32_16x16x32_bf16 v[68:71], v[216:219], v[208:211], v[68:71]
	v_mfma_f32_16x16x32_bf16 v[64:67], v[224:227], v[208:211], v[64:67]
	s_barrier
	ds_read_b128 v[180:183], v153 offset:16384
	ds_read_b128 v[184:187], v153 offset:17408
	ds_read_b128 v[188:191], v152 offset:16384
	ds_read_b128 v[192:195], v152 offset:17408
	ds_read_b128 v[196:199], v151 offset:16384
	ds_read_b128 v[200:203], v151 offset:17408
	ds_read_b128 v[204:207], v150 offset:16384
	ds_read_b128 v[208:211], v150 offset:17408
	s_mov_b64 s[68:69], 0x3882000
	v_readfirstlane_b32 s36, v146
	v_lshl_add_u64 v[232:233], v[230:231], 0, s[68:69]
	s_mov_b32 m0, s36
	s_mov_b64 s[68:69], 0x3883000
	v_readfirstlane_b32 s36, v145
	global_load_lds_dwordx4 v[232:233], off
	v_lshl_add_u64 v[232:233], v[230:231], 0, s[68:69]
	s_mov_b32 m0, s36
	s_nop 0
	global_load_lds_dwordx4 v[232:233], off
	s_barrier
	s_waitcnt lgkmcnt(0)
	s_waitcnt lgkmcnt(0)
	v_mfma_f32_16x16x32_bf16 v[60:63], v[164:167], v[180:183], v[60:63]
	v_mfma_f32_16x16x32_bf16 v[56:59], v[172:175], v[180:183], v[56:59]
	v_mfma_f32_16x16x32_bf16 v[52:55], v[164:167], v[188:191], v[52:55]
	v_mfma_f32_16x16x32_bf16 v[48:51], v[172:175], v[188:191], v[48:51]
	v_mfma_f32_16x16x32_bf16 v[44:47], v[164:167], v[196:199], v[44:47]
	v_mfma_f32_16x16x32_bf16 v[40:43], v[172:175], v[196:199], v[40:43]
	v_mfma_f32_16x16x32_bf16 v[36:39], v[164:167], v[204:207], v[36:39]
	v_mfma_f32_16x16x32_bf16 v[32:35], v[172:175], v[204:207], v[32:35]
	v_mfma_f32_16x16x32_bf16 v[60:63], v[168:171], v[184:187], v[60:63]
	v_mfma_f32_16x16x32_bf16 v[56:59], v[176:179], v[184:187], v[56:59]
	v_mfma_f32_16x16x32_bf16 v[52:55], v[168:171], v[192:195], v[52:55]
	v_mfma_f32_16x16x32_bf16 v[48:51], v[176:179], v[192:195], v[48:51]
	v_mfma_f32_16x16x32_bf16 v[44:47], v[168:171], v[200:203], v[44:47]
	v_mfma_f32_16x16x32_bf16 v[40:43], v[176:179], v[200:203], v[40:43]
	v_mfma_f32_16x16x32_bf16 v[36:39], v[168:171], v[208:211], v[36:39]
	v_mfma_f32_16x16x32_bf16 v[32:35], v[176:179], v[208:211], v[32:35]
	s_barrier
	v_readfirstlane_b32 s36, v144
	v_lshl_add_u64 v[166:167], v[228:229], 0, s[26:27]
	s_mov_b32 m0, s36
	v_readfirstlane_b32 s36, v143
	global_load_lds_dwordx4 v[166:167], off
	v_lshl_add_u64 v[166:167], v[228:229], 0, s[28:29]
	s_mov_b32 m0, s36
	s_nop 0
	global_load_lds_dwordx4 v[166:167], off
	s_waitcnt vmcnt(12)
	s_barrier
	v_mfma_f32_16x16x32_bf16 v[28:31], v[212:215], v[180:183], v[28:31]
	v_mfma_f32_16x16x32_bf16 v[24:27], v[220:223], v[180:183], v[24:27]
	v_mfma_f32_16x16x32_bf16 v[20:23], v[212:215], v[188:191], v[20:23]
	v_mfma_f32_16x16x32_bf16 v[16:19], v[220:223], v[188:191], v[16:19]
	v_mfma_f32_16x16x32_bf16 v[12:15], v[212:215], v[196:199], v[12:15]
	v_mfma_f32_16x16x32_bf16 v[8:11], v[220:223], v[196:199], v[8:11]
	v_mfma_f32_16x16x32_bf16 v[4:7], v[212:215], v[204:207], v[4:7]
	v_mfma_f32_16x16x32_bf16 v[0:3], v[220:223], v[204:207], v[0:3]
	v_mfma_f32_16x16x32_bf16 v[28:31], v[216:219], v[184:187], v[28:31]
	v_mfma_f32_16x16x32_bf16 v[24:27], v[224:227], v[184:187], v[24:27]
	v_mfma_f32_16x16x32_bf16 v[20:23], v[216:219], v[192:195], v[20:23]
	v_mfma_f32_16x16x32_bf16 v[16:19], v[224:227], v[192:195], v[16:19]
	v_mfma_f32_16x16x32_bf16 v[12:15], v[216:219], v[200:203], v[12:15]
	v_mfma_f32_16x16x32_bf16 v[8:11], v[224:227], v[200:203], v[8:11]
	v_mfma_f32_16x16x32_bf16 v[4:7], v[216:219], v[208:211], v[4:7]
	v_mfma_f32_16x16x32_bf16 v[0:3], v[224:227], v[208:211], v[0:3]
	s_barrier
	ds_read_b128 v[164:167], v155
	ds_read_b128 v[168:171], v155 offset:1024
	ds_read_b128 v[172:175], v155 offset:2048
	ds_read_b128 v[176:179], v155 offset:3072
	ds_read_b128 v[180:183], v153 offset:32768
	ds_read_b128 v[184:187], v153 offset:33792
	ds_read_b128 v[188:191], v152 offset:32768
	ds_read_b128 v[192:195], v152 offset:33792
	ds_read_b128 v[196:199], v151 offset:32768
	ds_read_b128 v[200:203], v151 offset:33792
	ds_read_b128 v[204:207], v150 offset:32768
	ds_read_b128 v[208:211], v150 offset:33792
	s_waitcnt lgkmcnt(8)
	s_waitcnt vmcnt(10)
	s_barrier
	s_waitcnt lgkmcnt(0)
	s_waitcnt lgkmcnt(0)
	v_mfma_f32_16x16x32_bf16 v[124:127], v[164:167], v[180:183], v[124:127]
	v_mfma_f32_16x16x32_bf16 v[120:123], v[172:175], v[180:183], v[120:123]
	v_mfma_f32_16x16x32_bf16 v[116:119], v[164:167], v[188:191], v[116:119]
	v_mfma_f32_16x16x32_bf16 v[112:115], v[172:175], v[188:191], v[112:115]
	v_mfma_f32_16x16x32_bf16 v[108:111], v[164:167], v[196:199], v[108:111]
	v_mfma_f32_16x16x32_bf16 v[104:107], v[172:175], v[196:199], v[104:107]
	v_mfma_f32_16x16x32_bf16 v[100:103], v[164:167], v[204:207], v[100:103]
	v_mfma_f32_16x16x32_bf16 v[96:99], v[172:175], v[204:207], v[96:99]
	v_mfma_f32_16x16x32_bf16 v[124:127], v[168:171], v[184:187], v[124:127]
	v_mfma_f32_16x16x32_bf16 v[120:123], v[176:179], v[184:187], v[120:123]
	v_mfma_f32_16x16x32_bf16 v[116:119], v[168:171], v[192:195], v[116:119]
	v_mfma_f32_16x16x32_bf16 v[112:115], v[176:179], v[192:195], v[112:115]
	v_mfma_f32_16x16x32_bf16 v[108:111], v[168:171], v[200:203], v[108:111]
	v_mfma_f32_16x16x32_bf16 v[104:107], v[176:179], v[200:203], v[104:107]
	v_mfma_f32_16x16x32_bf16 v[100:103], v[168:171], v[208:211], v[100:103]
	v_mfma_f32_16x16x32_bf16 v[96:99], v[176:179], v[208:211], v[96:99]
	s_barrier
	v_readfirstlane_b32 s36, v142
	v_lshl_add_u64 v[232:233], v[230:231], 0, s[30:31]
	s_mov_b32 m0, s36
	v_readfirstlane_b32 s36, v141
	ds_read_b128 v[212:215], v154
	ds_read_b128 v[216:219], v154 offset:1024
	ds_read_b128 v[220:223], v154 offset:2048
	ds_read_b128 v[224:227], v154 offset:3072
	global_load_lds_dwordx4 v[232:233], off
	v_lshl_add_u64 v[232:233], v[230:231], 0, s[34:35]
	s_mov_b32 m0, s36
	s_nop 0
	global_load_lds_dwordx4 v[232:233], off
	v_readfirstlane_b32 s36, v140
	v_lshl_add_u64 v[232:233], v[228:229], 0, s[44:45]
	s_mov_b32 m0, s36
	v_readfirstlane_b32 s36, v139
	global_load_lds_dwordx4 v[232:233], off
	v_lshl_add_u64 v[228:229], v[228:229], 0, s[46:47]
	s_mov_b32 m0, s36
	s_nop 0
	global_load_lds_dwordx4 v[228:229], off
	s_waitcnt vmcnt(12)
	s_barrier
	s_waitcnt lgkmcnt(0)
	s_waitcnt lgkmcnt(0)
	v_mfma_f32_16x16x32_bf16 v[92:95], v[212:215], v[180:183], v[92:95]
	v_mfma_f32_16x16x32_bf16 v[88:91], v[220:223], v[180:183], v[88:91]
	v_mfma_f32_16x16x32_bf16 v[84:87], v[212:215], v[188:191], v[84:87]
	v_mfma_f32_16x16x32_bf16 v[80:83], v[220:223], v[188:191], v[80:83]
	v_mfma_f32_16x16x32_bf16 v[76:79], v[212:215], v[196:199], v[76:79]
	v_mfma_f32_16x16x32_bf16 v[72:75], v[220:223], v[196:199], v[72:75]
	v_mfma_f32_16x16x32_bf16 v[68:71], v[212:215], v[204:207], v[68:71]
	v_mfma_f32_16x16x32_bf16 v[64:67], v[220:223], v[204:207], v[64:67]
	v_mfma_f32_16x16x32_bf16 v[92:95], v[216:219], v[184:187], v[92:95]
	v_mfma_f32_16x16x32_bf16 v[88:91], v[224:227], v[184:187], v[88:91]
	v_mfma_f32_16x16x32_bf16 v[84:87], v[216:219], v[192:195], v[84:87]
	v_mfma_f32_16x16x32_bf16 v[80:83], v[224:227], v[192:195], v[80:83]
	v_mfma_f32_16x16x32_bf16 v[76:79], v[216:219], v[200:203], v[76:79]
	v_mfma_f32_16x16x32_bf16 v[72:75], v[224:227], v[200:203], v[72:75]
	v_mfma_f32_16x16x32_bf16 v[68:71], v[216:219], v[208:211], v[68:71]
	v_mfma_f32_16x16x32_bf16 v[64:67], v[224:227], v[208:211], v[64:67]
	s_barrier
	ds_read_b128 v[180:183], v153 offset:49152
	ds_read_b128 v[184:187], v153 offset:50176
	ds_read_b128 v[188:191], v152 offset:49152
	ds_read_b128 v[192:195], v152 offset:50176
	ds_read_b128 v[196:199], v151 offset:49152
	ds_read_b128 v[200:203], v151 offset:50176
	ds_read_b128 v[204:207], v150 offset:49152
	ds_read_b128 v[208:211], v150 offset:50176
	v_readfirstlane_b32 s36, v138
	v_lshl_add_u64 v[232:233], v[230:231], 0, s[56:57]
	s_mov_b32 m0, s36
	v_readfirstlane_b32 s36, v137
	global_load_lds_dwordx4 v[232:233], off
	v_lshl_add_u64 v[232:233], v[230:231], 0, s[58:59]
	s_mov_b32 m0, s36
	s_nop 0
	global_load_lds_dwordx4 v[232:233], off
	s_barrier
	s_waitcnt lgkmcnt(0)
	s_waitcnt lgkmcnt(0)
	v_mfma_f32_16x16x32_bf16 v[60:63], v[164:167], v[180:183], v[60:63]
	v_mfma_f32_16x16x32_bf16 v[56:59], v[172:175], v[180:183], v[56:59]
	v_mfma_f32_16x16x32_bf16 v[52:55], v[164:167], v[188:191], v[52:55]
	v_mfma_f32_16x16x32_bf16 v[48:51], v[172:175], v[188:191], v[48:51]
	v_mfma_f32_16x16x32_bf16 v[44:47], v[164:167], v[196:199], v[44:47]
	v_mfma_f32_16x16x32_bf16 v[40:43], v[172:175], v[196:199], v[40:43]
	v_mfma_f32_16x16x32_bf16 v[36:39], v[164:167], v[204:207], v[36:39]
	v_mfma_f32_16x16x32_bf16 v[32:35], v[172:175], v[204:207], v[32:35]
	v_mfma_f32_16x16x32_bf16 v[60:63], v[168:171], v[184:187], v[60:63]
	v_mfma_f32_16x16x32_bf16 v[56:59], v[176:179], v[184:187], v[56:59]
	v_mfma_f32_16x16x32_bf16 v[52:55], v[168:171], v[192:195], v[52:55]
	v_mfma_f32_16x16x32_bf16 v[48:51], v[176:179], v[192:195], v[48:51]
	v_mfma_f32_16x16x32_bf16 v[44:47], v[168:171], v[200:203], v[44:47]
	v_mfma_f32_16x16x32_bf16 v[40:43], v[176:179], v[200:203], v[40:43]
	v_mfma_f32_16x16x32_bf16 v[36:39], v[168:171], v[208:211], v[36:39]
	v_mfma_f32_16x16x32_bf16 v[32:35], v[176:179], v[208:211], v[32:35]
	s_barrier
	v_lshl_add_u64 v[132:133], v[132:133], 0, s[60:61]
	v_lshl_add_u64 v[228:229], s[50:51], 0, v[132:133]
	s_mov_b64 s[68:69], 0xe080080
	v_readfirstlane_b32 s36, v161
	v_lshl_add_u64 v[166:167], v[228:229], 0, s[68:69]
	s_mov_b32 m0, s36
	s_mov_b64 s[68:69], 0xe0c0080
	v_readfirstlane_b32 s36, v160
	global_load_lds_dwordx4 v[166:167], off
	v_lshl_add_u64 v[166:167], v[228:229], 0, s[68:69]
	s_mov_b32 m0, s36
	s_nop 0
	global_load_lds_dwordx4 v[166:167], off
	s_waitcnt vmcnt(12)
	s_barrier
	v_mfma_f32_16x16x32_bf16 v[28:31], v[212:215], v[180:183], v[28:31]
	v_mfma_f32_16x16x32_bf16 v[24:27], v[220:223], v[180:183], v[24:27]
	v_mfma_f32_16x16x32_bf16 v[20:23], v[212:215], v[188:191], v[20:23]
	v_mfma_f32_16x16x32_bf16 v[16:19], v[220:223], v[188:191], v[16:19]
	v_mfma_f32_16x16x32_bf16 v[12:15], v[212:215], v[196:199], v[12:15]
	v_mfma_f32_16x16x32_bf16 v[8:11], v[220:223], v[196:199], v[8:11]
	v_mfma_f32_16x16x32_bf16 v[4:7], v[212:215], v[204:207], v[4:7]
	v_mfma_f32_16x16x32_bf16 v[0:3], v[220:223], v[204:207], v[0:3]
	v_mfma_f32_16x16x32_bf16 v[28:31], v[216:219], v[184:187], v[28:31]
	v_mfma_f32_16x16x32_bf16 v[24:27], v[224:227], v[184:187], v[24:27]
	v_mfma_f32_16x16x32_bf16 v[20:23], v[216:219], v[192:195], v[20:23]
	v_mfma_f32_16x16x32_bf16 v[16:19], v[224:227], v[192:195], v[16:19]
	v_mfma_f32_16x16x32_bf16 v[12:15], v[216:219], v[200:203], v[12:15]
	v_mfma_f32_16x16x32_bf16 v[8:11], v[224:227], v[200:203], v[8:11]
	v_mfma_f32_16x16x32_bf16 v[4:7], v[216:219], v[208:211], v[4:7]
	v_mfma_f32_16x16x32_bf16 v[0:3], v[224:227], v[208:211], v[0:3]
	s_add_i32 s24, s24, 2
	v_lshl_add_u64 v[130:131], v[130:131], 0, s[10:11]
	s_cmp_lt_u32 s24, 28
	s_barrier
	s_cbranch_scc1 .LBB0_465
	s_setprio 0
	s_lshl_b32 s24, s86, 5
	s_lshl_b32 s36, s86, 8
	s_and_b32 s24, s24, 0x1800
	s_and_b32 s36, s36, 0x700
	s_or_b32 s24, s36, s24
	v_lshlrev_b32_e32 v128, 3, v156
	v_lshlrev_b32_e32 v130, 5, v156
	v_and_b32_e32 v128, 0xffff0, v128
	v_and_b32_e32 v130, 32, v130
	s_lshl_b32 s36, s24, 12
	v_add_u32_e32 v130, v130, v158
	v_add_lshl_u32 v128, v157, v128, 12
	s_add_u32 s68, s70, s36
	v_lshl_add_u32 v128, v130, 1, v128
	s_addc_u32 s69, s71, 0
	v_lshl_add_u64 v[156:157], s[68:69], 0, v[128:129]
	v_readfirstlane_b32 s36, v161
	ds_read_b128 v[130:133], v162
	ds_read_b128 v[164:167], v162 offset:1024
	ds_read_b128 v[168:171], v162 offset:2048
	ds_read_b128 v[172:175], v162 offset:3072
	ds_read_b128 v[176:179], v153
	ds_read_b128 v[180:183], v153 offset:1024
	ds_read_b128 v[184:187], v152
	ds_read_b128 v[188:191], v152 offset:1024
	ds_read_b128 v[192:195], v151
	ds_read_b128 v[196:199], v151 offset:1024
	ds_read_b128 v[200:203], v150
	ds_read_b128 v[204:207], v150 offset:1024
	v_lshl_add_u64 v[162:163], v[156:157], 0, s[62:63]
	s_mov_b32 m0, s36
	v_readfirstlane_b32 s36, v160
	global_load_lds_dwordx4 v[162:163], off
	v_lshl_add_u64 v[156:157], v[156:157], 0, s[64:65]
	s_mov_b32 m0, s36
	s_nop 0
	global_load_lds_dwordx4 v[156:157], off
	s_waitcnt vmcnt(10)
	s_barrier
	s_waitcnt lgkmcnt(0)
	s_setprio 1
	s_waitcnt lgkmcnt(0)
	v_mfma_f32_16x16x32_bf16 v[124:127], v[130:133], v[176:179], v[124:127]
	v_mfma_f32_16x16x32_bf16 v[120:123], v[168:171], v[176:179], v[120:123]
	v_mfma_f32_16x16x32_bf16 v[116:119], v[130:133], v[184:187], v[116:119]
	v_mfma_f32_16x16x32_bf16 v[112:115], v[168:171], v[184:187], v[112:115]
	v_mfma_f32_16x16x32_bf16 v[108:111], v[130:133], v[192:195], v[108:111]
	v_mfma_f32_16x16x32_bf16 v[104:107], v[168:171], v[192:195], v[104:107]
	v_mfma_f32_16x16x32_bf16 v[100:103], v[130:133], v[200:203], v[100:103]
	v_mfma_f32_16x16x32_bf16 v[96:99], v[168:171], v[200:203], v[96:99]
	v_mfma_f32_16x16x32_bf16 v[124:127], v[164:167], v[180:183], v[124:127]
	v_mfma_f32_16x16x32_bf16 v[120:123], v[172:175], v[180:183], v[120:123]
	v_mfma_f32_16x16x32_bf16 v[116:119], v[164:167], v[188:191], v[116:119]
	v_mfma_f32_16x16x32_bf16 v[112:115], v[172:175], v[188:191], v[112:115]
	v_mfma_f32_16x16x32_bf16 v[108:111], v[164:167], v[196:199], v[108:111]
	v_mfma_f32_16x16x32_bf16 v[104:107], v[172:175], v[196:199], v[104:107]
	v_mfma_f32_16x16x32_bf16 v[100:103], v[164:167], v[204:207], v[100:103]
	v_mfma_f32_16x16x32_bf16 v[96:99], v[172:175], v[204:207], v[96:99]
	s_setprio 0
	s_barrier
	ds_read_b128 v[160:163], v159
	ds_read_b128 v[208:211], v159 offset:1024
	ds_read_b128 v[212:215], v159 offset:2048
	ds_read_b128 v[156:159], v159 offset:3072
	s_barrier
	s_waitcnt lgkmcnt(0)
	s_setprio 1
	s_waitcnt lgkmcnt(0)
	v_mfma_f32_16x16x32_bf16 v[92:95], v[160:163], v[176:179], v[92:95]
	v_mfma_f32_16x16x32_bf16 v[88:91], v[212:215], v[176:179], v[88:91]
	v_mfma_f32_16x16x32_bf16 v[84:87], v[160:163], v[184:187], v[84:87]
	v_mfma_f32_16x16x32_bf16 v[80:83], v[212:215], v[184:187], v[80:83]
	v_mfma_f32_16x16x32_bf16 v[76:79], v[160:163], v[192:195], v[76:79]
	v_mfma_f32_16x16x32_bf16 v[72:75], v[212:215], v[192:195], v[72:75]
	v_mfma_f32_16x16x32_bf16 v[68:71], v[160:163], v[200:203], v[68:71]
	v_mfma_f32_16x16x32_bf16 v[64:67], v[212:215], v[200:203], v[64:67]
	v_mfma_f32_16x16x32_bf16 v[176:179], v[208:211], v[180:183], v[92:95]
	v_mfma_f32_16x16x32_bf16 v[180:183], v[156:159], v[180:183], v[88:91]
	v_mfma_f32_16x16x32_bf16 v[184:187], v[208:211], v[188:191], v[84:87]
	v_mfma_f32_16x16x32_bf16 v[188:191], v[156:159], v[188:191], v[80:83]
	v_mfma_f32_16x16x32_bf16 v[192:195], v[208:211], v[196:199], v[76:79]
	v_mfma_f32_16x16x32_bf16 v[196:199], v[156:159], v[196:199], v[72:75]
	v_mfma_f32_16x16x32_bf16 v[200:203], v[208:211], v[204:207], v[68:71]
	v_mfma_f32_16x16x32_bf16 v[204:207], v[156:159], v[204:207], v[64:67]
	s_setprio 0
	s_barrier
	s_nop 0
	ds_read_b128 v[64:67], v153 offset:16384
	ds_read_b128 v[68:71], v153 offset:17408
	ds_read_b128 v[72:75], v152 offset:16384
	ds_read_b128 v[76:79], v152 offset:17408
	ds_read_b128 v[80:83], v151 offset:16384
	ds_read_b128 v[84:87], v151 offset:17408
	ds_read_b128 v[88:91], v150 offset:16384
	ds_read_b128 v[92:95], v150 offset:17408
	s_waitcnt vmcnt(4)
	s_barrier
	s_waitcnt lgkmcnt(0)
	s_setprio 1
	s_waitcnt lgkmcnt(0)
	v_mfma_f32_16x16x32_bf16 v[60:63], v[130:133], v[64:67], v[60:63]
	v_mfma_f32_16x16x32_bf16 v[56:59], v[168:171], v[64:67], v[56:59]
	v_mfma_f32_16x16x32_bf16 v[52:55], v[130:133], v[72:75], v[52:55]
	v_mfma_f32_16x16x32_bf16 v[48:51], v[168:171], v[72:75], v[48:51]
	v_mfma_f32_16x16x32_bf16 v[216:219], v[130:133], v[80:83], v[44:47]
	v_mfma_f32_16x16x32_bf16 v[220:223], v[168:171], v[80:83], v[40:43]
	v_mfma_f32_16x16x32_bf16 v[130:133], v[130:133], v[88:91], v[36:39]
	v_mfma_f32_16x16x32_bf16 v[168:171], v[168:171], v[88:91], v[32:35]
	v_mfma_f32_16x16x32_bf16 v[32:35], v[164:167], v[68:71], v[60:63]
	v_mfma_f32_16x16x32_bf16 v[36:39], v[172:175], v[68:71], v[56:59]
	v_mfma_f32_16x16x32_bf16 v[40:43], v[164:167], v[76:79], v[52:55]
	v_mfma_f32_16x16x32_bf16 v[44:47], v[172:175], v[76:79], v[48:51]
	v_mfma_f32_16x16x32_bf16 v[48:51], v[164:167], v[84:87], v[216:219]
	v_mfma_f32_16x16x32_bf16 v[52:55], v[172:175], v[84:87], v[220:223]
	v_mfma_f32_16x16x32_bf16 v[56:59], v[164:167], v[92:95], v[130:133]
	v_mfma_f32_16x16x32_bf16 v[60:63], v[172:175], v[92:95], v[168:171]
	s_setprio 0
	s_setprio 1
	v_mfma_f32_16x16x32_bf16 v[28:31], v[160:163], v[64:67], v[28:31]
	v_mfma_f32_16x16x32_bf16 v[24:27], v[212:215], v[64:67], v[24:27]
	v_mfma_f32_16x16x32_bf16 v[20:23], v[160:163], v[72:75], v[20:23]
	v_mfma_f32_16x16x32_bf16 v[64:67], v[212:215], v[72:75], v[16:19]
	v_mfma_f32_16x16x32_bf16 v[72:75], v[160:163], v[80:83], v[12:15]
	v_mfma_f32_16x16x32_bf16 v[8:11], v[212:215], v[80:83], v[8:11]
	v_mfma_f32_16x16x32_bf16 v[80:83], v[160:163], v[88:91], v[4:7]
	v_mfma_f32_16x16x32_bf16 v[0:3], v[212:215], v[88:91], v[0:3]
	v_mfma_f32_16x16x32_bf16 v[4:7], v[208:211], v[68:71], v[28:31]
	v_mfma_f32_16x16x32_bf16 v[12:15], v[156:159], v[68:71], v[24:27]
	v_mfma_f32_16x16x32_bf16 v[16:19], v[208:211], v[76:79], v[20:23]
	v_mfma_f32_16x16x32_bf16 v[20:23], v[156:159], v[76:79], v[64:67]
	v_mfma_f32_16x16x32_bf16 v[24:27], v[208:211], v[84:87], v[72:75]
	v_mfma_f32_16x16x32_bf16 v[28:31], v[156:159], v[84:87], v[8:11]
	v_mfma_f32_16x16x32_bf16 v[64:67], v[208:211], v[92:95], v[80:83]
	v_mfma_f32_16x16x32_bf16 v[68:71], v[156:159], v[92:95], v[0:3]
	s_setprio 0
	s_barrier
	ds_read_b128 v[8:11], v155
	ds_read_b128 v[0:3], v155 offset:1024
	ds_read_b128 v[76:79], v155 offset:2048
	ds_read_b128 v[72:75], v155 offset:3072
	ds_read_b128 v[130:133], v153 offset:32768
	ds_read_b128 v[156:159], v153 offset:33792
	ds_read_b128 v[160:163], v152 offset:32768
	ds_read_b128 v[164:167], v152 offset:33792
	ds_read_b128 v[168:171], v151 offset:32768
	ds_read_b128 v[172:175], v151 offset:33792
	ds_read_b128 v[208:211], v150 offset:32768
	ds_read_b128 v[212:215], v150 offset:33792
	s_waitcnt vmcnt(2)
	s_barrier
	s_waitcnt lgkmcnt(0)
	s_setprio 1
	s_waitcnt lgkmcnt(0)
	v_mfma_f32_16x16x32_bf16 v[80:83], v[8:11], v[130:133], v[124:127]
	v_mfma_f32_16x16x32_bf16 v[84:87], v[76:79], v[130:133], v[120:123]
	v_mfma_f32_16x16x32_bf16 v[88:91], v[8:11], v[160:163], v[116:119]
	v_mfma_f32_16x16x32_bf16 v[92:95], v[76:79], v[160:163], v[112:115]
	v_mfma_f32_16x16x32_bf16 v[108:111], v[8:11], v[168:171], v[108:111]
	v_mfma_f32_16x16x32_bf16 v[104:107], v[76:79], v[168:171], v[104:107]
	v_mfma_f32_16x16x32_bf16 v[100:103], v[8:11], v[208:211], v[100:103]
	v_mfma_f32_16x16x32_bf16 v[96:99], v[76:79], v[208:211], v[96:99]
	v_mfma_f32_16x16x32_bf16 v[112:115], v[0:3], v[156:159], v[80:83]
	v_mfma_f32_16x16x32_bf16 v[116:119], v[72:75], v[156:159], v[84:87]
	v_mfma_f32_16x16x32_bf16 v[120:123], v[0:3], v[164:167], v[88:91]
	v_mfma_f32_16x16x32_bf16 v[124:127], v[72:75], v[164:167], v[92:95]
	v_mfma_f32_16x16x32_bf16 v[108:111], v[0:3], v[172:175], v[108:111]
	v_mfma_f32_16x16x32_bf16 v[104:107], v[72:75], v[172:175], v[104:107]
	v_mfma_f32_16x16x32_bf16 v[100:103], v[0:3], v[212:215], v[100:103]
	v_mfma_f32_16x16x32_bf16 v[96:99], v[72:75], v[212:215], v[96:99]
	s_setprio 0
	s_barrier
	ds_read_b128 v[88:91], v154
	ds_read_b128 v[80:83], v154 offset:1024
	ds_read_b128 v[92:95], v154 offset:2048
	ds_read_b128 v[84:87], v154 offset:3072
	s_waitcnt vmcnt(0)
	s_barrier
	s_waitcnt lgkmcnt(0)
	s_setprio 1
	s_waitcnt lgkmcnt(0)
	v_mfma_f32_16x16x32_bf16 v[176:179], v[88:91], v[130:133], v[176:179]
	v_mfma_f32_16x16x32_bf16 v[130:133], v[92:95], v[130:133], v[180:183]
	v_mfma_f32_16x16x32_bf16 v[180:183], v[88:91], v[160:163], v[184:187]
	v_mfma_f32_16x16x32_bf16 v[160:163], v[92:95], v[160:163], v[188:191]
	v_mfma_f32_16x16x32_bf16 v[184:187], v[88:91], v[168:171], v[192:195]
	v_mfma_f32_16x16x32_bf16 v[168:171], v[92:95], v[168:171], v[196:199]
	v_mfma_f32_16x16x32_bf16 v[188:191], v[88:91], v[208:211], v[200:203]
	v_mfma_f32_16x16x32_bf16 v[192:195], v[92:95], v[208:211], v[204:207]
	v_mfma_f32_16x16x32_bf16 v[176:179], v[80:83], v[156:159], v[176:179]
	v_mfma_f32_16x16x32_bf16 v[130:133], v[84:87], v[156:159], v[130:133]
	v_mfma_f32_16x16x32_bf16 v[154:157], v[80:83], v[164:167], v[180:183]
	v_mfma_f32_16x16x32_bf16 v[158:161], v[84:87], v[164:167], v[160:163]
	v_mfma_f32_16x16x32_bf16 v[162:165], v[80:83], v[172:175], v[184:187]
	v_mfma_f32_16x16x32_bf16 v[166:169], v[84:87], v[172:175], v[168:171]
	v_mfma_f32_16x16x32_bf16 v[170:173], v[80:83], v[212:215], v[188:191]
	v_mfma_f32_16x16x32_bf16 v[180:183], v[84:87], v[212:215], v[192:195]
	s_setprio 0
	s_barrier
	v_mbcnt_lo_u32_b32 v128, -1, 0
	v_mbcnt_hi_u32_b32 v128, -1, v128
	v_cvt_pk_bf16_f32 v112, v112, v113
	v_cvt_pk_bf16_f32 v113, v114, v115
	v_cvt_pk_bf16_f32 v114, v116, v117
	v_cvt_pk_bf16_f32 v115, v118, v119
	s_lshl_b32 s68, s66, 9
	v_add_u32_e32 v174, s74, v128
	v_ashrrev_i32_e32 v175, 6, v174
	v_and_b32_e32 v184, 15, v128
	v_and_b32_e32 v185, 48, v128
	v_mul_lo_u32 v186, v175, s79
	v_bfe_u32 v187, v128, 3, 3
	v_lshlrev_b32_e32 v128, 4, v128
	v_add_u32_e32 v186, 0x20000, v186
	v_lshrrev_b32_e32 v174, 2, v174
	v_and_b32_e32 v128, 0x70, v128
	v_mul_u32_u24_e32 v184, 0x90, v184
	v_and_b32_e32 v174, 64, v174
	v_add3_u32 v184, v186, v184, v185
	v_or_b32_e32 v185, v186, v128
	v_or3_b32 v174, s24, v174, v187
	v_mad_u32_u24 v185, v187, s80, v185
	ds_write_b128 v184, v[112:115]
	v_cvt_pk_bf16_f32 v112, v176, v177
	v_cvt_pk_bf16_f32 v113, v178, v179
	v_cvt_pk_bf16_f32 v114, v130, v131
	v_cvt_pk_bf16_f32 v115, v132, v133
	ds_write_b128 v184, v[112:115] offset:64
	v_lshlrev_b32_e32 v175, 7, v175
	ds_read_b128 v[112:115], v185
	v_lshlrev_b32_e32 v116, 12, v174
	v_and_or_b32 v116, v175, s81, v116
	v_or3_b32 v128, v116, s68, v128
	ds_read_b128 v[116:119], v185 offset:1152
	v_lshl_add_u64 v[130:131], s[0:1], 0, v[128:129]
	s_mov_b32 s36, 0x8000
	s_waitcnt lgkmcnt(0)
	global_store_dwordx4 v128, v[112:115], s[0:1]
	v_cvt_pk_bf16_f32 v108, v108, v109
	v_cvt_pk_bf16_f32 v109, v110, v111
	v_cvt_pk_bf16_f32 v110, v104, v105
	v_cvt_pk_bf16_f32 v111, v106, v107
	v_cvt_pk_bf16_f32 v104, v162, v163
	s_nop 1
	v_add_co_u32_e32 v112, vcc, s36, v130
	v_cvt_pk_bf16_f32 v114, v124, v125
	v_cvt_pk_bf16_f32 v115, v126, v127
	v_cvt_pk_bf16_f32 v105, v164, v165
	v_cvt_pk_bf16_f32 v106, v166, v167
	s_nop 1
	v_addc_co_u32_e32 v113, vcc, 0, v131, vcc
	global_store_dwordx4 v[112:113], v[116:119], off
	v_cvt_pk_bf16_f32 v112, v120, v121
	v_cvt_pk_bf16_f32 v113, v122, v123
	ds_write_b128 v184, v[112:115]
	v_cvt_pk_bf16_f32 v112, v154, v155
	v_cvt_pk_bf16_f32 v113, v156, v157
	v_cvt_pk_bf16_f32 v114, v158, v159
	v_cvt_pk_bf16_f32 v115, v160, v161
	ds_write_b128 v184, v[112:115] offset:64
	ds_read_b128 v[112:115], v185
	ds_read_b128 v[116:119], v185 offset:1152
	v_add_co_u32_e32 v120, vcc, s76, v130
	ds_write_b128 v184, v[108:111]
	v_cvt_pk_bf16_f32 v107, v168, v169
	ds_write_b128 v184, v[104:107] offset:64
	v_addc_co_u32_e32 v121, vcc, 0, v131, vcc
	ds_read_b128 v[104:107], v185
	ds_read_b128 v[108:111], v185 offset:1152
	s_waitcnt lgkmcnt(0)
	global_store_dwordx4 v[120:121], v[112:115], off
	v_cvt_pk_bf16_f32 v100, v100, v101
	v_cvt_pk_bf16_f32 v101, v102, v103
	v_cvt_pk_bf16_f32 v102, v96, v97
	v_cvt_pk_bf16_f32 v103, v98, v99
	ds_write_b128 v184, v[100:103]
	s_nop 0
	v_add_co_u32_e32 v112, vcc, s77, v130
	v_cvt_pk_bf16_f32 v96, v170, v171
	v_cvt_pk_bf16_f32 v97, v172, v173
	v_cvt_pk_bf16_f32 v98, v180, v181
	v_cvt_pk_bf16_f32 v99, v182, v183
	s_nop 1
	v_addc_co_u32_e32 v113, vcc, 0, v131, vcc
	global_store_dwordx4 v[112:113], v[116:119], off
	v_add_co_u32_e32 v112, vcc, s78, v130
	ds_write_b128 v184, v[96:99] offset:64
	s_nop 0
	v_addc_co_u32_e32 v113, vcc, 0, v131, vcc
	ds_read_b128 v[96:99], v185
	ds_read_b128 v[100:103], v185 offset:1152
	global_store_dwordx4 v[112:113], v[104:107], off
	s_nop 1
	v_add_co_u32_e32 v104, vcc, s82, v130
	s_nop 1
	v_addc_co_u32_e32 v105, vcc, 0, v131, vcc
	global_store_dwordx4 v[104:105], v[108:111], off
	v_add_co_u32_e32 v104, vcc, s83, v130
	s_nop 1
	v_addc_co_u32_e32 v105, vcc, 0, v131, vcc
	s_waitcnt lgkmcnt(0)
	global_store_dwordx4 v[104:105], v[96:99], off
	s_nop 1
	v_add_co_u32_e32 v96, vcc, s91, v130
	s_nop 1
	v_addc_co_u32_e32 v97, vcc, 0, v131, vcc
	global_store_dwordx4 v[96:97], v[100:103], off
	ds_read_b128 v[96:99], v153 offset:49152
	ds_read_b128 v[100:103], v153 offset:50176
	ds_read_b128 v[104:107], v152 offset:49152
	ds_read_b128 v[108:111], v152 offset:50176
	ds_read_b128 v[112:115], v151 offset:49152
	ds_read_b128 v[116:119], v151 offset:50176
	ds_read_b128 v[120:123], v150 offset:49152
	ds_read_b128 v[124:127], v150 offset:50176
	s_barrier
	s_waitcnt lgkmcnt(0)
	s_setprio 1
	s_waitcnt lgkmcnt(0)
	v_mfma_f32_16x16x32_bf16 v[32:35], v[8:11], v[96:99], v[32:35]
	v_mfma_f32_16x16x32_bf16 v[36:39], v[76:79], v[96:99], v[36:39]
	v_mfma_f32_16x16x32_bf16 v[40:43], v[8:11], v[104:107], v[40:43]
	v_mfma_f32_16x16x32_bf16 v[130:133], v[76:79], v[104:107], v[44:47]
	v_mfma_f32_16x16x32_bf16 v[150:153], v[8:11], v[112:115], v[48:51]
	v_mfma_f32_16x16x32_bf16 v[52:55], v[76:79], v[112:115], v[52:55]
	v_mfma_f32_16x16x32_bf16 v[8:11], v[8:11], v[120:123], v[56:59]
	v_mfma_f32_16x16x32_bf16 v[60:63], v[76:79], v[120:123], v[60:63]
	v_mfma_f32_16x16x32_bf16 v[56:59], v[0:3], v[100:103], v[32:35]
	v_mfma_f32_16x16x32_bf16 v[48:51], v[72:75], v[100:103], v[36:39]
	v_mfma_f32_16x16x32_bf16 v[44:47], v[0:3], v[108:111], v[40:43]
	v_mfma_f32_16x16x32_bf16 v[40:43], v[72:75], v[108:111], v[130:133]
	v_mfma_f32_16x16x32_bf16 v[36:39], v[0:3], v[116:119], v[150:153]
	v_mfma_f32_16x16x32_bf16 v[32:35], v[72:75], v[116:119], v[52:55]
	v_mfma_f32_16x16x32_bf16 v[8:11], v[0:3], v[124:127], v[8:11]
	v_mfma_f32_16x16x32_bf16 v[0:3], v[72:75], v[124:127], v[60:63]
	s_setprio 0
	s_setprio 1
	v_mfma_f32_16x16x32_bf16 v[4:7], v[88:91], v[96:99], v[4:7]
	v_mfma_f32_16x16x32_bf16 v[12:15], v[92:95], v[96:99], v[12:15]
	v_mfma_f32_16x16x32_bf16 v[16:19], v[88:91], v[104:107], v[16:19]
	v_mfma_f32_16x16x32_bf16 v[20:23], v[92:95], v[104:107], v[20:23]
	v_mfma_f32_16x16x32_bf16 v[72:75], v[88:91], v[112:115], v[24:27]
	v_mfma_f32_16x16x32_bf16 v[76:79], v[92:95], v[112:115], v[28:31]
	v_mfma_f32_16x16x32_bf16 v[64:67], v[88:91], v[120:123], v[64:67]
	v_mfma_f32_16x16x32_bf16 v[68:71], v[92:95], v[120:123], v[68:71]
	v_mfma_f32_16x16x32_bf16 v[60:63], v[80:83], v[100:103], v[4:7]
	v_mfma_f32_16x16x32_bf16 v[52:55], v[84:87], v[100:103], v[12:15]
	v_mfma_f32_16x16x32_bf16 v[28:31], v[80:83], v[108:111], v[16:19]
	v_mfma_f32_16x16x32_bf16 v[24:27], v[84:87], v[108:111], v[20:23]
	v_mfma_f32_16x16x32_bf16 v[20:23], v[80:83], v[116:119], v[72:75]
	v_mfma_f32_16x16x32_bf16 v[16:19], v[84:87], v[116:119], v[76:79]
	v_mfma_f32_16x16x32_bf16 v[12:15], v[80:83], v[124:127], v[64:67]
	v_mfma_f32_16x16x32_bf16 v[4:7], v[84:87], v[124:127], v[68:71]
	s_setprio 0
	v_cmp_gt_u32_e32 vcc, s92, v136
	s_barrier
	s_and_saveexec_b64 s[66:67], vcc
	s_cbranch_execz .LBB0_468
	s_barrier

.LBB0_520:
	v_bfe_i32 v5, v179, 27, 1
	v_lshlrev_b32_e32 v169, 4, v179
	v_lshrrev_b32_e32 v5, 22, v5
	v_add_u32_e32 v5, v169, v5
	v_and_b32_e32 v5, 0xfffffc00, v5
	v_sub_u32_e32 v5, v169, v5
	v_lshrrev_b32_e32 v6, 4, v5
	v_bitop3_b32 v5, v6, v5, 32 bitop3:0x6c
	v_ashrrev_i32_e32 v6, 31, v5
	v_lshrrev_b32_e32 v6, 26, v6
	v_ashrrev_i32_e32 v4, 31, v179
	v_add_u32_e32 v6, v5, v6
	s_lshl_b32 s36, s81, 3
	v_lshrrev_b32_e32 v4, 26, v4
	v_ashrrev_i32_e32 v133, 6, v6
	v_and_b32_e32 v6, 0xc0, v6
	s_ff1_i32_b32 s37, s36
	v_and_b32_e32 v2, 15, v0
	v_and_b32_e32 v3, 48, v0
	v_add_u32_e32 v4, v179, v4
	v_sub_u32_e32 v5, v5, v6
	v_and_b32_e32 v6, 32, v0
	v_lshlrev_b32_e32 v10, 2, v0
	v_lshlrev_b32_e32 v0, 6, v0
	s_lshr_b32 s60, s82, s37
	s_add_i32 s36, s36, -1
	s_and_b32 s61, s82, 7
	v_ashrrev_i32_e32 v131, 6, v4
	v_lshlrev_b32_e32 v2, 6, v2
	v_and_b32_e32 v10, 32, v10
	v_and_b32_e32 v0, 0x3c0, v0
	s_and_b32 s36, s82, s36
	v_or_b32_e32 v9, v2, v3
	v_bitop3_b32 v2, v2, v10, v3 bitop3:0x36
	v_bitop3_b32 v3, v0, v10, v3 bitop3:0x36
	s_lshl_b32 s37, s60, 11
	s_lshl_b32 s46, s61, 8
	v_lshlrev_b32_e32 v0, 16, v131
	s_lshr_b32 s78, s36, 3
	s_or_b32 s46, s37, s46
	s_mov_b32 s47, s15
	v_and_b32_e32 v0, 0xfffe0000, v0
	s_lshl_b32 s36, s78, 14
	v_ashrrev_i16_sdwa v5, v167, sext(v5) dst_sel:DWORD dst_unused:UNUSED_PAD src0_sel:DWORD src1_sel:BYTE_0
	s_lshl_b64 s[46:47], s[46:47], 13
	v_lshl_add_u32 v0, v133, 13, v0
	v_bfe_i32 v134, v5, 0, 16
	v_and_or_b32 v0, v4, 64, v0
	s_add_u32 s46, s40, s46
	v_lshl_add_u32 v164, v134, 1, v0
	s_addc_u32 s47, s41, s47
	v_lshlrev_b32_e32 v14, 13, v1
	v_lshl_add_u64 v[0:1], s[46:47], 0, v[164:165]
	s_mul_i32 s46, s14, 0x1800
	s_mul_hi_u32 s37, s14, 0x1800
	s_add_u32 s46, s46, s36
	s_addc_u32 s37, s37, 0
	s_add_u32 s46, s62, s46
	v_bfe_i32 v7, v179, 6, 1
	s_addc_u32 s47, s63, s37
	s_lshl_b64 s[56:57], s[14:15], 12
	v_and_b32_e32 v7, s14, v7
	v_lshrrev_b32_e32 v8, 7, v179
	s_add_u32 s14, s56, s36
	v_add_lshl_u32 v7, v7, v8, 10
	v_lshlrev_b32_e32 v8, 6, v179
	s_addc_u32 s36, s57, 0
	v_and_b32_e32 v5, 0x3f0, v169
	v_and_b32_e32 v8, 0x3000, v8
	v_bitop3_b32 v11, v9, s65, v10 bitop3:0xde
	v_bitop3_b32 v12, v9, s67, v10 bitop3:0xde
	v_bitop3_b32 v13, v9, s68, v10 bitop3:0xde
	v_bitop3_b32 v9, v9, s69, v10 bitop3:0xde
	v_or_b32_e32 v10, 0x800, v14
	v_or_b32_e32 v15, 0x1000, v14
	v_or_b32_e32 v16, 0x1800, v14
	v_lshl_add_u64 v[128:129], v[0:1], 0, s[16:17]
	s_add_u32 s58, s62, s14
	v_mov_b32_e32 v0, 0
	v_bitop3_b32 v164, v5, v7, v6 bitop3:0xde
	s_addc_u32 s59, s63, s36
	s_mov_b32 s14, -2
	v_add_u32_e32 v138, v11, v8
	v_add_u32_e32 v193, v2, v14
	v_add_u32_e32 v192, v3, v10
	v_add_u32_e32 v191, v3, v15
	v_add_u32_e32 v190, v3, v16
	v_add_u32_e32 v137, 0xc000, v169
	v_add_u32_e32 v136, 0xe000, v169
	v_add_u32_e32 v135, v12, v8
	v_add_u32_e32 v189, 0x10000, v169
	v_add_u32_e32 v188, 0x12000, v169
	v_add_u32_e32 v187, 0x2000, v169
	v_add_u32_e32 v186, 0x14000, v169
	v_add_u32_e32 v185, 0x16000, v169
	v_add_u32_e32 v130, v13, v8
	v_add_u32_e32 v184, 0x4000, v169
	v_add_u32_e32 v183, 0x6000, v169
	v_add_u32_e32 v132, v9, v8
	v_add_u32_e32 v182, 0x18000, v169
	v_add_u32_e32 v181, 0x1a000, v169
	v_add_u32_e32 v177, 0x8000, v169
	v_add_u32_e32 v175, 0xa000, v169
	v_add_u32_e32 v173, 0x1c000, v169
	v_add_u32_e32 v171, 0x1e000, v169
	v_mov_b32_e32 v1, v0
	v_mov_b32_e32 v2, v0
	v_mov_b32_e32 v3, v0
	v_mov_b32_e32 v4, v0
	v_mov_b32_e32 v5, v0
	v_mov_b32_e32 v6, v0
	v_mov_b32_e32 v7, v0
	v_mov_b32_e32 v8, v0
	v_mov_b32_e32 v9, v0
	v_mov_b32_e32 v10, v0
	v_mov_b32_e32 v11, v0
	v_mov_b32_e32 v12, v0
	v_mov_b32_e32 v13, v0
	v_mov_b32_e32 v14, v0
	v_mov_b32_e32 v15, v0
	v_mov_b32_e32 v16, v0
	v_mov_b32_e32 v17, v0
	v_mov_b32_e32 v18, v0
	v_mov_b32_e32 v19, v0
	v_mov_b32_e32 v20, v0
	v_mov_b32_e32 v21, v0
	v_mov_b32_e32 v22, v0
	v_mov_b32_e32 v23, v0
	v_mov_b32_e32 v24, v0
	v_mov_b32_e32 v25, v0
	v_mov_b32_e32 v26, v0
	v_mov_b32_e32 v27, v0
	v_mov_b32_e32 v28, v0
	v_mov_b32_e32 v29, v0
	v_mov_b32_e32 v30, v0
	v_mov_b32_e32 v31, v0
	v_mov_b32_e32 v32, v0
	v_mov_b32_e32 v33, v0
	v_mov_b32_e32 v34, v0
	v_mov_b32_e32 v35, v0
	v_mov_b32_e32 v36, v0
	v_mov_b32_e32 v37, v0
	v_mov_b32_e32 v38, v0
	v_mov_b32_e32 v39, v0
	v_mov_b32_e32 v40, v0
	v_mov_b32_e32 v41, v0
	v_mov_b32_e32 v42, v0
	v_mov_b32_e32 v43, v0
	v_mov_b32_e32 v44, v0
	v_mov_b32_e32 v45, v0
	v_mov_b32_e32 v46, v0
	v_mov_b32_e32 v47, v0
	v_mov_b32_e32 v48, v0
	v_mov_b32_e32 v49, v0
	v_mov_b32_e32 v50, v0
	v_mov_b32_e32 v51, v0
	v_mov_b32_e32 v52, v0
	v_mov_b32_e32 v53, v0
	v_mov_b32_e32 v54, v0
	v_mov_b32_e32 v55, v0
	v_mov_b32_e32 v56, v0
	v_mov_b32_e32 v57, v0
	v_mov_b32_e32 v58, v0
	v_mov_b32_e32 v59, v0
	v_mov_b32_e32 v60, v0
	v_mov_b32_e32 v61, v0
	v_mov_b32_e32 v62, v0
	v_mov_b32_e32 v63, v0
	v_mov_b32_e32 v64, v0
	v_mov_b32_e32 v65, v0
	v_mov_b32_e32 v66, v0
	v_mov_b32_e32 v67, v0
	v_mov_b32_e32 v68, v0
	v_mov_b32_e32 v69, v0
	v_mov_b32_e32 v70, v0
	v_mov_b32_e32 v71, v0
	v_mov_b32_e32 v72, v0
	v_mov_b32_e32 v73, v0
	v_mov_b32_e32 v74, v0
	v_mov_b32_e32 v75, v0
	v_mov_b32_e32 v76, v0
	v_mov_b32_e32 v77, v0
	v_mov_b32_e32 v78, v0
	v_mov_b32_e32 v79, v0
	v_mov_b32_e32 v80, v0
	v_mov_b32_e32 v81, v0
	v_mov_b32_e32 v82, v0
	v_mov_b32_e32 v83, v0
	v_mov_b32_e32 v84, v0
	v_mov_b32_e32 v85, v0
	v_mov_b32_e32 v86, v0
	v_mov_b32_e32 v87, v0
	v_mov_b32_e32 v88, v0
	v_mov_b32_e32 v89, v0
	v_mov_b32_e32 v90, v0
	v_mov_b32_e32 v91, v0
	v_mov_b32_e32 v92, v0
	v_mov_b32_e32 v93, v0
	v_mov_b32_e32 v94, v0
	v_mov_b32_e32 v95, v0
	v_mov_b32_e32 v96, v0
	v_mov_b32_e32 v97, v0
	v_mov_b32_e32 v98, v0
	v_mov_b32_e32 v99, v0
	v_mov_b32_e32 v100, v0
	v_mov_b32_e32 v101, v0
	v_mov_b32_e32 v102, v0
	v_mov_b32_e32 v103, v0
	v_mov_b32_e32 v104, v0
	v_mov_b32_e32 v105, v0
	v_mov_b32_e32 v106, v0
	v_mov_b32_e32 v107, v0
	v_mov_b32_e32 v108, v0
	v_mov_b32_e32 v109, v0
	v_mov_b32_e32 v110, v0
	v_mov_b32_e32 v111, v0
	v_mov_b32_e32 v112, v0
	v_mov_b32_e32 v113, v0
	v_mov_b32_e32 v114, v0
	v_mov_b32_e32 v115, v0
	v_mov_b32_e32 v116, v0
	v_mov_b32_e32 v117, v0
	v_mov_b32_e32 v118, v0
	v_mov_b32_e32 v119, v0
	v_mov_b32_e32 v120, v0
	v_mov_b32_e32 v121, v0
	v_mov_b32_e32 v122, v0
	v_mov_b32_e32 v123, v0
	v_mov_b32_e32 v124, v0
	v_mov_b32_e32 v125, v0
	v_mov_b32_e32 v126, v0
	v_mov_b32_e32 v127, v0
	s_barrier
	v_readlane_b32 s98, v242, 1
	s_nop 3
	s_cmp_lt_u32 s98, 4
	s_cbranch_scc1 .Lprio_521
	s_setprio 1
.Lprio_521:
	v_readfirstlane_b32 s36, v137
	v_lshl_add_u64 v[142:143], v[128:129], 0, s[18:19]
	s_mov_b32 m0, s36
	v_readfirstlane_b32 s36, v136
	global_load_lds_dwordx4 v[142:143], off
	v_lshl_add_u64 v[142:143], v[128:129], 0, s[20:21]
	s_mov_b32 m0, s36
	s_nop 0
	global_load_lds_dwordx4 v[142:143], off
.LBB0_521:
	ds_read_b128 v[140:143], v138
	ds_read_b128 v[144:147], v138 offset:1024
	ds_read_b128 v[148:151], v138 offset:2048
	ds_read_b128 v[152:155], v138 offset:3072
	ds_read_b128 v[156:159], v193
	ds_read_b128 v[160:163], v193 offset:1024
	ds_read_b128 v[194:197], v192
	ds_read_b128 v[198:201], v192 offset:1024
	ds_read_b128 v[202:205], v191
	ds_read_b128 v[206:209], v191 offset:1024
	ds_read_b128 v[210:213], v190
	ds_read_b128 v[214:217], v190 offset:1024
	s_waitcnt lgkmcnt(8)
	s_waitcnt vmcnt(10)
	s_barrier
	s_waitcnt lgkmcnt(0)
	s_waitcnt lgkmcnt(0)
	v_mfma_f32_16x16x32_bf16 v[124:127], v[140:143], v[156:159], v[124:127]
	v_mfma_f32_16x16x32_bf16 v[120:123], v[148:151], v[156:159], v[120:123]
	v_mfma_f32_16x16x32_bf16 v[116:119], v[140:143], v[194:197], v[116:119]
	v_mfma_f32_16x16x32_bf16 v[112:115], v[148:151], v[194:197], v[112:115]
	v_mfma_f32_16x16x32_bf16 v[108:111], v[140:143], v[202:205], v[108:111]
	v_mfma_f32_16x16x32_bf16 v[104:107], v[148:151], v[202:205], v[104:107]
	v_mfma_f32_16x16x32_bf16 v[100:103], v[140:143], v[210:213], v[100:103]
	v_mfma_f32_16x16x32_bf16 v[96:99], v[148:151], v[210:213], v[96:99]
	v_mfma_f32_16x16x32_bf16 v[124:127], v[144:147], v[160:163], v[124:127]
	v_mfma_f32_16x16x32_bf16 v[120:123], v[152:155], v[160:163], v[120:123]
	v_mfma_f32_16x16x32_bf16 v[116:119], v[144:147], v[198:201], v[116:119]
	v_mfma_f32_16x16x32_bf16 v[112:115], v[152:155], v[198:201], v[112:115]
	v_mfma_f32_16x16x32_bf16 v[108:111], v[144:147], v[206:209], v[108:111]
	v_mfma_f32_16x16x32_bf16 v[104:107], v[152:155], v[206:209], v[104:107]
	v_mfma_f32_16x16x32_bf16 v[100:103], v[144:147], v[214:217], v[100:103]
	v_mfma_f32_16x16x32_bf16 v[96:99], v[152:155], v[214:217], v[96:99]
	s_barrier
	v_readfirstlane_b32 s36, v189
	v_lshl_add_u64 v[234:235], s[58:59], 0, v[164:165]
	s_mov_b32 m0, s36
	v_readfirstlane_b32 s36, v188
	ds_read_b128 v[218:221], v135
	ds_read_b128 v[222:225], v135 offset:1024
	ds_read_b128 v[226:229], v135 offset:2048
	ds_read_b128 v[230:233], v135 offset:3072
	global_load_lds_dwordx4 v[234:235], off
	v_lshl_add_u64 v[236:237], v[234:235], 0, s[2:3]
	s_mov_b32 m0, s36
	s_nop 0
	global_load_lds_dwordx4 v[236:237], off
	v_readfirstlane_b32 s36, v169
	v_lshl_add_u64 v[236:237], v[128:129], 0, s[22:23]
	s_mov_b32 m0, s36
	v_readfirstlane_b32 s36, v187
	global_load_lds_dwordx4 v[236:237], off
	v_lshl_add_u64 v[236:237], v[128:129], 0, s[24:25]
	s_mov_b32 m0, s36
	s_nop 0
	global_load_lds_dwordx4 v[236:237], off
	s_waitcnt vmcnt(12)
	s_barrier
	s_waitcnt lgkmcnt(0)
	s_waitcnt lgkmcnt(0)
	v_mfma_f32_16x16x32_bf16 v[92:95], v[218:221], v[156:159], v[92:95]
	v_mfma_f32_16x16x32_bf16 v[88:91], v[226:229], v[156:159], v[88:91]
	v_mfma_f32_16x16x32_bf16 v[84:87], v[218:221], v[194:197], v[84:87]
	v_mfma_f32_16x16x32_bf16 v[80:83], v[226:229], v[194:197], v[80:83]
	v_mfma_f32_16x16x32_bf16 v[76:79], v[218:221], v[202:205], v[76:79]
	v_mfma_f32_16x16x32_bf16 v[72:75], v[226:229], v[202:205], v[72:75]
	v_mfma_f32_16x16x32_bf16 v[68:71], v[218:221], v[210:213], v[68:71]
	v_mfma_f32_16x16x32_bf16 v[64:67], v[226:229], v[210:213], v[64:67]
	v_mfma_f32_16x16x32_bf16 v[92:95], v[222:225], v[160:163], v[92:95]
	v_mfma_f32_16x16x32_bf16 v[88:91], v[230:233], v[160:163], v[88:91]
	v_mfma_f32_16x16x32_bf16 v[84:87], v[222:225], v[198:201], v[84:87]
	v_mfma_f32_16x16x32_bf16 v[80:83], v[230:233], v[198:201], v[80:83]
	v_mfma_f32_16x16x32_bf16 v[76:79], v[222:225], v[206:209], v[76:79]
	v_mfma_f32_16x16x32_bf16 v[72:75], v[230:233], v[206:209], v[72:75]
	v_mfma_f32_16x16x32_bf16 v[68:71], v[222:225], v[214:217], v[68:71]
	v_mfma_f32_16x16x32_bf16 v[64:67], v[230:233], v[214:217], v[64:67]
	s_barrier
	ds_read_b128 v[156:159], v193 offset:16384
	ds_read_b128 v[160:163], v193 offset:17408
	ds_read_b128 v[194:197], v192 offset:16384
	ds_read_b128 v[198:201], v192 offset:17408
	ds_read_b128 v[202:205], v191 offset:16384
	ds_read_b128 v[206:209], v191 offset:17408
	ds_read_b128 v[210:213], v190 offset:16384
	ds_read_b128 v[214:217], v190 offset:17408
	v_readfirstlane_b32 s36, v186
	v_lshl_add_u64 v[236:237], v[234:235], 0, s[6:7]
	s_mov_b32 m0, s36
	v_readfirstlane_b32 s36, v185
	global_load_lds_dwordx4 v[236:237], off
	v_lshl_add_u64 v[236:237], v[234:235], 0, s[8:9]
	s_mov_b32 m0, s36
	s_nop 0
	global_load_lds_dwordx4 v[236:237], off
	s_barrier
	s_waitcnt lgkmcnt(0)
	s_waitcnt lgkmcnt(0)
	v_mfma_f32_16x16x32_bf16 v[60:63], v[140:143], v[156:159], v[60:63]
	v_mfma_f32_16x16x32_bf16 v[56:59], v[148:151], v[156:159], v[56:59]
	v_mfma_f32_16x16x32_bf16 v[52:55], v[140:143], v[194:197], v[52:55]
	v_mfma_f32_16x16x32_bf16 v[48:51], v[148:151], v[194:197], v[48:51]
	v_mfma_f32_16x16x32_bf16 v[44:47], v[140:143], v[202:205], v[44:47]
	v_mfma_f32_16x16x32_bf16 v[40:43], v[148:151], v[202:205], v[40:43]
	v_mfma_f32_16x16x32_bf16 v[36:39], v[140:143], v[210:213], v[36:39]
	v_mfma_f32_16x16x32_bf16 v[32:35], v[148:151], v[210:213], v[32:35]
	v_mfma_f32_16x16x32_bf16 v[60:63], v[144:147], v[160:163], v[60:63]
	v_mfma_f32_16x16x32_bf16 v[56:59], v[152:155], v[160:163], v[56:59]
	v_mfma_f32_16x16x32_bf16 v[52:55], v[144:147], v[198:201], v[52:55]
	v_mfma_f32_16x16x32_bf16 v[48:51], v[152:155], v[198:201], v[48:51]
	v_mfma_f32_16x16x32_bf16 v[44:47], v[144:147], v[206:209], v[44:47]
	v_mfma_f32_16x16x32_bf16 v[40:43], v[152:155], v[206:209], v[40:43]
	v_mfma_f32_16x16x32_bf16 v[36:39], v[144:147], v[214:217], v[36:39]
	v_mfma_f32_16x16x32_bf16 v[32:35], v[152:155], v[214:217], v[32:35]
	s_barrier
	v_readfirstlane_b32 s36, v184
	v_lshl_add_u64 v[142:143], v[128:129], 0, s[26:27]
	s_mov_b32 m0, s36
	v_readfirstlane_b32 s36, v183
	global_load_lds_dwordx4 v[142:143], off
	s_mov_b32 m0, s36
	s_nop 0
	global_load_lds_dwordx4 v[128:129], off
	s_waitcnt vmcnt(12)
	s_barrier
	v_mfma_f32_16x16x32_bf16 v[28:31], v[218:221], v[156:159], v[28:31]
	v_mfma_f32_16x16x32_bf16 v[24:27], v[226:229], v[156:159], v[24:27]
	v_mfma_f32_16x16x32_bf16 v[20:23], v[218:221], v[194:197], v[20:23]
	v_mfma_f32_16x16x32_bf16 v[16:19], v[226:229], v[194:197], v[16:19]
	v_mfma_f32_16x16x32_bf16 v[12:15], v[218:221], v[202:205], v[12:15]
	v_mfma_f32_16x16x32_bf16 v[8:11], v[226:229], v[202:205], v[8:11]
	v_mfma_f32_16x16x32_bf16 v[4:7], v[218:221], v[210:213], v[4:7]
	v_mfma_f32_16x16x32_bf16 v[0:3], v[226:229], v[210:213], v[0:3]
	v_mfma_f32_16x16x32_bf16 v[28:31], v[222:225], v[160:163], v[28:31]
	v_mfma_f32_16x16x32_bf16 v[24:27], v[230:233], v[160:163], v[24:27]
	v_mfma_f32_16x16x32_bf16 v[20:23], v[222:225], v[198:201], v[20:23]
	v_mfma_f32_16x16x32_bf16 v[16:19], v[230:233], v[198:201], v[16:19]
	v_mfma_f32_16x16x32_bf16 v[12:15], v[222:225], v[206:209], v[12:15]
	v_mfma_f32_16x16x32_bf16 v[8:11], v[230:233], v[206:209], v[8:11]
	v_mfma_f32_16x16x32_bf16 v[4:7], v[222:225], v[214:217], v[4:7]
	v_mfma_f32_16x16x32_bf16 v[0:3], v[230:233], v[214:217], v[0:3]
	s_barrier
	ds_read_b128 v[140:143], v130
	ds_read_b128 v[144:147], v130 offset:1024
	ds_read_b128 v[148:151], v130 offset:2048
	ds_read_b128 v[152:155], v130 offset:3072
	ds_read_b128 v[156:159], v193 offset:32768
	ds_read_b128 v[160:163], v193 offset:33792
	ds_read_b128 v[194:197], v192 offset:32768
	ds_read_b128 v[198:201], v192 offset:33792
	ds_read_b128 v[202:205], v191 offset:32768
	ds_read_b128 v[206:209], v191 offset:33792
	ds_read_b128 v[210:213], v190 offset:32768
	ds_read_b128 v[214:217], v190 offset:33792
	s_waitcnt lgkmcnt(8)
	s_waitcnt vmcnt(10)
	s_barrier
	s_waitcnt lgkmcnt(0)
	s_waitcnt lgkmcnt(0)
	v_mfma_f32_16x16x32_bf16 v[124:127], v[140:143], v[156:159], v[124:127]
	v_mfma_f32_16x16x32_bf16 v[120:123], v[148:151], v[156:159], v[120:123]
	v_mfma_f32_16x16x32_bf16 v[116:119], v[140:143], v[194:197], v[116:119]
	v_mfma_f32_16x16x32_bf16 v[112:115], v[148:151], v[194:197], v[112:115]
	v_mfma_f32_16x16x32_bf16 v[108:111], v[140:143], v[202:205], v[108:111]
	v_mfma_f32_16x16x32_bf16 v[104:107], v[148:151], v[202:205], v[104:107]
	v_mfma_f32_16x16x32_bf16 v[100:103], v[140:143], v[210:213], v[100:103]
	v_mfma_f32_16x16x32_bf16 v[96:99], v[148:151], v[210:213], v[96:99]
	v_mfma_f32_16x16x32_bf16 v[124:127], v[144:147], v[160:163], v[124:127]
	v_mfma_f32_16x16x32_bf16 v[120:123], v[152:155], v[160:163], v[120:123]
	v_mfma_f32_16x16x32_bf16 v[116:119], v[144:147], v[198:201], v[116:119]
	v_mfma_f32_16x16x32_bf16 v[112:115], v[152:155], v[198:201], v[112:115]
	v_mfma_f32_16x16x32_bf16 v[108:111], v[144:147], v[206:209], v[108:111]
	v_mfma_f32_16x16x32_bf16 v[104:107], v[152:155], v[206:209], v[104:107]
	v_mfma_f32_16x16x32_bf16 v[100:103], v[144:147], v[214:217], v[100:103]
	v_mfma_f32_16x16x32_bf16 v[96:99], v[152:155], v[214:217], v[96:99]
	s_barrier
	v_readfirstlane_b32 s36, v182
	v_lshl_add_u64 v[234:235], s[46:47], 0, v[164:165]
	s_mov_b32 m0, s36
	v_readfirstlane_b32 s36, v181
	ds_read_b128 v[218:221], v132
	ds_read_b128 v[222:225], v132 offset:1024
	ds_read_b128 v[226:229], v132 offset:2048
	ds_read_b128 v[230:233], v132 offset:3072
	global_load_lds_dwordx4 v[234:235], off
	v_lshl_add_u64 v[236:237], v[234:235], 0, s[2:3]
	s_mov_b32 m0, s36
	s_nop 0
	global_load_lds_dwordx4 v[236:237], off
	v_readfirstlane_b32 s36, v177
	v_lshl_add_u64 v[236:237], v[128:129], 0, s[28:29]
	s_mov_b32 m0, s36
	v_readfirstlane_b32 s36, v175
	global_load_lds_dwordx4 v[236:237], off
	v_lshl_add_u64 v[236:237], v[128:129], 0, s[30:31]
	s_mov_b32 m0, s36
	s_nop 0
	global_load_lds_dwordx4 v[236:237], off
	s_waitcnt vmcnt(12)
	s_barrier
	s_waitcnt lgkmcnt(0)
	s_waitcnt lgkmcnt(0)
	v_mfma_f32_16x16x32_bf16 v[92:95], v[218:221], v[156:159], v[92:95]
	v_mfma_f32_16x16x32_bf16 v[88:91], v[226:229], v[156:159], v[88:91]
	v_mfma_f32_16x16x32_bf16 v[84:87], v[218:221], v[194:197], v[84:87]
	v_mfma_f32_16x16x32_bf16 v[80:83], v[226:229], v[194:197], v[80:83]
	v_mfma_f32_16x16x32_bf16 v[76:79], v[218:221], v[202:205], v[76:79]
	v_mfma_f32_16x16x32_bf16 v[72:75], v[226:229], v[202:205], v[72:75]
	v_mfma_f32_16x16x32_bf16 v[68:71], v[218:221], v[210:213], v[68:71]
	v_mfma_f32_16x16x32_bf16 v[64:67], v[226:229], v[210:213], v[64:67]
	v_mfma_f32_16x16x32_bf16 v[92:95], v[222:225], v[160:163], v[92:95]
	v_mfma_f32_16x16x32_bf16 v[88:91], v[230:233], v[160:163], v[88:91]
	v_mfma_f32_16x16x32_bf16 v[84:87], v[222:225], v[198:201], v[84:87]
	v_mfma_f32_16x16x32_bf16 v[80:83], v[230:233], v[198:201], v[80:83]
	v_mfma_f32_16x16x32_bf16 v[76:79], v[222:225], v[206:209], v[76:79]
	v_mfma_f32_16x16x32_bf16 v[72:75], v[230:233], v[206:209], v[72:75]
	v_mfma_f32_16x16x32_bf16 v[68:71], v[222:225], v[214:217], v[68:71]
	v_mfma_f32_16x16x32_bf16 v[64:67], v[230:233], v[214:217], v[64:67]
	s_barrier
	ds_read_b128 v[156:159], v193 offset:49152
	ds_read_b128 v[160:163], v193 offset:50176
	ds_read_b128 v[194:197], v192 offset:49152
	ds_read_b128 v[198:201], v192 offset:50176
	ds_read_b128 v[202:205], v191 offset:49152
	ds_read_b128 v[206:209], v191 offset:50176
	ds_read_b128 v[210:213], v190 offset:49152
	ds_read_b128 v[214:217], v190 offset:50176
	v_readfirstlane_b32 s36, v173
	v_lshl_add_u64 v[236:237], v[234:235], 0, s[6:7]
	s_mov_b32 m0, s36
	v_readfirstlane_b32 s36, v171
	global_load_lds_dwordx4 v[236:237], off
	v_lshl_add_u64 v[236:237], v[234:235], 0, s[8:9]
	s_mov_b32 m0, s36
	s_nop 0
	global_load_lds_dwordx4 v[236:237], off
	s_barrier
	s_waitcnt lgkmcnt(0)
	s_waitcnt lgkmcnt(0)
	v_mfma_f32_16x16x32_bf16 v[60:63], v[140:143], v[156:159], v[60:63]
	v_mfma_f32_16x16x32_bf16 v[56:59], v[148:151], v[156:159], v[56:59]
	v_mfma_f32_16x16x32_bf16 v[52:55], v[140:143], v[194:197], v[52:55]
	v_mfma_f32_16x16x32_bf16 v[48:51], v[148:151], v[194:197], v[48:51]
	v_mfma_f32_16x16x32_bf16 v[44:47], v[140:143], v[202:205], v[44:47]
	v_mfma_f32_16x16x32_bf16 v[40:43], v[148:151], v[202:205], v[40:43]
	v_mfma_f32_16x16x32_bf16 v[36:39], v[140:143], v[210:213], v[36:39]
	v_mfma_f32_16x16x32_bf16 v[32:35], v[148:151], v[210:213], v[32:35]
	v_mfma_f32_16x16x32_bf16 v[60:63], v[144:147], v[160:163], v[60:63]
	v_mfma_f32_16x16x32_bf16 v[56:59], v[152:155], v[160:163], v[56:59]
	v_mfma_f32_16x16x32_bf16 v[52:55], v[144:147], v[198:201], v[52:55]
	v_mfma_f32_16x16x32_bf16 v[48:51], v[152:155], v[198:201], v[48:51]
	v_mfma_f32_16x16x32_bf16 v[44:47], v[144:147], v[206:209], v[44:47]
	v_mfma_f32_16x16x32_bf16 v[40:43], v[152:155], v[206:209], v[40:43]
	v_mfma_f32_16x16x32_bf16 v[36:39], v[144:147], v[214:217], v[36:39]
	v_mfma_f32_16x16x32_bf16 v[32:35], v[152:155], v[214:217], v[32:35]
	s_barrier
	v_lshl_add_u64 v[128:129], v[128:129], 0, s[34:35]
	v_readfirstlane_b32 s36, v137
	v_lshl_add_u64 v[142:143], v[128:129], 0, s[18:19]
	s_mov_b32 m0, s36
	v_readfirstlane_b32 s36, v136
	global_load_lds_dwordx4 v[142:143], off
	v_lshl_add_u64 v[142:143], v[128:129], 0, s[20:21]
	s_mov_b32 m0, s36
	s_nop 0
	global_load_lds_dwordx4 v[142:143], off
	s_waitcnt vmcnt(12)
	s_barrier
	v_mfma_f32_16x16x32_bf16 v[28:31], v[218:221], v[156:159], v[28:31]
	v_mfma_f32_16x16x32_bf16 v[24:27], v[226:229], v[156:159], v[24:27]
	v_mfma_f32_16x16x32_bf16 v[20:23], v[218:221], v[194:197], v[20:23]
	v_mfma_f32_16x16x32_bf16 v[16:19], v[226:229], v[194:197], v[16:19]
	v_mfma_f32_16x16x32_bf16 v[12:15], v[218:221], v[202:205], v[12:15]
	v_mfma_f32_16x16x32_bf16 v[8:11], v[226:229], v[202:205], v[8:11]
	v_mfma_f32_16x16x32_bf16 v[4:7], v[218:221], v[210:213], v[4:7]
	v_mfma_f32_16x16x32_bf16 v[0:3], v[226:229], v[210:213], v[0:3]
	v_mfma_f32_16x16x32_bf16 v[28:31], v[222:225], v[160:163], v[28:31]
	v_mfma_f32_16x16x32_bf16 v[24:27], v[230:233], v[160:163], v[24:27]
	v_mfma_f32_16x16x32_bf16 v[20:23], v[222:225], v[198:201], v[20:23]
	v_mfma_f32_16x16x32_bf16 v[16:19], v[230:233], v[198:201], v[16:19]
	v_mfma_f32_16x16x32_bf16 v[12:15], v[222:225], v[206:209], v[12:15]
	v_mfma_f32_16x16x32_bf16 v[8:11], v[230:233], v[206:209], v[8:11]
	v_mfma_f32_16x16x32_bf16 v[4:7], v[222:225], v[214:217], v[4:7]
	v_mfma_f32_16x16x32_bf16 v[0:3], v[230:233], v[214:217], v[0:3]
	s_add_i32 s14, s14, 2
	s_add_u32 s46, s46, s56
	s_addc_u32 s47, s47, s57
	s_add_u32 s58, s58, s56
	s_addc_u32 s59, s59, s57
	s_cmp_lt_u32 s14, 28
	s_barrier
	s_cbranch_scc1 .LBB0_521
	s_setprio 0
	s_lshl_b32 s14, s60, 3
	s_or_b32 s80, s61, s14
	s_lshl_b32 s46, s80, 8
	v_lshlrev_b32_e32 v128, 3, v131
	v_lshlrev_b32_e32 v129, 5, v131
	s_or_b32 s14, s46, 0x80
	v_and_b32_e32 v128, 0x7fff0, v128
	v_and_b32_e32 v129, 32, v129
	s_lshl_b64 s[56:57], s[14:15], 13
	v_add_u32_e32 v129, v129, v134
	v_add_lshl_u32 v128, v133, v128, 13
	s_add_u32 s56, s40, s56
	v_lshl_add_u32 v164, v129, 1, v128
	s_addc_u32 s57, s41, s57
	v_lshl_add_u64 v[128:129], s[56:57], 0, v[164:165]
	v_readfirstlane_b32 s14, v137
	ds_read_b128 v[140:143], v138
	ds_read_b128 v[144:147], v138 offset:1024
	ds_read_b128 v[148:151], v138 offset:2048
	ds_read_b128 v[152:155], v138 offset:3072
	ds_read_b128 v[156:159], v193
	ds_read_b128 v[160:163], v193 offset:1024
	ds_read_b128 v[194:197], v192
	ds_read_b128 v[198:201], v192 offset:1024
	ds_read_b128 v[202:205], v191
	ds_read_b128 v[206:209], v191 offset:1024
	ds_read_b128 v[210:213], v190
	ds_read_b128 v[214:217], v190 offset:1024
	v_lshl_add_u64 v[138:139], v[128:129], 0, s[38:39]
	s_mov_b32 m0, s14
	v_readfirstlane_b32 s14, v136
	global_load_lds_dwordx4 v[138:139], off
	v_lshl_add_u64 v[128:129], v[128:129], 0, s[44:45]
	s_mov_b32 m0, s14
	s_mov_b32 s47, s15
	global_load_lds_dwordx4 v[128:129], off
	s_waitcnt vmcnt(10)
	s_barrier
	s_waitcnt lgkmcnt(0)
	s_setprio 1
	s_waitcnt lgkmcnt(0)
	v_mfma_f32_16x16x32_bf16 v[124:127], v[140:143], v[156:159], v[124:127]
	v_mfma_f32_16x16x32_bf16 v[120:123], v[148:151], v[156:159], v[120:123]
	v_mfma_f32_16x16x32_bf16 v[116:119], v[140:143], v[194:197], v[116:119]
	v_mfma_f32_16x16x32_bf16 v[112:115], v[148:151], v[194:197], v[112:115]
	v_mfma_f32_16x16x32_bf16 v[108:111], v[140:143], v[202:205], v[108:111]
	v_mfma_f32_16x16x32_bf16 v[104:107], v[148:151], v[202:205], v[104:107]
	v_mfma_f32_16x16x32_bf16 v[100:103], v[140:143], v[210:213], v[100:103]
	v_mfma_f32_16x16x32_bf16 v[96:99], v[148:151], v[210:213], v[96:99]
	v_mfma_f32_16x16x32_bf16 v[124:127], v[144:147], v[160:163], v[124:127]
	v_mfma_f32_16x16x32_bf16 v[120:123], v[152:155], v[160:163], v[120:123]
	v_mfma_f32_16x16x32_bf16 v[116:119], v[144:147], v[198:201], v[116:119]
	v_mfma_f32_16x16x32_bf16 v[112:115], v[152:155], v[198:201], v[112:115]
	v_mfma_f32_16x16x32_bf16 v[108:111], v[144:147], v[206:209], v[108:111]
	v_mfma_f32_16x16x32_bf16 v[104:107], v[152:155], v[206:209], v[104:107]
	v_mfma_f32_16x16x32_bf16 v[100:103], v[144:147], v[214:217], v[100:103]
	v_mfma_f32_16x16x32_bf16 v[96:99], v[152:155], v[214:217], v[96:99]
	s_setprio 0
	s_barrier
	ds_read_b128 v[136:139], v135
	ds_read_b128 v[218:221], v135 offset:1024
	ds_read_b128 v[222:225], v135 offset:2048
	ds_read_b128 v[226:229], v135 offset:3072
	s_barrier
	s_waitcnt lgkmcnt(0)
	s_setprio 1
	s_waitcnt lgkmcnt(0)
	v_mfma_f32_16x16x32_bf16 v[92:95], v[136:139], v[156:159], v[92:95]
	v_mfma_f32_16x16x32_bf16 v[84:87], v[136:139], v[194:197], v[84:87]
	v_mfma_f32_16x16x32_bf16 v[80:83], v[222:225], v[194:197], v[80:83]
	v_mfma_f32_16x16x32_bf16 v[88:91], v[222:225], v[156:159], v[88:91]
	v_mfma_f32_16x16x32_bf16 v[76:79], v[136:139], v[202:205], v[76:79]
	v_mfma_f32_16x16x32_bf16 v[72:75], v[222:225], v[202:205], v[72:75]
	v_mfma_f32_16x16x32_bf16 v[68:71], v[136:139], v[210:213], v[68:71]
	v_mfma_f32_16x16x32_bf16 v[64:67], v[222:225], v[210:213], v[64:67]
	v_mfma_f32_16x16x32_bf16 v[156:159], v[218:221], v[160:163], v[92:95]
	v_mfma_f32_16x16x32_bf16 v[194:197], v[218:221], v[198:201], v[84:87]
	v_mfma_f32_16x16x32_bf16 v[198:201], v[226:229], v[198:201], v[80:83]
	v_mfma_f32_16x16x32_bf16 v[160:163], v[226:229], v[160:163], v[88:91]
	v_mfma_f32_16x16x32_bf16 v[202:205], v[218:221], v[206:209], v[76:79]
	v_mfma_f32_16x16x32_bf16 v[206:209], v[226:229], v[206:209], v[72:75]
	v_mfma_f32_16x16x32_bf16 v[210:213], v[218:221], v[214:217], v[68:71]
	v_mfma_f32_16x16x32_bf16 v[214:217], v[226:229], v[214:217], v[64:67]
	s_setprio 0
	s_barrier
	s_nop 0
	ds_read_b128 v[64:67], v193 offset:16384
	ds_read_b128 v[68:71], v193 offset:17408
	ds_read_b128 v[72:75], v192 offset:16384
	ds_read_b128 v[76:79], v192 offset:17408
	ds_read_b128 v[80:83], v191 offset:16384
	ds_read_b128 v[84:87], v191 offset:17408
	ds_read_b128 v[88:91], v190 offset:16384
	ds_read_b128 v[92:95], v190 offset:17408
	s_waitcnt vmcnt(4)
	s_barrier
	s_waitcnt lgkmcnt(0)
	s_setprio 1
	s_waitcnt lgkmcnt(0)
	v_mfma_f32_16x16x32_bf16 v[60:63], v[140:143], v[64:67], v[60:63]
	v_mfma_f32_16x16x32_bf16 v[56:59], v[148:151], v[64:67], v[56:59]
	v_mfma_f32_16x16x32_bf16 v[52:55], v[140:143], v[72:75], v[52:55]
	v_mfma_f32_16x16x32_bf16 v[48:51], v[148:151], v[72:75], v[48:51]
	v_mfma_f32_16x16x32_bf16 v[230:233], v[140:143], v[80:83], v[44:47]
	v_mfma_f32_16x16x32_bf16 v[234:237], v[148:151], v[80:83], v[40:43]
	v_mfma_f32_16x16x32_bf16 v[140:143], v[140:143], v[88:91], v[36:39]
	v_mfma_f32_16x16x32_bf16 v[148:151], v[148:151], v[88:91], v[32:35]
	v_mfma_f32_16x16x32_bf16 v[32:35], v[144:147], v[68:71], v[60:63]
	v_mfma_f32_16x16x32_bf16 v[36:39], v[152:155], v[68:71], v[56:59]
	v_mfma_f32_16x16x32_bf16 v[40:43], v[144:147], v[76:79], v[52:55]
	v_mfma_f32_16x16x32_bf16 v[44:47], v[152:155], v[76:79], v[48:51]
	v_mfma_f32_16x16x32_bf16 v[48:51], v[144:147], v[84:87], v[230:233]
	v_mfma_f32_16x16x32_bf16 v[52:55], v[152:155], v[84:87], v[234:237]
	v_mfma_f32_16x16x32_bf16 v[56:59], v[144:147], v[92:95], v[140:143]
	v_mfma_f32_16x16x32_bf16 v[60:63], v[152:155], v[92:95], v[148:151]
	s_setprio 0
	s_setprio 1
	v_mfma_f32_16x16x32_bf16 v[28:31], v[136:139], v[64:67], v[28:31]
	v_mfma_f32_16x16x32_bf16 v[24:27], v[222:225], v[64:67], v[24:27]
	v_mfma_f32_16x16x32_bf16 v[20:23], v[136:139], v[72:75], v[20:23]
	v_mfma_f32_16x16x32_bf16 v[64:67], v[222:225], v[72:75], v[16:19]
	v_mfma_f32_16x16x32_bf16 v[12:15], v[136:139], v[80:83], v[12:15]
	v_mfma_f32_16x16x32_bf16 v[8:11], v[222:225], v[80:83], v[8:11]
	v_mfma_f32_16x16x32_bf16 v[72:75], v[136:139], v[88:91], v[4:7]
	v_mfma_f32_16x16x32_bf16 v[80:83], v[222:225], v[88:91], v[0:3]
	v_mfma_f32_16x16x32_bf16 v[0:3], v[218:221], v[68:71], v[28:31]
	v_mfma_f32_16x16x32_bf16 v[4:7], v[226:229], v[68:71], v[24:27]
	v_mfma_f32_16x16x32_bf16 v[16:19], v[218:221], v[76:79], v[20:23]
	v_mfma_f32_16x16x32_bf16 v[20:23], v[226:229], v[76:79], v[64:67]
	v_mfma_f32_16x16x32_bf16 v[24:27], v[218:221], v[84:87], v[12:15]
	v_mfma_f32_16x16x32_bf16 v[28:31], v[226:229], v[84:87], v[8:11]
	v_mfma_f32_16x16x32_bf16 v[64:67], v[218:221], v[92:95], v[72:75]
	v_mfma_f32_16x16x32_bf16 v[68:71], v[226:229], v[92:95], v[80:83]
	s_setprio 0
	s_barrier
	ds_read_b128 v[12:15], v130
	ds_read_b128 v[8:11], v130 offset:1024
	ds_read_b128 v[76:79], v130 offset:2048
	ds_read_b128 v[72:75], v130 offset:3072
	ds_read_b128 v[140:143], v193 offset:32768
	ds_read_b128 v[148:151], v193 offset:33792
	ds_read_b128 v[218:221], v192 offset:32768
	ds_read_b128 v[222:225], v192 offset:33792
	ds_read_b128 v[226:229], v191 offset:32768
	ds_read_b128 v[230:233], v191 offset:33792
	ds_read_b128 v[234:237], v190 offset:32768
	ds_read_b128 v[238:241], v190 offset:33792
	s_waitcnt vmcnt(2)
	s_barrier
	s_waitcnt lgkmcnt(0)
	s_setprio 1
	s_waitcnt lgkmcnt(0)
	v_mfma_f32_16x16x32_bf16 v[80:83], v[12:15], v[140:143], v[124:127]
	v_mfma_f32_16x16x32_bf16 v[84:87], v[76:79], v[140:143], v[120:123]
	v_mfma_f32_16x16x32_bf16 v[88:91], v[12:15], v[218:221], v[116:119]
	v_mfma_f32_16x16x32_bf16 v[92:95], v[76:79], v[218:221], v[112:115]
	v_mfma_f32_16x16x32_bf16 v[108:111], v[12:15], v[226:229], v[108:111]
	v_mfma_f32_16x16x32_bf16 v[104:107], v[76:79], v[226:229], v[104:107]
	v_mfma_f32_16x16x32_bf16 v[100:103], v[12:15], v[234:237], v[100:103]
	v_mfma_f32_16x16x32_bf16 v[96:99], v[76:79], v[234:237], v[96:99]
	v_mfma_f32_16x16x32_bf16 v[152:155], v[8:11], v[148:151], v[80:83]
	v_mfma_f32_16x16x32_bf16 v[144:147], v[72:75], v[148:151], v[84:87]
	v_mfma_f32_16x16x32_bf16 v[136:139], v[8:11], v[222:225], v[88:91]
	v_mfma_f32_16x16x32_bf16 v[128:131], v[72:75], v[222:225], v[92:95]
	v_mfma_f32_16x16x32_bf16 v[120:123], v[8:11], v[230:233], v[108:111]
	v_mfma_f32_16x16x32_bf16 v[112:115], v[72:75], v[230:233], v[104:107]
	v_mfma_f32_16x16x32_bf16 v[104:107], v[8:11], v[238:241], v[100:103]
	v_mfma_f32_16x16x32_bf16 v[96:99], v[72:75], v[238:241], v[96:99]
	s_setprio 0
	s_barrier
	ds_read_b128 v[88:91], v132
	ds_read_b128 v[80:83], v132 offset:1024
	ds_read_b128 v[92:95], v132 offset:2048
	ds_read_b128 v[84:87], v132 offset:3072
	s_waitcnt vmcnt(0)
	s_barrier
	s_waitcnt lgkmcnt(0)
	s_setprio 1
	s_waitcnt lgkmcnt(0)
	v_mfma_f32_16x16x32_bf16 v[100:103], v[88:91], v[140:143], v[156:159]
	v_mfma_f32_16x16x32_bf16 v[108:111], v[92:95], v[140:143], v[160:163]
	v_mfma_f32_16x16x32_bf16 v[116:119], v[88:91], v[218:221], v[194:197]
	v_mfma_f32_16x16x32_bf16 v[124:127], v[92:95], v[218:221], v[198:201]
	v_mfma_f32_16x16x32_bf16 v[160:163], v[88:91], v[226:229], v[202:205]
	v_mfma_f32_16x16x32_bf16 v[194:197], v[92:95], v[226:229], v[206:209]
	v_mfma_f32_16x16x32_bf16 v[198:201], v[88:91], v[234:237], v[210:213]
	v_mfma_f32_16x16x32_bf16 v[202:205], v[92:95], v[234:237], v[214:217]
	v_mfma_f32_16x16x32_bf16 v[156:159], v[80:83], v[148:151], v[100:103]
	v_mfma_f32_16x16x32_bf16 v[148:151], v[84:87], v[148:151], v[108:111]
	v_mfma_f32_16x16x32_bf16 v[140:143], v[80:83], v[222:225], v[116:119]
	v_mfma_f32_16x16x32_bf16 v[132:135], v[84:87], v[222:225], v[124:127]
	v_mfma_f32_16x16x32_bf16 v[124:127], v[80:83], v[230:233], v[160:163]
	v_mfma_f32_16x16x32_bf16 v[116:119], v[84:87], v[230:233], v[194:197]
	v_mfma_f32_16x16x32_bf16 v[108:111], v[80:83], v[238:241], v[198:201]
	v_mfma_f32_16x16x32_bf16 v[100:103], v[84:87], v[238:241], v[202:205]
	s_setprio 0
	s_lshl_b64 s[56:57], s[46:47], 2
	s_barrier
	v_mbcnt_lo_u32_b32 v162, -1, 0
	v_mbcnt_hi_u32_b32 v162, -1, v162
	s_add_u32 s56, s87, s56
	v_add_u32_e32 v160, s64, v162
	s_addc_u32 s57, s88, s57
	v_and_b32_e32 v164, 0x100, v160
	v_and_b32_e32 v162, 15, v162
	v_lshl_add_u64 v[160:161], s[56:57], 0, v[164:165]
	v_lshlrev_b32_e32 v164, 2, v162
	v_lshl_add_u64 v[160:161], v[160:161], 0, v[164:165]
	global_load_dword v180, v[160:161], off
	global_load_dword v178, v[160:161], off offset:64
	global_load_dword v176, v[160:161], off offset:128
	global_load_dword v174, v[160:161], off offset:192
	global_load_dword v172, v[160:161], off offset:512
	global_load_dword v170, v[160:161], off offset:576
	global_load_dword v168, v[160:161], off offset:640
	global_load_dword v166, v[160:161], off offset:704
	v_mbcnt_lo_u32_b32 v194, -1, 0
	v_mbcnt_hi_u32_b32 v194, -1, v194
	s_cmp_lg_u32 s79, 0
	v_add_u32_e32 v160, s64, v194
	v_bfe_u32 v196, v160, 8, 1
	v_ashrrev_i32_e32 v199, 6, v160
	v_bfe_u32 v160, v194, 4, 2
	s_cselect_b64 s[56:57], -1, 0
	v_and_b32_e32 v197, 3, v199
	v_and_b32_e32 v195, 15, v194
	s_and_b64 vcc, exec, s[56:57]
	v_lshlrev_b32_e32 v198, 4, v160
	s_cbranch_vccz .LBB0_533
	s_lshl_b32 s14, s78, 22
	s_lshl_b32 s36, s80, 14
	s_add_i32 s36, s36, s14
	v_lshlrev_b32_e32 v160, 6, v195
	v_or3_b32 v160, s36, v160, v198
	v_lshl_add_u32 v160, v197, 20, v160
	v_lshl_or_b32 v164, v196, 12, v160
	s_waitcnt vmcnt(0)
	v_pk_mul_f32 v[160:161], v[154:155], v[180:181] op_sel_hi:[1,0]
	v_pk_mul_f32 v[200:201], v[146:147], v[180:181] op_sel_hi:[1,0]
	v_max_f32_e32 v160, 0, v160
	v_mul_f32_e32 v204, v160, v160
	v_max_f32_e32 v160, 0, v200
	v_pk_mul_f32 v[162:163], v[152:153], v[180:181] op_sel_hi:[1,0]
	v_mul_f32_e32 v200, v160, v160
	v_max_f32_e32 v160, 0, v161
	v_pk_mul_f32 v[202:203], v[144:145], v[180:181] op_sel_hi:[1,0]
	v_max_f32_e32 v162, 0, v162
	v_max_f32_e32 v163, 0, v163
	v_mul_f32_e32 v161, v160, v160
	v_max_f32_e32 v160, 0, v201
	v_mul_f32_e32 v162, v162, v162
	v_max_f32_e32 v202, 0, v202
	v_mul_f32_e32 v163, v163, v163
	v_max_f32_e32 v203, 0, v203
	v_mul_f32_e32 v201, v160, v160
	v_cvt_pk_bf16_f32 v160, v162, v163
	v_cvt_pk_bf16_f32 v161, v204, v161
	v_mul_f32_e32 v202, v202, v202
	v_mul_f32_e32 v203, v203, v203
	v_cvt_pk_bf16_f32 v162, v202, v203
	v_cvt_pk_bf16_f32 v163, v200, v201
	global_store_dwordx4 v164, v[160:163], s[0:1]
	v_pk_mul_f32 v[202:203], v[150:151], v[180:181] op_sel_hi:[1,0]
	v_lshl_add_u64 v[200:201], s[0:1], 0, v[164:165]
	v_pk_mul_f32 v[160:161], v[158:159], v[180:181] op_sel_hi:[1,0]
	v_pk_mul_f32 v[162:163], v[156:157], v[180:181] op_sel_hi:[1,0]
	v_max_f32_e32 v160, 0, v160
	v_mul_f32_e32 v206, v160, v160
	v_max_f32_e32 v160, 0, v202
	v_mul_f32_e32 v202, v160, v160
	v_max_f32_e32 v160, 0, v161
	v_pk_mul_f32 v[204:205], v[148:149], v[180:181] op_sel_hi:[1,0]
	v_max_f32_e32 v162, 0, v162
	v_max_f32_e32 v163, 0, v163
	v_mul_f32_e32 v161, v160, v160
	v_max_f32_e32 v160, 0, v203
	v_add_co_u32_e32 v200, vcc, s72, v200
	v_mul_f32_e32 v162, v162, v162
	v_max_f32_e32 v204, 0, v204
	v_mul_f32_e32 v163, v163, v163
	v_max_f32_e32 v205, 0, v205
	v_mul_f32_e32 v203, v160, v160
	v_cvt_pk_bf16_f32 v160, v162, v163
	v_cvt_pk_bf16_f32 v161, v206, v161
	v_addc_co_u32_e32 v201, vcc, 0, v201, vcc
	v_mul_f32_e32 v204, v204, v204
	v_mul_f32_e32 v205, v205, v205
	v_cvt_pk_bf16_f32 v162, v204, v205
	v_cvt_pk_bf16_f32 v163, v202, v203
	global_store_dwordx4 v[200:201], v[160:163], off
	v_pk_mul_f32 v[202:203], v[130:131], v[178:179] op_sel_hi:[1,0]
	v_pk_mul_f32 v[204:205], v[128:129], v[178:179] op_sel_hi:[1,0]
	v_pk_mul_f32 v[160:161], v[138:139], v[178:179] op_sel_hi:[1,0]
	v_pk_mul_f32 v[162:163], v[136:137], v[178:179] op_sel_hi:[1,0]
	v_max_f32_e32 v160, 0, v160
	v_mul_f32_e32 v206, v160, v160
	v_max_f32_e32 v160, 0, v202
	v_mul_f32_e32 v202, v160, v160
	v_max_f32_e32 v160, 0, v161
	v_max_f32_e32 v162, 0, v162
	v_max_f32_e32 v163, 0, v163
	v_mul_f32_e32 v161, v160, v160
	v_max_f32_e32 v160, 0, v203
	v_mul_f32_e32 v162, v162, v162
	v_max_f32_e32 v204, 0, v204
	v_mul_f32_e32 v163, v163, v163
	v_max_f32_e32 v205, 0, v205
	v_mul_f32_e32 v203, v160, v160
	v_cvt_pk_bf16_f32 v160, v162, v163
	v_cvt_pk_bf16_f32 v161, v206, v161
	v_mul_f32_e32 v204, v204, v204
	v_mul_f32_e32 v205, v205, v205
	v_cvt_pk_bf16_f32 v162, v204, v205
	v_cvt_pk_bf16_f32 v163, v202, v203
	global_store_dwordx4 v164, v[160:163], s[0:1] offset:1024
	v_pk_mul_f32 v[202:203], v[134:135], v[178:179] op_sel_hi:[1,0]
	v_pk_mul_f32 v[204:205], v[132:133], v[178:179] op_sel_hi:[1,0]
	v_pk_mul_f32 v[160:161], v[142:143], v[178:179] op_sel_hi:[1,0]
	v_pk_mul_f32 v[162:163], v[140:141], v[178:179] op_sel_hi:[1,0]
	v_max_f32_e32 v160, 0, v160
	v_mul_f32_e32 v206, v160, v160
	v_max_f32_e32 v160, 0, v202
	v_mul_f32_e32 v202, v160, v160
	v_max_f32_e32 v160, 0, v161
	v_max_f32_e32 v162, 0, v162
	v_max_f32_e32 v163, 0, v163
	v_mul_f32_e32 v161, v160, v160
	v_max_f32_e32 v160, 0, v203
	v_mul_f32_e32 v162, v162, v162
	v_max_f32_e32 v204, 0, v204
	v_mul_f32_e32 v163, v163, v163
	v_max_f32_e32 v205, 0, v205
	v_mul_f32_e32 v203, v160, v160
	v_cvt_pk_bf16_f32 v160, v162, v163
	v_cvt_pk_bf16_f32 v161, v206, v161
	v_mul_f32_e32 v204, v204, v204
	v_mul_f32_e32 v205, v205, v205
	v_cvt_pk_bf16_f32 v162, v204, v205
	v_cvt_pk_bf16_f32 v163, v202, v203
	global_store_dwordx4 v[200:201], v[160:163], off offset:1024
	v_pk_mul_f32 v[202:203], v[114:115], v[176:177] op_sel_hi:[1,0]
	v_pk_mul_f32 v[204:205], v[112:113], v[176:177] op_sel_hi:[1,0]
	v_pk_mul_f32 v[160:161], v[122:123], v[176:177] op_sel_hi:[1,0]
	v_pk_mul_f32 v[162:163], v[120:121], v[176:177] op_sel_hi:[1,0]
	v_max_f32_e32 v160, 0, v160
	v_mul_f32_e32 v206, v160, v160
	v_max_f32_e32 v160, 0, v202
	v_mul_f32_e32 v202, v160, v160
	v_max_f32_e32 v160, 0, v161
	v_max_f32_e32 v162, 0, v162
	v_max_f32_e32 v163, 0, v163
	v_mul_f32_e32 v161, v160, v160
	v_max_f32_e32 v160, 0, v203
	v_mul_f32_e32 v162, v162, v162
	v_max_f32_e32 v204, 0, v204
	v_mul_f32_e32 v163, v163, v163
	v_max_f32_e32 v205, 0, v205
	v_mul_f32_e32 v203, v160, v160
	v_cvt_pk_bf16_f32 v160, v162, v163
	v_cvt_pk_bf16_f32 v161, v206, v161
	v_mul_f32_e32 v204, v204, v204
	v_mul_f32_e32 v205, v205, v205
	v_cvt_pk_bf16_f32 v162, v204, v205
	v_cvt_pk_bf16_f32 v163, v202, v203
	global_store_dwordx4 v164, v[160:163], s[0:1] offset:2048
	v_pk_mul_f32 v[202:203], v[118:119], v[176:177] op_sel_hi:[1,0]
	v_pk_mul_f32 v[204:205], v[116:117], v[176:177] op_sel_hi:[1,0]
	v_pk_mul_f32 v[160:161], v[126:127], v[176:177] op_sel_hi:[1,0]
	v_pk_mul_f32 v[162:163], v[124:125], v[176:177] op_sel_hi:[1,0]
	v_max_f32_e32 v160, 0, v160
	v_mul_f32_e32 v206, v160, v160
	v_max_f32_e32 v160, 0, v202
	v_mul_f32_e32 v202, v160, v160
	v_max_f32_e32 v160, 0, v161
	v_max_f32_e32 v162, 0, v162
	v_max_f32_e32 v163, 0, v163
	v_mul_f32_e32 v161, v160, v160
	v_max_f32_e32 v160, 0, v203
	v_mul_f32_e32 v162, v162, v162
	v_max_f32_e32 v204, 0, v204
	v_mul_f32_e32 v163, v163, v163
	v_max_f32_e32 v205, 0, v205
	v_mul_f32_e32 v203, v160, v160
	v_cvt_pk_bf16_f32 v160, v162, v163
	v_cvt_pk_bf16_f32 v161, v206, v161
	v_mul_f32_e32 v204, v204, v204
	v_mul_f32_e32 v205, v205, v205
	v_cvt_pk_bf16_f32 v162, v204, v205
	v_cvt_pk_bf16_f32 v163, v202, v203
	global_store_dwordx4 v[200:201], v[160:163], off offset:2048
	v_pk_mul_f32 v[200:201], v[98:99], v[174:175] op_sel_hi:[1,0]
	v_pk_mul_f32 v[202:203], v[96:97], v[174:175] op_sel_hi:[1,0]
	v_pk_mul_f32 v[160:161], v[106:107], v[174:175] op_sel_hi:[1,0]
	v_pk_mul_f32 v[162:163], v[104:105], v[174:175] op_sel_hi:[1,0]
	v_max_f32_e32 v160, 0, v160
	v_mul_f32_e32 v204, v160, v160
	v_max_f32_e32 v160, 0, v200
	v_mul_f32_e32 v200, v160, v160
	v_max_f32_e32 v160, 0, v161
	v_max_f32_e32 v162, 0, v162
	v_max_f32_e32 v163, 0, v163
	v_mul_f32_e32 v161, v160, v160
	v_max_f32_e32 v160, 0, v201
	v_mul_f32_e32 v162, v162, v162
	v_max_f32_e32 v202, 0, v202
	v_mul_f32_e32 v163, v163, v163
	v_max_f32_e32 v203, 0, v203
	v_mul_f32_e32 v201, v160, v160
	v_cvt_pk_bf16_f32 v160, v162, v163
	v_cvt_pk_bf16_f32 v161, v204, v161
	v_mul_f32_e32 v202, v202, v202
	v_mul_f32_e32 v203, v203, v203
	v_cvt_pk_bf16_f32 v162, v202, v203
	v_cvt_pk_bf16_f32 v163, v200, v201
	global_store_dwordx4 v164, v[160:163], s[0:1] offset:3072
	v_pk_mul_f32 v[200:201], v[102:103], v[174:175] op_sel_hi:[1,0]
	v_pk_mul_f32 v[202:203], v[100:101], v[174:175] op_sel_hi:[1,0]
	v_pk_mul_f32 v[160:161], v[110:111], v[174:175] op_sel_hi:[1,0]
	v_pk_mul_f32 v[162:163], v[108:109], v[174:175] op_sel_hi:[1,0]
	v_max_f32_e32 v160, 0, v160
	v_mul_f32_e32 v204, v160, v160
	v_max_f32_e32 v160, 0, v200
	v_max_f32_e32 v162, 0, v162
	v_max_f32_e32 v163, 0, v163
	v_mul_f32_e32 v200, v160, v160
	v_max_f32_e32 v160, 0, v161
	v_mul_f32_e32 v162, v162, v162
	v_max_f32_e32 v202, 0, v202
	v_mul_f32_e32 v163, v163, v163
	v_max_f32_e32 v203, 0, v203
	v_mul_f32_e32 v161, v160, v160
	v_max_f32_e32 v160, 0, v201
	v_mul_f32_e32 v202, v202, v202
	v_mul_f32_e32 v203, v203, v203
	v_mul_f32_e32 v201, v160, v160
	v_cvt_pk_bf16_f32 v160, v162, v163
	v_cvt_pk_bf16_f32 v161, v204, v161
	v_cvt_pk_bf16_f32 v162, v202, v203
	v_cvt_pk_bf16_f32 v163, v200, v201
	v_add_u32_e32 v164, 0x80c00, v164
	s_cbranch_execnz .LBB0_525

.LBB0_560:
	v_and_b32_e32 v2, 15, v0
	s_bfe_u32 s66, s86, 0x30003
	v_and_b32_e32 v3, 48, v0
	v_lshlrev_b32_e32 v134, 4, v135
	v_and_b32_e32 v5, 32, v0
	s_movk_i32 s37, 0x3f0
	v_lshlrev_b32_e32 v2, 6, v2
	v_lshlrev_b32_e32 v9, 2, v0
	s_lshl_b32 s36, s66, 14
	v_bitop3_b32 v155, v134, v5, s37 bitop3:0x6c
	v_and_b32_e32 v6, 64, v135
	s_add_i32 s67, s20, -2
	v_or_b32_e32 v8, v2, v3
	v_and_b32_e32 v9, 32, v9
	s_mov_b32 s37, 0x14000
	v_lshlrev_b32_e32 v0, 6, v0
	v_and_b32_e32 v4, 0x3f0, v134
	v_lshlrev_b32_e32 v156, 13, v6
	v_lshlrev_b32_e32 v7, 3, v135
	v_mul_i32_i24_e32 v6, 0xffffe800, v6
	v_bitop3_b32 v11, v8, s37, v9 bitop3:0xde
	s_mov_b32 s37, 0x1c000
	v_and_b32_e32 v0, 0x3c0, v0
	s_add_u32 s68, s72, s36
	v_and_b32_e32 v157, 0xfffffc00, v7
	v_bitop3_b32 v2, v2, v9, v3 bitop3:0x36
	v_bitop3_b32 v10, v8, s76, v9 bitop3:0xde
	v_bitop3_b32 v12, v8, s77, v9 bitop3:0xde
	v_bitop3_b32 v8, v8, s37, v9 bitop3:0xde
	v_bitop3_b32 v3, v0, v9, v3 bitop3:0x36
	v_bitop3_b32 v0, v6, v4, v5 bitop3:0xf6
	s_addc_u32 s69, s73, 0
	s_lshl_b32 s36, s86, 11
	s_and_b32 s37, s86, 7
	v_add3_u32 v128, v0, v156, v157
	s_and_b32 s36, s36, 0x60000
	s_lshl_b32 s37, s37, 14
	v_lshlrev_b32_e32 v13, 13, v1
	v_lshl_add_u64 v[0:1], s[68:69], 0, v[128:129]
	s_mov_b64 s[68:69], 0xc3000
	s_or_b32 s36, s36, s37
	v_lshl_add_u64 v[130:131], v[0:1], 0, s[68:69]
	v_bitop3_b32 v0, v4, v156, v5 bitop3:0xde
	s_add_u32 s68, s70, s36
	v_add_u32_e32 v128, v0, v157
	s_addc_u32 s69, s71, 0
	v_lshlrev_b32_e32 v7, 6, v135
	v_lshl_add_u64 v[0:1], s[68:69], 0, v[128:129]
	s_mov_b64 s[68:69], 0x301000
	v_and_b32_e32 v7, 0x3000, v7
	v_or_b32_e32 v9, 0x800, v13
	v_or_b32_e32 v14, 0x1000, v13
	v_or_b32_e32 v15, 0x1800, v13
	v_lshl_add_u64 v[132:133], v[0:1], 0, s[68:69]
	v_mov_b32_e32 v0, 0
	s_mov_b32 s68, 0
	v_add_u32_e32 v161, v10, v7
	v_add_u32_e32 v152, v2, v13
	v_add_u32_e32 v151, v3, v9
	v_add_u32_e32 v150, v3, v14
	v_add_u32_e32 v149, v3, v15
	v_add_u32_e32 v160, 0xc000, v134
	v_add_u32_e32 v159, 0xe000, v134
	v_add_u32_e32 v158, v11, v7
	v_add_u32_e32 v148, 0x10000, v134
	v_add_u32_e32 v147, 0x12000, v134
	v_add_u32_e32 v146, 0x2000, v134
	v_add_u32_e32 v145, 0x14000, v134
	v_add_u32_e32 v144, 0x16000, v134
	v_add_u32_e32 v154, v12, v7
	v_add_u32_e32 v143, 0x4000, v134
	v_add_u32_e32 v142, 0x6000, v134
	v_add_u32_e32 v153, v8, v7
	v_add_u32_e32 v141, 0x18000, v134
	v_add_u32_e32 v140, 0x1a000, v134
	v_add_u32_e32 v139, 0x8000, v134
	v_add_u32_e32 v138, 0xa000, v134
	v_add_u32_e32 v137, 0x1c000, v134
	v_add_u32_e32 v136, 0x1e000, v134
	v_mov_b32_e32 v1, v0
	v_mov_b32_e32 v2, v0
	v_mov_b32_e32 v3, v0
	v_mov_b32_e32 v4, v0
	v_mov_b32_e32 v5, v0
	v_mov_b32_e32 v6, v0
	v_mov_b32_e32 v7, v0
	v_mov_b32_e32 v8, v0
	v_mov_b32_e32 v9, v0
	v_mov_b32_e32 v10, v0
	v_mov_b32_e32 v11, v0
	v_mov_b32_e32 v12, v0
	v_mov_b32_e32 v13, v0
	v_mov_b32_e32 v14, v0
	v_mov_b32_e32 v15, v0
	v_mov_b32_e32 v16, v0
	v_mov_b32_e32 v17, v0
	v_mov_b32_e32 v18, v0
	v_mov_b32_e32 v19, v0
	v_mov_b32_e32 v20, v0
	v_mov_b32_e32 v21, v0
	v_mov_b32_e32 v22, v0
	v_mov_b32_e32 v23, v0
	v_mov_b32_e32 v24, v0
	v_mov_b32_e32 v25, v0
	v_mov_b32_e32 v26, v0
	v_mov_b32_e32 v27, v0
	v_mov_b32_e32 v28, v0
	v_mov_b32_e32 v29, v0
	v_mov_b32_e32 v30, v0
	v_mov_b32_e32 v31, v0
	v_mov_b32_e32 v32, v0
	v_mov_b32_e32 v33, v0
	v_mov_b32_e32 v34, v0
	v_mov_b32_e32 v35, v0
	v_mov_b32_e32 v36, v0
	v_mov_b32_e32 v37, v0
	v_mov_b32_e32 v38, v0
	v_mov_b32_e32 v39, v0
	v_mov_b32_e32 v40, v0
	v_mov_b32_e32 v41, v0
	v_mov_b32_e32 v42, v0
	v_mov_b32_e32 v43, v0
	v_mov_b32_e32 v44, v0
	v_mov_b32_e32 v45, v0
	v_mov_b32_e32 v46, v0
	v_mov_b32_e32 v47, v0
	v_mov_b32_e32 v48, v0
	v_mov_b32_e32 v49, v0
	v_mov_b32_e32 v50, v0
	v_mov_b32_e32 v51, v0
	v_mov_b32_e32 v52, v0
	v_mov_b32_e32 v53, v0
	v_mov_b32_e32 v54, v0
	v_mov_b32_e32 v55, v0
	v_mov_b32_e32 v56, v0
	v_mov_b32_e32 v57, v0
	v_mov_b32_e32 v58, v0
	v_mov_b32_e32 v59, v0
	v_mov_b32_e32 v60, v0
	v_mov_b32_e32 v61, v0
	v_mov_b32_e32 v62, v0
	v_mov_b32_e32 v63, v0
	v_mov_b32_e32 v64, v0
	v_mov_b32_e32 v65, v0
	v_mov_b32_e32 v66, v0
	v_mov_b32_e32 v67, v0
	v_mov_b32_e32 v68, v0
	v_mov_b32_e32 v69, v0
	v_mov_b32_e32 v70, v0
	v_mov_b32_e32 v71, v0
	v_mov_b32_e32 v72, v0
	v_mov_b32_e32 v73, v0
	v_mov_b32_e32 v74, v0
	v_mov_b32_e32 v75, v0
	v_mov_b32_e32 v76, v0
	v_mov_b32_e32 v77, v0
	v_mov_b32_e32 v78, v0
	v_mov_b32_e32 v79, v0
	v_mov_b32_e32 v80, v0
	v_mov_b32_e32 v81, v0
	v_mov_b32_e32 v82, v0
	v_mov_b32_e32 v83, v0
	v_mov_b32_e32 v84, v0
	v_mov_b32_e32 v85, v0
	v_mov_b32_e32 v86, v0
	v_mov_b32_e32 v87, v0
	v_mov_b32_e32 v88, v0
	v_mov_b32_e32 v89, v0
	v_mov_b32_e32 v90, v0
	v_mov_b32_e32 v91, v0
	v_mov_b32_e32 v92, v0
	v_mov_b32_e32 v93, v0
	v_mov_b32_e32 v94, v0
	v_mov_b32_e32 v95, v0
	v_mov_b32_e32 v96, v0
	v_mov_b32_e32 v97, v0
	v_mov_b32_e32 v98, v0
	v_mov_b32_e32 v99, v0
	v_mov_b32_e32 v100, v0
	v_mov_b32_e32 v101, v0
	v_mov_b32_e32 v102, v0
	v_mov_b32_e32 v103, v0
	v_mov_b32_e32 v104, v0
	v_mov_b32_e32 v105, v0
	v_mov_b32_e32 v106, v0
	v_mov_b32_e32 v107, v0
	v_mov_b32_e32 v108, v0
	v_mov_b32_e32 v109, v0
	v_mov_b32_e32 v110, v0
	v_mov_b32_e32 v111, v0
	v_mov_b32_e32 v112, v0
	v_mov_b32_e32 v113, v0
	v_mov_b32_e32 v114, v0
	v_mov_b32_e32 v115, v0
	v_mov_b32_e32 v116, v0
	v_mov_b32_e32 v117, v0
	v_mov_b32_e32 v118, v0
	v_mov_b32_e32 v119, v0
	v_mov_b32_e32 v120, v0
	v_mov_b32_e32 v121, v0
	v_mov_b32_e32 v122, v0
	v_mov_b32_e32 v123, v0
	v_mov_b32_e32 v124, v0
	v_mov_b32_e32 v125, v0
	v_mov_b32_e32 v126, v0
	v_mov_b32_e32 v127, v0
	s_barrier
	v_readlane_b32 s98, v242, 1
	s_nop 3
	s_cmp_lt_u32 s98, 4
	s_cbranch_scc1 .Lprio_561
	s_setprio 1
.Lprio_561:
	v_readfirstlane_b32 s36, v160
	v_lshl_add_u64 v[164:165], v[132:133], 0, s[22:23]
	s_mov_b32 m0, s36
	v_readfirstlane_b32 s36, v159
	global_load_lds_dwordx4 v[164:165], off
	v_lshl_add_u64 v[164:165], v[132:133], 0, s[24:25]
	s_mov_b32 m0, s36
	s_nop 0
	global_load_lds_dwordx4 v[164:165], off
.LBB0_561:
	ds_read_b128 v[162:165], v161
	ds_read_b128 v[166:169], v161 offset:1024
	ds_read_b128 v[170:173], v161 offset:2048
	ds_read_b128 v[174:177], v161 offset:3072
	ds_read_b128 v[178:181], v152
	ds_read_b128 v[182:185], v152 offset:1024
	ds_read_b128 v[186:189], v151
	ds_read_b128 v[190:193], v151 offset:1024
	ds_read_b128 v[194:197], v150
	ds_read_b128 v[198:201], v150 offset:1024
	ds_read_b128 v[202:205], v149
	ds_read_b128 v[206:209], v149 offset:1024
	s_waitcnt lgkmcnt(8)
	s_waitcnt vmcnt(10)
	s_barrier
	s_waitcnt lgkmcnt(0)
	s_waitcnt lgkmcnt(0)
	v_mfma_f32_16x16x32_bf16 v[124:127], v[162:165], v[178:181], v[124:127]
	v_mfma_f32_16x16x32_bf16 v[120:123], v[170:173], v[178:181], v[120:123]
	v_mfma_f32_16x16x32_bf16 v[116:119], v[162:165], v[186:189], v[116:119]
	v_mfma_f32_16x16x32_bf16 v[112:115], v[170:173], v[186:189], v[112:115]
	v_mfma_f32_16x16x32_bf16 v[108:111], v[162:165], v[194:197], v[108:111]
	v_mfma_f32_16x16x32_bf16 v[104:107], v[170:173], v[194:197], v[104:107]
	v_mfma_f32_16x16x32_bf16 v[100:103], v[162:165], v[202:205], v[100:103]
	v_mfma_f32_16x16x32_bf16 v[96:99], v[170:173], v[202:205], v[96:99]
	v_mfma_f32_16x16x32_bf16 v[124:127], v[166:169], v[182:185], v[124:127]
	v_mfma_f32_16x16x32_bf16 v[120:123], v[174:177], v[182:185], v[120:123]
	v_mfma_f32_16x16x32_bf16 v[116:119], v[166:169], v[190:193], v[116:119]
	v_mfma_f32_16x16x32_bf16 v[112:115], v[174:177], v[190:193], v[112:115]
	v_mfma_f32_16x16x32_bf16 v[108:111], v[166:169], v[198:201], v[108:111]
	v_mfma_f32_16x16x32_bf16 v[104:107], v[174:177], v[198:201], v[104:107]
	v_mfma_f32_16x16x32_bf16 v[100:103], v[166:169], v[206:209], v[100:103]
	v_mfma_f32_16x16x32_bf16 v[96:99], v[174:177], v[206:209], v[96:99]
	s_barrier
	v_readfirstlane_b32 s36, v148
	v_lshl_add_u64 v[226:227], v[130:131], 0, s[26:27]
	s_mov_b32 m0, s36
	v_readfirstlane_b32 s36, v147
	ds_read_b128 v[210:213], v158
	ds_read_b128 v[214:217], v158 offset:1024
	ds_read_b128 v[218:221], v158 offset:2048
	ds_read_b128 v[222:225], v158 offset:3072
	global_load_lds_dwordx4 v[226:227], off
	v_lshl_add_u64 v[226:227], v[130:131], 0, s[28:29]
	s_mov_b32 m0, s36
	s_add_i32 s68, s68, 2
	global_load_lds_dwordx4 v[226:227], off
	v_readfirstlane_b32 s36, v134
	v_lshl_add_u64 v[226:227], v[132:133], 0, s[30:31]
	s_mov_b32 m0, s36
	v_readfirstlane_b32 s36, v146
	global_load_lds_dwordx4 v[226:227], off
	v_lshl_add_u64 v[226:227], v[132:133], 0, s[34:35]
	s_mov_b32 m0, s36
	s_nop 0
	global_load_lds_dwordx4 v[226:227], off
	s_waitcnt vmcnt(12)
	s_barrier
	s_waitcnt lgkmcnt(0)
	s_waitcnt lgkmcnt(0)
	v_mfma_f32_16x16x32_bf16 v[92:95], v[210:213], v[178:181], v[92:95]
	v_mfma_f32_16x16x32_bf16 v[88:91], v[218:221], v[178:181], v[88:91]
	v_mfma_f32_16x16x32_bf16 v[84:87], v[210:213], v[186:189], v[84:87]
	v_mfma_f32_16x16x32_bf16 v[80:83], v[218:221], v[186:189], v[80:83]
	v_mfma_f32_16x16x32_bf16 v[76:79], v[210:213], v[194:197], v[76:79]
	v_mfma_f32_16x16x32_bf16 v[72:75], v[218:221], v[194:197], v[72:75]
	v_mfma_f32_16x16x32_bf16 v[68:71], v[210:213], v[202:205], v[68:71]
	v_mfma_f32_16x16x32_bf16 v[64:67], v[218:221], v[202:205], v[64:67]
	v_mfma_f32_16x16x32_bf16 v[92:95], v[214:217], v[182:185], v[92:95]
	v_mfma_f32_16x16x32_bf16 v[88:91], v[222:225], v[182:185], v[88:91]
	v_mfma_f32_16x16x32_bf16 v[84:87], v[214:217], v[190:193], v[84:87]
	v_mfma_f32_16x16x32_bf16 v[80:83], v[222:225], v[190:193], v[80:83]
	v_mfma_f32_16x16x32_bf16 v[76:79], v[214:217], v[198:201], v[76:79]
	v_mfma_f32_16x16x32_bf16 v[72:75], v[222:225], v[198:201], v[72:75]
	v_mfma_f32_16x16x32_bf16 v[68:71], v[214:217], v[206:209], v[68:71]
	v_mfma_f32_16x16x32_bf16 v[64:67], v[222:225], v[206:209], v[64:67]
	s_barrier
	ds_read_b128 v[178:181], v152 offset:16384
	ds_read_b128 v[182:185], v152 offset:17408
	ds_read_b128 v[186:189], v151 offset:16384
	ds_read_b128 v[190:193], v151 offset:17408
	ds_read_b128 v[194:197], v150 offset:16384
	ds_read_b128 v[198:201], v150 offset:17408
	ds_read_b128 v[202:205], v149 offset:16384
	ds_read_b128 v[206:209], v149 offset:17408
	v_readfirstlane_b32 s36, v145
	v_lshl_add_u64 v[226:227], v[130:131], 0, s[38:39]
	s_mov_b32 m0, s36
	v_readfirstlane_b32 s36, v144
	global_load_lds_dwordx4 v[226:227], off
	v_lshl_add_u64 v[226:227], v[130:131], 0, s[44:45]
	s_mov_b32 m0, s36
	s_nop 0
	global_load_lds_dwordx4 v[226:227], off
	s_barrier
	s_waitcnt lgkmcnt(0)
	s_waitcnt lgkmcnt(0)
	v_mfma_f32_16x16x32_bf16 v[60:63], v[162:165], v[178:181], v[60:63]
	v_mfma_f32_16x16x32_bf16 v[56:59], v[170:173], v[178:181], v[56:59]
	v_mfma_f32_16x16x32_bf16 v[52:55], v[162:165], v[186:189], v[52:55]
	v_mfma_f32_16x16x32_bf16 v[48:51], v[170:173], v[186:189], v[48:51]
	v_mfma_f32_16x16x32_bf16 v[44:47], v[162:165], v[194:197], v[44:47]
	v_mfma_f32_16x16x32_bf16 v[40:43], v[170:173], v[194:197], v[40:43]
	v_mfma_f32_16x16x32_bf16 v[36:39], v[162:165], v[202:205], v[36:39]
	v_mfma_f32_16x16x32_bf16 v[32:35], v[170:173], v[202:205], v[32:35]
	v_mfma_f32_16x16x32_bf16 v[60:63], v[166:169], v[182:185], v[60:63]
	v_mfma_f32_16x16x32_bf16 v[56:59], v[174:177], v[182:185], v[56:59]
	v_mfma_f32_16x16x32_bf16 v[52:55], v[166:169], v[190:193], v[52:55]
	v_mfma_f32_16x16x32_bf16 v[48:51], v[174:177], v[190:193], v[48:51]
	v_mfma_f32_16x16x32_bf16 v[44:47], v[166:169], v[198:201], v[44:47]
	v_mfma_f32_16x16x32_bf16 v[40:43], v[174:177], v[198:201], v[40:43]
	v_mfma_f32_16x16x32_bf16 v[36:39], v[166:169], v[206:209], v[36:39]
	v_mfma_f32_16x16x32_bf16 v[32:35], v[174:177], v[206:209], v[32:35]
	s_barrier
	v_readfirstlane_b32 s36, v143
	v_lshl_add_u64 v[164:165], v[132:133], 0, s[46:47]
	s_mov_b32 m0, s36
	v_readfirstlane_b32 s36, v142
	global_load_lds_dwordx4 v[164:165], off
	v_lshl_add_u64 v[164:165], v[132:133], 0, s[50:51]
	s_mov_b32 m0, s36
	s_nop 0
	global_load_lds_dwordx4 v[164:165], off
	s_waitcnt vmcnt(12)
	s_barrier
	v_mfma_f32_16x16x32_bf16 v[28:31], v[210:213], v[178:181], v[28:31]
	v_mfma_f32_16x16x32_bf16 v[24:27], v[218:221], v[178:181], v[24:27]
	v_mfma_f32_16x16x32_bf16 v[20:23], v[210:213], v[186:189], v[20:23]
	v_mfma_f32_16x16x32_bf16 v[16:19], v[218:221], v[186:189], v[16:19]
	v_mfma_f32_16x16x32_bf16 v[12:15], v[210:213], v[194:197], v[12:15]
	v_mfma_f32_16x16x32_bf16 v[8:11], v[218:221], v[194:197], v[8:11]
	v_mfma_f32_16x16x32_bf16 v[4:7], v[210:213], v[202:205], v[4:7]
	v_mfma_f32_16x16x32_bf16 v[0:3], v[218:221], v[202:205], v[0:3]
	v_mfma_f32_16x16x32_bf16 v[28:31], v[214:217], v[182:185], v[28:31]
	v_mfma_f32_16x16x32_bf16 v[24:27], v[222:225], v[182:185], v[24:27]
	v_mfma_f32_16x16x32_bf16 v[20:23], v[214:217], v[190:193], v[20:23]
	v_mfma_f32_16x16x32_bf16 v[16:19], v[222:225], v[190:193], v[16:19]
	v_mfma_f32_16x16x32_bf16 v[12:15], v[214:217], v[198:201], v[12:15]
	v_mfma_f32_16x16x32_bf16 v[8:11], v[222:225], v[198:201], v[8:11]
	v_mfma_f32_16x16x32_bf16 v[4:7], v[214:217], v[206:209], v[4:7]
	v_mfma_f32_16x16x32_bf16 v[0:3], v[222:225], v[206:209], v[0:3]
	s_barrier
	ds_read_b128 v[162:165], v154
	ds_read_b128 v[166:169], v154 offset:1024
	ds_read_b128 v[170:173], v154 offset:2048
	ds_read_b128 v[174:177], v154 offset:3072
	ds_read_b128 v[178:181], v152 offset:32768
	ds_read_b128 v[182:185], v152 offset:33792
	ds_read_b128 v[186:189], v151 offset:32768
	ds_read_b128 v[190:193], v151 offset:33792
	ds_read_b128 v[194:197], v150 offset:32768
	ds_read_b128 v[198:201], v150 offset:33792
	ds_read_b128 v[202:205], v149 offset:32768
	ds_read_b128 v[206:209], v149 offset:33792
	s_waitcnt lgkmcnt(8)
	s_waitcnt vmcnt(10)
	s_barrier
	s_waitcnt lgkmcnt(0)
	s_waitcnt lgkmcnt(0)
	v_mfma_f32_16x16x32_bf16 v[124:127], v[162:165], v[178:181], v[124:127]
	v_mfma_f32_16x16x32_bf16 v[120:123], v[170:173], v[178:181], v[120:123]
	v_mfma_f32_16x16x32_bf16 v[116:119], v[162:165], v[186:189], v[116:119]
	v_mfma_f32_16x16x32_bf16 v[112:115], v[170:173], v[186:189], v[112:115]
	v_mfma_f32_16x16x32_bf16 v[108:111], v[162:165], v[194:197], v[108:111]
	v_mfma_f32_16x16x32_bf16 v[104:107], v[170:173], v[194:197], v[104:107]
	v_mfma_f32_16x16x32_bf16 v[100:103], v[162:165], v[202:205], v[100:103]
	v_mfma_f32_16x16x32_bf16 v[96:99], v[170:173], v[202:205], v[96:99]
	v_mfma_f32_16x16x32_bf16 v[124:127], v[166:169], v[182:185], v[124:127]
	v_mfma_f32_16x16x32_bf16 v[120:123], v[174:177], v[182:185], v[120:123]
	v_mfma_f32_16x16x32_bf16 v[116:119], v[166:169], v[190:193], v[116:119]
	v_mfma_f32_16x16x32_bf16 v[112:115], v[174:177], v[190:193], v[112:115]
	v_mfma_f32_16x16x32_bf16 v[108:111], v[166:169], v[198:201], v[108:111]
	v_mfma_f32_16x16x32_bf16 v[104:107], v[174:177], v[198:201], v[104:107]
	v_mfma_f32_16x16x32_bf16 v[100:103], v[166:169], v[206:209], v[100:103]
	v_mfma_f32_16x16x32_bf16 v[96:99], v[174:177], v[206:209], v[96:99]
	s_barrier
	v_readfirstlane_b32 s36, v141
	v_lshl_add_u64 v[226:227], v[130:131], 0, s[56:57]
	s_mov_b32 m0, s36
	v_readfirstlane_b32 s36, v140
	ds_read_b128 v[210:213], v153
	ds_read_b128 v[214:217], v153 offset:1024
	ds_read_b128 v[218:221], v153 offset:2048
	ds_read_b128 v[222:225], v153 offset:3072
	global_load_lds_dwordx4 v[226:227], off
	v_lshl_add_u64 v[226:227], v[130:131], 0, s[58:59]
	s_mov_b32 m0, s36
	s_nop 0
	global_load_lds_dwordx4 v[226:227], off
	v_readfirstlane_b32 s36, v139
	v_lshl_add_u64 v[226:227], v[132:133], 0, s[60:61]
	s_mov_b32 m0, s36
	v_readfirstlane_b32 s36, v138
	global_load_lds_dwordx4 v[226:227], off
	s_mov_b32 m0, s36
	s_nop 0
	global_load_lds_dwordx4 v[132:133], off
	s_waitcnt vmcnt(12)
	s_barrier
	s_waitcnt lgkmcnt(0)
	s_waitcnt lgkmcnt(0)
	v_mfma_f32_16x16x32_bf16 v[92:95], v[210:213], v[178:181], v[92:95]
	v_mfma_f32_16x16x32_bf16 v[88:91], v[218:221], v[178:181], v[88:91]
	v_mfma_f32_16x16x32_bf16 v[84:87], v[210:213], v[186:189], v[84:87]
	v_mfma_f32_16x16x32_bf16 v[80:83], v[218:221], v[186:189], v[80:83]
	v_mfma_f32_16x16x32_bf16 v[76:79], v[210:213], v[194:197], v[76:79]
	v_mfma_f32_16x16x32_bf16 v[72:75], v[218:221], v[194:197], v[72:75]
	v_mfma_f32_16x16x32_bf16 v[68:71], v[210:213], v[202:205], v[68:71]
	v_mfma_f32_16x16x32_bf16 v[64:67], v[218:221], v[202:205], v[64:67]
	v_mfma_f32_16x16x32_bf16 v[92:95], v[214:217], v[182:185], v[92:95]
	v_mfma_f32_16x16x32_bf16 v[88:91], v[222:225], v[182:185], v[88:91]
	v_mfma_f32_16x16x32_bf16 v[84:87], v[214:217], v[190:193], v[84:87]
	v_mfma_f32_16x16x32_bf16 v[80:83], v[222:225], v[190:193], v[80:83]
	v_mfma_f32_16x16x32_bf16 v[76:79], v[214:217], v[198:201], v[76:79]
	v_mfma_f32_16x16x32_bf16 v[72:75], v[222:225], v[198:201], v[72:75]
	v_mfma_f32_16x16x32_bf16 v[68:71], v[214:217], v[206:209], v[68:71]
	v_mfma_f32_16x16x32_bf16 v[64:67], v[222:225], v[206:209], v[64:67]
	s_barrier
	ds_read_b128 v[178:181], v152 offset:49152
	ds_read_b128 v[182:185], v152 offset:50176
	ds_read_b128 v[186:189], v151 offset:49152
	ds_read_b128 v[190:193], v151 offset:50176
	ds_read_b128 v[194:197], v150 offset:49152
	ds_read_b128 v[198:201], v150 offset:50176
	ds_read_b128 v[202:205], v149 offset:49152
	ds_read_b128 v[206:209], v149 offset:50176
	v_readfirstlane_b32 s36, v137
	v_lshl_add_u64 v[226:227], v[130:131], 0, s[60:61]
	s_mov_b32 m0, s36
	v_readfirstlane_b32 s36, v136
	global_load_lds_dwordx4 v[226:227], off
	s_mov_b32 m0, s36
	s_nop 0
	global_load_lds_dwordx4 v[130:131], off
	s_barrier
	s_waitcnt lgkmcnt(0)
	s_waitcnt lgkmcnt(0)
	v_mfma_f32_16x16x32_bf16 v[60:63], v[162:165], v[178:181], v[60:63]
	v_mfma_f32_16x16x32_bf16 v[56:59], v[170:173], v[178:181], v[56:59]
	v_mfma_f32_16x16x32_bf16 v[52:55], v[162:165], v[186:189], v[52:55]
	v_mfma_f32_16x16x32_bf16 v[48:51], v[170:173], v[186:189], v[48:51]
	v_mfma_f32_16x16x32_bf16 v[44:47], v[162:165], v[194:197], v[44:47]
	v_mfma_f32_16x16x32_bf16 v[40:43], v[170:173], v[194:197], v[40:43]
	v_mfma_f32_16x16x32_bf16 v[36:39], v[162:165], v[202:205], v[36:39]
	v_mfma_f32_16x16x32_bf16 v[32:35], v[170:173], v[202:205], v[32:35]
	v_mfma_f32_16x16x32_bf16 v[60:63], v[166:169], v[182:185], v[60:63]
	v_mfma_f32_16x16x32_bf16 v[56:59], v[174:177], v[182:185], v[56:59]
	v_mfma_f32_16x16x32_bf16 v[52:55], v[166:169], v[190:193], v[52:55]
	v_mfma_f32_16x16x32_bf16 v[48:51], v[174:177], v[190:193], v[48:51]
	v_mfma_f32_16x16x32_bf16 v[44:47], v[166:169], v[198:201], v[44:47]
	v_mfma_f32_16x16x32_bf16 v[40:43], v[174:177], v[198:201], v[40:43]
	v_mfma_f32_16x16x32_bf16 v[36:39], v[166:169], v[206:209], v[36:39]
	v_mfma_f32_16x16x32_bf16 v[32:35], v[174:177], v[206:209], v[32:35]
	s_barrier
	v_lshl_add_u64 v[132:133], v[132:133], 0, s[64:65]
	v_readfirstlane_b32 s36, v160
	v_lshl_add_u64 v[164:165], v[132:133], 0, s[22:23]
	s_mov_b32 m0, s36
	v_readfirstlane_b32 s36, v159
	global_load_lds_dwordx4 v[164:165], off
	v_lshl_add_u64 v[164:165], v[132:133], 0, s[24:25]
	s_mov_b32 m0, s36
	s_nop 0
	global_load_lds_dwordx4 v[164:165], off
	s_waitcnt vmcnt(12)
	s_barrier
	v_mfma_f32_16x16x32_bf16 v[28:31], v[210:213], v[178:181], v[28:31]
	v_mfma_f32_16x16x32_bf16 v[24:27], v[218:221], v[178:181], v[24:27]
	v_mfma_f32_16x16x32_bf16 v[20:23], v[210:213], v[186:189], v[20:23]
	v_mfma_f32_16x16x32_bf16 v[16:19], v[218:221], v[186:189], v[16:19]
	v_mfma_f32_16x16x32_bf16 v[12:15], v[210:213], v[194:197], v[12:15]
	v_mfma_f32_16x16x32_bf16 v[8:11], v[218:221], v[194:197], v[8:11]
	v_mfma_f32_16x16x32_bf16 v[4:7], v[210:213], v[202:205], v[4:7]
	v_mfma_f32_16x16x32_bf16 v[0:3], v[218:221], v[202:205], v[0:3]
	v_mfma_f32_16x16x32_bf16 v[28:31], v[214:217], v[182:185], v[28:31]
	v_mfma_f32_16x16x32_bf16 v[24:27], v[222:225], v[182:185], v[24:27]
	v_mfma_f32_16x16x32_bf16 v[20:23], v[214:217], v[190:193], v[20:23]
	v_mfma_f32_16x16x32_bf16 v[16:19], v[222:225], v[190:193], v[16:19]
	v_mfma_f32_16x16x32_bf16 v[12:15], v[214:217], v[198:201], v[12:15]
	v_mfma_f32_16x16x32_bf16 v[8:11], v[222:225], v[198:201], v[8:11]
	v_mfma_f32_16x16x32_bf16 v[4:7], v[214:217], v[206:209], v[4:7]
	v_mfma_f32_16x16x32_bf16 v[0:3], v[222:225], v[206:209], v[0:3]
	v_lshl_add_u64 v[130:131], v[130:131], 0, s[62:63]
	s_cmp_lt_u32 s68, s67
	s_barrier
	s_cbranch_scc1 .LBB0_561
	s_setprio 0
	s_lshl_b32 s36, s86, 5
	s_lshl_b32 s37, s86, 8
	s_and_b32 s36, s36, 0x1800
	s_and_b32 s37, s37, 0x700
	s_or_b32 s96, s37, s36
	s_lshl_b32 s36, s96, 6
	s_add_u32 s36, s70, s36
	s_addc_u32 s37, s71, 0
	s_add_i32 s20, s20, -1
	s_lshl_b64 s[68:69], s[20:21], 20
	v_add_u32_e32 v128, v156, v157
	s_add_u32 s68, s36, s68
	v_or_b32_e32 v128, v128, v155
	s_addc_u32 s69, s37, s69
	v_lshl_add_u64 v[156:157], s[68:69], 0, v[128:129]
	v_readfirstlane_b32 s20, v160
	v_lshl_add_u64 v[206:207], v[156:157], 0, s[4:5]
	s_mov_b32 m0, s20
	v_readfirstlane_b32 s20, v159
	ds_read_b128 v[130:133], v161
	ds_read_b128 v[162:165], v161 offset:1024
	ds_read_b128 v[166:169], v161 offset:2048
	ds_read_b128 v[170:173], v161 offset:3072
	ds_read_b128 v[174:177], v152
	ds_read_b128 v[178:181], v152 offset:1024
	ds_read_b128 v[182:185], v151
	ds_read_b128 v[186:189], v151 offset:1024
	ds_read_b128 v[190:193], v150
	ds_read_b128 v[194:197], v150 offset:1024
	ds_read_b128 v[198:201], v149
	ds_read_b128 v[202:205], v149 offset:1024
	global_load_lds_dwordx4 v[206:207], off
	v_lshl_add_u64 v[156:157], v[156:157], 0, s[6:7]
	s_mov_b32 m0, s20
	s_nop 0
	global_load_lds_dwordx4 v[156:157], off
	s_waitcnt vmcnt(10)
	s_barrier
	s_waitcnt lgkmcnt(0)
	s_setprio 1
	s_waitcnt lgkmcnt(0)
	v_mfma_f32_16x16x32_bf16 v[124:127], v[130:133], v[174:177], v[124:127]
	v_mfma_f32_16x16x32_bf16 v[120:123], v[166:169], v[174:177], v[120:123]
	v_mfma_f32_16x16x32_bf16 v[116:119], v[130:133], v[182:185], v[116:119]
	v_mfma_f32_16x16x32_bf16 v[112:115], v[166:169], v[182:185], v[112:115]
	v_mfma_f32_16x16x32_bf16 v[108:111], v[130:133], v[190:193], v[108:111]
	v_mfma_f32_16x16x32_bf16 v[104:107], v[166:169], v[190:193], v[104:107]
	v_mfma_f32_16x16x32_bf16 v[100:103], v[130:133], v[198:201], v[100:103]
	v_mfma_f32_16x16x32_bf16 v[96:99], v[166:169], v[198:201], v[96:99]
	v_mfma_f32_16x16x32_bf16 v[124:127], v[162:165], v[178:181], v[124:127]
	v_mfma_f32_16x16x32_bf16 v[120:123], v[170:173], v[178:181], v[120:123]
	v_mfma_f32_16x16x32_bf16 v[116:119], v[162:165], v[186:189], v[116:119]
	v_mfma_f32_16x16x32_bf16 v[112:115], v[170:173], v[186:189], v[112:115]
	v_mfma_f32_16x16x32_bf16 v[108:111], v[162:165], v[194:197], v[108:111]
	v_mfma_f32_16x16x32_bf16 v[104:107], v[170:173], v[194:197], v[104:107]
	v_mfma_f32_16x16x32_bf16 v[100:103], v[162:165], v[202:205], v[100:103]
	v_mfma_f32_16x16x32_bf16 v[96:99], v[170:173], v[202:205], v[96:99]
	s_setprio 0
	s_barrier
	ds_read_b128 v[206:209], v158
	ds_read_b128 v[210:213], v158 offset:1024
	ds_read_b128 v[214:217], v158 offset:2048
	ds_read_b128 v[156:159], v158 offset:3072
	s_barrier
	s_waitcnt lgkmcnt(0)
	s_setprio 1
	s_waitcnt lgkmcnt(0)
	v_mfma_f32_16x16x32_bf16 v[92:95], v[206:209], v[174:177], v[92:95]
	v_mfma_f32_16x16x32_bf16 v[88:91], v[214:217], v[174:177], v[88:91]
	v_mfma_f32_16x16x32_bf16 v[84:87], v[206:209], v[182:185], v[84:87]
	v_mfma_f32_16x16x32_bf16 v[80:83], v[214:217], v[182:185], v[80:83]
	v_mfma_f32_16x16x32_bf16 v[76:79], v[206:209], v[190:193], v[76:79]
	v_mfma_f32_16x16x32_bf16 v[72:75], v[214:217], v[190:193], v[72:75]
	v_mfma_f32_16x16x32_bf16 v[68:71], v[206:209], v[198:201], v[68:71]
	v_mfma_f32_16x16x32_bf16 v[64:67], v[214:217], v[198:201], v[64:67]
	v_mfma_f32_16x16x32_bf16 v[174:177], v[210:213], v[178:181], v[92:95]
	v_mfma_f32_16x16x32_bf16 v[178:181], v[156:159], v[178:181], v[88:91]
	v_mfma_f32_16x16x32_bf16 v[182:185], v[210:213], v[186:189], v[84:87]
	v_mfma_f32_16x16x32_bf16 v[186:189], v[156:159], v[186:189], v[80:83]
	v_mfma_f32_16x16x32_bf16 v[190:193], v[210:213], v[194:197], v[76:79]
	v_mfma_f32_16x16x32_bf16 v[194:197], v[156:159], v[194:197], v[72:75]
	v_mfma_f32_16x16x32_bf16 v[198:201], v[210:213], v[202:205], v[68:71]
	v_mfma_f32_16x16x32_bf16 v[202:205], v[156:159], v[202:205], v[64:67]
	s_setprio 0
	s_barrier
	s_nop 0
	ds_read_b128 v[64:67], v152 offset:16384
	ds_read_b128 v[68:71], v152 offset:17408
	ds_read_b128 v[72:75], v151 offset:16384
	ds_read_b128 v[76:79], v151 offset:17408
	ds_read_b128 v[80:83], v150 offset:16384
	ds_read_b128 v[84:87], v150 offset:17408
	ds_read_b128 v[88:91], v149 offset:16384
	ds_read_b128 v[92:95], v149 offset:17408
	s_waitcnt vmcnt(4)
	s_barrier
	s_waitcnt lgkmcnt(0)
	s_setprio 1
	s_waitcnt lgkmcnt(0)
	v_mfma_f32_16x16x32_bf16 v[60:63], v[130:133], v[64:67], v[60:63]
	v_mfma_f32_16x16x32_bf16 v[56:59], v[166:169], v[64:67], v[56:59]
	v_mfma_f32_16x16x32_bf16 v[52:55], v[130:133], v[72:75], v[52:55]
	v_mfma_f32_16x16x32_bf16 v[48:51], v[166:169], v[72:75], v[48:51]
	v_mfma_f32_16x16x32_bf16 v[218:221], v[130:133], v[80:83], v[44:47]
	v_mfma_f32_16x16x32_bf16 v[222:225], v[166:169], v[80:83], v[40:43]
	v_mfma_f32_16x16x32_bf16 v[130:133], v[130:133], v[88:91], v[36:39]
	v_mfma_f32_16x16x32_bf16 v[166:169], v[166:169], v[88:91], v[32:35]
	v_mfma_f32_16x16x32_bf16 v[32:35], v[162:165], v[68:71], v[60:63]
	v_mfma_f32_16x16x32_bf16 v[36:39], v[170:173], v[68:71], v[56:59]
	v_mfma_f32_16x16x32_bf16 v[40:43], v[162:165], v[76:79], v[52:55]
	v_mfma_f32_16x16x32_bf16 v[44:47], v[170:173], v[76:79], v[48:51]
	v_mfma_f32_16x16x32_bf16 v[48:51], v[162:165], v[84:87], v[218:221]
	v_mfma_f32_16x16x32_bf16 v[52:55], v[170:173], v[84:87], v[222:225]
	v_mfma_f32_16x16x32_bf16 v[56:59], v[162:165], v[92:95], v[130:133]
	v_mfma_f32_16x16x32_bf16 v[60:63], v[170:173], v[92:95], v[166:169]
	s_setprio 0
	s_setprio 1
	v_mfma_f32_16x16x32_bf16 v[28:31], v[206:209], v[64:67], v[28:31]
	v_mfma_f32_16x16x32_bf16 v[24:27], v[214:217], v[64:67], v[24:27]
	v_mfma_f32_16x16x32_bf16 v[20:23], v[206:209], v[72:75], v[20:23]
	v_mfma_f32_16x16x32_bf16 v[64:67], v[214:217], v[72:75], v[16:19]
	v_mfma_f32_16x16x32_bf16 v[72:75], v[206:209], v[80:83], v[12:15]
	v_mfma_f32_16x16x32_bf16 v[8:11], v[214:217], v[80:83], v[8:11]
	v_mfma_f32_16x16x32_bf16 v[80:83], v[206:209], v[88:91], v[4:7]
	v_mfma_f32_16x16x32_bf16 v[0:3], v[214:217], v[88:91], v[0:3]
	v_mfma_f32_16x16x32_bf16 v[4:7], v[210:213], v[68:71], v[28:31]
	v_mfma_f32_16x16x32_bf16 v[12:15], v[156:159], v[68:71], v[24:27]
	v_mfma_f32_16x16x32_bf16 v[16:19], v[210:213], v[76:79], v[20:23]
	v_mfma_f32_16x16x32_bf16 v[20:23], v[156:159], v[76:79], v[64:67]
	v_mfma_f32_16x16x32_bf16 v[24:27], v[210:213], v[84:87], v[72:75]
	v_mfma_f32_16x16x32_bf16 v[28:31], v[156:159], v[84:87], v[8:11]
	v_mfma_f32_16x16x32_bf16 v[64:67], v[210:213], v[92:95], v[80:83]
	v_mfma_f32_16x16x32_bf16 v[68:71], v[156:159], v[92:95], v[0:3]
	s_setprio 0
	s_barrier
	ds_read_b128 v[8:11], v154
	ds_read_b128 v[0:3], v154 offset:1024
	ds_read_b128 v[76:79], v154 offset:2048
	ds_read_b128 v[72:75], v154 offset:3072
	ds_read_b128 v[130:133], v152 offset:32768
	ds_read_b128 v[154:157], v152 offset:33792
	ds_read_b128 v[158:161], v151 offset:32768
	ds_read_b128 v[162:165], v151 offset:33792
	ds_read_b128 v[166:169], v150 offset:32768
	ds_read_b128 v[170:173], v150 offset:33792
	ds_read_b128 v[206:209], v149 offset:32768
	ds_read_b128 v[210:213], v149 offset:33792
	s_waitcnt vmcnt(2)
	s_barrier
	s_waitcnt lgkmcnt(0)
	s_setprio 1
	s_waitcnt lgkmcnt(0)
	v_mfma_f32_16x16x32_bf16 v[80:83], v[8:11], v[130:133], v[124:127]
	v_mfma_f32_16x16x32_bf16 v[84:87], v[76:79], v[130:133], v[120:123]
	v_mfma_f32_16x16x32_bf16 v[88:91], v[8:11], v[158:161], v[116:119]
	v_mfma_f32_16x16x32_bf16 v[92:95], v[76:79], v[158:161], v[112:115]
	v_mfma_f32_16x16x32_bf16 v[108:111], v[8:11], v[166:169], v[108:111]
	v_mfma_f32_16x16x32_bf16 v[104:107], v[76:79], v[166:169], v[104:107]
	v_mfma_f32_16x16x32_bf16 v[100:103], v[8:11], v[206:209], v[100:103]
	v_mfma_f32_16x16x32_bf16 v[96:99], v[76:79], v[206:209], v[96:99]
	v_mfma_f32_16x16x32_bf16 v[112:115], v[0:3], v[154:157], v[80:83]
	v_mfma_f32_16x16x32_bf16 v[116:119], v[72:75], v[154:157], v[84:87]
	v_mfma_f32_16x16x32_bf16 v[120:123], v[0:3], v[162:165], v[88:91]
	v_mfma_f32_16x16x32_bf16 v[124:127], v[72:75], v[162:165], v[92:95]
	v_mfma_f32_16x16x32_bf16 v[108:111], v[0:3], v[170:173], v[108:111]
	v_mfma_f32_16x16x32_bf16 v[104:107], v[72:75], v[170:173], v[104:107]
	v_mfma_f32_16x16x32_bf16 v[100:103], v[0:3], v[210:213], v[100:103]
	v_mfma_f32_16x16x32_bf16 v[96:99], v[72:75], v[210:213], v[96:99]
	s_setprio 0
	s_barrier
	ds_read_b128 v[88:91], v153
	ds_read_b128 v[80:83], v153 offset:1024
	ds_read_b128 v[92:95], v153 offset:2048
	ds_read_b128 v[84:87], v153 offset:3072
	s_waitcnt vmcnt(0)
	s_barrier
	s_waitcnt lgkmcnt(0)
	s_setprio 1
	s_waitcnt lgkmcnt(0)
	v_mfma_f32_16x16x32_bf16 v[174:177], v[88:91], v[130:133], v[174:177]
	v_mfma_f32_16x16x32_bf16 v[130:133], v[92:95], v[130:133], v[178:181]
	v_mfma_f32_16x16x32_bf16 v[178:181], v[88:91], v[158:161], v[182:185]
	v_mfma_f32_16x16x32_bf16 v[158:161], v[92:95], v[158:161], v[186:189]
	v_mfma_f32_16x16x32_bf16 v[182:185], v[88:91], v[166:169], v[190:193]
	v_mfma_f32_16x16x32_bf16 v[166:169], v[92:95], v[166:169], v[194:197]
	v_mfma_f32_16x16x32_bf16 v[186:189], v[88:91], v[206:209], v[198:201]
	v_mfma_f32_16x16x32_bf16 v[190:193], v[92:95], v[206:209], v[202:205]
	v_mfma_f32_16x16x32_bf16 v[174:177], v[80:83], v[154:157], v[174:177]
	v_mfma_f32_16x16x32_bf16 v[130:133], v[84:87], v[154:157], v[130:133]
	v_mfma_f32_16x16x32_bf16 v[154:157], v[80:83], v[162:165], v[178:181]
	v_mfma_f32_16x16x32_bf16 v[158:161], v[84:87], v[162:165], v[158:161]
	v_mfma_f32_16x16x32_bf16 v[162:165], v[80:83], v[170:173], v[182:185]
	v_mfma_f32_16x16x32_bf16 v[166:169], v[84:87], v[170:173], v[166:169]
	v_mfma_f32_16x16x32_bf16 v[170:173], v[80:83], v[210:213], v[186:189]
	v_mfma_f32_16x16x32_bf16 v[178:181], v[84:87], v[210:213], v[190:193]
	s_setprio 0
	s_barrier
	v_mbcnt_lo_u32_b32 v128, -1, 0
	v_mbcnt_hi_u32_b32 v128, -1, v128
	v_cvt_pk_bf16_f32 v112, v112, v113
	v_cvt_pk_bf16_f32 v113, v114, v115
	v_cvt_pk_bf16_f32 v114, v116, v117
	v_cvt_pk_bf16_f32 v115, v118, v119
	s_lshl_b32 s89, s66, 9
	v_add_u32_e32 v153, s74, v128
	v_ashrrev_i32_e32 v182, 6, v153
	v_and_b32_e32 v183, 15, v128
	v_and_b32_e32 v184, 48, v128
	v_mul_lo_u32 v185, v182, s79
	v_bfe_u32 v186, v128, 3, 3
	v_lshlrev_b32_e32 v128, 4, v128
	v_add_u32_e32 v185, 0x20000, v185
	v_lshrrev_b32_e32 v153, 2, v153
	v_and_b32_e32 v128, 0x70, v128
	v_mul_u32_u24_e32 v183, 0x90, v183
	v_and_b32_e32 v153, 64, v153
	v_add3_u32 v183, v185, v183, v184
	v_or_b32_e32 v184, v185, v128
	v_or3_b32 v153, s96, v153, v186
	v_mad_u32_u24 v184, v186, s81, v184
	ds_write_b128 v183, v[112:115]
	v_cvt_pk_bf16_f32 v112, v174, v175
	v_cvt_pk_bf16_f32 v113, v176, v177
	v_cvt_pk_bf16_f32 v114, v130, v131
	v_cvt_pk_bf16_f32 v115, v132, v133
	ds_write_b128 v183, v[112:115] offset:64
	v_lshlrev_b32_e32 v182, 7, v182
	ds_read_b128 v[112:115], v184
	v_lshlrev_b32_e32 v116, 12, v153
	v_and_or_b32 v116, v182, s82, v116
	v_or3_b32 v128, v116, s89, v128
	ds_read_b128 v[116:119], v184 offset:1152
	v_lshl_add_u64 v[130:131], s[0:1], 0, v[128:129]
	s_mov_b32 s20, 0x8000
	s_waitcnt lgkmcnt(0)
	global_store_dwordx4 v128, v[112:115], s[0:1]
	v_cvt_pk_bf16_f32 v108, v108, v109
	v_cvt_pk_bf16_f32 v109, v110, v111
	v_cvt_pk_bf16_f32 v110, v104, v105
	v_cvt_pk_bf16_f32 v111, v106, v107
	v_cvt_pk_bf16_f32 v104, v162, v163
	s_nop 1
	v_add_co_u32_e32 v112, vcc, s20, v130
	v_cvt_pk_bf16_f32 v114, v124, v125
	v_cvt_pk_bf16_f32 v115, v126, v127
	v_cvt_pk_bf16_f32 v105, v164, v165
	v_cvt_pk_bf16_f32 v106, v166, v167
	s_nop 1
	v_addc_co_u32_e32 v113, vcc, 0, v131, vcc
	global_store_dwordx4 v[112:113], v[116:119], off
	v_cvt_pk_bf16_f32 v112, v120, v121
	v_cvt_pk_bf16_f32 v113, v122, v123
	ds_write_b128 v183, v[112:115]
	v_cvt_pk_bf16_f32 v112, v154, v155
	v_cvt_pk_bf16_f32 v113, v156, v157
	v_cvt_pk_bf16_f32 v114, v158, v159
	v_cvt_pk_bf16_f32 v115, v160, v161
	ds_write_b128 v183, v[112:115] offset:64
	ds_read_b128 v[112:115], v184
	ds_read_b128 v[116:119], v184 offset:1152
	v_add_co_u32_e32 v120, vcc, s76, v130
	ds_write_b128 v183, v[108:111]
	v_cvt_pk_bf16_f32 v107, v168, v169
	ds_write_b128 v183, v[104:107] offset:64
	v_addc_co_u32_e32 v121, vcc, 0, v131, vcc
	ds_read_b128 v[104:107], v184
	ds_read_b128 v[108:111], v184 offset:1152
	s_waitcnt lgkmcnt(0)
	global_store_dwordx4 v[120:121], v[112:115], off
	v_cvt_pk_bf16_f32 v100, v100, v101
	v_cvt_pk_bf16_f32 v101, v102, v103
	v_cvt_pk_bf16_f32 v102, v96, v97
	v_cvt_pk_bf16_f32 v103, v98, v99
	ds_write_b128 v183, v[100:103]
	s_nop 0
	v_add_co_u32_e32 v112, vcc, s77, v130
	v_cvt_pk_bf16_f32 v96, v170, v171
	v_cvt_pk_bf16_f32 v97, v172, v173
	v_cvt_pk_bf16_f32 v98, v178, v179
	v_cvt_pk_bf16_f32 v99, v180, v181
	s_nop 1
	v_addc_co_u32_e32 v113, vcc, 0, v131, vcc
	global_store_dwordx4 v[112:113], v[116:119], off
	v_add_co_u32_e32 v112, vcc, s80, v130
	ds_write_b128 v183, v[96:99] offset:64
	s_nop 0
	v_addc_co_u32_e32 v113, vcc, 0, v131, vcc
	ds_read_b128 v[96:99], v184
	ds_read_b128 v[100:103], v184 offset:1152
	global_store_dwordx4 v[112:113], v[104:107], off
	s_nop 1
	v_add_co_u32_e32 v104, vcc, s83, v130
	s_nop 1
	v_addc_co_u32_e32 v105, vcc, 0, v131, vcc
	global_store_dwordx4 v[104:105], v[108:111], off
	v_add_co_u32_e32 v104, vcc, s85, v130
	s_nop 1
	v_addc_co_u32_e32 v105, vcc, 0, v131, vcc
	s_waitcnt lgkmcnt(0)
	global_store_dwordx4 v[104:105], v[96:99], off
	s_nop 1
	v_add_co_u32_e32 v96, vcc, s87, v130
	s_nop 1
	v_addc_co_u32_e32 v97, vcc, 0, v131, vcc
	global_store_dwordx4 v[96:97], v[100:103], off
	ds_read_b128 v[96:99], v152 offset:49152
	ds_read_b128 v[100:103], v152 offset:50176
	ds_read_b128 v[104:107], v151 offset:49152
	ds_read_b128 v[108:111], v151 offset:50176
	ds_read_b128 v[112:115], v150 offset:49152
	ds_read_b128 v[116:119], v150 offset:50176
	ds_read_b128 v[120:123], v149 offset:49152
	ds_read_b128 v[124:127], v149 offset:50176
	s_barrier
	s_waitcnt lgkmcnt(0)
	s_setprio 1
	s_waitcnt lgkmcnt(0)
	v_mfma_f32_16x16x32_bf16 v[32:35], v[8:11], v[96:99], v[32:35]
	v_mfma_f32_16x16x32_bf16 v[36:39], v[76:79], v[96:99], v[36:39]
	v_mfma_f32_16x16x32_bf16 v[40:43], v[8:11], v[104:107], v[40:43]
	v_mfma_f32_16x16x32_bf16 v[130:133], v[76:79], v[104:107], v[44:47]
	v_mfma_f32_16x16x32_bf16 v[150:153], v[8:11], v[112:115], v[48:51]
	v_mfma_f32_16x16x32_bf16 v[52:55], v[76:79], v[112:115], v[52:55]
	v_mfma_f32_16x16x32_bf16 v[8:11], v[8:11], v[120:123], v[56:59]
	v_mfma_f32_16x16x32_bf16 v[60:63], v[76:79], v[120:123], v[60:63]
	v_mfma_f32_16x16x32_bf16 v[56:59], v[0:3], v[100:103], v[32:35]
	v_mfma_f32_16x16x32_bf16 v[48:51], v[72:75], v[100:103], v[36:39]
	v_mfma_f32_16x16x32_bf16 v[44:47], v[0:3], v[108:111], v[40:43]
	v_mfma_f32_16x16x32_bf16 v[40:43], v[72:75], v[108:111], v[130:133]
	v_mfma_f32_16x16x32_bf16 v[36:39], v[0:3], v[116:119], v[150:153]
	v_mfma_f32_16x16x32_bf16 v[32:35], v[72:75], v[116:119], v[52:55]
	v_mfma_f32_16x16x32_bf16 v[8:11], v[0:3], v[124:127], v[8:11]
	v_mfma_f32_16x16x32_bf16 v[0:3], v[72:75], v[124:127], v[60:63]
	s_setprio 0
	s_setprio 1
	v_mfma_f32_16x16x32_bf16 v[4:7], v[88:91], v[96:99], v[4:7]
	v_mfma_f32_16x16x32_bf16 v[12:15], v[92:95], v[96:99], v[12:15]
	v_mfma_f32_16x16x32_bf16 v[16:19], v[88:91], v[104:107], v[16:19]
	v_mfma_f32_16x16x32_bf16 v[20:23], v[92:95], v[104:107], v[20:23]
	v_mfma_f32_16x16x32_bf16 v[72:75], v[88:91], v[112:115], v[24:27]
	v_mfma_f32_16x16x32_bf16 v[76:79], v[92:95], v[112:115], v[28:31]
	v_mfma_f32_16x16x32_bf16 v[64:67], v[88:91], v[120:123], v[64:67]
	v_mfma_f32_16x16x32_bf16 v[68:71], v[92:95], v[120:123], v[68:71]
	v_mfma_f32_16x16x32_bf16 v[60:63], v[80:83], v[100:103], v[4:7]
	v_mfma_f32_16x16x32_bf16 v[52:55], v[84:87], v[100:103], v[12:15]
	v_mfma_f32_16x16x32_bf16 v[28:31], v[80:83], v[108:111], v[16:19]
	v_mfma_f32_16x16x32_bf16 v[24:27], v[84:87], v[108:111], v[20:23]
	v_mfma_f32_16x16x32_bf16 v[20:23], v[80:83], v[116:119], v[72:75]
	v_mfma_f32_16x16x32_bf16 v[16:19], v[84:87], v[116:119], v[76:79]
	v_mfma_f32_16x16x32_bf16 v[12:15], v[80:83], v[124:127], v[64:67]
	v_mfma_f32_16x16x32_bf16 v[4:7], v[84:87], v[124:127], v[68:71]
	s_setprio 0
	v_cmp_gt_u32_e32 vcc, s88, v135
	s_barrier
	s_and_saveexec_b64 s[66:67], vcc
	s_cbranch_execz .LBB0_564
	s_barrier
